# static young-half priority: per-segment s_setprio flips deleted in all GEMM K-loops, one s_setprio 1 for waves 4-7 per GEMM phase
# baseline (speedup 1.0000x reference)
; #define PG8_STAGE(bufoff, gbase, voff) do { _Pragma("unroll") for (int _i = 0; _i < 2; ++_i) \
;         __builtin_amdgcn_global_load_lds((const unsigned*)((const char*)(gbase) + (voff)[_i]), (PG8_LAS unsigned*)(lds + (bufoff) + ldsw + _i * 8192), 16, 0, 0); } while (0)
; #define PG8_WAIT_V(n) asm volatile("s_waitcnt vmcnt(" #n ")" ::: "memory")
; #define PG8_BAR __builtin_amdgcn_s_barrier()
; template <class Epi, class Sched, bool ALIGN_EPI = false, bool SP2 = false>
; __device__ __forceinline__ void gemm_phase(PG8_LAS unsigned char* lds, const Gemm g, const Sched& S, const Epi& E) {
;     ...
;     const int wid = __builtin_amdgcn_readfirstlane(tid >> 6), lane = tid & 63, wr = wid >> 2, wc = wid & 3, fr = lane & 15, fq = lane >> 4;
;     const int K = g.K, nt = K / BK;
;     unsigned voffA[2], voffB[2];
; #pragma unroll
;     for (int i = 0; i < 2; ++i) { int R, C; stage_rc(tid * 16 + i * 8192, R, C); const int Rb = Epi::PERM ? ((R & ~31) + perm32(R & 31)) : R;
;         voffA[i] = (unsigned)(R * K + C) * 2u; voffB[i] = (unsigned)(Rb * K + C) * 2u; }
;     const size_t kstep = (size_t)(BK * 2);
;     const size_t hstep = (size_t)HALF * K * 2;
;     const size_t tstep = 2 * hstep;
;     const unsigned ldsw = (unsigned)wid * 1024u;
;     const int aoff = lds_byte(wr * 64 + fr, fq * 8), boff = lds_byte(wc * 32 + fr, fq * 8);
;     ...
;         PG8_STAGE(PG8_SB(0, 0), cB, voffB); PG8_STAGE(PG8_SB(0, 1), cB + hstep, voffB); PG8_STAGE(PG8_SA(0, 0), cA, voffA); PG8_STAGE(PG8_SA(0, 1), cA + hstep, voffA);
;         if (wr == 1) PG8_BAR;
;         PG8_WAIT_V(2); PG8_BAR;
;         PG8_STAGE(PG8_SB(1, 0), cB + kstep, voffB); PG8_STAGE(PG8_SA(1, 0), cA + kstep, voffA); PG8_STAGE(PG8_SB(1, 1), cB + hstep + kstep, voffB);
;         PG8_WAIT_V(6); PG8_BAR;
.LBB0_186:
	s_lshl_b32 s4, s4, 5
	s_and_b32 s14, s4, 0x60
	s_mov_b64 s[4:5], 0x80
	s_add_i32 m0, s21, 0x18000
	v_lshl_add_u64 v[6:7], v[6:7], 0, s[4:5]
	s_lshl_b32 s7, s6, 13
	s_lshl_b32 s15, s14, 7
	s_waitcnt vmcnt(2)
	s_barrier
	global_load_lds_dwordx4 v[6:7], off
	v_lshl_add_u64 v[4:5], v[4:5], 0, s[4:5]
	s_add_i32 m0, s21, 0x1a000
	s_add_i32 s42, s21, 0x8000
	s_add_i32 s43, s21, 0xa000
	global_load_lds_dwordx4 v[4:5], off
	v_lshl_add_u64 v[0:1], v[0:1], 0, s[4:5]
	s_mov_b32 m0, s42
	s_add_u32 s8, s24, 0x40080
	global_load_lds_dwordx4 v[0:1], off
	v_lshl_add_u64 v[0:1], v[2:3], 0, s[4:5]
	s_mov_b32 m0, s43
	s_addc_u32 s9, s25, 0
	global_load_lds_dwordx4 v[0:1], off
	s_add_i32 m0, s21, 0x1c000
	v_lshl_add_u64 v[0:1], s[8:9], 0, v[132:133]
	global_load_lds_dwordx4 v[0:1], off
	v_lshl_add_u64 v[0:1], s[8:9], 0, v[128:129]
	s_add_i32 m0, s21, 0x1e000
	s_cmpk_lt_u32 s1, 0x100
	global_load_lds_dwordx4 v[0:1], off
	v_lshrrev_b32_e32 v1, 1, v9
	v_and_b32_e32 v1, 24, v1
	v_and_b32_e32 v0, 15, v9
	v_lshlrev_b32_e32 v2, 1, v1
	v_lshl_or_b32 v144, s6, 6, v0
	v_lshl_or_b32 v0, v0, 6, v2
	v_lshlrev_b32_e32 v2, 2, v9
	v_and_b32_e32 v2, 32, v2
	v_bitop3_b32 v3, v0, s7, v2 bitop3:0xde
	v_bitop3_b32 v145, v0, s15, v2 bitop3:0xde
	v_lshlrev_b32_e32 v0, 14, v13
	v_and_b32_e32 v0, 0xffff8000, v0
	v_or_b32_e32 v146, s14, v1
	v_lshl_add_u32 v0, v12, 11, v0
	v_and_b32_e32 v1, 1, v13
	v_lshl_or_b32 v0, v1, 6, v0
	v_lshl_add_u32 v136, v14, 1, v0
	v_lshlrev_b32_e32 v0, 14, v8
	v_and_b32_e32 v0, 0xffff8000, v0
	s_waitcnt vmcnt(0)
	v_lshl_add_u32 v0, v10, 11, v0
	v_and_b32_e32 v1, 1, v8
	s_sext_i32_i8 s49, s0
	s_cselect_b64 s[6:7], -1, 0
	v_readlane_b32 s0, v235, 6
	v_lshl_or_b32 v0, v1, 6, v0
	s_add_i32 s46, 0, 0x10000
	s_add_i32 s47, 0, 0x14000
	s_ashr_i32 s44, s0, 31
	s_mov_b32 s45, s0
	v_mov_b32_e32 v137, v133
	v_lshl_add_u32 v138, v11, 1, v0
	v_mov_b32_e32 v139, v133
	v_mov_b64_e32 v[140:141], 0xb00
	v_mov_b64_e32 v[142:143], 0xaff
	v_add_u32_e32 v147, s46, v145
	v_add_u32_e32 v148, s47, v145
	v_add_u32_e32 v149, 0, v3
	s_movk_i32 s48, 0x1600
	s_barrier
	v_readlane_b32 s1, v235, 7
	s_mov_b32 s98, 0
	v_readfirstlane_b32 s99, v189
	s_nop 0
	s_lshr_b32 s99, s99, 6
	s_cmp_ge_u32 s99, 4
	s_cbranch_scc0 .Lprio_189
	s_setprio 1
.Lprio_189:
	s_branch .LBB0_189
.LBB0_187:
	s_mov_b64 s[0:1], 0

; #define PG8_STAGE(bufoff, gbase, voff) do { _Pragma("unroll") for (int _i = 0; _i < 2; ++_i) \
;         __builtin_amdgcn_global_load_lds((const unsigned*)((const char*)(gbase) + (voff)[_i]), (PG8_LAS unsigned*)(lds + (bufoff) + ldsw + _i * 8192), 16, 0, 0); } while (0)
; #define PG8_LDA(dst, b, h) do { _Pragma("unroll") for (int m = 0; m < 4; ++m) _Pragma("unroll") for (int k = 0; k < 2; ++k) dst[m][k] = *(const PG8_LAS bf16x8*)(lds + PG8_SA(b, h) + aoff + m * 2048 + k * 1024); } while (0)
; #define PG8_SCHED __builtin_amdgcn_sched_barrier(0)
; __device__ __forceinline__ float silu_f(float x) { return x * sigmoid_f(x); }
; template <class Epi, class Sched, bool ALIGN_EPI = false, bool SP2 = false>
; __device__ __forceinline__ void gemm_phase(PG8_LAS unsigned char* lds, const Gemm g, const Sched& S, const Epi& E) {
;     ...
;         const bool has_next = S.next(ui + 1, nxt);
;         const char* nA = has_next ? (const char*)g.A + (size_t)nxt.pm * tstep : cA; const char* nB = has_next ? (const char*)g.Bt + (size_t)nxt.pn * tstep : cB;
;         for (int t = 0; t < nt; t += 2) {
;             const bool last = (t == nt - 2);
;             const char* a1 = cA + (size_t)(t + 1) * kstep;
;             const char* a2 = last ? nA : cA + (size_t)(t + 2) * kstep; const char* b2 = last ? nB : cB + (size_t)(t + 2) * kstep;
;             const char* a3 = a2 + kstep; const char* b3 = b2 + kstep;
;             if (last && has_next) S.a_ready(nxt);
;             if constexpr (SP2) {
;             PG8_LDB(B0, 0, 0); PG8_LDB(B1, 0, 1); PG8_SCHED; PG8_LDA(At, 0, 0); PG8_STAGE(PG8_SA(1, 1), a1 + hstep, voffA);
;     __device__ __forceinline__ void operator()(const f32x4 (&acc)[2][2][4][2], const pg8::Unit& u, int wr, int wc, int fr, int fq) const {
;     ...
;             for (int m = 0; m < 4; ++m) {
;                 const int row = row0 + ai * 128 + m * 16;
;                 const float rs = sumsq ? rsqrtf(sumsq[row] * (1.f / 1024.f) + EPS) : 1.f;
;                 float o[8];
; #pragma unroll
;                 for (int n = 0; n < 2; ++n)
; #pragma unroll
;                     for (int e = 0; e < 4; ++e) { const float g = acc[ai][0][m][n][e] * rs, up = acc[ai][1][m][n][e] * rs; o[4 * n + e] = silu_f(g) * up; }
;                 u32x4 w; w.x = pk2(o[0], o[1]); w.y = pk2(o[2], o[3]); w.z = pk2(o[4], o[5]); w.w = pk2(o[6], o[7]);
;                 *(u32x4*)(H + (size_t)row * DFF + col) = w;
.LBB0_191:
	s_ashr_i32 s15, s14, 31
	s_lshl_b64 s[16:17], s[14:15], 19
	v_readlane_b32 s18, v235, 31
	v_readlane_b32 s19, v235, 32
	s_add_u32 s16, s18, s16
	s_addc_u32 s17, s19, s17
	s_and_b64 s[18:19], s[0:1], exec
	s_cselect_b32 s15, s17, s23
	s_cselect_b32 s50, s16, s22
	s_ashr_i32 s9, s8, 31
	s_lshl_b64 s[18:19], s[8:9], 19
	s_add_u32 s18, s33, s18
	s_addc_u32 s19, s34, s19
	s_and_b64 s[30:31], s[0:1], exec
	s_cselect_b32 s9, s19, s25
	s_cselect_b32 s51, s18, s24
	s_add_u32 s22, s22, 0x40080
	s_addc_u32 s23, s23, 0
	s_add_u32 s52, s24, 0x100
	s_addc_u32 s53, s25, 0
	s_mov_b32 s54, -2
	s_cmp_eq_u32 s98, 0
	s_cbranch_scc1 .Lp1_plain
	ds_read_b128 v[150:153], v147
	ds_read_b128 v[154:157], v147 offset:1024
	ds_read_b128 v[158:161], v147 offset:2048
	ds_read_b128 v[162:165], v147 offset:3072
	ds_read_b128 v[166:169], v148
	ds_read_b128 v[170:173], v148 offset:1024
	ds_read_b128 v[174:177], v148 offset:2048
	ds_read_b128 v[178:181], v148 offset:3072
	s_add_u32 s24, s22, 0xfffc0080
	s_addc_u32 s25, s23, -1
	s_cmp_eq_u32 s54, 12
	s_cselect_b32 s31, s15, s25
	s_cselect_b32 s30, s50, s24
	s_cselect_b32 s25, s9, s53
	s_cselect_b32 s24, s51, s52
	v_lshl_add_u64 v[186:187], s[22:23], 0, v[136:137]
	s_add_i32 m0, s21, 0xc000
	ds_read_b128 v[182:185], v149
	ds_read_b128 v[192:195], v149 offset:1024
	ds_read_b128 v[196:199], v149 offset:2048
	ds_read_b128 v[200:203], v149 offset:3072
	ds_read_b128 v[204:207], v149 offset:4096
	ds_read_b128 v[208:211], v149 offset:5120
	ds_read_b128 v[212:215], v149 offset:6144
	ds_read_b128 v[216:219], v149 offset:7168
	global_load_lds_dwordx4 v[186:187], off
	v_lshl_add_u64 v[186:187], s[22:23], 0, v[138:139]
	s_add_i32 m0, s21, 0xe000
	s_nop 0
	global_load_lds_dwordx4 v[186:187], off
	s_nop 1
	v_add_f32_e32 v64, 1.0, v70
	v_rcp_f32_e32 v64, v64
	v_add_f32_e32 v65, 1.0, v71
	v_rcp_f32_e32 v65, v65
	v_add_u32_e32 v66, 0x80, v228
	v_mul_f32_e32 v60, v60, v64
	v_mul_f32_e32 v52, v60, v52
	v_mul_f32_e32 v60, v61, v65
	v_mul_f32_e32 v61, 0xbfb8aa3b, v62
	v_exp_f32_e32 v61, v61
	v_mul_f32_e32 v64, 0xbfb8aa3b, v63
	v_exp_f32_e32 v64, v64
	v_mul_f32_e32 v53, v60, v53
	v_add_f32_e32 v60, 1.0, v61
	v_rcp_f32_e32 v60, v60
	v_add_f32_e32 v61, 1.0, v64
	v_mul_f32_e32 v64, 0xbfb8aa3b, v56
	v_rcp_f32_e32 v61, v61
	v_exp_f32_e32 v64, v64
	v_mul_f32_e32 v60, v62, v60
	v_mul_f32_e32 v54, v60, v54
	v_mul_f32_e32 v60, v63, v61
	v_add_f32_e32 v61, 1.0, v64
	v_rcp_f32_e32 v61, v61
	v_mul_f32_e32 v62, 0xbfb8aa3b, v57
	v_exp_f32_e32 v62, v62
	v_mul_f32_e32 v55, v60, v55
	v_mul_f32_e32 v56, v56, v61
	v_mul_f32_e32 v56, v56, v48
	v_add_f32_e32 v48, 1.0, v62
	v_mul_f32_e32 v60, 0xbfb8aa3b, v58
	v_rcp_f32_e32 v48, v48
	v_exp_f32_e32 v60, v60
	v_mul_f32_e32 v61, 0xbfb8aa3b, v59
	v_exp_f32_e32 v61, v61
	v_mul_f32_e32 v48, v57, v48
	v_add_f32_e32 v57, 1.0, v60
	v_rcp_f32_e32 v57, v57
	v_add_f32_e32 v60, 1.0, v61
	v_rcp_f32_e32 v60, v60
	v_mul_f32_e32 v61, v48, v49
	v_mul_f32_e32 v48, v58, v57
	v_mul_f32_e32 v57, v48, v50
	v_mul_f32_e32 v48, v59, v60
	v_mul_f32_e32 v51, v48, v51
	v_cvt_pk_bf16_f32 v48, v52, v53
	v_cvt_pk_bf16_f32 v49, v54, v55
	v_mul_f32_e32 v54, 0xbfb8aa3b, v44
	v_exp_f32_e32 v54, v54
	v_mul_f32_e32 v55, 0xbfb8aa3b, v45
	v_exp_f32_e32 v55, v55
	v_mad_i64_i32 v[52:53], s[100:101], v66, s48, v[112:113]
	v_lshl_add_u64 v[52:53], v[52:53], 0, v[114:115]
	v_cvt_pk_bf16_f32 v50, v56, v61
	v_cvt_pk_bf16_f32 v51, v57, v51
	global_store_dwordx4 v[52:53], v[48:51], off
	s_nop 1
	v_add_f32_e32 v48, 1.0, v54
	v_rcp_f32_e32 v48, v48
	v_add_f32_e32 v49, 1.0, v55
	v_rcp_f32_e32 v49, v49
	v_add_u32_e32 v50, 0x90, v228
	v_mul_f32_e32 v44, v44, v48
	v_mul_f32_e32 v36, v44, v36
	v_mul_f32_e32 v44, v45, v49
	v_mul_f32_e32 v45, 0xbfb8aa3b, v46
	v_exp_f32_e32 v45, v45
	v_mul_f32_e32 v48, 0xbfb8aa3b, v47
	v_exp_f32_e32 v48, v48
	v_mul_f32_e32 v37, v44, v37
	v_add_f32_e32 v44, 1.0, v45
	v_rcp_f32_e32 v44, v44
	v_add_f32_e32 v45, 1.0, v48
	v_mul_f32_e32 v48, 0xbfb8aa3b, v40
	v_rcp_f32_e32 v45, v45
	v_exp_f32_e32 v48, v48
	v_mul_f32_e32 v44, v46, v44
	v_mul_f32_e32 v38, v44, v38
	v_mul_f32_e32 v44, v47, v45
	v_add_f32_e32 v45, 1.0, v48
	v_rcp_f32_e32 v45, v45
	v_mul_f32_e32 v46, 0xbfb8aa3b, v41
	v_exp_f32_e32 v46, v46
	v_mul_f32_e32 v39, v44, v39
	v_mul_f32_e32 v40, v40, v45
	v_mul_f32_e32 v40, v40, v32
	v_add_f32_e32 v32, 1.0, v46
	v_mul_f32_e32 v44, 0xbfb8aa3b, v42
	v_rcp_f32_e32 v32, v32
	v_exp_f32_e32 v44, v44
	v_mul_f32_e32 v45, 0xbfb8aa3b, v43
	v_exp_f32_e32 v45, v45
	v_mul_f32_e32 v32, v41, v32
	v_add_f32_e32 v41, 1.0, v44
	v_rcp_f32_e32 v41, v41
	v_add_f32_e32 v44, 1.0, v45
	v_rcp_f32_e32 v44, v44
	v_mul_f32_e32 v45, v32, v33
	v_mul_f32_e32 v32, v42, v41
	v_mul_f32_e32 v41, v32, v34
	v_mul_f32_e32 v32, v43, v44
	v_mul_f32_e32 v35, v32, v35
	v_cvt_pk_bf16_f32 v32, v36, v37
	v_cvt_pk_bf16_f32 v33, v38, v39
	v_mul_f32_e32 v38, 0xbfb8aa3b, v28
	v_exp_f32_e32 v38, v38
	v_mul_f32_e32 v39, 0xbfb8aa3b, v29
	v_exp_f32_e32 v39, v39
	v_mad_i64_i32 v[36:37], s[100:101], v50, s48, v[112:113]
	v_lshl_add_u64 v[36:37], v[36:37], 0, v[114:115]
	v_cvt_pk_bf16_f32 v34, v40, v45
	v_cvt_pk_bf16_f32 v35, v41, v35
	global_store_dwordx4 v[36:37], v[32:35], off
	s_nop 1
	v_add_f32_e32 v32, 1.0, v38
	v_rcp_f32_e32 v32, v32
	v_add_f32_e32 v33, 1.0, v39
	v_rcp_f32_e32 v33, v33
	v_add_u32_e32 v34, 0xa0, v228
	v_mul_f32_e32 v28, v28, v32
	v_mul_f32_e32 v20, v28, v20
	v_mul_f32_e32 v28, v29, v33
	v_mul_f32_e32 v29, 0xbfb8aa3b, v30
	v_exp_f32_e32 v29, v29
	v_mul_f32_e32 v32, 0xbfb8aa3b, v31
	v_exp_f32_e32 v32, v32
	v_mul_f32_e32 v21, v28, v21
	v_add_f32_e32 v28, 1.0, v29
	v_rcp_f32_e32 v28, v28
	v_add_f32_e32 v29, 1.0, v32
	v_mul_f32_e32 v32, 0xbfb8aa3b, v24
	v_rcp_f32_e32 v29, v29
; #define PG8_STAGE(bufoff, gbase, voff) do { _Pragma("unroll") for (int _i = 0; _i < 2; ++_i) \
;         __builtin_amdgcn_global_load_lds((const unsigned*)((const char*)(gbase) + (voff)[_i]), (PG8_LAS unsigned*)(lds + (bufoff) + ldsw + _i * 8192), 16, 0, 0); } while (0)
; #define PG8_LDA(dst, b, h) do { _Pragma("unroll") for (int m = 0; m < 4; ++m) _Pragma("unroll") for (int k = 0; k < 2; ++k) dst[m][k] = *(const PG8_LAS bf16x8*)(lds + PG8_SA(b, h) + aoff + m * 2048 + k * 1024); } while (0)
; #define PG8_LDB(dst, b, h) do { _Pragma("unroll") for (int n = 0; n < 2; ++n) _Pragma("unroll") for (int k = 0; k < 2; ++k) dst[n][k] = *(const PG8_LAS bf16x8*)(lds + PG8_SB(b, h) + boff + n * 2048 + k * 1024); } while (0)
; #define PG8_MMA(ai, bj, At, Bt) do { __builtin_amdgcn_s_setprio(1); _Pragma("unroll") for (int m = 0; m < 4; ++m) _Pragma("unroll") for (int n = 0; n < 2; ++n) _Pragma("unroll") for (int k = 0; k < 2; ++k) \
;         acc[ai][bj][m][n] = __builtin_amdgcn_mfma_f32_16x16x32_bf16(Bt[n][k], At[m][k], acc[ai][bj][m][n], 0, 0, 0); __builtin_amdgcn_s_setprio(0); } while (0)
; #define PG8_WAIT_V(n) asm volatile("s_waitcnt vmcnt(" #n ")" ::: "memory")
; template <class Epi, class Sched, bool ALIGN_EPI = false, bool SP2 = false>
; __device__ __forceinline__ void gemm_phase(PG8_LAS unsigned char* lds, const Gemm g, const Sched& S, const Epi& E) {
;     ...
;             PG8_LDB(B0, 0, 0); PG8_LDB(B1, 0, 1); PG8_SCHED; PG8_LDA(At, 0, 0); PG8_STAGE(PG8_SA(1, 1), a1 + hstep, voffA);
;             PG8_WAIT_V(8); PG8_WAIT_L(0); PG8_BAR; PG8_MMA(0, 0, At, B0); PG8_MMA(0, 1, At, B1); PG8_BAR; PG8_SCHED;
;             PG8_LDA(At, 0, 1); PG8_STAGE(PG8_SB(0, 0), b2, voffB); PG8_STAGE(PG8_SB(0, 1), b2 + hstep, voffB); PG8_STAGE(PG8_SA(0, 0), a2, voffA);
;             PG8_WAIT_V(8); PG8_WAIT_L(0); PG8_BAR; PG8_MMA(1, 0, At, B0); PG8_MMA(1, 1, At, B1); PG8_BAR; PG8_SCHED;
;     __device__ __forceinline__ void operator()(const f32x4 (&acc)[2][2][4][2], const pg8::Unit& u, int wr, int wc, int fr, int fq) const {
;     ...
;                     for (int e = 0; e < 4; ++e) { const float g = acc[ai][0][m][n][e] * rs, up = acc[ai][1][m][n][e] * rs; o[4 * n + e] = silu_f(g) * up; }
;                 u32x4 w; w.x = pk2(o[0], o[1]); w.y = pk2(o[2], o[3]); w.z = pk2(o[4], o[5]); w.w = pk2(o[6], o[7]);
;                 *(u32x4*)(H + (size_t)row * DFF + col) = w;
	v_exp_f32_e32 v32, v32
	v_mul_f32_e32 v28, v30, v28
	v_mul_f32_e32 v22, v28, v22
	v_mul_f32_e32 v28, v31, v29
	v_add_f32_e32 v29, 1.0, v32
	v_rcp_f32_e32 v29, v29
	v_mul_f32_e32 v30, 0xbfb8aa3b, v25
	v_exp_f32_e32 v30, v30
	v_mul_f32_e32 v23, v28, v23
	v_mul_f32_e32 v24, v24, v29
	v_mul_f32_e32 v24, v24, v16
	v_add_f32_e32 v16, 1.0, v30
	v_mul_f32_e32 v28, 0xbfb8aa3b, v26
	v_rcp_f32_e32 v16, v16
	v_exp_f32_e32 v28, v28
	v_mul_f32_e32 v29, 0xbfb8aa3b, v27
	v_exp_f32_e32 v29, v29
	v_mul_f32_e32 v16, v25, v16
	v_add_f32_e32 v25, 1.0, v28
	v_rcp_f32_e32 v25, v25
	v_add_f32_e32 v28, 1.0, v29
	v_rcp_f32_e32 v28, v28
	v_mul_f32_e32 v29, v16, v17
	v_mul_f32_e32 v16, v26, v25
	v_mul_f32_e32 v25, v16, v18
	v_mul_f32_e32 v16, v27, v28
	v_mul_f32_e32 v19, v16, v19
	v_cvt_pk_bf16_f32 v16, v20, v21
	v_cvt_pk_bf16_f32 v17, v22, v23
	v_mul_f32_e32 v22, 0xbfb8aa3b, v12
	v_exp_f32_e32 v22, v22
	v_mul_f32_e32 v23, 0xbfb8aa3b, v13
	v_exp_f32_e32 v23, v23
	v_mad_i64_i32 v[20:21], s[100:101], v34, s48, v[112:113]
	v_lshl_add_u64 v[20:21], v[20:21], 0, v[114:115]
	v_cvt_pk_bf16_f32 v18, v24, v29
	v_cvt_pk_bf16_f32 v19, v25, v19
	global_store_dwordx4 v[20:21], v[16:19], off
	s_nop 1
	v_add_f32_e32 v16, 1.0, v22
	v_rcp_f32_e32 v16, v16
	v_add_f32_e32 v17, 1.0, v23
	v_rcp_f32_e32 v17, v17
	v_add_u32_e32 v18, 0xb0, v228
	v_mul_f32_e32 v12, v12, v16
	v_mul_f32_e32 v4, v12, v4
	v_mul_f32_e32 v12, v13, v17
	v_mul_f32_e32 v13, 0xbfb8aa3b, v14
	v_exp_f32_e32 v13, v13
	v_mul_f32_e32 v16, 0xbfb8aa3b, v15
	v_exp_f32_e32 v16, v16
	v_mul_f32_e32 v5, v12, v5
	v_add_f32_e32 v12, 1.0, v13
	v_rcp_f32_e32 v12, v12
	v_add_f32_e32 v13, 1.0, v16
	v_mul_f32_e32 v16, 0xbfb8aa3b, v8
	v_rcp_f32_e32 v13, v13
	v_exp_f32_e32 v16, v16
	v_mul_f32_e32 v12, v14, v12
	v_mul_f32_e32 v6, v12, v6
	v_mul_f32_e32 v12, v15, v13
	v_add_f32_e32 v13, 1.0, v16
	v_rcp_f32_e32 v13, v13
	v_mul_f32_e32 v14, 0xbfb8aa3b, v9
	v_exp_f32_e32 v14, v14
	v_mul_f32_e32 v7, v12, v7
	v_mul_f32_e32 v8, v8, v13
	v_mul_f32_e32 v8, v8, v0
	v_add_f32_e32 v0, 1.0, v14
	v_mul_f32_e32 v12, 0xbfb8aa3b, v10
	v_rcp_f32_e32 v0, v0
	v_exp_f32_e32 v12, v12
	v_mul_f32_e32 v13, 0xbfb8aa3b, v11
	v_exp_f32_e32 v13, v13
	v_mul_f32_e32 v0, v9, v0
	v_add_f32_e32 v9, 1.0, v12
	v_rcp_f32_e32 v9, v9
	v_add_f32_e32 v12, 1.0, v13
	v_rcp_f32_e32 v12, v12
	v_mul_f32_e32 v13, v0, v1
	v_mul_f32_e32 v0, v10, v9
	v_mul_f32_e32 v9, v0, v2
	v_mul_f32_e32 v0, v11, v12
	v_mul_f32_e32 v3, v0, v3
	v_cvt_pk_bf16_f32 v0, v4, v5
	v_mad_i64_i32 v[4:5], s[100:101], v18, s48, v[112:113]
	v_lshl_add_u64 v[4:5], v[4:5], 0, v[114:115]
	v_cvt_pk_bf16_f32 v1, v6, v7
	v_cvt_pk_bf16_f32 v2, v8, v13
	v_cvt_pk_bf16_f32 v3, v9, v3
	global_store_dwordx4 v[4:5], v[0:3], off
	s_waitcnt vmcnt(16)
	s_waitcnt lgkmcnt(0)
	s_barrier
	v_mfma_f32_16x16x32_bf16 v[124:127], v[150:153], v[182:185], 0
	v_mfma_f32_16x16x32_bf16 v[120:123], v[158:161], v[182:185], 0
	v_mfma_f32_16x16x32_bf16 v[108:111], v[150:153], v[196:199], 0
	v_mfma_f32_16x16x32_bf16 v[104:107], v[158:161], v[196:199], 0
	v_mfma_f32_16x16x32_bf16 v[92:95], v[150:153], v[204:207], 0
	v_mfma_f32_16x16x32_bf16 v[88:91], v[158:161], v[204:207], 0
	v_mfma_f32_16x16x32_bf16 v[76:79], v[150:153], v[212:215], 0
	v_mfma_f32_16x16x32_bf16 v[72:75], v[158:161], v[212:215], 0
	v_mfma_f32_16x16x32_bf16 v[124:127], v[154:157], v[192:195], v[124:127]
	v_mfma_f32_16x16x32_bf16 v[120:123], v[162:165], v[192:195], v[120:123]
	v_mfma_f32_16x16x32_bf16 v[108:111], v[154:157], v[200:203], v[108:111]
	v_mfma_f32_16x16x32_bf16 v[104:107], v[162:165], v[200:203], v[104:107]
	v_mfma_f32_16x16x32_bf16 v[92:95], v[154:157], v[208:211], v[92:95]
	v_mfma_f32_16x16x32_bf16 v[88:91], v[162:165], v[208:211], v[88:91]
	v_mfma_f32_16x16x32_bf16 v[76:79], v[154:157], v[216:219], v[76:79]
	v_mfma_f32_16x16x32_bf16 v[72:75], v[162:165], v[216:219], v[72:75]
	v_mfma_f32_16x16x32_bf16 v[116:119], v[166:169], v[182:185], 0
	v_mfma_f32_16x16x32_bf16 v[112:115], v[174:177], v[182:185], 0
	v_mfma_f32_16x16x32_bf16 v[100:103], v[166:169], v[196:199], 0
	v_mfma_f32_16x16x32_bf16 v[96:99], v[174:177], v[196:199], 0
	v_mfma_f32_16x16x32_bf16 v[84:87], v[166:169], v[204:207], 0
	v_mfma_f32_16x16x32_bf16 v[80:83], v[174:177], v[204:207], 0
	v_mfma_f32_16x16x32_bf16 v[68:71], v[166:169], v[212:215], 0
	v_mfma_f32_16x16x32_bf16 v[64:67], v[174:177], v[212:215], 0
	v_mfma_f32_16x16x32_bf16 v[116:119], v[170:173], v[192:195], v[116:119]
	v_mfma_f32_16x16x32_bf16 v[112:115], v[178:181], v[192:195], v[112:115]
	v_mfma_f32_16x16x32_bf16 v[100:103], v[170:173], v[200:203], v[100:103]
	v_mfma_f32_16x16x32_bf16 v[96:99], v[178:181], v[200:203], v[96:99]
	v_mfma_f32_16x16x32_bf16 v[84:87], v[170:173], v[208:211], v[84:87]
	v_mfma_f32_16x16x32_bf16 v[80:83], v[178:181], v[208:211], v[80:83]
	v_mfma_f32_16x16x32_bf16 v[68:71], v[170:173], v[216:219], v[68:71]
	v_mfma_f32_16x16x32_bf16 v[64:67], v[178:181], v[216:219], v[64:67]
	s_barrier
	s_add_i32 s55, s46, s35
	v_lshl_add_u64 v[186:187], s[24:25], 0, v[132:133]
	s_mov_b32 m0, s55
	ds_read_b128 v[182:185], v149 offset:16384
	ds_read_b128 v[192:195], v149 offset:17408
	ds_read_b128 v[196:199], v149 offset:18432
	ds_read_b128 v[200:203], v149 offset:19456
	ds_read_b128 v[204:207], v149 offset:20480
	ds_read_b128 v[208:211], v149 offset:21504
	ds_read_b128 v[212:215], v149 offset:22528
	ds_read_b128 v[216:219], v149 offset:23552
	global_load_lds_dwordx4 v[186:187], off
	s_add_i32 m0, s55, 0x2000
	s_add_u32 s56, s24, 0x40000
	v_lshl_add_u64 v[220:221], s[24:25], 0, v[128:129]
	s_addc_u32 s57, s25, 0
	s_add_i32 s55, s47, s35
	global_load_lds_dwordx4 v[220:221], off
	v_lshl_add_u64 v[222:223], s[56:57], 0, v[132:133]
	s_mov_b32 m0, s55
	v_lshl_add_u64 v[224:225], s[30:31], 0, v[130:131]
	global_load_lds_dwordx4 v[222:223], off
	v_lshl_add_u64 v[222:223], s[56:57], 0, v[128:129]
	s_add_i32 m0, s55, 0x2000
	s_nop 0
	global_load_lds_dwordx4 v[222:223], off
	v_lshl_add_u64 v[222:223], s[30:31], 0, v[134:135]
	s_mov_b32 m0, s21
	s_nop 0
	global_load_lds_dwordx4 v[222:223], off
	s_mov_b32 m0, s38
	s_nop 0
	global_load_lds_dwordx4 v[224:225], off
	s_waitcnt vmcnt(16)
	s_waitcnt lgkmcnt(0)
	s_barrier
; #define PG8_STAGE(bufoff, gbase, voff) do { _Pragma("unroll") for (int _i = 0; _i < 2; ++_i) \
;         __builtin_amdgcn_global_load_lds((const unsigned*)((const char*)(gbase) + (voff)[_i]), (PG8_LAS unsigned*)(lds + (bufoff) + ldsw + _i * 8192), 16, 0, 0); } while (0)
; #define PG8_LDA(dst, b, h) do { _Pragma("unroll") for (int m = 0; m < 4; ++m) _Pragma("unroll") for (int k = 0; k < 2; ++k) dst[m][k] = *(const PG8_LAS bf16x8*)(lds + PG8_SA(b, h) + aoff + m * 2048 + k * 1024); } while (0)
; #define PG8_LDB(dst, b, h) do { _Pragma("unroll") for (int n = 0; n < 2; ++n) _Pragma("unroll") for (int k = 0; k < 2; ++k) dst[n][k] = *(const PG8_LAS bf16x8*)(lds + PG8_SB(b, h) + boff + n * 2048 + k * 1024); } while (0)
; #define PG8_MMA(ai, bj, At, Bt) do { __builtin_amdgcn_s_setprio(1); _Pragma("unroll") for (int m = 0; m < 4; ++m) _Pragma("unroll") for (int n = 0; n < 2; ++n) _Pragma("unroll") for (int k = 0; k < 2; ++k) \
;         acc[ai][bj][m][n] = __builtin_amdgcn_mfma_f32_16x16x32_bf16(Bt[n][k], At[m][k], acc[ai][bj][m][n], 0, 0, 0); __builtin_amdgcn_s_setprio(0); } while (0)
; #define PG8_WAIT_V(n) asm volatile("s_waitcnt vmcnt(" #n ")" ::: "memory")
; #define PG8_WAIT_L(n) asm volatile("s_waitcnt lgkmcnt(" #n ")" ::: "memory")
; #define PG8_BAR __builtin_amdgcn_s_barrier()
; #define PG8_SCHED __builtin_amdgcn_sched_barrier(0)
; template <class Epi, class Sched, bool ALIGN_EPI = false, bool SP2 = false>
; __device__ __forceinline__ void gemm_phase(PG8_LAS unsigned char* lds, const Gemm g, const Sched& S, const Epi& E) {
;     ...
;             PG8_WAIT_V(8); PG8_WAIT_L(0); PG8_BAR; PG8_MMA(0, 0, At, B0); PG8_MMA(0, 1, At, B1); PG8_BAR; PG8_SCHED;
;             PG8_LDA(At, 0, 1); PG8_STAGE(PG8_SB(0, 0), b2, voffB); PG8_STAGE(PG8_SB(0, 1), b2 + hstep, voffB); PG8_STAGE(PG8_SA(0, 0), a2, voffA);
;             PG8_WAIT_V(8); PG8_WAIT_L(0); PG8_BAR; PG8_MMA(1, 0, At, B0); PG8_MMA(1, 1, At, B1); PG8_BAR; PG8_SCHED;
;             PG8_LDB(B0, 1, 0); PG8_LDB(B1, 1, 1); PG8_SCHED; PG8_LDA(At, 1, 0); PG8_STAGE(PG8_SA(0, 1), a2 + hstep, voffA);
;             PG8_WAIT_V(8); PG8_WAIT_L(0); PG8_BAR; PG8_MMA(0, 0, At, B0); PG8_MMA(0, 1, At, B1); PG8_BAR; PG8_SCHED;
	v_mfma_f32_16x16x32_bf16 v[60:63], v[150:153], v[182:185], 0
	v_mfma_f32_16x16x32_bf16 v[56:59], v[158:161], v[182:185], 0
	v_mfma_f32_16x16x32_bf16 v[44:47], v[150:153], v[196:199], 0
	v_mfma_f32_16x16x32_bf16 v[40:43], v[158:161], v[196:199], 0
	v_mfma_f32_16x16x32_bf16 v[28:31], v[150:153], v[204:207], 0
	v_mfma_f32_16x16x32_bf16 v[24:27], v[158:161], v[204:207], 0
	v_mfma_f32_16x16x32_bf16 v[12:15], v[150:153], v[212:215], 0
	v_mfma_f32_16x16x32_bf16 v[8:11], v[158:161], v[212:215], 0
	v_mfma_f32_16x16x32_bf16 v[60:63], v[154:157], v[192:195], v[60:63]
	v_mfma_f32_16x16x32_bf16 v[56:59], v[162:165], v[192:195], v[56:59]
	v_mfma_f32_16x16x32_bf16 v[44:47], v[154:157], v[200:203], v[44:47]
	v_mfma_f32_16x16x32_bf16 v[40:43], v[162:165], v[200:203], v[40:43]
	v_mfma_f32_16x16x32_bf16 v[28:31], v[154:157], v[208:211], v[28:31]
	v_mfma_f32_16x16x32_bf16 v[24:27], v[162:165], v[208:211], v[24:27]
	v_mfma_f32_16x16x32_bf16 v[12:15], v[154:157], v[216:219], v[12:15]
	v_mfma_f32_16x16x32_bf16 v[8:11], v[162:165], v[216:219], v[8:11]
	v_mfma_f32_16x16x32_bf16 v[52:55], v[166:169], v[182:185], 0
	v_mfma_f32_16x16x32_bf16 v[48:51], v[174:177], v[182:185], 0
	v_mfma_f32_16x16x32_bf16 v[36:39], v[166:169], v[196:199], 0
	v_mfma_f32_16x16x32_bf16 v[32:35], v[174:177], v[196:199], 0
	v_mfma_f32_16x16x32_bf16 v[20:23], v[166:169], v[204:207], 0
	v_mfma_f32_16x16x32_bf16 v[16:19], v[174:177], v[204:207], 0
	v_mfma_f32_16x16x32_bf16 v[4:7], v[166:169], v[212:215], 0
	v_mfma_f32_16x16x32_bf16 v[0:3], v[174:177], v[212:215], 0
	v_mfma_f32_16x16x32_bf16 v[52:55], v[170:173], v[192:195], v[52:55]
	v_mfma_f32_16x16x32_bf16 v[48:51], v[178:181], v[192:195], v[48:51]
	v_mfma_f32_16x16x32_bf16 v[36:39], v[170:173], v[200:203], v[36:39]
	v_mfma_f32_16x16x32_bf16 v[32:35], v[178:181], v[200:203], v[32:35]
	v_mfma_f32_16x16x32_bf16 v[20:23], v[170:173], v[208:211], v[20:23]
	v_mfma_f32_16x16x32_bf16 v[16:19], v[178:181], v[208:211], v[16:19]
	v_mfma_f32_16x16x32_bf16 v[4:7], v[170:173], v[216:219], v[4:7]
	v_mfma_f32_16x16x32_bf16 v[0:3], v[178:181], v[216:219], v[0:3]
	s_barrier
	s_add_i32 s55, 0, 0x18000
	s_add_i32 s56, 0, 0x1c000
	v_add_u32_e32 v162, s55, v145
	v_add_u32_e32 v178, s56, v145
	ds_read_b128 v[150:153], v162
	ds_read_b128 v[154:157], v162 offset:1024
	ds_read_b128 v[158:161], v162 offset:2048
	ds_read_b128 v[162:165], v162 offset:3072
	ds_read_b128 v[166:169], v178
	ds_read_b128 v[170:173], v178 offset:1024
	ds_read_b128 v[174:177], v178 offset:2048
	ds_read_b128 v[178:181], v178 offset:3072
	s_add_u32 s30, s30, 0x40000
	s_addc_u32 s31, s31, 0
	s_mov_b32 m0, s39
	v_lshl_add_u64 v[226:227], s[30:31], 0, v[134:135]
	ds_read_b128 v[182:185], v149 offset:32768
	ds_read_b128 v[192:195], v149 offset:33792
	ds_read_b128 v[196:199], v149 offset:34816
	ds_read_b128 v[200:203], v149 offset:35840
	ds_read_b128 v[204:207], v149 offset:36864
	ds_read_b128 v[208:211], v149 offset:37888
	ds_read_b128 v[212:215], v149 offset:38912
	ds_read_b128 v[216:219], v149 offset:39936
	global_load_lds_dwordx4 v[226:227], off
	v_lshl_add_u64 v[226:227], s[30:31], 0, v[130:131]
	s_mov_b32 m0, s40
	s_nop 0
	global_load_lds_dwordx4 v[226:227], off
	s_waitcnt vmcnt(8)
	s_waitcnt lgkmcnt(0)
	s_barrier
	v_mfma_f32_16x16x32_bf16 v[124:127], v[150:153], v[182:185], v[124:127]
	v_mfma_f32_16x16x32_bf16 v[120:123], v[158:161], v[182:185], v[120:123]
	v_mfma_f32_16x16x32_bf16 v[108:111], v[150:153], v[196:199], v[108:111]
	v_mfma_f32_16x16x32_bf16 v[104:107], v[158:161], v[196:199], v[104:107]
	v_mfma_f32_16x16x32_bf16 v[92:95], v[150:153], v[204:207], v[92:95]
	v_mfma_f32_16x16x32_bf16 v[88:91], v[158:161], v[204:207], v[88:91]
	v_mfma_f32_16x16x32_bf16 v[76:79], v[150:153], v[212:215], v[76:79]
	v_mfma_f32_16x16x32_bf16 v[72:75], v[158:161], v[212:215], v[72:75]
	v_mfma_f32_16x16x32_bf16 v[124:127], v[154:157], v[192:195], v[124:127]
	v_mfma_f32_16x16x32_bf16 v[120:123], v[162:165], v[192:195], v[120:123]
	v_mfma_f32_16x16x32_bf16 v[108:111], v[154:157], v[200:203], v[108:111]
	v_mfma_f32_16x16x32_bf16 v[104:107], v[162:165], v[200:203], v[104:107]
	v_mfma_f32_16x16x32_bf16 v[92:95], v[154:157], v[208:211], v[92:95]
	v_mfma_f32_16x16x32_bf16 v[88:91], v[162:165], v[208:211], v[88:91]
	v_mfma_f32_16x16x32_bf16 v[76:79], v[154:157], v[216:219], v[76:79]
	v_mfma_f32_16x16x32_bf16 v[72:75], v[162:165], v[216:219], v[72:75]
	v_mfma_f32_16x16x32_bf16 v[116:119], v[166:169], v[182:185], v[116:119]
	v_mfma_f32_16x16x32_bf16 v[112:115], v[174:177], v[182:185], v[112:115]
	v_mfma_f32_16x16x32_bf16 v[100:103], v[166:169], v[196:199], v[100:103]
	v_mfma_f32_16x16x32_bf16 v[96:99], v[174:177], v[196:199], v[96:99]
	v_mfma_f32_16x16x32_bf16 v[84:87], v[166:169], v[204:207], v[84:87]
	v_mfma_f32_16x16x32_bf16 v[80:83], v[174:177], v[204:207], v[80:83]
	v_mfma_f32_16x16x32_bf16 v[68:71], v[166:169], v[212:215], v[68:71]
	v_mfma_f32_16x16x32_bf16 v[64:67], v[174:177], v[212:215], v[64:67]
	v_mfma_f32_16x16x32_bf16 v[116:119], v[170:173], v[192:195], v[116:119]
	v_mfma_f32_16x16x32_bf16 v[112:115], v[178:181], v[192:195], v[112:115]
	v_mfma_f32_16x16x32_bf16 v[100:103], v[170:173], v[200:203], v[100:103]
	v_mfma_f32_16x16x32_bf16 v[96:99], v[178:181], v[200:203], v[96:99]
	v_mfma_f32_16x16x32_bf16 v[84:87], v[170:173], v[208:211], v[84:87]
	v_mfma_f32_16x16x32_bf16 v[80:83], v[178:181], v[208:211], v[80:83]
	v_mfma_f32_16x16x32_bf16 v[68:71], v[170:173], v[216:219], v[68:71]
	v_mfma_f32_16x16x32_bf16 v[64:67], v[178:181], v[216:219], v[64:67]
	s_barrier
; #define PG8_STAGE(bufoff, gbase, voff) do { _Pragma("unroll") for (int _i = 0; _i < 2; ++_i) \
;         __builtin_amdgcn_global_load_lds((const unsigned*)((const char*)(gbase) + (voff)[_i]), (PG8_LAS unsigned*)(lds + (bufoff) + ldsw + _i * 8192), 16, 0, 0); } while (0)
; #define PG8_LDA(dst, b, h) do { _Pragma("unroll") for (int m = 0; m < 4; ++m) _Pragma("unroll") for (int k = 0; k < 2; ++k) dst[m][k] = *(const PG8_LAS bf16x8*)(lds + PG8_SA(b, h) + aoff + m * 2048 + k * 1024); } while (0)
; #define PG8_LDB(dst, b, h) do { _Pragma("unroll") for (int n = 0; n < 2; ++n) _Pragma("unroll") for (int k = 0; k < 2; ++k) dst[n][k] = *(const PG8_LAS bf16x8*)(lds + PG8_SB(b, h) + boff + n * 2048 + k * 1024); } while (0)
; #define PG8_MMA(ai, bj, At, Bt) do { __builtin_amdgcn_s_setprio(1); _Pragma("unroll") for (int m = 0; m < 4; ++m) _Pragma("unroll") for (int n = 0; n < 2; ++n) _Pragma("unroll") for (int k = 0; k < 2; ++k) \
;         acc[ai][bj][m][n] = __builtin_amdgcn_mfma_f32_16x16x32_bf16(Bt[n][k], At[m][k], acc[ai][bj][m][n], 0, 0, 0); __builtin_amdgcn_s_setprio(0); } while (0)
; #define PG8_WAIT_V(n) asm volatile("s_waitcnt vmcnt(" #n ")" ::: "memory")
; #define PG8_WAIT_L(n) asm volatile("s_waitcnt lgkmcnt(" #n ")" ::: "memory")
; #define PG8_BAR __builtin_amdgcn_s_barrier()
; template <class Epi, class Sched, bool ALIGN_EPI = false, bool SP2 = false>
; __device__ __forceinline__ void gemm_phase(PG8_LAS unsigned char* lds, const Gemm g, const Sched& S, const Epi& E) {
;     ...
;             PG8_LDB(B0, 0, 0); PG8_LDB(B1, 0, 1); PG8_SCHED; PG8_LDA(At, 0, 0); PG8_STAGE(PG8_SA(1, 1), a1 + hstep, voffA);
;             PG8_WAIT_V(8); PG8_WAIT_L(0); PG8_BAR; PG8_MMA(0, 0, At, B0); PG8_MMA(0, 1, At, B1); PG8_BAR; PG8_SCHED;
;             PG8_LDA(At, 0, 1); PG8_STAGE(PG8_SB(0, 0), b2, voffB); PG8_STAGE(PG8_SB(0, 1), b2 + hstep, voffB); PG8_STAGE(PG8_SA(0, 0), a2, voffA);
;             PG8_WAIT_V(8); PG8_WAIT_L(0); PG8_BAR; PG8_MMA(1, 0, At, B0); PG8_MMA(1, 1, At, B1); PG8_BAR; PG8_SCHED;
;     ...
;             PG8_WAIT_V(8); PG8_WAIT_L(0); PG8_BAR; PG8_MMA(0, 0, At, B0); PG8_MMA(0, 1, At, B1); PG8_BAR; PG8_SCHED;
;             PG8_LDA(At, 1, 1); PG8_STAGE(PG8_SB(1, 0), b3, voffB); PG8_STAGE(PG8_SB(1, 1), b3 + hstep, voffB); PG8_STAGE(PG8_SA(1, 0), a3, voffA);
;             PG8_WAIT_V(8); PG8_WAIT_L(0); PG8_BAR; PG8_MMA(1, 0, At, B0); PG8_MMA(1, 1, At, B1); PG8_BAR; PG8_SCHED;
	s_add_i32 s30, s55, s35
	v_lshl_add_u64 v[186:187], v[186:187], 0, s[4:5]
	s_mov_b32 m0, s30
	ds_read_b128 v[182:185], v149 offset:49152
	ds_read_b128 v[192:195], v149 offset:50176
	ds_read_b128 v[196:199], v149 offset:51200
	ds_read_b128 v[200:203], v149 offset:52224
	ds_read_b128 v[204:207], v149 offset:53248
	ds_read_b128 v[208:211], v149 offset:54272
	ds_read_b128 v[212:215], v149 offset:55296
	ds_read_b128 v[216:219], v149 offset:56320
	global_load_lds_dwordx4 v[186:187], off
	s_add_i32 m0, s30, 0x2000
	s_add_u32 s24, s24, 0x40080
	v_lshl_add_u64 v[186:187], v[220:221], 0, s[4:5]
	s_addc_u32 s25, s25, 0
	s_add_i32 s30, s56, s35
	global_load_lds_dwordx4 v[186:187], off
	v_lshl_add_u64 v[186:187], s[24:25], 0, v[132:133]
	s_mov_b32 m0, s30
	s_nop 0
	global_load_lds_dwordx4 v[186:187], off
	v_lshl_add_u64 v[186:187], s[24:25], 0, v[128:129]
	s_add_i32 m0, s30, 0x2000
	s_nop 0
	global_load_lds_dwordx4 v[186:187], off
	v_lshl_add_u64 v[186:187], v[222:223], 0, s[4:5]
	s_mov_b32 m0, s42
	s_nop 0
	global_load_lds_dwordx4 v[186:187], off
	v_lshl_add_u64 v[186:187], v[224:225], 0, s[4:5]
	s_mov_b32 m0, s43
	s_nop 0
	global_load_lds_dwordx4 v[186:187], off
	s_waitcnt vmcnt(8)
	s_waitcnt lgkmcnt(0)
	s_barrier
	v_mfma_f32_16x16x32_bf16 v[60:63], v[150:153], v[182:185], v[60:63]
	v_mfma_f32_16x16x32_bf16 v[56:59], v[158:161], v[182:185], v[56:59]
	v_mfma_f32_16x16x32_bf16 v[44:47], v[150:153], v[196:199], v[44:47]
	v_mfma_f32_16x16x32_bf16 v[40:43], v[158:161], v[196:199], v[40:43]
	v_mfma_f32_16x16x32_bf16 v[28:31], v[150:153], v[204:207], v[28:31]
	v_mfma_f32_16x16x32_bf16 v[24:27], v[158:161], v[204:207], v[24:27]
	v_mfma_f32_16x16x32_bf16 v[12:15], v[150:153], v[212:215], v[12:15]
	v_mfma_f32_16x16x32_bf16 v[8:11], v[158:161], v[212:215], v[8:11]
	v_mfma_f32_16x16x32_bf16 v[60:63], v[154:157], v[192:195], v[60:63]
	v_mfma_f32_16x16x32_bf16 v[56:59], v[162:165], v[192:195], v[56:59]
	v_mfma_f32_16x16x32_bf16 v[44:47], v[154:157], v[200:203], v[44:47]
	v_mfma_f32_16x16x32_bf16 v[40:43], v[162:165], v[200:203], v[40:43]
	v_mfma_f32_16x16x32_bf16 v[28:31], v[154:157], v[208:211], v[28:31]
	v_mfma_f32_16x16x32_bf16 v[24:27], v[162:165], v[208:211], v[24:27]
	v_mfma_f32_16x16x32_bf16 v[12:15], v[154:157], v[216:219], v[12:15]
	v_mfma_f32_16x16x32_bf16 v[8:11], v[162:165], v[216:219], v[8:11]
	v_mfma_f32_16x16x32_bf16 v[52:55], v[166:169], v[182:185], v[52:55]
	v_mfma_f32_16x16x32_bf16 v[48:51], v[174:177], v[182:185], v[48:51]
	v_mfma_f32_16x16x32_bf16 v[36:39], v[166:169], v[196:199], v[36:39]
	v_mfma_f32_16x16x32_bf16 v[32:35], v[174:177], v[196:199], v[32:35]
	v_mfma_f32_16x16x32_bf16 v[20:23], v[166:169], v[204:207], v[20:23]
	v_mfma_f32_16x16x32_bf16 v[16:19], v[174:177], v[204:207], v[16:19]
	v_mfma_f32_16x16x32_bf16 v[4:7], v[166:169], v[212:215], v[4:7]
	v_mfma_f32_16x16x32_bf16 v[0:3], v[174:177], v[212:215], v[0:3]
	v_mfma_f32_16x16x32_bf16 v[52:55], v[170:173], v[192:195], v[52:55]
	v_mfma_f32_16x16x32_bf16 v[48:51], v[178:181], v[192:195], v[48:51]
	v_mfma_f32_16x16x32_bf16 v[36:39], v[170:173], v[200:203], v[36:39]
	v_mfma_f32_16x16x32_bf16 v[32:35], v[178:181], v[200:203], v[32:35]
	v_mfma_f32_16x16x32_bf16 v[20:23], v[170:173], v[208:211], v[20:23]
	v_mfma_f32_16x16x32_bf16 v[16:19], v[178:181], v[208:211], v[16:19]
	v_mfma_f32_16x16x32_bf16 v[4:7], v[170:173], v[216:219], v[4:7]
	v_mfma_f32_16x16x32_bf16 v[0:3], v[178:181], v[216:219], v[0:3]
	s_barrier
	s_add_i32 s54, s54, 2
	s_add_u32 s22, s22, 0x100
	s_addc_u32 s23, s23, 0
	s_add_u32 s52, s52, 0x100
	s_addc_u32 s53, s53, 0
	s_branch .LBB0_192
.Lp1_plain:
	ds_read_b128 v[150:153], v147
	ds_read_b128 v[154:157], v147 offset:1024
	ds_read_b128 v[158:161], v147 offset:2048
	ds_read_b128 v[162:165], v147 offset:3072
	ds_read_b128 v[166:169], v148
	ds_read_b128 v[170:173], v148 offset:1024
	ds_read_b128 v[174:177], v148 offset:2048
	ds_read_b128 v[178:181], v148 offset:3072
	s_add_u32 s24, s22, 0xfffc0080
	s_addc_u32 s25, s23, -1
	s_cmp_eq_u32 s54, 12
	s_cselect_b32 s31, s15, s25
	s_cselect_b32 s30, s50, s24
	s_cselect_b32 s25, s9, s53
	s_cselect_b32 s24, s51, s52
	v_lshl_add_u64 v[186:187], s[22:23], 0, v[136:137]
	s_add_i32 m0, s21, 0xc000
	ds_read_b128 v[182:185], v149
	ds_read_b128 v[192:195], v149 offset:1024
	ds_read_b128 v[196:199], v149 offset:2048
	ds_read_b128 v[200:203], v149 offset:3072
	ds_read_b128 v[204:207], v149 offset:4096
	ds_read_b128 v[208:211], v149 offset:5120
	ds_read_b128 v[212:215], v149 offset:6144
	ds_read_b128 v[216:219], v149 offset:7168
	global_load_lds_dwordx4 v[186:187], off
	v_lshl_add_u64 v[186:187], s[22:23], 0, v[138:139]
	s_add_i32 m0, s21, 0xe000
	s_nop 0
	global_load_lds_dwordx4 v[186:187], off
	s_waitcnt vmcnt(16)
	s_waitcnt lgkmcnt(0)
	s_barrier
; #define PG8_STAGE(bufoff, gbase, voff) do { _Pragma("unroll") for (int _i = 0; _i < 2; ++_i) \
;         __builtin_amdgcn_global_load_lds((const unsigned*)((const char*)(gbase) + (voff)[_i]), (PG8_LAS unsigned*)(lds + (bufoff) + ldsw + _i * 8192), 16, 0, 0); } while (0)
; #define PG8_LDA(dst, b, h) do { _Pragma("unroll") for (int m = 0; m < 4; ++m) _Pragma("unroll") for (int k = 0; k < 2; ++k) dst[m][k] = *(const PG8_LAS bf16x8*)(lds + PG8_SA(b, h) + aoff + m * 2048 + k * 1024); } while (0)
; #define PG8_LDB(dst, b, h) do { _Pragma("unroll") for (int n = 0; n < 2; ++n) _Pragma("unroll") for (int k = 0; k < 2; ++k) dst[n][k] = *(const PG8_LAS bf16x8*)(lds + PG8_SB(b, h) + boff + n * 2048 + k * 1024); } while (0)
; #define PG8_MMA(ai, bj, At, Bt) do { __builtin_amdgcn_s_setprio(1); _Pragma("unroll") for (int m = 0; m < 4; ++m) _Pragma("unroll") for (int n = 0; n < 2; ++n) _Pragma("unroll") for (int k = 0; k < 2; ++k) \
;         acc[ai][bj][m][n] = __builtin_amdgcn_mfma_f32_16x16x32_bf16(Bt[n][k], At[m][k], acc[ai][bj][m][n], 0, 0, 0); __builtin_amdgcn_s_setprio(0); } while (0)
; #define PG8_WAIT_V(n) asm volatile("s_waitcnt vmcnt(" #n ")" ::: "memory")
; #define PG8_WAIT_L(n) asm volatile("s_waitcnt lgkmcnt(" #n ")" ::: "memory")
; #define PG8_BAR __builtin_amdgcn_s_barrier()
; #define PG8_SCHED __builtin_amdgcn_sched_barrier(0)
; template <class Epi, class Sched, bool ALIGN_EPI = false, bool SP2 = false>
; __device__ __forceinline__ void gemm_phase(PG8_LAS unsigned char* lds, const Gemm g, const Sched& S, const Epi& E) {
;     ...
;             PG8_LDB(B0, 0, 0); PG8_LDB(B1, 0, 1); PG8_SCHED; PG8_LDA(At, 0, 0); PG8_STAGE(PG8_SA(1, 1), a1 + hstep, voffA);
;             PG8_WAIT_V(8); PG8_WAIT_L(0); PG8_BAR; PG8_MMA(0, 0, At, B0); PG8_MMA(0, 1, At, B1); PG8_BAR; PG8_SCHED;
;             PG8_LDA(At, 0, 1); PG8_STAGE(PG8_SB(0, 0), b2, voffB); PG8_STAGE(PG8_SB(0, 1), b2 + hstep, voffB); PG8_STAGE(PG8_SA(0, 0), a2, voffA);
;             PG8_WAIT_V(8); PG8_WAIT_L(0); PG8_BAR; PG8_MMA(1, 0, At, B0); PG8_MMA(1, 1, At, B1); PG8_BAR; PG8_SCHED;
	v_mfma_f32_16x16x32_bf16 v[124:127], v[150:153], v[182:185], 0
	v_mfma_f32_16x16x32_bf16 v[120:123], v[158:161], v[182:185], 0
	v_mfma_f32_16x16x32_bf16 v[108:111], v[150:153], v[196:199], 0
	v_mfma_f32_16x16x32_bf16 v[104:107], v[158:161], v[196:199], 0
	v_mfma_f32_16x16x32_bf16 v[92:95], v[150:153], v[204:207], 0
	v_mfma_f32_16x16x32_bf16 v[88:91], v[158:161], v[204:207], 0
	v_mfma_f32_16x16x32_bf16 v[76:79], v[150:153], v[212:215], 0
	v_mfma_f32_16x16x32_bf16 v[72:75], v[158:161], v[212:215], 0
	v_mfma_f32_16x16x32_bf16 v[124:127], v[154:157], v[192:195], v[124:127]
	v_mfma_f32_16x16x32_bf16 v[120:123], v[162:165], v[192:195], v[120:123]
	v_mfma_f32_16x16x32_bf16 v[108:111], v[154:157], v[200:203], v[108:111]
	v_mfma_f32_16x16x32_bf16 v[104:107], v[162:165], v[200:203], v[104:107]
	v_mfma_f32_16x16x32_bf16 v[92:95], v[154:157], v[208:211], v[92:95]
	v_mfma_f32_16x16x32_bf16 v[88:91], v[162:165], v[208:211], v[88:91]
	v_mfma_f32_16x16x32_bf16 v[76:79], v[154:157], v[216:219], v[76:79]
	v_mfma_f32_16x16x32_bf16 v[72:75], v[162:165], v[216:219], v[72:75]
	v_mfma_f32_16x16x32_bf16 v[116:119], v[166:169], v[182:185], 0
	v_mfma_f32_16x16x32_bf16 v[112:115], v[174:177], v[182:185], 0
	v_mfma_f32_16x16x32_bf16 v[100:103], v[166:169], v[196:199], 0
	v_mfma_f32_16x16x32_bf16 v[96:99], v[174:177], v[196:199], 0
	v_mfma_f32_16x16x32_bf16 v[84:87], v[166:169], v[204:207], 0
	v_mfma_f32_16x16x32_bf16 v[80:83], v[174:177], v[204:207], 0
	v_mfma_f32_16x16x32_bf16 v[68:71], v[166:169], v[212:215], 0
	v_mfma_f32_16x16x32_bf16 v[64:67], v[174:177], v[212:215], 0
	v_mfma_f32_16x16x32_bf16 v[116:119], v[170:173], v[192:195], v[116:119]
	v_mfma_f32_16x16x32_bf16 v[112:115], v[178:181], v[192:195], v[112:115]
	v_mfma_f32_16x16x32_bf16 v[100:103], v[170:173], v[200:203], v[100:103]
	v_mfma_f32_16x16x32_bf16 v[96:99], v[178:181], v[200:203], v[96:99]
	v_mfma_f32_16x16x32_bf16 v[84:87], v[170:173], v[208:211], v[84:87]
	v_mfma_f32_16x16x32_bf16 v[80:83], v[178:181], v[208:211], v[80:83]
	v_mfma_f32_16x16x32_bf16 v[68:71], v[170:173], v[216:219], v[68:71]
	v_mfma_f32_16x16x32_bf16 v[64:67], v[178:181], v[216:219], v[64:67]
	s_barrier
	s_add_i32 s55, s46, s35
	v_lshl_add_u64 v[186:187], s[24:25], 0, v[132:133]
	s_mov_b32 m0, s55
	ds_read_b128 v[182:185], v149 offset:16384
	ds_read_b128 v[192:195], v149 offset:17408
	ds_read_b128 v[196:199], v149 offset:18432
	ds_read_b128 v[200:203], v149 offset:19456
	ds_read_b128 v[204:207], v149 offset:20480
	ds_read_b128 v[208:211], v149 offset:21504
	ds_read_b128 v[212:215], v149 offset:22528
	ds_read_b128 v[216:219], v149 offset:23552
	global_load_lds_dwordx4 v[186:187], off
	s_add_i32 m0, s55, 0x2000
	s_add_u32 s56, s24, 0x40000
	v_lshl_add_u64 v[220:221], s[24:25], 0, v[128:129]
	s_addc_u32 s57, s25, 0
	s_add_i32 s55, s47, s35
	global_load_lds_dwordx4 v[220:221], off
	v_lshl_add_u64 v[222:223], s[56:57], 0, v[132:133]
	s_mov_b32 m0, s55
	v_lshl_add_u64 v[224:225], s[30:31], 0, v[130:131]
	global_load_lds_dwordx4 v[222:223], off
	v_lshl_add_u64 v[222:223], s[56:57], 0, v[128:129]
	s_add_i32 m0, s55, 0x2000
	s_nop 0
	global_load_lds_dwordx4 v[222:223], off
	v_lshl_add_u64 v[222:223], s[30:31], 0, v[134:135]
	s_mov_b32 m0, s21
	s_nop 0
	global_load_lds_dwordx4 v[222:223], off
	s_mov_b32 m0, s38
	s_nop 0
	global_load_lds_dwordx4 v[224:225], off
	s_waitcnt vmcnt(16)
	s_waitcnt lgkmcnt(0)
	s_barrier
	v_mfma_f32_16x16x32_bf16 v[60:63], v[150:153], v[182:185], 0
	v_mfma_f32_16x16x32_bf16 v[56:59], v[158:161], v[182:185], 0
	v_mfma_f32_16x16x32_bf16 v[44:47], v[150:153], v[196:199], 0
	v_mfma_f32_16x16x32_bf16 v[40:43], v[158:161], v[196:199], 0
	v_mfma_f32_16x16x32_bf16 v[28:31], v[150:153], v[204:207], 0
	v_mfma_f32_16x16x32_bf16 v[24:27], v[158:161], v[204:207], 0
	v_mfma_f32_16x16x32_bf16 v[12:15], v[150:153], v[212:215], 0
	v_mfma_f32_16x16x32_bf16 v[8:11], v[158:161], v[212:215], 0
	v_mfma_f32_16x16x32_bf16 v[60:63], v[154:157], v[192:195], v[60:63]
	v_mfma_f32_16x16x32_bf16 v[56:59], v[162:165], v[192:195], v[56:59]
	v_mfma_f32_16x16x32_bf16 v[44:47], v[154:157], v[200:203], v[44:47]
	v_mfma_f32_16x16x32_bf16 v[40:43], v[162:165], v[200:203], v[40:43]
	v_mfma_f32_16x16x32_bf16 v[28:31], v[154:157], v[208:211], v[28:31]
	v_mfma_f32_16x16x32_bf16 v[24:27], v[162:165], v[208:211], v[24:27]
	v_mfma_f32_16x16x32_bf16 v[12:15], v[154:157], v[216:219], v[12:15]
	v_mfma_f32_16x16x32_bf16 v[8:11], v[162:165], v[216:219], v[8:11]
	v_mfma_f32_16x16x32_bf16 v[52:55], v[166:169], v[182:185], 0
	v_mfma_f32_16x16x32_bf16 v[48:51], v[174:177], v[182:185], 0
	v_mfma_f32_16x16x32_bf16 v[36:39], v[166:169], v[196:199], 0
	v_mfma_f32_16x16x32_bf16 v[32:35], v[174:177], v[196:199], 0
	v_mfma_f32_16x16x32_bf16 v[20:23], v[166:169], v[204:207], 0
	v_mfma_f32_16x16x32_bf16 v[16:19], v[174:177], v[204:207], 0
	v_mfma_f32_16x16x32_bf16 v[4:7], v[166:169], v[212:215], 0
	v_mfma_f32_16x16x32_bf16 v[0:3], v[174:177], v[212:215], 0
	v_mfma_f32_16x16x32_bf16 v[52:55], v[170:173], v[192:195], v[52:55]
	v_mfma_f32_16x16x32_bf16 v[48:51], v[178:181], v[192:195], v[48:51]
	v_mfma_f32_16x16x32_bf16 v[36:39], v[170:173], v[200:203], v[36:39]
	v_mfma_f32_16x16x32_bf16 v[32:35], v[178:181], v[200:203], v[32:35]
	v_mfma_f32_16x16x32_bf16 v[20:23], v[170:173], v[208:211], v[20:23]
	v_mfma_f32_16x16x32_bf16 v[16:19], v[178:181], v[208:211], v[16:19]
	v_mfma_f32_16x16x32_bf16 v[4:7], v[170:173], v[216:219], v[4:7]
	v_mfma_f32_16x16x32_bf16 v[0:3], v[178:181], v[216:219], v[0:3]
	s_barrier
; #define PG8_STAGE(bufoff, gbase, voff) do { _Pragma("unroll") for (int _i = 0; _i < 2; ++_i) \
;         __builtin_amdgcn_global_load_lds((const unsigned*)((const char*)(gbase) + (voff)[_i]), (PG8_LAS unsigned*)(lds + (bufoff) + ldsw + _i * 8192), 16, 0, 0); } while (0)
; #define PG8_LDA(dst, b, h) do { _Pragma("unroll") for (int m = 0; m < 4; ++m) _Pragma("unroll") for (int k = 0; k < 2; ++k) dst[m][k] = *(const PG8_LAS bf16x8*)(lds + PG8_SA(b, h) + aoff + m * 2048 + k * 1024); } while (0)
; #define PG8_LDB(dst, b, h) do { _Pragma("unroll") for (int n = 0; n < 2; ++n) _Pragma("unroll") for (int k = 0; k < 2; ++k) dst[n][k] = *(const PG8_LAS bf16x8*)(lds + PG8_SB(b, h) + boff + n * 2048 + k * 1024); } while (0)
; #define PG8_MMA(ai, bj, At, Bt) do { __builtin_amdgcn_s_setprio(1); _Pragma("unroll") for (int m = 0; m < 4; ++m) _Pragma("unroll") for (int n = 0; n < 2; ++n) _Pragma("unroll") for (int k = 0; k < 2; ++k) \
;         acc[ai][bj][m][n] = __builtin_amdgcn_mfma_f32_16x16x32_bf16(Bt[n][k], At[m][k], acc[ai][bj][m][n], 0, 0, 0); __builtin_amdgcn_s_setprio(0); } while (0)
; #define PG8_WAIT_V(n) asm volatile("s_waitcnt vmcnt(" #n ")" ::: "memory")
; #define PG8_WAIT_L(n) asm volatile("s_waitcnt lgkmcnt(" #n ")" ::: "memory")
; #define PG8_BAR __builtin_amdgcn_s_barrier()
; #define PG8_SCHED __builtin_amdgcn_sched_barrier(0)
; template <class Epi, class Sched, bool ALIGN_EPI = false, bool SP2 = false>
; __device__ __forceinline__ void gemm_phase(PG8_LAS unsigned char* lds, const Gemm g, const Sched& S, const Epi& E) {
;     ...
;             PG8_LDB(B0, 1, 0); PG8_LDB(B1, 1, 1); PG8_SCHED; PG8_LDA(At, 1, 0); PG8_STAGE(PG8_SA(0, 1), a2 + hstep, voffA);
;             PG8_WAIT_V(8); PG8_WAIT_L(0); PG8_BAR; PG8_MMA(0, 0, At, B0); PG8_MMA(0, 1, At, B1); PG8_BAR; PG8_SCHED;
;             PG8_LDA(At, 1, 1); PG8_STAGE(PG8_SB(1, 0), b3, voffB); PG8_STAGE(PG8_SB(1, 1), b3 + hstep, voffB); PG8_STAGE(PG8_SA(1, 0), a3, voffA);
;             PG8_WAIT_V(8); PG8_WAIT_L(0); PG8_BAR; PG8_MMA(1, 0, At, B0); PG8_MMA(1, 1, At, B1); PG8_BAR; PG8_SCHED;
	s_add_i32 s55, 0, 0x18000
	s_add_i32 s56, 0, 0x1c000
	v_add_u32_e32 v162, s55, v145
	v_add_u32_e32 v178, s56, v145
	ds_read_b128 v[150:153], v162
	ds_read_b128 v[154:157], v162 offset:1024
	ds_read_b128 v[158:161], v162 offset:2048
	ds_read_b128 v[162:165], v162 offset:3072
	ds_read_b128 v[166:169], v178
	ds_read_b128 v[170:173], v178 offset:1024
	ds_read_b128 v[174:177], v178 offset:2048
	ds_read_b128 v[178:181], v178 offset:3072
	s_add_u32 s30, s30, 0x40000
	s_addc_u32 s31, s31, 0
	s_mov_b32 m0, s39
	v_lshl_add_u64 v[226:227], s[30:31], 0, v[134:135]
	ds_read_b128 v[182:185], v149 offset:32768
	ds_read_b128 v[192:195], v149 offset:33792
	ds_read_b128 v[196:199], v149 offset:34816
	ds_read_b128 v[200:203], v149 offset:35840
	ds_read_b128 v[204:207], v149 offset:36864
	ds_read_b128 v[208:211], v149 offset:37888
	ds_read_b128 v[212:215], v149 offset:38912
	ds_read_b128 v[216:219], v149 offset:39936
	global_load_lds_dwordx4 v[226:227], off
	v_lshl_add_u64 v[226:227], s[30:31], 0, v[130:131]
	s_mov_b32 m0, s40
	s_nop 0
	global_load_lds_dwordx4 v[226:227], off
	s_waitcnt vmcnt(8)
	s_waitcnt lgkmcnt(0)
	s_barrier
	v_mfma_f32_16x16x32_bf16 v[124:127], v[150:153], v[182:185], v[124:127]
	v_mfma_f32_16x16x32_bf16 v[120:123], v[158:161], v[182:185], v[120:123]
	v_mfma_f32_16x16x32_bf16 v[108:111], v[150:153], v[196:199], v[108:111]
	v_mfma_f32_16x16x32_bf16 v[104:107], v[158:161], v[196:199], v[104:107]
	v_mfma_f32_16x16x32_bf16 v[92:95], v[150:153], v[204:207], v[92:95]
	v_mfma_f32_16x16x32_bf16 v[88:91], v[158:161], v[204:207], v[88:91]
	v_mfma_f32_16x16x32_bf16 v[76:79], v[150:153], v[212:215], v[76:79]
	v_mfma_f32_16x16x32_bf16 v[72:75], v[158:161], v[212:215], v[72:75]
	v_mfma_f32_16x16x32_bf16 v[124:127], v[154:157], v[192:195], v[124:127]
	v_mfma_f32_16x16x32_bf16 v[120:123], v[162:165], v[192:195], v[120:123]
	v_mfma_f32_16x16x32_bf16 v[108:111], v[154:157], v[200:203], v[108:111]
	v_mfma_f32_16x16x32_bf16 v[104:107], v[162:165], v[200:203], v[104:107]
	v_mfma_f32_16x16x32_bf16 v[92:95], v[154:157], v[208:211], v[92:95]
	v_mfma_f32_16x16x32_bf16 v[88:91], v[162:165], v[208:211], v[88:91]
	v_mfma_f32_16x16x32_bf16 v[76:79], v[154:157], v[216:219], v[76:79]
	v_mfma_f32_16x16x32_bf16 v[72:75], v[162:165], v[216:219], v[72:75]
	v_mfma_f32_16x16x32_bf16 v[116:119], v[166:169], v[182:185], v[116:119]
	v_mfma_f32_16x16x32_bf16 v[112:115], v[174:177], v[182:185], v[112:115]
	v_mfma_f32_16x16x32_bf16 v[100:103], v[166:169], v[196:199], v[100:103]
	v_mfma_f32_16x16x32_bf16 v[96:99], v[174:177], v[196:199], v[96:99]
	v_mfma_f32_16x16x32_bf16 v[84:87], v[166:169], v[204:207], v[84:87]
	v_mfma_f32_16x16x32_bf16 v[80:83], v[174:177], v[204:207], v[80:83]
	v_mfma_f32_16x16x32_bf16 v[68:71], v[166:169], v[212:215], v[68:71]
	v_mfma_f32_16x16x32_bf16 v[64:67], v[174:177], v[212:215], v[64:67]
	v_mfma_f32_16x16x32_bf16 v[116:119], v[170:173], v[192:195], v[116:119]
	v_mfma_f32_16x16x32_bf16 v[112:115], v[178:181], v[192:195], v[112:115]
	v_mfma_f32_16x16x32_bf16 v[100:103], v[170:173], v[200:203], v[100:103]
	v_mfma_f32_16x16x32_bf16 v[96:99], v[178:181], v[200:203], v[96:99]
	v_mfma_f32_16x16x32_bf16 v[84:87], v[170:173], v[208:211], v[84:87]
	v_mfma_f32_16x16x32_bf16 v[80:83], v[178:181], v[208:211], v[80:83]
	v_mfma_f32_16x16x32_bf16 v[68:71], v[170:173], v[216:219], v[68:71]
	v_mfma_f32_16x16x32_bf16 v[64:67], v[178:181], v[216:219], v[64:67]
	s_barrier
	s_add_i32 s30, s55, s35
	v_lshl_add_u64 v[186:187], v[186:187], 0, s[4:5]
	s_mov_b32 m0, s30
	ds_read_b128 v[182:185], v149 offset:49152
	ds_read_b128 v[192:195], v149 offset:50176
	ds_read_b128 v[196:199], v149 offset:51200
	ds_read_b128 v[200:203], v149 offset:52224
	ds_read_b128 v[204:207], v149 offset:53248
	ds_read_b128 v[208:211], v149 offset:54272
	ds_read_b128 v[212:215], v149 offset:55296
	ds_read_b128 v[216:219], v149 offset:56320
	global_load_lds_dwordx4 v[186:187], off
	s_add_i32 m0, s30, 0x2000
	s_add_u32 s24, s24, 0x40080
	v_lshl_add_u64 v[186:187], v[220:221], 0, s[4:5]
	s_addc_u32 s25, s25, 0
	s_add_i32 s30, s56, s35
	global_load_lds_dwordx4 v[186:187], off
	v_lshl_add_u64 v[186:187], s[24:25], 0, v[132:133]
	s_mov_b32 m0, s30
	s_nop 0
	global_load_lds_dwordx4 v[186:187], off
	v_lshl_add_u64 v[186:187], s[24:25], 0, v[128:129]
	s_add_i32 m0, s30, 0x2000
	s_nop 0
	global_load_lds_dwordx4 v[186:187], off
	v_lshl_add_u64 v[186:187], v[222:223], 0, s[4:5]
	s_mov_b32 m0, s42
	s_nop 0
	global_load_lds_dwordx4 v[186:187], off
	v_lshl_add_u64 v[186:187], v[224:225], 0, s[4:5]
	s_mov_b32 m0, s43
	s_nop 0
	global_load_lds_dwordx4 v[186:187], off
	s_waitcnt vmcnt(8)
	s_waitcnt lgkmcnt(0)
	s_barrier
	v_mfma_f32_16x16x32_bf16 v[60:63], v[150:153], v[182:185], v[60:63]
	v_mfma_f32_16x16x32_bf16 v[56:59], v[158:161], v[182:185], v[56:59]
	v_mfma_f32_16x16x32_bf16 v[44:47], v[150:153], v[196:199], v[44:47]
	v_mfma_f32_16x16x32_bf16 v[40:43], v[158:161], v[196:199], v[40:43]
	v_mfma_f32_16x16x32_bf16 v[28:31], v[150:153], v[204:207], v[28:31]
	v_mfma_f32_16x16x32_bf16 v[24:27], v[158:161], v[204:207], v[24:27]
	v_mfma_f32_16x16x32_bf16 v[12:15], v[150:153], v[212:215], v[12:15]
	v_mfma_f32_16x16x32_bf16 v[8:11], v[158:161], v[212:215], v[8:11]
	v_mfma_f32_16x16x32_bf16 v[60:63], v[154:157], v[192:195], v[60:63]
	v_mfma_f32_16x16x32_bf16 v[56:59], v[162:165], v[192:195], v[56:59]
	v_mfma_f32_16x16x32_bf16 v[44:47], v[154:157], v[200:203], v[44:47]
	v_mfma_f32_16x16x32_bf16 v[40:43], v[162:165], v[200:203], v[40:43]
	v_mfma_f32_16x16x32_bf16 v[28:31], v[154:157], v[208:211], v[28:31]
	v_mfma_f32_16x16x32_bf16 v[24:27], v[162:165], v[208:211], v[24:27]
	v_mfma_f32_16x16x32_bf16 v[12:15], v[154:157], v[216:219], v[12:15]
	v_mfma_f32_16x16x32_bf16 v[8:11], v[162:165], v[216:219], v[8:11]
	v_mfma_f32_16x16x32_bf16 v[52:55], v[166:169], v[182:185], v[52:55]
	v_mfma_f32_16x16x32_bf16 v[48:51], v[174:177], v[182:185], v[48:51]
	v_mfma_f32_16x16x32_bf16 v[36:39], v[166:169], v[196:199], v[36:39]
	v_mfma_f32_16x16x32_bf16 v[32:35], v[174:177], v[196:199], v[32:35]
	v_mfma_f32_16x16x32_bf16 v[20:23], v[166:169], v[204:207], v[20:23]
	v_mfma_f32_16x16x32_bf16 v[16:19], v[174:177], v[204:207], v[16:19]
	v_mfma_f32_16x16x32_bf16 v[4:7], v[166:169], v[212:215], v[4:7]
	v_mfma_f32_16x16x32_bf16 v[0:3], v[174:177], v[212:215], v[0:3]
	v_mfma_f32_16x16x32_bf16 v[52:55], v[170:173], v[192:195], v[52:55]
	v_mfma_f32_16x16x32_bf16 v[48:51], v[178:181], v[192:195], v[48:51]
	v_mfma_f32_16x16x32_bf16 v[36:39], v[170:173], v[200:203], v[36:39]
	v_mfma_f32_16x16x32_bf16 v[32:35], v[178:181], v[200:203], v[32:35]
	v_mfma_f32_16x16x32_bf16 v[20:23], v[170:173], v[208:211], v[20:23]
	v_mfma_f32_16x16x32_bf16 v[16:19], v[178:181], v[208:211], v[16:19]
	v_mfma_f32_16x16x32_bf16 v[4:7], v[170:173], v[216:219], v[4:7]
	v_mfma_f32_16x16x32_bf16 v[0:3], v[178:181], v[216:219], v[0:3]
	s_barrier
	s_add_i32 s54, s54, 2
	s_add_u32 s22, s22, 0x100
	s_addc_u32 s23, s23, 0
	s_add_u32 s52, s52, 0x100
	s_addc_u32 s53, s53, 0
; #define PG8_STAGE(bufoff, gbase, voff) do { _Pragma("unroll") for (int _i = 0; _i < 2; ++_i) \
;         __builtin_amdgcn_global_load_lds((const unsigned*)((const char*)(gbase) + (voff)[_i]), (PG8_LAS unsigned*)(lds + (bufoff) + ldsw + _i * 8192), 16, 0, 0); } while (0)
; #define PG8_LDA(dst, b, h) do { _Pragma("unroll") for (int m = 0; m < 4; ++m) _Pragma("unroll") for (int k = 0; k < 2; ++k) dst[m][k] = *(const PG8_LAS bf16x8*)(lds + PG8_SA(b, h) + aoff + m * 2048 + k * 1024); } while (0)
; #define PG8_LDB(dst, b, h) do { _Pragma("unroll") for (int n = 0; n < 2; ++n) _Pragma("unroll") for (int k = 0; k < 2; ++k) dst[n][k] = *(const PG8_LAS bf16x8*)(lds + PG8_SB(b, h) + boff + n * 2048 + k * 1024); } while (0)
; #define PG8_MMA(ai, bj, At, Bt) do { __builtin_amdgcn_s_setprio(1); _Pragma("unroll") for (int m = 0; m < 4; ++m) _Pragma("unroll") for (int n = 0; n < 2; ++n) _Pragma("unroll") for (int k = 0; k < 2; ++k) \
;         acc[ai][bj][m][n] = __builtin_amdgcn_mfma_f32_16x16x32_bf16(Bt[n][k], At[m][k], acc[ai][bj][m][n], 0, 0, 0); __builtin_amdgcn_s_setprio(0); } while (0)
; #define PG8_WAIT_V(n) asm volatile("s_waitcnt vmcnt(" #n ")" ::: "memory")
; #define PG8_WAIT_L(n) asm volatile("s_waitcnt lgkmcnt(" #n ")" ::: "memory")
; #define PG8_BAR __builtin_amdgcn_s_barrier()
; #define PG8_SCHED __builtin_amdgcn_sched_barrier(0)
; template <class Epi, class Sched, bool ALIGN_EPI = false, bool SP2 = false>
; __device__ __forceinline__ void gemm_phase(PG8_LAS unsigned char* lds, const Gemm g, const Sched& S, const Epi& E) {
;     ...
;             PG8_LDB(B0, 0, 0); PG8_LDB(B1, 0, 1); PG8_SCHED; PG8_LDA(At, 0, 0); PG8_STAGE(PG8_SA(1, 1), a1 + hstep, voffA);
;             PG8_WAIT_V(8); PG8_WAIT_L(0); PG8_BAR; PG8_MMA(0, 0, At, B0); PG8_MMA(0, 1, At, B1); PG8_BAR; PG8_SCHED;
;             PG8_LDA(At, 0, 1); PG8_STAGE(PG8_SB(0, 0), b2, voffB); PG8_STAGE(PG8_SB(0, 1), b2 + hstep, voffB); PG8_STAGE(PG8_SA(0, 0), a2, voffA);
;             PG8_WAIT_V(8); PG8_WAIT_L(0); PG8_BAR; PG8_MMA(1, 0, At, B0); PG8_MMA(1, 1, At, B1); PG8_BAR; PG8_SCHED;
.LBB0_192:
	ds_read_b128 v[150:153], v147
	ds_read_b128 v[154:157], v147 offset:1024
	ds_read_b128 v[158:161], v147 offset:2048
	ds_read_b128 v[162:165], v147 offset:3072
	ds_read_b128 v[166:169], v148
	ds_read_b128 v[170:173], v148 offset:1024
	ds_read_b128 v[174:177], v148 offset:2048
	ds_read_b128 v[178:181], v148 offset:3072
	s_add_u32 s24, s22, 0xfffc0080
	s_addc_u32 s25, s23, -1
	s_cmp_eq_u32 s54, 12
	s_cselect_b32 s31, s15, s25
	s_cselect_b32 s30, s50, s24
	s_cselect_b32 s25, s9, s53
	s_cselect_b32 s24, s51, s52
	v_lshl_add_u64 v[186:187], s[22:23], 0, v[136:137]
	s_add_i32 m0, s21, 0xc000
	ds_read_b128 v[182:185], v149
	ds_read_b128 v[192:195], v149 offset:1024
	ds_read_b128 v[196:199], v149 offset:2048
	ds_read_b128 v[200:203], v149 offset:3072
	ds_read_b128 v[204:207], v149 offset:4096
	ds_read_b128 v[208:211], v149 offset:5120
	ds_read_b128 v[212:215], v149 offset:6144
	ds_read_b128 v[216:219], v149 offset:7168
	global_load_lds_dwordx4 v[186:187], off
	v_lshl_add_u64 v[186:187], s[22:23], 0, v[138:139]
	s_add_i32 m0, s21, 0xe000
	s_nop 0
	global_load_lds_dwordx4 v[186:187], off
	s_waitcnt vmcnt(8)
	s_waitcnt lgkmcnt(0)
	s_barrier
	v_mfma_f32_16x16x32_bf16 v[124:127], v[150:153], v[182:185], v[124:127]
	v_mfma_f32_16x16x32_bf16 v[120:123], v[158:161], v[182:185], v[120:123]
	v_mfma_f32_16x16x32_bf16 v[108:111], v[150:153], v[196:199], v[108:111]
	v_mfma_f32_16x16x32_bf16 v[104:107], v[158:161], v[196:199], v[104:107]
	v_mfma_f32_16x16x32_bf16 v[92:95], v[150:153], v[204:207], v[92:95]
	v_mfma_f32_16x16x32_bf16 v[88:91], v[158:161], v[204:207], v[88:91]
	v_mfma_f32_16x16x32_bf16 v[76:79], v[150:153], v[212:215], v[76:79]
	v_mfma_f32_16x16x32_bf16 v[72:75], v[158:161], v[212:215], v[72:75]
	v_mfma_f32_16x16x32_bf16 v[124:127], v[154:157], v[192:195], v[124:127]
	v_mfma_f32_16x16x32_bf16 v[120:123], v[162:165], v[192:195], v[120:123]
	v_mfma_f32_16x16x32_bf16 v[108:111], v[154:157], v[200:203], v[108:111]
	v_mfma_f32_16x16x32_bf16 v[104:107], v[162:165], v[200:203], v[104:107]
	v_mfma_f32_16x16x32_bf16 v[92:95], v[154:157], v[208:211], v[92:95]
	v_mfma_f32_16x16x32_bf16 v[88:91], v[162:165], v[208:211], v[88:91]
	v_mfma_f32_16x16x32_bf16 v[76:79], v[154:157], v[216:219], v[76:79]
	v_mfma_f32_16x16x32_bf16 v[72:75], v[162:165], v[216:219], v[72:75]
	v_mfma_f32_16x16x32_bf16 v[116:119], v[166:169], v[182:185], v[116:119]
	v_mfma_f32_16x16x32_bf16 v[112:115], v[174:177], v[182:185], v[112:115]
	v_mfma_f32_16x16x32_bf16 v[100:103], v[166:169], v[196:199], v[100:103]
	v_mfma_f32_16x16x32_bf16 v[96:99], v[174:177], v[196:199], v[96:99]
	v_mfma_f32_16x16x32_bf16 v[84:87], v[166:169], v[204:207], v[84:87]
	v_mfma_f32_16x16x32_bf16 v[80:83], v[174:177], v[204:207], v[80:83]
	v_mfma_f32_16x16x32_bf16 v[68:71], v[166:169], v[212:215], v[68:71]
	v_mfma_f32_16x16x32_bf16 v[64:67], v[174:177], v[212:215], v[64:67]
	v_mfma_f32_16x16x32_bf16 v[116:119], v[170:173], v[192:195], v[116:119]
	v_mfma_f32_16x16x32_bf16 v[112:115], v[178:181], v[192:195], v[112:115]
	v_mfma_f32_16x16x32_bf16 v[100:103], v[170:173], v[200:203], v[100:103]
	v_mfma_f32_16x16x32_bf16 v[96:99], v[178:181], v[200:203], v[96:99]
	v_mfma_f32_16x16x32_bf16 v[84:87], v[170:173], v[208:211], v[84:87]
	v_mfma_f32_16x16x32_bf16 v[80:83], v[178:181], v[208:211], v[80:83]
	v_mfma_f32_16x16x32_bf16 v[68:71], v[170:173], v[216:219], v[68:71]
	v_mfma_f32_16x16x32_bf16 v[64:67], v[178:181], v[216:219], v[64:67]
	s_barrier
	s_add_i32 s55, s46, s35
	v_lshl_add_u64 v[186:187], s[24:25], 0, v[132:133]
	s_mov_b32 m0, s55
	ds_read_b128 v[182:185], v149 offset:16384
	ds_read_b128 v[192:195], v149 offset:17408
	ds_read_b128 v[196:199], v149 offset:18432
	ds_read_b128 v[200:203], v149 offset:19456
	ds_read_b128 v[204:207], v149 offset:20480
	ds_read_b128 v[208:211], v149 offset:21504
	ds_read_b128 v[212:215], v149 offset:22528
	ds_read_b128 v[216:219], v149 offset:23552
	global_load_lds_dwordx4 v[186:187], off
	s_add_i32 m0, s55, 0x2000
	s_add_u32 s56, s24, 0x40000
	v_lshl_add_u64 v[220:221], s[24:25], 0, v[128:129]
	s_addc_u32 s57, s25, 0
	s_add_i32 s55, s47, s35
	global_load_lds_dwordx4 v[220:221], off
	v_lshl_add_u64 v[222:223], s[56:57], 0, v[132:133]
	s_mov_b32 m0, s55
	v_lshl_add_u64 v[224:225], s[30:31], 0, v[130:131]
	global_load_lds_dwordx4 v[222:223], off
	v_lshl_add_u64 v[222:223], s[56:57], 0, v[128:129]
	s_add_i32 m0, s55, 0x2000
	s_nop 0
	global_load_lds_dwordx4 v[222:223], off
	v_lshl_add_u64 v[222:223], s[30:31], 0, v[134:135]
	s_mov_b32 m0, s21
	s_nop 0
	global_load_lds_dwordx4 v[222:223], off
	s_mov_b32 m0, s38
	s_nop 0
	global_load_lds_dwordx4 v[224:225], off
	s_waitcnt vmcnt(8)
	s_waitcnt lgkmcnt(0)
	s_barrier
; #define PG8_STAGE(bufoff, gbase, voff) do { _Pragma("unroll") for (int _i = 0; _i < 2; ++_i) \
;         __builtin_amdgcn_global_load_lds((const unsigned*)((const char*)(gbase) + (voff)[_i]), (PG8_LAS unsigned*)(lds + (bufoff) + ldsw + _i * 8192), 16, 0, 0); } while (0)
; #define PG8_LDA(dst, b, h) do { _Pragma("unroll") for (int m = 0; m < 4; ++m) _Pragma("unroll") for (int k = 0; k < 2; ++k) dst[m][k] = *(const PG8_LAS bf16x8*)(lds + PG8_SA(b, h) + aoff + m * 2048 + k * 1024); } while (0)
; #define PG8_LDB(dst, b, h) do { _Pragma("unroll") for (int n = 0; n < 2; ++n) _Pragma("unroll") for (int k = 0; k < 2; ++k) dst[n][k] = *(const PG8_LAS bf16x8*)(lds + PG8_SB(b, h) + boff + n * 2048 + k * 1024); } while (0)
; #define PG8_MMA(ai, bj, At, Bt) do { __builtin_amdgcn_s_setprio(1); _Pragma("unroll") for (int m = 0; m < 4; ++m) _Pragma("unroll") for (int n = 0; n < 2; ++n) _Pragma("unroll") for (int k = 0; k < 2; ++k) \
;         acc[ai][bj][m][n] = __builtin_amdgcn_mfma_f32_16x16x32_bf16(Bt[n][k], At[m][k], acc[ai][bj][m][n], 0, 0, 0); __builtin_amdgcn_s_setprio(0); } while (0)
; #define PG8_WAIT_V(n) asm volatile("s_waitcnt vmcnt(" #n ")" ::: "memory")
; #define PG8_WAIT_L(n) asm volatile("s_waitcnt lgkmcnt(" #n ")" ::: "memory")
; #define PG8_BAR __builtin_amdgcn_s_barrier()
; #define PG8_SCHED __builtin_amdgcn_sched_barrier(0)
; template <class Epi, class Sched, bool ALIGN_EPI = false, bool SP2 = false>
; __device__ __forceinline__ void gemm_phase(PG8_LAS unsigned char* lds, const Gemm g, const Sched& S, const Epi& E) {
;     ...
;             PG8_WAIT_V(8); PG8_WAIT_L(0); PG8_BAR; PG8_MMA(0, 0, At, B0); PG8_MMA(0, 1, At, B1); PG8_BAR; PG8_SCHED;
;             PG8_LDA(At, 0, 1); PG8_STAGE(PG8_SB(0, 0), b2, voffB); PG8_STAGE(PG8_SB(0, 1), b2 + hstep, voffB); PG8_STAGE(PG8_SA(0, 0), a2, voffA);
;             PG8_WAIT_V(8); PG8_WAIT_L(0); PG8_BAR; PG8_MMA(1, 0, At, B0); PG8_MMA(1, 1, At, B1); PG8_BAR; PG8_SCHED;
;             PG8_LDB(B0, 1, 0); PG8_LDB(B1, 1, 1); PG8_SCHED; PG8_LDA(At, 1, 0); PG8_STAGE(PG8_SA(0, 1), a2 + hstep, voffA);
;             PG8_WAIT_V(8); PG8_WAIT_L(0); PG8_BAR; PG8_MMA(0, 0, At, B0); PG8_MMA(0, 1, At, B1); PG8_BAR; PG8_SCHED;
	v_mfma_f32_16x16x32_bf16 v[60:63], v[150:153], v[182:185], v[60:63]
	v_mfma_f32_16x16x32_bf16 v[56:59], v[158:161], v[182:185], v[56:59]
	v_mfma_f32_16x16x32_bf16 v[44:47], v[150:153], v[196:199], v[44:47]
	v_mfma_f32_16x16x32_bf16 v[40:43], v[158:161], v[196:199], v[40:43]
	v_mfma_f32_16x16x32_bf16 v[28:31], v[150:153], v[204:207], v[28:31]
	v_mfma_f32_16x16x32_bf16 v[24:27], v[158:161], v[204:207], v[24:27]
	v_mfma_f32_16x16x32_bf16 v[12:15], v[150:153], v[212:215], v[12:15]
	v_mfma_f32_16x16x32_bf16 v[8:11], v[158:161], v[212:215], v[8:11]
	v_mfma_f32_16x16x32_bf16 v[60:63], v[154:157], v[192:195], v[60:63]
	v_mfma_f32_16x16x32_bf16 v[56:59], v[162:165], v[192:195], v[56:59]
	v_mfma_f32_16x16x32_bf16 v[44:47], v[154:157], v[200:203], v[44:47]
	v_mfma_f32_16x16x32_bf16 v[40:43], v[162:165], v[200:203], v[40:43]
	v_mfma_f32_16x16x32_bf16 v[28:31], v[154:157], v[208:211], v[28:31]
	v_mfma_f32_16x16x32_bf16 v[24:27], v[162:165], v[208:211], v[24:27]
	v_mfma_f32_16x16x32_bf16 v[12:15], v[154:157], v[216:219], v[12:15]
	v_mfma_f32_16x16x32_bf16 v[8:11], v[162:165], v[216:219], v[8:11]
	v_mfma_f32_16x16x32_bf16 v[52:55], v[166:169], v[182:185], v[52:55]
	v_mfma_f32_16x16x32_bf16 v[48:51], v[174:177], v[182:185], v[48:51]
	v_mfma_f32_16x16x32_bf16 v[36:39], v[166:169], v[196:199], v[36:39]
	v_mfma_f32_16x16x32_bf16 v[32:35], v[174:177], v[196:199], v[32:35]
	v_mfma_f32_16x16x32_bf16 v[20:23], v[166:169], v[204:207], v[20:23]
	v_mfma_f32_16x16x32_bf16 v[16:19], v[174:177], v[204:207], v[16:19]
	v_mfma_f32_16x16x32_bf16 v[4:7], v[166:169], v[212:215], v[4:7]
	v_mfma_f32_16x16x32_bf16 v[0:3], v[174:177], v[212:215], v[0:3]
	v_mfma_f32_16x16x32_bf16 v[52:55], v[170:173], v[192:195], v[52:55]
	v_mfma_f32_16x16x32_bf16 v[48:51], v[178:181], v[192:195], v[48:51]
	v_mfma_f32_16x16x32_bf16 v[36:39], v[170:173], v[200:203], v[36:39]
	v_mfma_f32_16x16x32_bf16 v[32:35], v[178:181], v[200:203], v[32:35]
	v_mfma_f32_16x16x32_bf16 v[20:23], v[170:173], v[208:211], v[20:23]
	v_mfma_f32_16x16x32_bf16 v[16:19], v[178:181], v[208:211], v[16:19]
	v_mfma_f32_16x16x32_bf16 v[4:7], v[170:173], v[216:219], v[4:7]
	v_mfma_f32_16x16x32_bf16 v[0:3], v[178:181], v[216:219], v[0:3]
	s_barrier
	s_add_i32 s55, 0, 0x18000
	s_add_i32 s56, 0, 0x1c000
	v_add_u32_e32 v162, s55, v145
	v_add_u32_e32 v178, s56, v145
	ds_read_b128 v[150:153], v162
	ds_read_b128 v[154:157], v162 offset:1024
	ds_read_b128 v[158:161], v162 offset:2048
	ds_read_b128 v[162:165], v162 offset:3072
	ds_read_b128 v[166:169], v178
	ds_read_b128 v[170:173], v178 offset:1024
	ds_read_b128 v[174:177], v178 offset:2048
	ds_read_b128 v[178:181], v178 offset:3072
	s_add_u32 s30, s30, 0x40000
	s_addc_u32 s31, s31, 0
	s_mov_b32 m0, s39
	v_lshl_add_u64 v[226:227], s[30:31], 0, v[134:135]
	ds_read_b128 v[182:185], v149 offset:32768
	ds_read_b128 v[192:195], v149 offset:33792
	ds_read_b128 v[196:199], v149 offset:34816
	ds_read_b128 v[200:203], v149 offset:35840
	ds_read_b128 v[204:207], v149 offset:36864
	ds_read_b128 v[208:211], v149 offset:37888
	ds_read_b128 v[212:215], v149 offset:38912
	ds_read_b128 v[216:219], v149 offset:39936
	global_load_lds_dwordx4 v[226:227], off
	v_lshl_add_u64 v[226:227], s[30:31], 0, v[130:131]
	s_mov_b32 m0, s40
	s_nop 0
	global_load_lds_dwordx4 v[226:227], off
	s_waitcnt vmcnt(8)
	s_waitcnt lgkmcnt(0)
	s_barrier
	v_mfma_f32_16x16x32_bf16 v[124:127], v[150:153], v[182:185], v[124:127]
	v_mfma_f32_16x16x32_bf16 v[120:123], v[158:161], v[182:185], v[120:123]
	v_mfma_f32_16x16x32_bf16 v[108:111], v[150:153], v[196:199], v[108:111]
	v_mfma_f32_16x16x32_bf16 v[104:107], v[158:161], v[196:199], v[104:107]
	v_mfma_f32_16x16x32_bf16 v[92:95], v[150:153], v[204:207], v[92:95]
	v_mfma_f32_16x16x32_bf16 v[88:91], v[158:161], v[204:207], v[88:91]
	v_mfma_f32_16x16x32_bf16 v[76:79], v[150:153], v[212:215], v[76:79]
	v_mfma_f32_16x16x32_bf16 v[72:75], v[158:161], v[212:215], v[72:75]
	v_mfma_f32_16x16x32_bf16 v[124:127], v[154:157], v[192:195], v[124:127]
	v_mfma_f32_16x16x32_bf16 v[120:123], v[162:165], v[192:195], v[120:123]
	v_mfma_f32_16x16x32_bf16 v[108:111], v[154:157], v[200:203], v[108:111]
	v_mfma_f32_16x16x32_bf16 v[104:107], v[162:165], v[200:203], v[104:107]
	v_mfma_f32_16x16x32_bf16 v[92:95], v[154:157], v[208:211], v[92:95]
	v_mfma_f32_16x16x32_bf16 v[88:91], v[162:165], v[208:211], v[88:91]
	v_mfma_f32_16x16x32_bf16 v[76:79], v[154:157], v[216:219], v[76:79]
	v_mfma_f32_16x16x32_bf16 v[72:75], v[162:165], v[216:219], v[72:75]
	v_mfma_f32_16x16x32_bf16 v[116:119], v[166:169], v[182:185], v[116:119]
	v_mfma_f32_16x16x32_bf16 v[112:115], v[174:177], v[182:185], v[112:115]
	v_mfma_f32_16x16x32_bf16 v[100:103], v[166:169], v[196:199], v[100:103]
	v_mfma_f32_16x16x32_bf16 v[96:99], v[174:177], v[196:199], v[96:99]
	v_mfma_f32_16x16x32_bf16 v[84:87], v[166:169], v[204:207], v[84:87]
	v_mfma_f32_16x16x32_bf16 v[80:83], v[174:177], v[204:207], v[80:83]
	v_mfma_f32_16x16x32_bf16 v[68:71], v[166:169], v[212:215], v[68:71]
	v_mfma_f32_16x16x32_bf16 v[64:67], v[174:177], v[212:215], v[64:67]
	v_mfma_f32_16x16x32_bf16 v[116:119], v[170:173], v[192:195], v[116:119]
	v_mfma_f32_16x16x32_bf16 v[112:115], v[178:181], v[192:195], v[112:115]
	v_mfma_f32_16x16x32_bf16 v[100:103], v[170:173], v[200:203], v[100:103]
	v_mfma_f32_16x16x32_bf16 v[96:99], v[178:181], v[200:203], v[96:99]
	v_mfma_f32_16x16x32_bf16 v[84:87], v[170:173], v[208:211], v[84:87]
	v_mfma_f32_16x16x32_bf16 v[80:83], v[178:181], v[208:211], v[80:83]
	v_mfma_f32_16x16x32_bf16 v[68:71], v[170:173], v[216:219], v[68:71]
	v_mfma_f32_16x16x32_bf16 v[64:67], v[178:181], v[216:219], v[64:67]
	s_barrier
; #define PG8_STAGE(bufoff, gbase, voff) do { _Pragma("unroll") for (int _i = 0; _i < 2; ++_i) \
;         __builtin_amdgcn_global_load_lds((const unsigned*)((const char*)(gbase) + (voff)[_i]), (PG8_LAS unsigned*)(lds + (bufoff) + ldsw + _i * 8192), 16, 0, 0); } while (0)
; #define PG8_LDA(dst, b, h) do { _Pragma("unroll") for (int m = 0; m < 4; ++m) _Pragma("unroll") for (int k = 0; k < 2; ++k) dst[m][k] = *(const PG8_LAS bf16x8*)(lds + PG8_SA(b, h) + aoff + m * 2048 + k * 1024); } while (0)
; #define PG8_MMA(ai, bj, At, Bt) do { __builtin_amdgcn_s_setprio(1); _Pragma("unroll") for (int m = 0; m < 4; ++m) _Pragma("unroll") for (int n = 0; n < 2; ++n) _Pragma("unroll") for (int k = 0; k < 2; ++k) \
;         acc[ai][bj][m][n] = __builtin_amdgcn_mfma_f32_16x16x32_bf16(Bt[n][k], At[m][k], acc[ai][bj][m][n], 0, 0, 0); __builtin_amdgcn_s_setprio(0); } while (0)
; #define PG8_WAIT_V(n) asm volatile("s_waitcnt vmcnt(" #n ")" ::: "memory")
; #define PG8_WAIT_L(n) asm volatile("s_waitcnt lgkmcnt(" #n ")" ::: "memory")
; #define PG8_BAR __builtin_amdgcn_s_barrier()
; #define PG8_SCHED __builtin_amdgcn_sched_barrier(0)
; template <class Epi, class Sched, bool ALIGN_EPI = false, bool SP2 = false>
; __device__ __forceinline__ void gemm_phase(PG8_LAS unsigned char* lds, const Gemm g, const Sched& S, const Epi& E) {
;     ...
;         for (int t = 0; t < nt; t += 2) {
;     ...
;             PG8_WAIT_V(8); PG8_WAIT_L(0); PG8_BAR; PG8_MMA(0, 0, At, B0); PG8_MMA(0, 1, At, B1); PG8_BAR; PG8_SCHED;
;             PG8_LDA(At, 1, 1); PG8_STAGE(PG8_SB(1, 0), b3, voffB); PG8_STAGE(PG8_SB(1, 1), b3 + hstep, voffB); PG8_STAGE(PG8_SA(1, 0), a3, voffA);
;             PG8_WAIT_V(8); PG8_WAIT_L(0); PG8_BAR; PG8_MMA(1, 0, At, B0); PG8_MMA(1, 1, At, B1); PG8_BAR; PG8_SCHED;
	s_add_i32 s30, s55, s35
	v_lshl_add_u64 v[186:187], v[186:187], 0, s[4:5]
	s_mov_b32 m0, s30
	ds_read_b128 v[182:185], v149 offset:49152
	ds_read_b128 v[192:195], v149 offset:50176
	ds_read_b128 v[196:199], v149 offset:51200
	ds_read_b128 v[200:203], v149 offset:52224
	ds_read_b128 v[204:207], v149 offset:53248
	ds_read_b128 v[208:211], v149 offset:54272
	ds_read_b128 v[212:215], v149 offset:55296
	ds_read_b128 v[216:219], v149 offset:56320
	global_load_lds_dwordx4 v[186:187], off
	s_add_i32 m0, s30, 0x2000
	s_add_u32 s24, s24, 0x40080
	v_lshl_add_u64 v[186:187], v[220:221], 0, s[4:5]
	s_addc_u32 s25, s25, 0
	s_add_i32 s30, s56, s35
	global_load_lds_dwordx4 v[186:187], off
	v_lshl_add_u64 v[186:187], s[24:25], 0, v[132:133]
	s_mov_b32 m0, s30
	s_nop 0
	global_load_lds_dwordx4 v[186:187], off
	v_lshl_add_u64 v[186:187], s[24:25], 0, v[128:129]
	s_add_i32 m0, s30, 0x2000
	s_nop 0
	global_load_lds_dwordx4 v[186:187], off
	v_lshl_add_u64 v[186:187], v[222:223], 0, s[4:5]
	s_mov_b32 m0, s42
	s_nop 0
	global_load_lds_dwordx4 v[186:187], off
	v_lshl_add_u64 v[186:187], v[224:225], 0, s[4:5]
	s_mov_b32 m0, s43
	s_nop 0
	global_load_lds_dwordx4 v[186:187], off
	s_waitcnt vmcnt(8)
	s_waitcnt lgkmcnt(0)
	s_barrier
	v_mfma_f32_16x16x32_bf16 v[60:63], v[150:153], v[182:185], v[60:63]
	v_mfma_f32_16x16x32_bf16 v[56:59], v[158:161], v[182:185], v[56:59]
	v_mfma_f32_16x16x32_bf16 v[44:47], v[150:153], v[196:199], v[44:47]
	v_mfma_f32_16x16x32_bf16 v[40:43], v[158:161], v[196:199], v[40:43]
	v_mfma_f32_16x16x32_bf16 v[28:31], v[150:153], v[204:207], v[28:31]
	v_mfma_f32_16x16x32_bf16 v[24:27], v[158:161], v[204:207], v[24:27]
	v_mfma_f32_16x16x32_bf16 v[12:15], v[150:153], v[212:215], v[12:15]
	v_mfma_f32_16x16x32_bf16 v[8:11], v[158:161], v[212:215], v[8:11]
	v_mfma_f32_16x16x32_bf16 v[60:63], v[154:157], v[192:195], v[60:63]
	v_mfma_f32_16x16x32_bf16 v[56:59], v[162:165], v[192:195], v[56:59]
	v_mfma_f32_16x16x32_bf16 v[44:47], v[154:157], v[200:203], v[44:47]
	v_mfma_f32_16x16x32_bf16 v[40:43], v[162:165], v[200:203], v[40:43]
	v_mfma_f32_16x16x32_bf16 v[28:31], v[154:157], v[208:211], v[28:31]
	v_mfma_f32_16x16x32_bf16 v[24:27], v[162:165], v[208:211], v[24:27]
	v_mfma_f32_16x16x32_bf16 v[12:15], v[154:157], v[216:219], v[12:15]
	v_mfma_f32_16x16x32_bf16 v[8:11], v[162:165], v[216:219], v[8:11]
	v_mfma_f32_16x16x32_bf16 v[52:55], v[166:169], v[182:185], v[52:55]
	v_mfma_f32_16x16x32_bf16 v[48:51], v[174:177], v[182:185], v[48:51]
	v_mfma_f32_16x16x32_bf16 v[36:39], v[166:169], v[196:199], v[36:39]
	v_mfma_f32_16x16x32_bf16 v[32:35], v[174:177], v[196:199], v[32:35]
	v_mfma_f32_16x16x32_bf16 v[20:23], v[166:169], v[204:207], v[20:23]
	v_mfma_f32_16x16x32_bf16 v[16:19], v[174:177], v[204:207], v[16:19]
	v_mfma_f32_16x16x32_bf16 v[4:7], v[166:169], v[212:215], v[4:7]
	v_mfma_f32_16x16x32_bf16 v[0:3], v[174:177], v[212:215], v[0:3]
	v_mfma_f32_16x16x32_bf16 v[52:55], v[170:173], v[192:195], v[52:55]
	v_mfma_f32_16x16x32_bf16 v[48:51], v[178:181], v[192:195], v[48:51]
	v_mfma_f32_16x16x32_bf16 v[36:39], v[170:173], v[200:203], v[36:39]
	v_mfma_f32_16x16x32_bf16 v[32:35], v[178:181], v[200:203], v[32:35]
	v_mfma_f32_16x16x32_bf16 v[20:23], v[170:173], v[208:211], v[20:23]
	v_mfma_f32_16x16x32_bf16 v[16:19], v[178:181], v[208:211], v[16:19]
	v_mfma_f32_16x16x32_bf16 v[4:7], v[170:173], v[216:219], v[4:7]
	v_mfma_f32_16x16x32_bf16 v[0:3], v[178:181], v[216:219], v[0:3]
	s_barrier
	s_add_i32 s54, s54, 2
	s_add_u32 s22, s22, 0x100
	s_addc_u32 s23, s23, 0
	s_add_u32 s52, s52, 0x100
	s_addc_u32 s53, s53, 0
	s_cmp_gt_u32 s54, 13
	s_cbranch_scc0 .LBB0_192
	s_and_b64 vcc, exec, s[6:7]
	s_cbranch_vccz .LBB0_195
	s_barrier

; #define PG8_WAIT_V(n) asm volatile("s_waitcnt vmcnt(" #n ")" ::: "memory")
; #define PG8_BAR __builtin_amdgcn_s_barrier()
; template <class Epi, class Sched, bool ALIGN_EPI = false, bool SP2 = false>
; __device__ __forceinline__ void gemm_phase(PG8_LAS unsigned char* lds, const Gemm g, const Sched& S, const Epi& E) {
;     ...
;     PG8_WAIT_V(0);
;     if constexpr (!ALIGN_EPI) { if (wr == 0) PG8_BAR; }
;     PG8_BAR;
.LBB0_198:
	s_setprio 0
	s_waitcnt vmcnt(0)
	s_barrier

; #define PG8_STAGE(bufoff, gbase, voff) do { _Pragma("unroll") for (int _i = 0; _i < 2; ++_i) \
;         __builtin_amdgcn_global_load_lds((const unsigned*)((const char*)(gbase) + (voff)[_i]), (PG8_LAS unsigned*)(lds + (bufoff) + ldsw + _i * 8192), 16, 0, 0); } while (0)
; #define PG8_WAIT_V(n) asm volatile("s_waitcnt vmcnt(" #n ")" ::: "memory")
; #define PG8_BAR __builtin_amdgcn_s_barrier()
; template <class Epi, class Sched, bool ALIGN_EPI = false, bool SP2 = false>
; __device__ __forceinline__ void gemm_phase(PG8_LAS unsigned char* lds, const Gemm g, const Sched& S, const Epi& E) {
;     ...
;     for (int i = 0; i < 2; ++i) { int R, C; stage_rc(tid * 16 + i * 8192, R, C); const int Rb = Epi::PERM ? ((R & ~31) + perm32(R & 31)) : R;
;         voffA[i] = (unsigned)(R * K + C) * 2u; voffB[i] = (unsigned)(Rb * K + C) * 2u; }
;     const size_t kstep = (size_t)(BK * 2);
;     const size_t hstep = (size_t)HALF * K * 2;
;     const size_t tstep = 2 * hstep;
;     const unsigned ldsw = (unsigned)wid * 1024u;
;     const int aoff = lds_byte(wr * 64 + fr, fq * 8), boff = lds_byte(wc * 32 + fr, fq * 8);
;     ...
;         PG8_STAGE(PG8_SB(0, 0), cB, voffB); PG8_STAGE(PG8_SB(0, 1), cB + hstep, voffB); PG8_STAGE(PG8_SA(0, 0), cA, voffA); PG8_STAGE(PG8_SA(0, 1), cA + hstep, voffA);
;         if (wr == 1) PG8_BAR;
;         PG8_WAIT_V(2); PG8_BAR;
;         PG8_STAGE(PG8_SB(1, 0), cB + kstep, voffB); PG8_STAGE(PG8_SA(1, 0), cA + kstep, voffA); PG8_STAGE(PG8_SB(1, 1), cB + hstep + kstep, voffB);
;         PG8_WAIT_V(6); PG8_BAR;
.LBB0_260:
	s_lshl_b32 s5, s5, 5
	s_mov_b64 s[14:15], 0x80
	s_and_b32 s18, s5, 0x60
	s_add_i32 m0, s42, 0x18000
	v_lshl_add_u64 v[6:7], v[6:7], 0, s[14:15]
	s_lshl_b32 s16, s0, 13
	s_lshl_b32 s5, s18, 7
	s_waitcnt vmcnt(2)
	s_barrier
	global_load_lds_dwordx4 v[6:7], off
	v_lshl_add_u64 v[4:5], v[4:5], 0, s[14:15]
	s_add_i32 m0, s42, 0x1a000
	s_add_i32 s47, s42, 0x8000
	s_add_i32 s48, s42, 0xa000
	global_load_lds_dwordx4 v[4:5], off
	v_lshl_add_u64 v[0:1], v[0:1], 0, s[14:15]
	s_mov_b32 m0, s47
	s_add_u32 s6, s34, 0xb0080
	global_load_lds_dwordx4 v[0:1], off
	v_lshl_add_u64 v[0:1], v[2:3], 0, s[14:15]
	s_mov_b32 m0, s48
	s_addc_u32 s7, s35, 0
	global_load_lds_dwordx4 v[0:1], off
	s_add_i32 m0, s42, 0x1c000
	v_lshl_add_u64 v[0:1], s[6:7], 0, v[138:139]
	global_load_lds_dwordx4 v[0:1], off
	v_lshl_add_u64 v[0:1], s[6:7], 0, v[142:143]
	s_add_i32 m0, s42, 0x1e000
	s_cmpk_lt_u32 s4, 0x100
	global_load_lds_dwordx4 v[0:1], off
	v_bfe_u32 v1, v8, 4, 2
	v_and_b32_e32 v0, 15, v8
	v_lshlrev_b32_e32 v2, 4, v1
	v_lshl_or_b32 v158, s0, 6, v0
	v_lshl_or_b32 v0, v0, 6, v2
	v_lshlrev_b32_e32 v2, 2, v8
	v_and_b32_e32 v2, 32, v2
	v_readlane_b32 s0, v235, 0
	v_bitop3_b32 v3, v0, s16, v2 bitop3:0xde
	v_bitop3_b32 v159, v0, s5, v2 bitop3:0xde
	s_cselect_b64 s[16:17], -1, 0
	v_cmp_eq_u32_e64 s[4:5], 0, v1
	s_ashr_i32 s51, s0, 31
	v_lshl_or_b32 v160, v1, 3, s18
	v_lshrrev_b32_e32 v1, 1, v9
	v_mul_lo_u32 v0, v11, s1
	s_mov_b32 s0, 0xb000
	v_mad_u64_u32 v[0:1], s[18:19], v1, s0, v[0:1]
	v_or_b32_e32 v0, v0, v10
	s_mov_b64 s[6:7], 0xb0080
	v_add_lshl_u32 v0, v0, v12, 1
	v_mov_b32_e32 v1, v139
	v_lshl_add_u64 v[144:145], v[0:1], 0, s[6:7]
	v_lshrrev_b32_e32 v1, 1, v13
	v_mul_lo_u32 v0, v14, s1
	v_mad_u64_u32 v[0:1], s[0:1], v1, s0, v[0:1]
	s_waitcnt vmcnt(6)
	v_readlane_b32 s20, v235, 6
	v_or_b32_e32 v0, v0, v15
	v_readlane_b32 s21, v235, 7
	v_add_lshl_u32 v0, v0, v16, 1
	v_mov_b32_e32 v1, v139
	s_add_i32 s52, 0, 0x10000
	s_add_i32 s53, 0, 0x14000
	s_ashr_i32 s49, s20, 31
	s_mov_b32 s50, s20
	v_lshl_add_u64 v[146:147], v[0:1], 0, s[6:7]
	v_mov_b64_e32 v[148:149], 0x200
	v_mov_b64_e32 v[150:151], 0x1ff
	v_add_u32_e32 v161, s52, v159
	v_add_u32_e32 v162, s53, v159
	v_add_u32_e32 v163, 0, v3
	s_mov_b64 s[18:19], 0x20000
	s_mov_b64 s[20:21], 0x24000
	s_mov_b64 s[22:23], 0x28000
	s_mov_b64 s[24:25], 0x2c000
	v_mbcnt_hi_u32_b32 v164, -1, v190
	s_barrier
	v_readfirstlane_b32 s99, v189
	s_nop 0
	s_lshr_b32 s99, s99, 6
	s_cmp_ge_u32 s99, 4
	s_cbranch_scc0 .Lprio_263
	s_setprio 1
.Lprio_263:
	s_branch .LBB0_263
.LBB0_261:
	s_mov_b64 s[6:7], 0

; #define PG8_STAGE(bufoff, gbase, voff) do { _Pragma("unroll") for (int _i = 0; _i < 2; ++_i) \
;         __builtin_amdgcn_global_load_lds((const unsigned*)((const char*)(gbase) + (voff)[_i]), (PG8_LAS unsigned*)(lds + (bufoff) + ldsw + _i * 8192), 16, 0, 0); } while (0)
; #define PG8_LDA(dst, b, h) do { _Pragma("unroll") for (int m = 0; m < 4; ++m) _Pragma("unroll") for (int k = 0; k < 2; ++k) dst[m][k] = *(const PG8_LAS bf16x8*)(lds + PG8_SA(b, h) + aoff + m * 2048 + k * 1024); } while (0)
; #define PG8_LDB(dst, b, h) do { _Pragma("unroll") for (int n = 0; n < 2; ++n) _Pragma("unroll") for (int k = 0; k < 2; ++k) dst[n][k] = *(const PG8_LAS bf16x8*)(lds + PG8_SB(b, h) + boff + n * 2048 + k * 1024); } while (0)
; #define PG8_MMA(ai, bj, At, Bt) do { __builtin_amdgcn_s_setprio(1); _Pragma("unroll") for (int m = 0; m < 4; ++m) _Pragma("unroll") for (int n = 0; n < 2; ++n) _Pragma("unroll") for (int k = 0; k < 2; ++k) \
;         acc[ai][bj][m][n] = __builtin_amdgcn_mfma_f32_16x16x32_bf16(Bt[n][k], At[m][k], acc[ai][bj][m][n], 0, 0, 0); __builtin_amdgcn_s_setprio(0); } while (0)
; #define PG8_WAIT_V(n) asm volatile("s_waitcnt vmcnt(" #n ")" ::: "memory")
; #define PG8_WAIT_L(n) asm volatile("s_waitcnt lgkmcnt(" #n ")" ::: "memory")
; #define PG8_BAR __builtin_amdgcn_s_barrier()
; #define PG8_SCHED __builtin_amdgcn_sched_barrier(0)
; template <class Epi, class Sched, bool ALIGN_EPI = false, bool SP2 = false>
; __device__ __forceinline__ void gemm_phase(PG8_LAS unsigned char* lds, const Gemm g, const Sched& S, const Epi& E) {
;     ...
;             PG8_LDB(B0, 0, 0); PG8_LDB(B1, 0, 1); PG8_SCHED; PG8_LDA(At, 0, 0); PG8_STAGE(PG8_SA(1, 1), a1 + hstep, voffA);
;             PG8_WAIT_V(8); PG8_WAIT_L(0); PG8_BAR; PG8_MMA(0, 0, At, B0); PG8_MMA(0, 1, At, B1); PG8_BAR; PG8_SCHED;
;             PG8_LDA(At, 0, 1); PG8_STAGE(PG8_SB(0, 0), b2, voffB); PG8_STAGE(PG8_SB(0, 1), b2 + hstep, voffB); PG8_STAGE(PG8_SA(0, 0), a2, voffA);
;             PG8_WAIT_V(8); PG8_WAIT_L(0); PG8_BAR; PG8_MMA(1, 0, At, B0); PG8_MMA(1, 1, At, B1); PG8_BAR; PG8_SCHED;
.LBB0_273:
	s_add_u32 s58, s34, 0x100
	s_addc_u32 s59, s35, 0
	s_mov_b32 s60, -2
	s_waitcnt lgkmcnt(0)
	ds_read_b128 v[128:131], v161
	ds_read_b128 v[132:135], v161 offset:1024
	ds_read_b128 v[152:155], v161 offset:2048
	ds_read_b128 v[166:169], v161 offset:3072
	ds_read_b128 v[170:173], v162
	ds_read_b128 v[174:177], v162 offset:1024
	ds_read_b128 v[178:181], v162 offset:2048
	ds_read_b128 v[182:185], v162 offset:3072
	s_add_u32 s34, s8, 0x100
	s_addc_u32 s35, s9, 0
	s_cmp_eq_u32 s60, 40
	s_cselect_b32 s39, s1, s35
	s_cselect_b32 s38, s0, s34
	s_cselect_b32 s37, s31, s59
	s_cselect_b32 s36, s30, s58
	v_lshl_add_u64 v[156:157], s[8:9], 0, v[144:145]
	s_add_i32 m0, s42, 0xc000
	ds_read_b128 v[192:195], v163
	ds_read_b128 v[196:199], v163 offset:1024
	ds_read_b128 v[200:203], v163 offset:2048
	ds_read_b128 v[204:207], v163 offset:3072
	ds_read_b128 v[208:211], v163 offset:4096
	ds_read_b128 v[212:215], v163 offset:5120
	ds_read_b128 v[216:219], v163 offset:6144
	ds_read_b128 v[220:223], v163 offset:7168
	global_load_lds_dwordx4 v[156:157], off
	v_lshl_add_u64 v[156:157], s[8:9], 0, v[146:147]
	s_add_i32 m0, s42, 0xe000
	s_nop 0
	global_load_lds_dwordx4 v[156:157], off
	s_waitcnt vmcnt(8)
	s_waitcnt lgkmcnt(0)
	s_barrier
	v_mfma_f32_16x16x32_bf16 v[124:127], v[128:131], v[192:195], 0
	v_mfma_f32_16x16x32_bf16 v[120:123], v[152:155], v[192:195], 0
	v_mfma_f32_16x16x32_bf16 v[108:111], v[128:131], v[200:203], 0
	v_mfma_f32_16x16x32_bf16 v[104:107], v[152:155], v[200:203], 0
	v_mfma_f32_16x16x32_bf16 v[92:95], v[128:131], v[208:211], 0
	v_mfma_f32_16x16x32_bf16 v[88:91], v[152:155], v[208:211], 0
	v_mfma_f32_16x16x32_bf16 v[76:79], v[128:131], v[216:219], 0
	v_mfma_f32_16x16x32_bf16 v[72:75], v[152:155], v[216:219], 0
	v_mfma_f32_16x16x32_bf16 v[124:127], v[132:135], v[196:199], v[124:127]
	v_mfma_f32_16x16x32_bf16 v[120:123], v[166:169], v[196:199], v[120:123]
	v_mfma_f32_16x16x32_bf16 v[108:111], v[132:135], v[204:207], v[108:111]
	v_mfma_f32_16x16x32_bf16 v[104:107], v[166:169], v[204:207], v[104:107]
	v_mfma_f32_16x16x32_bf16 v[92:95], v[132:135], v[212:215], v[92:95]
	v_mfma_f32_16x16x32_bf16 v[88:91], v[166:169], v[212:215], v[88:91]
	v_mfma_f32_16x16x32_bf16 v[76:79], v[132:135], v[220:223], v[76:79]
	v_mfma_f32_16x16x32_bf16 v[72:75], v[166:169], v[220:223], v[72:75]
	v_mfma_f32_16x16x32_bf16 v[116:119], v[170:173], v[192:195], 0
	v_mfma_f32_16x16x32_bf16 v[112:115], v[178:181], v[192:195], 0
	v_mfma_f32_16x16x32_bf16 v[100:103], v[170:173], v[200:203], 0
	v_mfma_f32_16x16x32_bf16 v[96:99], v[178:181], v[200:203], 0
	v_mfma_f32_16x16x32_bf16 v[84:87], v[170:173], v[208:211], 0
	v_mfma_f32_16x16x32_bf16 v[80:83], v[178:181], v[208:211], 0
	v_mfma_f32_16x16x32_bf16 v[68:71], v[170:173], v[216:219], 0
	v_mfma_f32_16x16x32_bf16 v[64:67], v[178:181], v[216:219], 0
	v_mfma_f32_16x16x32_bf16 v[116:119], v[174:177], v[196:199], v[116:119]
	v_mfma_f32_16x16x32_bf16 v[112:115], v[182:185], v[196:199], v[112:115]
	v_mfma_f32_16x16x32_bf16 v[100:103], v[174:177], v[204:207], v[100:103]
	v_mfma_f32_16x16x32_bf16 v[96:99], v[182:185], v[204:207], v[96:99]
	v_mfma_f32_16x16x32_bf16 v[84:87], v[174:177], v[212:215], v[84:87]
	v_mfma_f32_16x16x32_bf16 v[80:83], v[182:185], v[212:215], v[80:83]
	v_mfma_f32_16x16x32_bf16 v[68:71], v[174:177], v[220:223], v[68:71]
	v_mfma_f32_16x16x32_bf16 v[64:67], v[182:185], v[220:223], v[64:67]
	s_barrier
	s_add_i32 s8, s52, s41
	v_lshl_add_u64 v[156:157], s[36:37], 0, v[138:139]
	s_mov_b32 m0, s8
	ds_read_b128 v[192:195], v163 offset:16384
	ds_read_b128 v[196:199], v163 offset:17408
	ds_read_b128 v[200:203], v163 offset:18432
	ds_read_b128 v[204:207], v163 offset:19456
	ds_read_b128 v[208:211], v163 offset:20480
	ds_read_b128 v[212:215], v163 offset:21504
	ds_read_b128 v[216:219], v163 offset:22528
	ds_read_b128 v[220:223], v163 offset:23552
	global_load_lds_dwordx4 v[156:157], off
	s_add_i32 m0, s8, 0x2000
	s_add_u32 s8, s36, 0xb0000
	v_lshl_add_u64 v[186:187], s[36:37], 0, v[142:143]
	s_addc_u32 s9, s37, 0
	s_add_i32 s61, s53, s41
	global_load_lds_dwordx4 v[186:187], off
	v_lshl_add_u64 v[224:225], s[8:9], 0, v[138:139]
	s_mov_b32 m0, s61
	v_lshl_add_u64 v[226:227], s[38:39], 0, v[140:141]
	global_load_lds_dwordx4 v[224:225], off
	v_lshl_add_u64 v[224:225], s[8:9], 0, v[142:143]
	s_add_i32 m0, s61, 0x2000
	s_nop 0
	global_load_lds_dwordx4 v[224:225], off
	v_lshl_add_u64 v[224:225], s[38:39], 0, v[136:137]
	s_mov_b32 m0, s42
	s_nop 0
	global_load_lds_dwordx4 v[224:225], off
	s_mov_b32 m0, s43
	s_nop 0
	global_load_lds_dwordx4 v[226:227], off
	s_waitcnt vmcnt(8)
	s_waitcnt lgkmcnt(0)
	s_barrier
; #define PG8_STAGE(bufoff, gbase, voff) do { _Pragma("unroll") for (int _i = 0; _i < 2; ++_i) \
;         __builtin_amdgcn_global_load_lds((const unsigned*)((const char*)(gbase) + (voff)[_i]), (PG8_LAS unsigned*)(lds + (bufoff) + ldsw + _i * 8192), 16, 0, 0); } while (0)
; #define PG8_LDA(dst, b, h) do { _Pragma("unroll") for (int m = 0; m < 4; ++m) _Pragma("unroll") for (int k = 0; k < 2; ++k) dst[m][k] = *(const PG8_LAS bf16x8*)(lds + PG8_SA(b, h) + aoff + m * 2048 + k * 1024); } while (0)
; #define PG8_LDB(dst, b, h) do { _Pragma("unroll") for (int n = 0; n < 2; ++n) _Pragma("unroll") for (int k = 0; k < 2; ++k) dst[n][k] = *(const PG8_LAS bf16x8*)(lds + PG8_SB(b, h) + boff + n * 2048 + k * 1024); } while (0)
; #define PG8_MMA(ai, bj, At, Bt) do { __builtin_amdgcn_s_setprio(1); _Pragma("unroll") for (int m = 0; m < 4; ++m) _Pragma("unroll") for (int n = 0; n < 2; ++n) _Pragma("unroll") for (int k = 0; k < 2; ++k) \
;         acc[ai][bj][m][n] = __builtin_amdgcn_mfma_f32_16x16x32_bf16(Bt[n][k], At[m][k], acc[ai][bj][m][n], 0, 0, 0); __builtin_amdgcn_s_setprio(0); } while (0)
; #define PG8_WAIT_V(n) asm volatile("s_waitcnt vmcnt(" #n ")" ::: "memory")
; template <class Epi, class Sched, bool ALIGN_EPI = false, bool SP2 = false>
; __device__ __forceinline__ void gemm_phase(PG8_LAS unsigned char* lds, const Gemm g, const Sched& S, const Epi& E) {
;     ...
;             PG8_LDB(B0, 0, 0); PG8_LDB(B1, 0, 1); PG8_SCHED; PG8_LDA(At, 0, 0); PG8_STAGE(PG8_SA(1, 1), a1 + hstep, voffA);
;             PG8_WAIT_V(8); PG8_WAIT_L(0); PG8_BAR; PG8_MMA(0, 0, At, B0); PG8_MMA(0, 1, At, B1); PG8_BAR; PG8_SCHED;
;             PG8_LDA(At, 0, 1); PG8_STAGE(PG8_SB(0, 0), b2, voffB); PG8_STAGE(PG8_SB(0, 1), b2 + hstep, voffB); PG8_STAGE(PG8_SA(0, 0), a2, voffA);
;             PG8_WAIT_V(8); PG8_WAIT_L(0); PG8_BAR; PG8_MMA(1, 0, At, B0); PG8_MMA(1, 1, At, B1); PG8_BAR; PG8_SCHED;
;             PG8_LDB(B0, 1, 0); PG8_LDB(B1, 1, 1); PG8_SCHED; PG8_LDA(At, 1, 0); PG8_STAGE(PG8_SA(0, 1), a2 + hstep, voffA);
;             PG8_WAIT_V(8); PG8_WAIT_L(0); PG8_BAR; PG8_MMA(0, 0, At, B0); PG8_MMA(0, 1, At, B1); PG8_BAR; PG8_SCHED;
;             PG8_LDA(At, 1, 1); PG8_STAGE(PG8_SB(1, 0), b3, voffB); PG8_STAGE(PG8_SB(1, 1), b3 + hstep, voffB); PG8_STAGE(PG8_SA(1, 0), a3, voffA);
;             PG8_WAIT_V(8); PG8_WAIT_L(0); PG8_BAR; PG8_MMA(1, 0, At, B0); PG8_MMA(1, 1, At, B1); PG8_BAR; PG8_SCHED;
	v_mfma_f32_16x16x32_bf16 v[60:63], v[128:131], v[192:195], 0
	v_mfma_f32_16x16x32_bf16 v[56:59], v[152:155], v[192:195], 0
	v_mfma_f32_16x16x32_bf16 v[44:47], v[128:131], v[200:203], 0
	v_mfma_f32_16x16x32_bf16 v[40:43], v[152:155], v[200:203], 0
	v_mfma_f32_16x16x32_bf16 v[28:31], v[128:131], v[208:211], 0
	v_mfma_f32_16x16x32_bf16 v[24:27], v[152:155], v[208:211], 0
	v_mfma_f32_16x16x32_bf16 v[12:15], v[128:131], v[216:219], 0
	v_mfma_f32_16x16x32_bf16 v[8:11], v[152:155], v[216:219], 0
	v_mfma_f32_16x16x32_bf16 v[60:63], v[132:135], v[196:199], v[60:63]
	v_mfma_f32_16x16x32_bf16 v[56:59], v[166:169], v[196:199], v[56:59]
	v_mfma_f32_16x16x32_bf16 v[44:47], v[132:135], v[204:207], v[44:47]
	v_mfma_f32_16x16x32_bf16 v[40:43], v[166:169], v[204:207], v[40:43]
	v_mfma_f32_16x16x32_bf16 v[28:31], v[132:135], v[212:215], v[28:31]
	v_mfma_f32_16x16x32_bf16 v[24:27], v[166:169], v[212:215], v[24:27]
	v_mfma_f32_16x16x32_bf16 v[12:15], v[132:135], v[220:223], v[12:15]
	v_mfma_f32_16x16x32_bf16 v[8:11], v[166:169], v[220:223], v[8:11]
	v_mfma_f32_16x16x32_bf16 v[52:55], v[170:173], v[192:195], 0
	v_mfma_f32_16x16x32_bf16 v[48:51], v[178:181], v[192:195], 0
	v_mfma_f32_16x16x32_bf16 v[36:39], v[170:173], v[200:203], 0
	v_mfma_f32_16x16x32_bf16 v[32:35], v[178:181], v[200:203], 0
	v_mfma_f32_16x16x32_bf16 v[20:23], v[170:173], v[208:211], 0
	v_mfma_f32_16x16x32_bf16 v[16:19], v[178:181], v[208:211], 0
	v_mfma_f32_16x16x32_bf16 v[4:7], v[170:173], v[216:219], 0
	v_mfma_f32_16x16x32_bf16 v[0:3], v[178:181], v[216:219], 0
	v_mfma_f32_16x16x32_bf16 v[52:55], v[174:177], v[196:199], v[52:55]
	v_mfma_f32_16x16x32_bf16 v[48:51], v[182:185], v[196:199], v[48:51]
	v_mfma_f32_16x16x32_bf16 v[36:39], v[174:177], v[204:207], v[36:39]
	v_mfma_f32_16x16x32_bf16 v[32:35], v[182:185], v[204:207], v[32:35]
	v_mfma_f32_16x16x32_bf16 v[20:23], v[174:177], v[212:215], v[20:23]
	v_mfma_f32_16x16x32_bf16 v[16:19], v[182:185], v[212:215], v[16:19]
	v_mfma_f32_16x16x32_bf16 v[4:7], v[174:177], v[220:223], v[4:7]
	v_mfma_f32_16x16x32_bf16 v[0:3], v[182:185], v[220:223], v[0:3]
	s_barrier
	s_add_i32 s61, 0, 0x18000
	v_add_u32_e32 v165, s61, v159
	s_add_i32 s62, 0, 0x1c000
	ds_read_b128 v[128:131], v165
	ds_read_b128 v[132:135], v165 offset:1024
	ds_read_b128 v[152:155], v165 offset:2048
	ds_read_b128 v[166:169], v165 offset:3072
	v_add_u32_e32 v165, s62, v159
	ds_read_b128 v[170:173], v165
	ds_read_b128 v[174:177], v165 offset:1024
	ds_read_b128 v[178:181], v165 offset:2048
	ds_read_b128 v[182:185], v165 offset:3072
	s_add_u32 s8, s38, 0xb0000
	s_addc_u32 s9, s39, 0
	s_mov_b32 m0, s44
	v_lshl_add_u64 v[228:229], s[8:9], 0, v[136:137]
	ds_read_b128 v[192:195], v163 offset:32768
	ds_read_b128 v[196:199], v163 offset:33792
	ds_read_b128 v[200:203], v163 offset:34816
	ds_read_b128 v[204:207], v163 offset:35840
	ds_read_b128 v[208:211], v163 offset:36864
	ds_read_b128 v[212:215], v163 offset:37888
	ds_read_b128 v[216:219], v163 offset:38912
	ds_read_b128 v[220:223], v163 offset:39936
	global_load_lds_dwordx4 v[228:229], off
	v_lshl_add_u64 v[228:229], s[8:9], 0, v[140:141]
	s_mov_b32 m0, s45
	s_nop 0
	global_load_lds_dwordx4 v[228:229], off
	s_waitcnt vmcnt(8)
	s_waitcnt lgkmcnt(0)
	s_barrier
	v_mfma_f32_16x16x32_bf16 v[124:127], v[128:131], v[192:195], v[124:127]
	v_mfma_f32_16x16x32_bf16 v[120:123], v[152:155], v[192:195], v[120:123]
	v_mfma_f32_16x16x32_bf16 v[108:111], v[128:131], v[200:203], v[108:111]
	v_mfma_f32_16x16x32_bf16 v[104:107], v[152:155], v[200:203], v[104:107]
	v_mfma_f32_16x16x32_bf16 v[92:95], v[128:131], v[208:211], v[92:95]
	v_mfma_f32_16x16x32_bf16 v[88:91], v[152:155], v[208:211], v[88:91]
	v_mfma_f32_16x16x32_bf16 v[76:79], v[128:131], v[216:219], v[76:79]
	v_mfma_f32_16x16x32_bf16 v[72:75], v[152:155], v[216:219], v[72:75]
	v_mfma_f32_16x16x32_bf16 v[124:127], v[132:135], v[196:199], v[124:127]
	v_mfma_f32_16x16x32_bf16 v[120:123], v[166:169], v[196:199], v[120:123]
	v_mfma_f32_16x16x32_bf16 v[108:111], v[132:135], v[204:207], v[108:111]
	v_mfma_f32_16x16x32_bf16 v[104:107], v[166:169], v[204:207], v[104:107]
	v_mfma_f32_16x16x32_bf16 v[92:95], v[132:135], v[212:215], v[92:95]
	v_mfma_f32_16x16x32_bf16 v[88:91], v[166:169], v[212:215], v[88:91]
	v_mfma_f32_16x16x32_bf16 v[76:79], v[132:135], v[220:223], v[76:79]
	v_mfma_f32_16x16x32_bf16 v[72:75], v[166:169], v[220:223], v[72:75]
	v_mfma_f32_16x16x32_bf16 v[116:119], v[170:173], v[192:195], v[116:119]
	v_mfma_f32_16x16x32_bf16 v[112:115], v[178:181], v[192:195], v[112:115]
	v_mfma_f32_16x16x32_bf16 v[100:103], v[170:173], v[200:203], v[100:103]
	v_mfma_f32_16x16x32_bf16 v[96:99], v[178:181], v[200:203], v[96:99]
	v_mfma_f32_16x16x32_bf16 v[84:87], v[170:173], v[208:211], v[84:87]
	v_mfma_f32_16x16x32_bf16 v[80:83], v[178:181], v[208:211], v[80:83]
	v_mfma_f32_16x16x32_bf16 v[68:71], v[170:173], v[216:219], v[68:71]
	v_mfma_f32_16x16x32_bf16 v[64:67], v[178:181], v[216:219], v[64:67]
	v_mfma_f32_16x16x32_bf16 v[116:119], v[174:177], v[196:199], v[116:119]
	v_mfma_f32_16x16x32_bf16 v[112:115], v[182:185], v[196:199], v[112:115]
	v_mfma_f32_16x16x32_bf16 v[100:103], v[174:177], v[204:207], v[100:103]
	v_mfma_f32_16x16x32_bf16 v[96:99], v[182:185], v[204:207], v[96:99]
	v_mfma_f32_16x16x32_bf16 v[84:87], v[174:177], v[212:215], v[84:87]
	v_mfma_f32_16x16x32_bf16 v[80:83], v[182:185], v[212:215], v[80:83]
	v_mfma_f32_16x16x32_bf16 v[68:71], v[174:177], v[220:223], v[68:71]
	v_mfma_f32_16x16x32_bf16 v[64:67], v[182:185], v[220:223], v[64:67]
	s_barrier
; #define PG8_STAGE(bufoff, gbase, voff) do { _Pragma("unroll") for (int _i = 0; _i < 2; ++_i) \
;         __builtin_amdgcn_global_load_lds((const unsigned*)((const char*)(gbase) + (voff)[_i]), (PG8_LAS unsigned*)(lds + (bufoff) + ldsw + _i * 8192), 16, 0, 0); } while (0)
; #define PG8_LDA(dst, b, h) do { _Pragma("unroll") for (int m = 0; m < 4; ++m) _Pragma("unroll") for (int k = 0; k < 2; ++k) dst[m][k] = *(const PG8_LAS bf16x8*)(lds + PG8_SA(b, h) + aoff + m * 2048 + k * 1024); } while (0)
; #define PG8_LDB(dst, b, h) do { _Pragma("unroll") for (int n = 0; n < 2; ++n) _Pragma("unroll") for (int k = 0; k < 2; ++k) dst[n][k] = *(const PG8_LAS bf16x8*)(lds + PG8_SB(b, h) + boff + n * 2048 + k * 1024); } while (0)
; template <class Epi, class Sched, bool ALIGN_EPI = false, bool SP2 = false>
; __device__ __forceinline__ void gemm_phase(PG8_LAS unsigned char* lds, const Gemm g, const Sched& S, const Epi& E) {
;     ...
;         for (int t = 0; t < nt; t += 2) {
;             const bool last = (t == nt - 2);
;             const char* a1 = cA + (size_t)(t + 1) * kstep;
;             const char* a2 = last ? nA : cA + (size_t)(t + 2) * kstep; const char* b2 = last ? nB : cB + (size_t)(t + 2) * kstep;
;             const char* a3 = a2 + kstep; const char* b3 = b2 + kstep;
;             if (last && has_next) S.a_ready(nxt);
;             if constexpr (SP2) {
;             PG8_LDB(B0, 0, 0); PG8_LDB(B1, 0, 1); PG8_SCHED; PG8_LDA(At, 0, 0); PG8_STAGE(PG8_SA(1, 1), a1 + hstep, voffA);
;             PG8_WAIT_V(8); PG8_WAIT_L(0); PG8_BAR; PG8_MMA(0, 0, At, B0); PG8_MMA(0, 1, At, B1); PG8_BAR; PG8_SCHED;
;             PG8_LDA(At, 0, 1); PG8_STAGE(PG8_SB(0, 0), b2, voffB); PG8_STAGE(PG8_SB(0, 1), b2 + hstep, voffB); PG8_STAGE(PG8_SA(0, 0), a2, voffA);
;             PG8_WAIT_V(8); PG8_WAIT_L(0); PG8_BAR; PG8_MMA(1, 0, At, B0); PG8_MMA(1, 1, At, B1); PG8_BAR; PG8_SCHED;
;             PG8_LDB(B0, 1, 0); PG8_LDB(B1, 1, 1); PG8_SCHED; PG8_LDA(At, 1, 0); PG8_STAGE(PG8_SA(0, 1), a2 + hstep, voffA);
;             PG8_WAIT_V(8); PG8_WAIT_L(0); PG8_BAR; PG8_MMA(0, 0, At, B0); PG8_MMA(0, 1, At, B1); PG8_BAR; PG8_SCHED;
;             PG8_LDA(At, 1, 1); PG8_STAGE(PG8_SB(1, 0), b3, voffB); PG8_STAGE(PG8_SB(1, 1), b3 + hstep, voffB); PG8_STAGE(PG8_SA(1, 0), a3, voffA);
;             PG8_WAIT_V(8); PG8_WAIT_L(0); PG8_BAR; PG8_MMA(1, 0, At, B0); PG8_MMA(1, 1, At, B1); PG8_BAR; PG8_SCHED;
	s_add_i32 s8, s61, s41
	v_lshl_add_u64 v[156:157], v[156:157], 0, s[14:15]
	s_mov_b32 m0, s8
	ds_read_b128 v[192:195], v163 offset:49152
	ds_read_b128 v[196:199], v163 offset:50176
	ds_read_b128 v[200:203], v163 offset:51200
	ds_read_b128 v[204:207], v163 offset:52224
	ds_read_b128 v[208:211], v163 offset:53248
	ds_read_b128 v[212:215], v163 offset:54272
	ds_read_b128 v[216:219], v163 offset:55296
	ds_read_b128 v[220:223], v163 offset:56320
	global_load_lds_dwordx4 v[156:157], off
	s_add_i32 m0, s8, 0x2000
	s_add_u32 s8, s36, 0xb0080
	v_lshl_add_u64 v[156:157], v[186:187], 0, s[14:15]
	s_addc_u32 s9, s37, 0
	s_add_i32 s36, s62, s41
	global_load_lds_dwordx4 v[156:157], off
	v_lshl_add_u64 v[156:157], s[8:9], 0, v[138:139]
	s_mov_b32 m0, s36
	s_nop 0
	global_load_lds_dwordx4 v[156:157], off
	v_lshl_add_u64 v[156:157], s[8:9], 0, v[142:143]
	s_add_i32 m0, s36, 0x2000
	s_nop 0
	global_load_lds_dwordx4 v[156:157], off
	v_lshl_add_u64 v[156:157], v[224:225], 0, s[14:15]
	s_mov_b32 m0, s47
	s_nop 0
	global_load_lds_dwordx4 v[156:157], off
	v_lshl_add_u64 v[156:157], v[226:227], 0, s[14:15]
	s_mov_b32 m0, s48
	s_nop 0
	global_load_lds_dwordx4 v[156:157], off
	s_waitcnt vmcnt(8)
	s_waitcnt lgkmcnt(0)
	s_barrier
	v_mfma_f32_16x16x32_bf16 v[60:63], v[128:131], v[192:195], v[60:63]
	v_mfma_f32_16x16x32_bf16 v[56:59], v[152:155], v[192:195], v[56:59]
	v_mfma_f32_16x16x32_bf16 v[44:47], v[128:131], v[200:203], v[44:47]
	v_mfma_f32_16x16x32_bf16 v[40:43], v[152:155], v[200:203], v[40:43]
	v_mfma_f32_16x16x32_bf16 v[28:31], v[128:131], v[208:211], v[28:31]
	v_mfma_f32_16x16x32_bf16 v[24:27], v[152:155], v[208:211], v[24:27]
	v_mfma_f32_16x16x32_bf16 v[12:15], v[128:131], v[216:219], v[12:15]
	v_mfma_f32_16x16x32_bf16 v[8:11], v[152:155], v[216:219], v[8:11]
	v_mfma_f32_16x16x32_bf16 v[60:63], v[132:135], v[196:199], v[60:63]
	v_mfma_f32_16x16x32_bf16 v[56:59], v[166:169], v[196:199], v[56:59]
	v_mfma_f32_16x16x32_bf16 v[44:47], v[132:135], v[204:207], v[44:47]
	v_mfma_f32_16x16x32_bf16 v[40:43], v[166:169], v[204:207], v[40:43]
	v_mfma_f32_16x16x32_bf16 v[28:31], v[132:135], v[212:215], v[28:31]
	v_mfma_f32_16x16x32_bf16 v[24:27], v[166:169], v[212:215], v[24:27]
	v_mfma_f32_16x16x32_bf16 v[12:15], v[132:135], v[220:223], v[12:15]
	v_mfma_f32_16x16x32_bf16 v[8:11], v[166:169], v[220:223], v[8:11]
	v_mfma_f32_16x16x32_bf16 v[52:55], v[170:173], v[192:195], v[52:55]
	v_mfma_f32_16x16x32_bf16 v[48:51], v[178:181], v[192:195], v[48:51]
	v_mfma_f32_16x16x32_bf16 v[36:39], v[170:173], v[200:203], v[36:39]
	v_mfma_f32_16x16x32_bf16 v[32:35], v[178:181], v[200:203], v[32:35]
	v_mfma_f32_16x16x32_bf16 v[20:23], v[170:173], v[208:211], v[20:23]
	v_mfma_f32_16x16x32_bf16 v[16:19], v[178:181], v[208:211], v[16:19]
	v_mfma_f32_16x16x32_bf16 v[4:7], v[170:173], v[216:219], v[4:7]
	v_mfma_f32_16x16x32_bf16 v[0:3], v[178:181], v[216:219], v[0:3]
	v_mfma_f32_16x16x32_bf16 v[52:55], v[174:177], v[196:199], v[52:55]
	v_mfma_f32_16x16x32_bf16 v[48:51], v[182:185], v[196:199], v[48:51]
	v_mfma_f32_16x16x32_bf16 v[36:39], v[174:177], v[204:207], v[36:39]
	v_mfma_f32_16x16x32_bf16 v[32:35], v[182:185], v[204:207], v[32:35]
	v_mfma_f32_16x16x32_bf16 v[20:23], v[174:177], v[212:215], v[20:23]
	v_mfma_f32_16x16x32_bf16 v[16:19], v[182:185], v[212:215], v[16:19]
	v_mfma_f32_16x16x32_bf16 v[4:7], v[174:177], v[220:223], v[4:7]
	v_mfma_f32_16x16x32_bf16 v[0:3], v[182:185], v[220:223], v[0:3]
	s_barrier
	s_add_i32 s60, s60, 2
	s_add_u32 s58, s58, 0x100
	s_addc_u32 s59, s59, 0
	s_mov_b64 s[8:9], s[34:35]
.LBB0_274:
	ds_read_b128 v[128:131], v161
	ds_read_b128 v[132:135], v161 offset:1024
	ds_read_b128 v[152:155], v161 offset:2048
	ds_read_b128 v[166:169], v161 offset:3072
	ds_read_b128 v[170:173], v162
	ds_read_b128 v[174:177], v162 offset:1024
	ds_read_b128 v[178:181], v162 offset:2048
	ds_read_b128 v[182:185], v162 offset:3072
	s_add_u32 s34, s8, 0x100
	s_addc_u32 s35, s9, 0
	s_cmp_eq_u32 s60, 40
	s_cselect_b32 s39, s1, s35
	s_cselect_b32 s38, s0, s34
	s_cselect_b32 s37, s31, s59
	s_cselect_b32 s36, s30, s58
	v_lshl_add_u64 v[156:157], s[8:9], 0, v[144:145]
	s_add_i32 m0, s42, 0xc000
	ds_read_b128 v[192:195], v163
	ds_read_b128 v[196:199], v163 offset:1024
	ds_read_b128 v[200:203], v163 offset:2048
	ds_read_b128 v[204:207], v163 offset:3072
	ds_read_b128 v[208:211], v163 offset:4096
	ds_read_b128 v[212:215], v163 offset:5120
	ds_read_b128 v[216:219], v163 offset:6144
	ds_read_b128 v[220:223], v163 offset:7168
	global_load_lds_dwordx4 v[156:157], off
	v_lshl_add_u64 v[156:157], s[8:9], 0, v[146:147]
	s_add_i32 m0, s42, 0xe000
	s_nop 0
	global_load_lds_dwordx4 v[156:157], off
	s_waitcnt vmcnt(8)
	s_waitcnt lgkmcnt(0)
	s_barrier
; #define PG8_STAGE(bufoff, gbase, voff) do { _Pragma("unroll") for (int _i = 0; _i < 2; ++_i) \
;         __builtin_amdgcn_global_load_lds((const unsigned*)((const char*)(gbase) + (voff)[_i]), (PG8_LAS unsigned*)(lds + (bufoff) + ldsw + _i * 8192), 16, 0, 0); } while (0)
; #define PG8_LDA(dst, b, h) do { _Pragma("unroll") for (int m = 0; m < 4; ++m) _Pragma("unroll") for (int k = 0; k < 2; ++k) dst[m][k] = *(const PG8_LAS bf16x8*)(lds + PG8_SA(b, h) + aoff + m * 2048 + k * 1024); } while (0)
; #define PG8_LDB(dst, b, h) do { _Pragma("unroll") for (int n = 0; n < 2; ++n) _Pragma("unroll") for (int k = 0; k < 2; ++k) dst[n][k] = *(const PG8_LAS bf16x8*)(lds + PG8_SB(b, h) + boff + n * 2048 + k * 1024); } while (0)
; #define PG8_MMA(ai, bj, At, Bt) do { __builtin_amdgcn_s_setprio(1); _Pragma("unroll") for (int m = 0; m < 4; ++m) _Pragma("unroll") for (int n = 0; n < 2; ++n) _Pragma("unroll") for (int k = 0; k < 2; ++k) \
;         acc[ai][bj][m][n] = __builtin_amdgcn_mfma_f32_16x16x32_bf16(Bt[n][k], At[m][k], acc[ai][bj][m][n], 0, 0, 0); __builtin_amdgcn_s_setprio(0); } while (0)
; #define PG8_WAIT_V(n) asm volatile("s_waitcnt vmcnt(" #n ")" ::: "memory")
; template <class Epi, class Sched, bool ALIGN_EPI = false, bool SP2 = false>
; __device__ __forceinline__ void gemm_phase(PG8_LAS unsigned char* lds, const Gemm g, const Sched& S, const Epi& E) {
;     ...
;             PG8_LDB(B0, 0, 0); PG8_LDB(B1, 0, 1); PG8_SCHED; PG8_LDA(At, 0, 0); PG8_STAGE(PG8_SA(1, 1), a1 + hstep, voffA);
;             PG8_WAIT_V(8); PG8_WAIT_L(0); PG8_BAR; PG8_MMA(0, 0, At, B0); PG8_MMA(0, 1, At, B1); PG8_BAR; PG8_SCHED;
;             PG8_LDA(At, 0, 1); PG8_STAGE(PG8_SB(0, 0), b2, voffB); PG8_STAGE(PG8_SB(0, 1), b2 + hstep, voffB); PG8_STAGE(PG8_SA(0, 0), a2, voffA);
;             PG8_WAIT_V(8); PG8_WAIT_L(0); PG8_BAR; PG8_MMA(1, 0, At, B0); PG8_MMA(1, 1, At, B1); PG8_BAR; PG8_SCHED;
;             PG8_LDB(B0, 1, 0); PG8_LDB(B1, 1, 1); PG8_SCHED; PG8_LDA(At, 1, 0); PG8_STAGE(PG8_SA(0, 1), a2 + hstep, voffA);
;             PG8_WAIT_V(8); PG8_WAIT_L(0); PG8_BAR; PG8_MMA(0, 0, At, B0); PG8_MMA(0, 1, At, B1); PG8_BAR; PG8_SCHED;
;             PG8_LDA(At, 1, 1); PG8_STAGE(PG8_SB(1, 0), b3, voffB); PG8_STAGE(PG8_SB(1, 1), b3 + hstep, voffB); PG8_STAGE(PG8_SA(1, 0), a3, voffA);
;             PG8_WAIT_V(8); PG8_WAIT_L(0); PG8_BAR; PG8_MMA(1, 0, At, B0); PG8_MMA(1, 1, At, B1); PG8_BAR; PG8_SCHED;
	v_mfma_f32_16x16x32_bf16 v[124:127], v[128:131], v[192:195], v[124:127]
	v_mfma_f32_16x16x32_bf16 v[120:123], v[152:155], v[192:195], v[120:123]
	v_mfma_f32_16x16x32_bf16 v[108:111], v[128:131], v[200:203], v[108:111]
	v_mfma_f32_16x16x32_bf16 v[104:107], v[152:155], v[200:203], v[104:107]
	v_mfma_f32_16x16x32_bf16 v[92:95], v[128:131], v[208:211], v[92:95]
	v_mfma_f32_16x16x32_bf16 v[88:91], v[152:155], v[208:211], v[88:91]
	v_mfma_f32_16x16x32_bf16 v[76:79], v[128:131], v[216:219], v[76:79]
	v_mfma_f32_16x16x32_bf16 v[72:75], v[152:155], v[216:219], v[72:75]
	v_mfma_f32_16x16x32_bf16 v[124:127], v[132:135], v[196:199], v[124:127]
	v_mfma_f32_16x16x32_bf16 v[120:123], v[166:169], v[196:199], v[120:123]
	v_mfma_f32_16x16x32_bf16 v[108:111], v[132:135], v[204:207], v[108:111]
	v_mfma_f32_16x16x32_bf16 v[104:107], v[166:169], v[204:207], v[104:107]
	v_mfma_f32_16x16x32_bf16 v[92:95], v[132:135], v[212:215], v[92:95]
	v_mfma_f32_16x16x32_bf16 v[88:91], v[166:169], v[212:215], v[88:91]
	v_mfma_f32_16x16x32_bf16 v[76:79], v[132:135], v[220:223], v[76:79]
	v_mfma_f32_16x16x32_bf16 v[72:75], v[166:169], v[220:223], v[72:75]
	v_mfma_f32_16x16x32_bf16 v[116:119], v[170:173], v[192:195], v[116:119]
	v_mfma_f32_16x16x32_bf16 v[112:115], v[178:181], v[192:195], v[112:115]
	v_mfma_f32_16x16x32_bf16 v[100:103], v[170:173], v[200:203], v[100:103]
	v_mfma_f32_16x16x32_bf16 v[96:99], v[178:181], v[200:203], v[96:99]
	v_mfma_f32_16x16x32_bf16 v[84:87], v[170:173], v[208:211], v[84:87]
	v_mfma_f32_16x16x32_bf16 v[80:83], v[178:181], v[208:211], v[80:83]
	v_mfma_f32_16x16x32_bf16 v[68:71], v[170:173], v[216:219], v[68:71]
	v_mfma_f32_16x16x32_bf16 v[64:67], v[178:181], v[216:219], v[64:67]
	v_mfma_f32_16x16x32_bf16 v[116:119], v[174:177], v[196:199], v[116:119]
	v_mfma_f32_16x16x32_bf16 v[112:115], v[182:185], v[196:199], v[112:115]
	v_mfma_f32_16x16x32_bf16 v[100:103], v[174:177], v[204:207], v[100:103]
	v_mfma_f32_16x16x32_bf16 v[96:99], v[182:185], v[204:207], v[96:99]
	v_mfma_f32_16x16x32_bf16 v[84:87], v[174:177], v[212:215], v[84:87]
	v_mfma_f32_16x16x32_bf16 v[80:83], v[182:185], v[212:215], v[80:83]
	v_mfma_f32_16x16x32_bf16 v[68:71], v[174:177], v[220:223], v[68:71]
	v_mfma_f32_16x16x32_bf16 v[64:67], v[182:185], v[220:223], v[64:67]
	s_barrier
	s_add_i32 s8, s52, s41
	v_lshl_add_u64 v[156:157], s[36:37], 0, v[138:139]
	s_mov_b32 m0, s8
	ds_read_b128 v[192:195], v163 offset:16384
	ds_read_b128 v[196:199], v163 offset:17408
	ds_read_b128 v[200:203], v163 offset:18432
	ds_read_b128 v[204:207], v163 offset:19456
	ds_read_b128 v[208:211], v163 offset:20480
	ds_read_b128 v[212:215], v163 offset:21504
	ds_read_b128 v[216:219], v163 offset:22528
	ds_read_b128 v[220:223], v163 offset:23552
	global_load_lds_dwordx4 v[156:157], off
	s_add_i32 m0, s8, 0x2000
	s_add_u32 s8, s36, 0xb0000
	v_lshl_add_u64 v[186:187], s[36:37], 0, v[142:143]
	s_addc_u32 s9, s37, 0
	s_add_i32 s61, s53, s41
	global_load_lds_dwordx4 v[186:187], off
	v_lshl_add_u64 v[224:225], s[8:9], 0, v[138:139]
	s_mov_b32 m0, s61
	v_lshl_add_u64 v[226:227], s[38:39], 0, v[140:141]
	global_load_lds_dwordx4 v[224:225], off
	v_lshl_add_u64 v[224:225], s[8:9], 0, v[142:143]
	s_add_i32 m0, s61, 0x2000
	s_nop 0
	global_load_lds_dwordx4 v[224:225], off
	v_lshl_add_u64 v[224:225], s[38:39], 0, v[136:137]
	s_mov_b32 m0, s42
	s_nop 0
	global_load_lds_dwordx4 v[224:225], off
	s_mov_b32 m0, s43
	s_nop 0
	global_load_lds_dwordx4 v[226:227], off
	s_waitcnt vmcnt(8)
	s_waitcnt lgkmcnt(0)
	s_barrier
	v_mfma_f32_16x16x32_bf16 v[60:63], v[128:131], v[192:195], v[60:63]
	v_mfma_f32_16x16x32_bf16 v[56:59], v[152:155], v[192:195], v[56:59]
	v_mfma_f32_16x16x32_bf16 v[44:47], v[128:131], v[200:203], v[44:47]
	v_mfma_f32_16x16x32_bf16 v[40:43], v[152:155], v[200:203], v[40:43]
	v_mfma_f32_16x16x32_bf16 v[28:31], v[128:131], v[208:211], v[28:31]
	v_mfma_f32_16x16x32_bf16 v[24:27], v[152:155], v[208:211], v[24:27]
	v_mfma_f32_16x16x32_bf16 v[12:15], v[128:131], v[216:219], v[12:15]
	v_mfma_f32_16x16x32_bf16 v[8:11], v[152:155], v[216:219], v[8:11]
	v_mfma_f32_16x16x32_bf16 v[60:63], v[132:135], v[196:199], v[60:63]
	v_mfma_f32_16x16x32_bf16 v[56:59], v[166:169], v[196:199], v[56:59]
	v_mfma_f32_16x16x32_bf16 v[44:47], v[132:135], v[204:207], v[44:47]
	v_mfma_f32_16x16x32_bf16 v[40:43], v[166:169], v[204:207], v[40:43]
	v_mfma_f32_16x16x32_bf16 v[28:31], v[132:135], v[212:215], v[28:31]
	v_mfma_f32_16x16x32_bf16 v[24:27], v[166:169], v[212:215], v[24:27]
	v_mfma_f32_16x16x32_bf16 v[12:15], v[132:135], v[220:223], v[12:15]
	v_mfma_f32_16x16x32_bf16 v[8:11], v[166:169], v[220:223], v[8:11]
	v_mfma_f32_16x16x32_bf16 v[52:55], v[170:173], v[192:195], v[52:55]
	v_mfma_f32_16x16x32_bf16 v[48:51], v[178:181], v[192:195], v[48:51]
	v_mfma_f32_16x16x32_bf16 v[36:39], v[170:173], v[200:203], v[36:39]
	v_mfma_f32_16x16x32_bf16 v[32:35], v[178:181], v[200:203], v[32:35]
	v_mfma_f32_16x16x32_bf16 v[20:23], v[170:173], v[208:211], v[20:23]
	v_mfma_f32_16x16x32_bf16 v[16:19], v[178:181], v[208:211], v[16:19]
	v_mfma_f32_16x16x32_bf16 v[4:7], v[170:173], v[216:219], v[4:7]
	v_mfma_f32_16x16x32_bf16 v[0:3], v[178:181], v[216:219], v[0:3]
	v_mfma_f32_16x16x32_bf16 v[52:55], v[174:177], v[196:199], v[52:55]
	v_mfma_f32_16x16x32_bf16 v[48:51], v[182:185], v[196:199], v[48:51]
	v_mfma_f32_16x16x32_bf16 v[36:39], v[174:177], v[204:207], v[36:39]
	v_mfma_f32_16x16x32_bf16 v[32:35], v[182:185], v[204:207], v[32:35]
	v_mfma_f32_16x16x32_bf16 v[20:23], v[174:177], v[212:215], v[20:23]
	v_mfma_f32_16x16x32_bf16 v[16:19], v[182:185], v[212:215], v[16:19]
	v_mfma_f32_16x16x32_bf16 v[4:7], v[174:177], v[220:223], v[4:7]
	v_mfma_f32_16x16x32_bf16 v[0:3], v[182:185], v[220:223], v[0:3]
	s_barrier
; #define PG8_STAGE(bufoff, gbase, voff) do { _Pragma("unroll") for (int _i = 0; _i < 2; ++_i) \
;         __builtin_amdgcn_global_load_lds((const unsigned*)((const char*)(gbase) + (voff)[_i]), (PG8_LAS unsigned*)(lds + (bufoff) + ldsw + _i * 8192), 16, 0, 0); } while (0)
; #define PG8_LDA(dst, b, h) do { _Pragma("unroll") for (int m = 0; m < 4; ++m) _Pragma("unroll") for (int k = 0; k < 2; ++k) dst[m][k] = *(const PG8_LAS bf16x8*)(lds + PG8_SA(b, h) + aoff + m * 2048 + k * 1024); } while (0)
; #define PG8_LDB(dst, b, h) do { _Pragma("unroll") for (int n = 0; n < 2; ++n) _Pragma("unroll") for (int k = 0; k < 2; ++k) dst[n][k] = *(const PG8_LAS bf16x8*)(lds + PG8_SB(b, h) + boff + n * 2048 + k * 1024); } while (0)
; #define PG8_MMA(ai, bj, At, Bt) do { __builtin_amdgcn_s_setprio(1); _Pragma("unroll") for (int m = 0; m < 4; ++m) _Pragma("unroll") for (int n = 0; n < 2; ++n) _Pragma("unroll") for (int k = 0; k < 2; ++k) \
;         acc[ai][bj][m][n] = __builtin_amdgcn_mfma_f32_16x16x32_bf16(Bt[n][k], At[m][k], acc[ai][bj][m][n], 0, 0, 0); __builtin_amdgcn_s_setprio(0); } while (0)
; #define PG8_WAIT_V(n) asm volatile("s_waitcnt vmcnt(" #n ")" ::: "memory")
; #define PG8_WAIT_L(n) asm volatile("s_waitcnt lgkmcnt(" #n ")" ::: "memory")
; #define PG8_BAR __builtin_amdgcn_s_barrier()
; #define PG8_SCHED __builtin_amdgcn_sched_barrier(0)
; template <class Epi, class Sched, bool ALIGN_EPI = false, bool SP2 = false>
; __device__ __forceinline__ void gemm_phase(PG8_LAS unsigned char* lds, const Gemm g, const Sched& S, const Epi& E) {
;     ...
;             PG8_LDB(B0, 1, 0); PG8_LDB(B1, 1, 1); PG8_SCHED; PG8_LDA(At, 1, 0); PG8_STAGE(PG8_SA(0, 1), a2 + hstep, voffA);
;             PG8_WAIT_V(8); PG8_WAIT_L(0); PG8_BAR; PG8_MMA(0, 0, At, B0); PG8_MMA(0, 1, At, B1); PG8_BAR; PG8_SCHED;
;             PG8_LDA(At, 1, 1); PG8_STAGE(PG8_SB(1, 0), b3, voffB); PG8_STAGE(PG8_SB(1, 1), b3 + hstep, voffB); PG8_STAGE(PG8_SA(1, 0), a3, voffA);
;             PG8_WAIT_V(8); PG8_WAIT_L(0); PG8_BAR; PG8_MMA(1, 0, At, B0); PG8_MMA(1, 1, At, B1); PG8_BAR; PG8_SCHED;
;     ...
;         if constexpr (ALIGN_EPI) { if (wr == 0) PG8_BAR; }
;         if constexpr (!Epi::AFTER_DRAIN) { E(acc, cur, wr, wc, fr, fq); S.done(cur); }
;         if (!has_next) break;
	s_add_i32 s61, 0, 0x18000
	v_add_u32_e32 v165, s61, v159
	s_add_i32 s62, 0, 0x1c000
	ds_read_b128 v[128:131], v165
	ds_read_b128 v[132:135], v165 offset:1024
	ds_read_b128 v[152:155], v165 offset:2048
	ds_read_b128 v[166:169], v165 offset:3072
	v_add_u32_e32 v165, s62, v159
	ds_read_b128 v[170:173], v165
	ds_read_b128 v[174:177], v165 offset:1024
	ds_read_b128 v[178:181], v165 offset:2048
	ds_read_b128 v[182:185], v165 offset:3072
	s_add_u32 s8, s38, 0xb0000
	s_addc_u32 s9, s39, 0
	s_mov_b32 m0, s44
	v_lshl_add_u64 v[228:229], s[8:9], 0, v[136:137]
	ds_read_b128 v[192:195], v163 offset:32768
	ds_read_b128 v[196:199], v163 offset:33792
	ds_read_b128 v[200:203], v163 offset:34816
	ds_read_b128 v[204:207], v163 offset:35840
	ds_read_b128 v[208:211], v163 offset:36864
	ds_read_b128 v[212:215], v163 offset:37888
	ds_read_b128 v[216:219], v163 offset:38912
	ds_read_b128 v[220:223], v163 offset:39936
	global_load_lds_dwordx4 v[228:229], off
	v_lshl_add_u64 v[228:229], s[8:9], 0, v[140:141]
	s_mov_b32 m0, s45
	s_nop 0
	global_load_lds_dwordx4 v[228:229], off
	s_waitcnt vmcnt(8)
	s_waitcnt lgkmcnt(0)
	s_barrier
	v_mfma_f32_16x16x32_bf16 v[124:127], v[128:131], v[192:195], v[124:127]
	v_mfma_f32_16x16x32_bf16 v[120:123], v[152:155], v[192:195], v[120:123]
	v_mfma_f32_16x16x32_bf16 v[108:111], v[128:131], v[200:203], v[108:111]
	v_mfma_f32_16x16x32_bf16 v[104:107], v[152:155], v[200:203], v[104:107]
	v_mfma_f32_16x16x32_bf16 v[92:95], v[128:131], v[208:211], v[92:95]
	v_mfma_f32_16x16x32_bf16 v[88:91], v[152:155], v[208:211], v[88:91]
	v_mfma_f32_16x16x32_bf16 v[76:79], v[128:131], v[216:219], v[76:79]
	v_mfma_f32_16x16x32_bf16 v[72:75], v[152:155], v[216:219], v[72:75]
	v_mfma_f32_16x16x32_bf16 v[124:127], v[132:135], v[196:199], v[124:127]
	v_mfma_f32_16x16x32_bf16 v[120:123], v[166:169], v[196:199], v[120:123]
	v_mfma_f32_16x16x32_bf16 v[108:111], v[132:135], v[204:207], v[108:111]
	v_mfma_f32_16x16x32_bf16 v[104:107], v[166:169], v[204:207], v[104:107]
	v_mfma_f32_16x16x32_bf16 v[92:95], v[132:135], v[212:215], v[92:95]
	v_mfma_f32_16x16x32_bf16 v[88:91], v[166:169], v[212:215], v[88:91]
	v_mfma_f32_16x16x32_bf16 v[76:79], v[132:135], v[220:223], v[76:79]
	v_mfma_f32_16x16x32_bf16 v[72:75], v[166:169], v[220:223], v[72:75]
	v_mfma_f32_16x16x32_bf16 v[116:119], v[170:173], v[192:195], v[116:119]
	v_mfma_f32_16x16x32_bf16 v[112:115], v[178:181], v[192:195], v[112:115]
	v_mfma_f32_16x16x32_bf16 v[100:103], v[170:173], v[200:203], v[100:103]
	v_mfma_f32_16x16x32_bf16 v[96:99], v[178:181], v[200:203], v[96:99]
	v_mfma_f32_16x16x32_bf16 v[84:87], v[170:173], v[208:211], v[84:87]
	v_mfma_f32_16x16x32_bf16 v[80:83], v[178:181], v[208:211], v[80:83]
	v_mfma_f32_16x16x32_bf16 v[68:71], v[170:173], v[216:219], v[68:71]
	v_mfma_f32_16x16x32_bf16 v[64:67], v[178:181], v[216:219], v[64:67]
	v_mfma_f32_16x16x32_bf16 v[116:119], v[174:177], v[196:199], v[116:119]
	v_mfma_f32_16x16x32_bf16 v[112:115], v[182:185], v[196:199], v[112:115]
	v_mfma_f32_16x16x32_bf16 v[100:103], v[174:177], v[204:207], v[100:103]
	v_mfma_f32_16x16x32_bf16 v[96:99], v[182:185], v[204:207], v[96:99]
	v_mfma_f32_16x16x32_bf16 v[84:87], v[174:177], v[212:215], v[84:87]
	v_mfma_f32_16x16x32_bf16 v[80:83], v[182:185], v[212:215], v[80:83]
	v_mfma_f32_16x16x32_bf16 v[68:71], v[174:177], v[220:223], v[68:71]
	v_mfma_f32_16x16x32_bf16 v[64:67], v[182:185], v[220:223], v[64:67]
	s_barrier
	s_add_i32 s8, s61, s41
	v_lshl_add_u64 v[156:157], v[156:157], 0, s[14:15]
	s_mov_b32 m0, s8
	ds_read_b128 v[192:195], v163 offset:49152
	ds_read_b128 v[196:199], v163 offset:50176
	ds_read_b128 v[200:203], v163 offset:51200
	ds_read_b128 v[204:207], v163 offset:52224
	ds_read_b128 v[208:211], v163 offset:53248
	ds_read_b128 v[212:215], v163 offset:54272
	ds_read_b128 v[216:219], v163 offset:55296
	ds_read_b128 v[220:223], v163 offset:56320
	global_load_lds_dwordx4 v[156:157], off
	s_add_i32 m0, s8, 0x2000
	s_add_u32 s8, s36, 0xb0080
	v_lshl_add_u64 v[156:157], v[186:187], 0, s[14:15]
	s_addc_u32 s9, s37, 0
	s_add_i32 s36, s62, s41
	global_load_lds_dwordx4 v[156:157], off
	v_lshl_add_u64 v[156:157], s[8:9], 0, v[138:139]
	s_mov_b32 m0, s36
	s_nop 0
	global_load_lds_dwordx4 v[156:157], off
	v_lshl_add_u64 v[156:157], s[8:9], 0, v[142:143]
	s_add_i32 m0, s36, 0x2000
	s_nop 0
	global_load_lds_dwordx4 v[156:157], off
	v_lshl_add_u64 v[156:157], v[224:225], 0, s[14:15]
	s_mov_b32 m0, s47
	s_nop 0
	global_load_lds_dwordx4 v[156:157], off
	v_lshl_add_u64 v[156:157], v[226:227], 0, s[14:15]
	s_mov_b32 m0, s48
	s_nop 0
	global_load_lds_dwordx4 v[156:157], off
	s_waitcnt vmcnt(8)
	s_waitcnt lgkmcnt(0)
	s_barrier
	v_mfma_f32_16x16x32_bf16 v[60:63], v[128:131], v[192:195], v[60:63]
	v_mfma_f32_16x16x32_bf16 v[56:59], v[152:155], v[192:195], v[56:59]
	v_mfma_f32_16x16x32_bf16 v[44:47], v[128:131], v[200:203], v[44:47]
	v_mfma_f32_16x16x32_bf16 v[40:43], v[152:155], v[200:203], v[40:43]
	v_mfma_f32_16x16x32_bf16 v[28:31], v[128:131], v[208:211], v[28:31]
	v_mfma_f32_16x16x32_bf16 v[24:27], v[152:155], v[208:211], v[24:27]
	v_mfma_f32_16x16x32_bf16 v[12:15], v[128:131], v[216:219], v[12:15]
	v_mfma_f32_16x16x32_bf16 v[8:11], v[152:155], v[216:219], v[8:11]
	v_mfma_f32_16x16x32_bf16 v[60:63], v[132:135], v[196:199], v[60:63]
	v_mfma_f32_16x16x32_bf16 v[56:59], v[166:169], v[196:199], v[56:59]
	v_mfma_f32_16x16x32_bf16 v[44:47], v[132:135], v[204:207], v[44:47]
	v_mfma_f32_16x16x32_bf16 v[40:43], v[166:169], v[204:207], v[40:43]
	v_mfma_f32_16x16x32_bf16 v[28:31], v[132:135], v[212:215], v[28:31]
	v_mfma_f32_16x16x32_bf16 v[24:27], v[166:169], v[212:215], v[24:27]
	v_mfma_f32_16x16x32_bf16 v[12:15], v[132:135], v[220:223], v[12:15]
	v_mfma_f32_16x16x32_bf16 v[8:11], v[166:169], v[220:223], v[8:11]
	v_mfma_f32_16x16x32_bf16 v[52:55], v[170:173], v[192:195], v[52:55]
	v_mfma_f32_16x16x32_bf16 v[48:51], v[178:181], v[192:195], v[48:51]
	v_mfma_f32_16x16x32_bf16 v[36:39], v[170:173], v[200:203], v[36:39]
	v_mfma_f32_16x16x32_bf16 v[32:35], v[178:181], v[200:203], v[32:35]
	v_mfma_f32_16x16x32_bf16 v[20:23], v[170:173], v[208:211], v[20:23]
	v_mfma_f32_16x16x32_bf16 v[16:19], v[178:181], v[208:211], v[16:19]
	v_mfma_f32_16x16x32_bf16 v[4:7], v[170:173], v[216:219], v[4:7]
	v_mfma_f32_16x16x32_bf16 v[0:3], v[178:181], v[216:219], v[0:3]
	v_mfma_f32_16x16x32_bf16 v[52:55], v[174:177], v[196:199], v[52:55]
	v_mfma_f32_16x16x32_bf16 v[48:51], v[182:185], v[196:199], v[48:51]
	v_mfma_f32_16x16x32_bf16 v[36:39], v[174:177], v[204:207], v[36:39]
	v_mfma_f32_16x16x32_bf16 v[32:35], v[182:185], v[204:207], v[32:35]
	v_mfma_f32_16x16x32_bf16 v[20:23], v[174:177], v[212:215], v[20:23]
	v_mfma_f32_16x16x32_bf16 v[16:19], v[182:185], v[212:215], v[16:19]
	v_mfma_f32_16x16x32_bf16 v[4:7], v[174:177], v[220:223], v[4:7]
	v_mfma_f32_16x16x32_bf16 v[0:3], v[182:185], v[220:223], v[0:3]
	s_barrier
	s_add_i32 s60, s60, 2
	s_add_u32 s58, s58, 0x100
	s_addc_u32 s59, s59, 0
	s_cmp_gt_u32 s60, 41
	s_mov_b64 s[8:9], s[34:35]
	s_cbranch_scc0 .LBB0_274
	s_and_b64 vcc, exec, s[16:17]
	s_cbranch_vccz .LBB0_277
	s_barrier

; #define PG8_STAGE(bufoff, gbase, voff) do { _Pragma("unroll") for (int _i = 0; _i < 2; ++_i) \
;         __builtin_amdgcn_global_load_lds((const unsigned*)((const char*)(gbase) + (voff)[_i]), (PG8_LAS unsigned*)(lds + (bufoff) + ldsw + _i * 8192), 16, 0, 0); } while (0)
; #define PG8_WAIT_V(n) asm volatile("s_waitcnt vmcnt(" #n ")" ::: "memory")
; #define PG8_BAR __builtin_amdgcn_s_barrier()
; template <class Epi, class Sched, bool ALIGN_EPI = false, bool SP2 = false>
; __device__ __forceinline__ void gemm_phase(PG8_LAS unsigned char* lds, const Gemm g, const Sched& S, const Epi& E) {
;     ...
;     for (int i = 0; i < 2; ++i) { int R, C; stage_rc(tid * 16 + i * 8192, R, C); const int Rb = Epi::PERM ? ((R & ~31) + perm32(R & 31)) : R;
;         voffA[i] = (unsigned)(R * K + C) * 2u; voffB[i] = (unsigned)(Rb * K + C) * 2u; }
;     const size_t kstep = (size_t)(BK * 2);
;     const size_t hstep = (size_t)HALF * K * 2;
;     const size_t tstep = 2 * hstep;
;     const unsigned ldsw = (unsigned)wid * 1024u;
;     const int aoff = lds_byte(wr * 64 + fr, fq * 8), boff = lds_byte(wc * 32 + fr, fq * 8);
;     ...
;         PG8_STAGE(PG8_SB(0, 0), cB, voffB); PG8_STAGE(PG8_SB(0, 1), cB + hstep, voffB); PG8_STAGE(PG8_SA(0, 0), cA, voffA); PG8_STAGE(PG8_SA(0, 1), cA + hstep, voffA);
;         if (wr == 1) PG8_BAR;
;         PG8_WAIT_V(2); PG8_BAR;
;         PG8_STAGE(PG8_SB(1, 0), cB + kstep, voffB); PG8_STAGE(PG8_SA(1, 0), cA + kstep, voffA); PG8_STAGE(PG8_SB(1, 1), cB + hstep + kstep, voffB);
;         PG8_WAIT_V(6); PG8_BAR;
.LBB0_368:
	s_mov_b64 s[16:17], 0x80
	s_and_b32 s1, s6, 3
	s_add_i32 m0, s44, 0x18000
	v_lshl_add_u64 v[6:7], v[6:7], 0, s[16:17]
	s_lshl_b32 s12, s7, 13
	s_lshl_b32 s24, s1, 5
	s_lshl_b32 s20, s1, 12
	s_waitcnt vmcnt(2)
	s_barrier
	global_load_lds_dwordx4 v[6:7], off
	v_lshl_add_u64 v[4:5], v[4:5], 0, s[16:17]
	s_add_i32 m0, s44, 0x1a000
	s_add_i32 s48, s44, 0x8000
	s_add_i32 s49, s44, 0xa000
	global_load_lds_dwordx4 v[4:5], off
	v_lshl_add_u64 v[0:1], v[0:1], 0, s[16:17]
	s_mov_b32 m0, s48
	s_add_u32 s18, s38, 0x40080
	global_load_lds_dwordx4 v[0:1], off
	v_lshl_add_u64 v[0:1], v[2:3], 0, s[16:17]
	s_mov_b32 m0, s49
	s_addc_u32 s19, s39, 0
	global_load_lds_dwordx4 v[0:1], off
	s_add_i32 m0, s44, 0x1c000
	v_lshl_add_u64 v[0:1], s[18:19], 0, v[148:149]
	global_load_lds_dwordx4 v[0:1], off
	v_lshl_add_u64 v[0:1], s[18:19], 0, v[144:145]
	s_add_i32 m0, s44, 0x1e000
	v_bfe_u32 v2, v10, 4, 2
	global_load_lds_dwordx4 v[0:1], off
	v_lshrrev_b32_e32 v0, 4, v10
	v_and_b32_e32 v1, 15, v10
	v_lshlrev_b32_e32 v154, 3, v2
	v_lshlrev_b32_e32 v2, 4, v2
	v_bitop3_b32 v0, s6, v0, 3 bitop3:0xa8
	s_sext_i32_i8 s57, s4
	v_lshl_or_b32 v155, s7, 6, v1
	v_lshl_or_b32 v1, v1, 6, v2
	v_lshlrev_b32_e32 v2, 2, v10
	s_cmpk_lt_u32 s5, 0x100
	v_cmp_eq_u32_e64 s[4:5], 0, v0
	v_lshlrev_b32_e32 v0, 14, v13
	v_and_b32_e32 v2, 32, v2
	v_and_b32_e32 v0, 0xffff8000, v0
	v_bitop3_b32 v3, v1, s12, v2 bitop3:0xde
	v_bitop3_b32 v170, v1, s20, v2 bitop3:0xde
	v_lshl_add_u32 v0, v12, 11, v0
	v_and_b32_e32 v1, 1, v13
	v_lshl_or_b32 v0, v1, 6, v0
	v_lshl_add_u32 v156, v14, 1, v0
	v_lshlrev_b32_e32 v0, 14, v8
	v_and_b32_e32 v0, 0xffff8000, v0
	s_waitcnt vmcnt(6)
	v_lshl_add_u32 v0, v9, 11, v0
	v_and_b32_e32 v1, 1, v8
	s_cselect_b64 s[18:19], -1, 0
	s_lshl_b32 s1, s1, 6
	v_readlane_b32 s6, v235, 6
	v_lshl_or_b32 v0, v1, 6, v0
	s_add_i32 s52, 0, 0x10000
	s_add_i32 s53, 0, 0x14000
	s_ashr_i32 s50, s6, 31
	s_mov_b32 s51, s6
	v_mov_b32_e32 v157, v153
	v_lshl_add_u32 v158, v11, 1, v0
	v_mov_b32_e32 v159, v153
	v_mov_b64_e32 v[160:161], 0x700
	v_mov_b64_e32 v[162:163], 0x6ff
	v_add_u32_e32 v171, s52, v170
	v_add_u32_e32 v172, s53, v170
	v_add_u32_e32 v173, 0, v3
	v_mov_b32_e32 v174, 0x358637bd
	s_mov_b32 s54, 0x800000
	s_mov_b64 s[20:21], 0x1400
	s_mov_b64 s[22:23], 0x1600
	s_movk_i32 s55, 0x1c00
	s_lshl_b32 s24, s24, 1
	s_lshl_b32 s12, s1, 1
	v_mov_b32_e32 v175, 0x3e38aa3b
	v_mbcnt_hi_u32_b32 v176, -1, v190
	s_mov_b32 s56, s13
	s_barrier
	v_readlane_b32 s7, v235, 7
	v_readfirstlane_b32 s99, v189
	s_nop 0
	s_lshr_b32 s99, s99, 6
	s_cmp_ge_u32 s99, 4
	s_cbranch_scc0 .Lprio_371
	s_setprio 1
.Lprio_371:
	s_branch .LBB0_371
.LBB0_369:
	s_mov_b64 s[0:1], 0

; #define PG8_STAGE(bufoff, gbase, voff) do { _Pragma("unroll") for (int _i = 0; _i < 2; ++_i) \
;         __builtin_amdgcn_global_load_lds((const unsigned*)((const char*)(gbase) + (voff)[_i]), (PG8_LAS unsigned*)(lds + (bufoff) + ldsw + _i * 8192), 16, 0, 0); } while (0)
; #define PG8_LDA(dst, b, h) do { _Pragma("unroll") for (int m = 0; m < 4; ++m) _Pragma("unroll") for (int k = 0; k < 2; ++k) dst[m][k] = *(const PG8_LAS bf16x8*)(lds + PG8_SA(b, h) + aoff + m * 2048 + k * 1024); } while (0)
; #define PG8_LDB(dst, b, h) do { _Pragma("unroll") for (int n = 0; n < 2; ++n) _Pragma("unroll") for (int k = 0; k < 2; ++k) dst[n][k] = *(const PG8_LAS bf16x8*)(lds + PG8_SB(b, h) + boff + n * 2048 + k * 1024); } while (0)
; #define PG8_WAIT_V(n) asm volatile("s_waitcnt vmcnt(" #n ")" ::: "memory")
; #define PG8_WAIT_L(n) asm volatile("s_waitcnt lgkmcnt(" #n ")" ::: "memory")
; #define PG8_BAR __builtin_amdgcn_s_barrier()
; #define PG8_SCHED __builtin_amdgcn_sched_barrier(0)
; template <class Epi, class Sched, bool ALIGN_EPI = false, bool SP2 = false>
; __device__ __forceinline__ void gemm_phase(PG8_LAS unsigned char* lds, const Gemm g, const Sched& S, const Epi& E) {
;     ...
;         const bool has_next = S.next(ui + 1, nxt);
;         const char* nA = has_next ? (const char*)g.A + (size_t)nxt.pm * tstep : cA; const char* nB = has_next ? (const char*)g.Bt + (size_t)nxt.pn * tstep : cB;
;         for (int t = 0; t < nt; t += 2) {
;             const bool last = (t == nt - 2);
;             const char* a1 = cA + (size_t)(t + 1) * kstep;
;             const char* a2 = last ? nA : cA + (size_t)(t + 2) * kstep; const char* b2 = last ? nB : cB + (size_t)(t + 2) * kstep;
;             const char* a3 = a2 + kstep; const char* b3 = b2 + kstep;
;             if (last && has_next) S.a_ready(nxt);
;             if constexpr (SP2) {
;             PG8_LDB(B0, 0, 0); PG8_LDB(B1, 0, 1); PG8_SCHED; PG8_LDA(At, 0, 0); PG8_STAGE(PG8_SA(1, 1), a1 + hstep, voffA);
;             PG8_WAIT_V(8); PG8_WAIT_L(0); PG8_BAR; PG8_MMA(0, 0, At, B0); PG8_MMA(0, 1, At, B1); PG8_BAR; PG8_SCHED;
;             PG8_LDA(At, 0, 1); PG8_STAGE(PG8_SB(0, 0), b2, voffB); PG8_STAGE(PG8_SB(0, 1), b2 + hstep, voffB); PG8_STAGE(PG8_SA(0, 0), a2, voffA);
;             PG8_WAIT_V(8); PG8_WAIT_L(0); PG8_BAR; PG8_MMA(1, 0, At, B0); PG8_MMA(1, 1, At, B1); PG8_BAR; PG8_SCHED;
.LBB0_373:
	s_ashr_i32 s31, s30, 31
	s_lshl_b64 s[34:35], s[30:31], 19
	v_readlane_b32 s36, v235, 31
	v_readlane_b32 s37, v235, 32
	s_add_u32 s34, s36, s34
	s_addc_u32 s35, s37, s35
	s_and_b64 s[36:37], s[6:7], exec
	s_cselect_b32 s1, s35, s3
	s_cselect_b32 s25, s34, s2
	s_ashr_i32 s29, s28, 31
	s_lshl_b64 s[36:37], s[28:29], 19
	s_add_u32 s36, s10, s36
	s_addc_u32 s37, s11, s37
	s_and_b64 s[40:41], s[6:7], exec
	s_cselect_b32 s29, s37, s39
	s_cselect_b32 s31, s36, s38
	s_add_u32 s2, s2, 0x40080
	s_addc_u32 s3, s3, 0
	s_add_u32 s58, s38, 0x100
	s_addc_u32 s59, s39, 0
	s_mov_b32 s60, -2
	ds_read_b128 v[128:131], v171
	ds_read_b128 v[132:135], v171 offset:1024
	ds_read_b128 v[136:139], v171 offset:2048
	ds_read_b128 v[140:143], v171 offset:3072
	ds_read_b128 v[164:167], v172
	ds_read_b128 v[178:181], v172 offset:1024
	ds_read_b128 v[182:185], v172 offset:2048
	ds_read_b128 v[192:195], v172 offset:3072
	s_add_u32 s38, s2, 0xfffc0080
	s_addc_u32 s39, s3, -1
	s_cmp_eq_u32 s60, 12
	s_cselect_b32 s41, s1, s39
	s_cselect_b32 s40, s25, s38
	s_cselect_b32 s39, s29, s59
	s_cselect_b32 s38, s31, s58
	v_lshl_add_u64 v[168:169], s[2:3], 0, v[156:157]
	s_add_i32 m0, s44, 0xc000
	ds_read_b128 v[196:199], v173
	ds_read_b128 v[200:203], v173 offset:1024
	ds_read_b128 v[204:207], v173 offset:2048
	ds_read_b128 v[208:211], v173 offset:3072
	ds_read_b128 v[212:215], v173 offset:4096
	ds_read_b128 v[216:219], v173 offset:5120
	ds_read_b128 v[220:223], v173 offset:6144
	ds_read_b128 v[224:227], v173 offset:7168
	global_load_lds_dwordx4 v[168:169], off
	v_lshl_add_u64 v[168:169], s[2:3], 0, v[158:159]
	s_add_i32 m0, s44, 0xe000
	s_nop 0
	global_load_lds_dwordx4 v[168:169], off
	s_waitcnt vmcnt(8)
	s_waitcnt lgkmcnt(0)
	s_barrier
	v_mfma_f32_16x16x32_bf16 v[124:127], v[128:131], v[196:199], 0
	v_mfma_f32_16x16x32_bf16 v[120:123], v[136:139], v[196:199], 0
	v_mfma_f32_16x16x32_bf16 v[108:111], v[128:131], v[204:207], 0
	v_mfma_f32_16x16x32_bf16 v[104:107], v[136:139], v[204:207], 0
	v_mfma_f32_16x16x32_bf16 v[92:95], v[128:131], v[212:215], 0
	v_mfma_f32_16x16x32_bf16 v[88:91], v[136:139], v[212:215], 0
	v_mfma_f32_16x16x32_bf16 v[76:79], v[128:131], v[220:223], 0
	v_mfma_f32_16x16x32_bf16 v[72:75], v[136:139], v[220:223], 0
	v_mfma_f32_16x16x32_bf16 v[124:127], v[132:135], v[200:203], v[124:127]
	v_mfma_f32_16x16x32_bf16 v[120:123], v[140:143], v[200:203], v[120:123]
	v_mfma_f32_16x16x32_bf16 v[108:111], v[132:135], v[208:211], v[108:111]
	v_mfma_f32_16x16x32_bf16 v[104:107], v[140:143], v[208:211], v[104:107]
	v_mfma_f32_16x16x32_bf16 v[92:95], v[132:135], v[216:219], v[92:95]
	v_mfma_f32_16x16x32_bf16 v[88:91], v[140:143], v[216:219], v[88:91]
	v_mfma_f32_16x16x32_bf16 v[76:79], v[132:135], v[224:227], v[76:79]
	v_mfma_f32_16x16x32_bf16 v[72:75], v[140:143], v[224:227], v[72:75]
	v_mfma_f32_16x16x32_bf16 v[116:119], v[164:167], v[196:199], 0
	v_mfma_f32_16x16x32_bf16 v[112:115], v[182:185], v[196:199], 0
	v_mfma_f32_16x16x32_bf16 v[100:103], v[164:167], v[204:207], 0
	v_mfma_f32_16x16x32_bf16 v[96:99], v[182:185], v[204:207], 0
	v_mfma_f32_16x16x32_bf16 v[84:87], v[164:167], v[212:215], 0
	v_mfma_f32_16x16x32_bf16 v[80:83], v[182:185], v[212:215], 0
	v_mfma_f32_16x16x32_bf16 v[68:71], v[164:167], v[220:223], 0
	v_mfma_f32_16x16x32_bf16 v[64:67], v[182:185], v[220:223], 0
	v_mfma_f32_16x16x32_bf16 v[116:119], v[178:181], v[200:203], v[116:119]
	v_mfma_f32_16x16x32_bf16 v[112:115], v[192:195], v[200:203], v[112:115]
	v_mfma_f32_16x16x32_bf16 v[100:103], v[178:181], v[208:211], v[100:103]
	v_mfma_f32_16x16x32_bf16 v[96:99], v[192:195], v[208:211], v[96:99]
	v_mfma_f32_16x16x32_bf16 v[84:87], v[178:181], v[216:219], v[84:87]
	v_mfma_f32_16x16x32_bf16 v[80:83], v[192:195], v[216:219], v[80:83]
	v_mfma_f32_16x16x32_bf16 v[68:71], v[178:181], v[224:227], v[68:71]
	v_mfma_f32_16x16x32_bf16 v[64:67], v[192:195], v[224:227], v[64:67]
	s_barrier
	s_add_i32 s61, s52, s33
	v_lshl_add_u64 v[168:169], s[38:39], 0, v[148:149]
	s_mov_b32 m0, s61
	ds_read_b128 v[196:199], v173 offset:16384
	ds_read_b128 v[200:203], v173 offset:17408
	ds_read_b128 v[204:207], v173 offset:18432
	ds_read_b128 v[208:211], v173 offset:19456
	ds_read_b128 v[212:215], v173 offset:20480
	ds_read_b128 v[216:219], v173 offset:21504
	ds_read_b128 v[220:223], v173 offset:22528
	ds_read_b128 v[224:227], v173 offset:23552
	global_load_lds_dwordx4 v[168:169], off
	s_add_i32 m0, s61, 0x2000
	s_add_u32 s62, s38, 0x40000
	v_lshl_add_u64 v[186:187], s[38:39], 0, v[144:145]
	s_addc_u32 s63, s39, 0
	s_add_i32 s61, s53, s33
	global_load_lds_dwordx4 v[186:187], off
	v_lshl_add_u64 v[228:229], s[62:63], 0, v[148:149]
	s_mov_b32 m0, s61
	v_lshl_add_u64 v[230:231], s[40:41], 0, v[146:147]
	global_load_lds_dwordx4 v[228:229], off
	v_lshl_add_u64 v[228:229], s[62:63], 0, v[144:145]
	s_add_i32 m0, s61, 0x2000
	s_nop 0
	global_load_lds_dwordx4 v[228:229], off
	v_lshl_add_u64 v[228:229], s[40:41], 0, v[150:151]
	s_mov_b32 m0, s44
	s_nop 0
	global_load_lds_dwordx4 v[228:229], off
	s_mov_b32 m0, s45
	s_nop 0
	global_load_lds_dwordx4 v[230:231], off
	s_waitcnt vmcnt(8)
	s_waitcnt lgkmcnt(0)
	s_barrier
; #define PG8_STAGE(bufoff, gbase, voff) do { _Pragma("unroll") for (int _i = 0; _i < 2; ++_i) \
;         __builtin_amdgcn_global_load_lds((const unsigned*)((const char*)(gbase) + (voff)[_i]), (PG8_LAS unsigned*)(lds + (bufoff) + ldsw + _i * 8192), 16, 0, 0); } while (0)
; #define PG8_LDA(dst, b, h) do { _Pragma("unroll") for (int m = 0; m < 4; ++m) _Pragma("unroll") for (int k = 0; k < 2; ++k) dst[m][k] = *(const PG8_LAS bf16x8*)(lds + PG8_SA(b, h) + aoff + m * 2048 + k * 1024); } while (0)
; #define PG8_LDB(dst, b, h) do { _Pragma("unroll") for (int n = 0; n < 2; ++n) _Pragma("unroll") for (int k = 0; k < 2; ++k) dst[n][k] = *(const PG8_LAS bf16x8*)(lds + PG8_SB(b, h) + boff + n * 2048 + k * 1024); } while (0)
; #define PG8_MMA(ai, bj, At, Bt) do { __builtin_amdgcn_s_setprio(1); _Pragma("unroll") for (int m = 0; m < 4; ++m) _Pragma("unroll") for (int n = 0; n < 2; ++n) _Pragma("unroll") for (int k = 0; k < 2; ++k) \
;         acc[ai][bj][m][n] = __builtin_amdgcn_mfma_f32_16x16x32_bf16(Bt[n][k], At[m][k], acc[ai][bj][m][n], 0, 0, 0); __builtin_amdgcn_s_setprio(0); } while (0)
; #define PG8_WAIT_V(n) asm volatile("s_waitcnt vmcnt(" #n ")" ::: "memory")
; template <class Epi, class Sched, bool ALIGN_EPI = false, bool SP2 = false>
; __device__ __forceinline__ void gemm_phase(PG8_LAS unsigned char* lds, const Gemm g, const Sched& S, const Epi& E) {
;     ...
;             PG8_LDB(B0, 0, 0); PG8_LDB(B1, 0, 1); PG8_SCHED; PG8_LDA(At, 0, 0); PG8_STAGE(PG8_SA(1, 1), a1 + hstep, voffA);
;             PG8_WAIT_V(8); PG8_WAIT_L(0); PG8_BAR; PG8_MMA(0, 0, At, B0); PG8_MMA(0, 1, At, B1); PG8_BAR; PG8_SCHED;
;             PG8_LDA(At, 0, 1); PG8_STAGE(PG8_SB(0, 0), b2, voffB); PG8_STAGE(PG8_SB(0, 1), b2 + hstep, voffB); PG8_STAGE(PG8_SA(0, 0), a2, voffA);
;             PG8_WAIT_V(8); PG8_WAIT_L(0); PG8_BAR; PG8_MMA(1, 0, At, B0); PG8_MMA(1, 1, At, B1); PG8_BAR; PG8_SCHED;
;             PG8_LDB(B0, 1, 0); PG8_LDB(B1, 1, 1); PG8_SCHED; PG8_LDA(At, 1, 0); PG8_STAGE(PG8_SA(0, 1), a2 + hstep, voffA);
;             PG8_WAIT_V(8); PG8_WAIT_L(0); PG8_BAR; PG8_MMA(0, 0, At, B0); PG8_MMA(0, 1, At, B1); PG8_BAR; PG8_SCHED;
;             PG8_LDA(At, 1, 1); PG8_STAGE(PG8_SB(1, 0), b3, voffB); PG8_STAGE(PG8_SB(1, 1), b3 + hstep, voffB); PG8_STAGE(PG8_SA(1, 0), a3, voffA);
;             PG8_WAIT_V(8); PG8_WAIT_L(0); PG8_BAR; PG8_MMA(1, 0, At, B0); PG8_MMA(1, 1, At, B1); PG8_BAR; PG8_SCHED;
	v_mfma_f32_16x16x32_bf16 v[60:63], v[128:131], v[196:199], 0
	v_mfma_f32_16x16x32_bf16 v[56:59], v[136:139], v[196:199], 0
	v_mfma_f32_16x16x32_bf16 v[44:47], v[128:131], v[204:207], 0
	v_mfma_f32_16x16x32_bf16 v[40:43], v[136:139], v[204:207], 0
	v_mfma_f32_16x16x32_bf16 v[28:31], v[128:131], v[212:215], 0
	v_mfma_f32_16x16x32_bf16 v[24:27], v[136:139], v[212:215], 0
	v_mfma_f32_16x16x32_bf16 v[12:15], v[128:131], v[220:223], 0
	v_mfma_f32_16x16x32_bf16 v[8:11], v[136:139], v[220:223], 0
	v_mfma_f32_16x16x32_bf16 v[60:63], v[132:135], v[200:203], v[60:63]
	v_mfma_f32_16x16x32_bf16 v[56:59], v[140:143], v[200:203], v[56:59]
	v_mfma_f32_16x16x32_bf16 v[44:47], v[132:135], v[208:211], v[44:47]
	v_mfma_f32_16x16x32_bf16 v[40:43], v[140:143], v[208:211], v[40:43]
	v_mfma_f32_16x16x32_bf16 v[28:31], v[132:135], v[216:219], v[28:31]
	v_mfma_f32_16x16x32_bf16 v[24:27], v[140:143], v[216:219], v[24:27]
	v_mfma_f32_16x16x32_bf16 v[12:15], v[132:135], v[224:227], v[12:15]
	v_mfma_f32_16x16x32_bf16 v[8:11], v[140:143], v[224:227], v[8:11]
	v_mfma_f32_16x16x32_bf16 v[52:55], v[164:167], v[196:199], 0
	v_mfma_f32_16x16x32_bf16 v[48:51], v[182:185], v[196:199], 0
	v_mfma_f32_16x16x32_bf16 v[36:39], v[164:167], v[204:207], 0
	v_mfma_f32_16x16x32_bf16 v[32:35], v[182:185], v[204:207], 0
	v_mfma_f32_16x16x32_bf16 v[20:23], v[164:167], v[212:215], 0
	v_mfma_f32_16x16x32_bf16 v[16:19], v[182:185], v[212:215], 0
	v_mfma_f32_16x16x32_bf16 v[4:7], v[164:167], v[220:223], 0
	v_mfma_f32_16x16x32_bf16 v[0:3], v[182:185], v[220:223], 0
	v_mfma_f32_16x16x32_bf16 v[52:55], v[178:181], v[200:203], v[52:55]
	v_mfma_f32_16x16x32_bf16 v[48:51], v[192:195], v[200:203], v[48:51]
	v_mfma_f32_16x16x32_bf16 v[36:39], v[178:181], v[208:211], v[36:39]
	v_mfma_f32_16x16x32_bf16 v[32:35], v[192:195], v[208:211], v[32:35]
	v_mfma_f32_16x16x32_bf16 v[20:23], v[178:181], v[216:219], v[20:23]
	v_mfma_f32_16x16x32_bf16 v[16:19], v[192:195], v[216:219], v[16:19]
	v_mfma_f32_16x16x32_bf16 v[4:7], v[178:181], v[224:227], v[4:7]
	v_mfma_f32_16x16x32_bf16 v[0:3], v[192:195], v[224:227], v[0:3]
	s_barrier
	s_add_i32 s61, 0, 0x18000
	s_add_i32 s62, 0, 0x1c000
	v_add_u32_e32 v140, s61, v170
	v_add_u32_e32 v152, s62, v170
	ds_read_b128 v[128:131], v140
	ds_read_b128 v[132:135], v140 offset:1024
	ds_read_b128 v[136:139], v140 offset:2048
	ds_read_b128 v[140:143], v140 offset:3072
	ds_read_b128 v[164:167], v152
	ds_read_b128 v[178:181], v152 offset:1024
	ds_read_b128 v[182:185], v152 offset:2048
	ds_read_b128 v[192:195], v152 offset:3072
	s_add_u32 s40, s40, 0x40000
	s_addc_u32 s41, s41, 0
	s_mov_b32 m0, s46
	v_lshl_add_u64 v[232:233], s[40:41], 0, v[150:151]
	ds_read_b128 v[196:199], v173 offset:32768
	ds_read_b128 v[200:203], v173 offset:33792
	ds_read_b128 v[204:207], v173 offset:34816
	ds_read_b128 v[208:211], v173 offset:35840
	ds_read_b128 v[212:215], v173 offset:36864
	ds_read_b128 v[216:219], v173 offset:37888
	ds_read_b128 v[220:223], v173 offset:38912
	ds_read_b128 v[224:227], v173 offset:39936
	global_load_lds_dwordx4 v[232:233], off
	v_lshl_add_u64 v[232:233], s[40:41], 0, v[146:147]
	s_mov_b32 m0, s47
	s_nop 0
	global_load_lds_dwordx4 v[232:233], off
	s_waitcnt vmcnt(8)
	s_waitcnt lgkmcnt(0)
	s_barrier
	v_mfma_f32_16x16x32_bf16 v[124:127], v[128:131], v[196:199], v[124:127]
	v_mfma_f32_16x16x32_bf16 v[120:123], v[136:139], v[196:199], v[120:123]
	v_mfma_f32_16x16x32_bf16 v[108:111], v[128:131], v[204:207], v[108:111]
	v_mfma_f32_16x16x32_bf16 v[104:107], v[136:139], v[204:207], v[104:107]
	v_mfma_f32_16x16x32_bf16 v[92:95], v[128:131], v[212:215], v[92:95]
	v_mfma_f32_16x16x32_bf16 v[88:91], v[136:139], v[212:215], v[88:91]
	v_mfma_f32_16x16x32_bf16 v[76:79], v[128:131], v[220:223], v[76:79]
	v_mfma_f32_16x16x32_bf16 v[72:75], v[136:139], v[220:223], v[72:75]
	v_mfma_f32_16x16x32_bf16 v[124:127], v[132:135], v[200:203], v[124:127]
	v_mfma_f32_16x16x32_bf16 v[120:123], v[140:143], v[200:203], v[120:123]
	v_mfma_f32_16x16x32_bf16 v[108:111], v[132:135], v[208:211], v[108:111]
	v_mfma_f32_16x16x32_bf16 v[104:107], v[140:143], v[208:211], v[104:107]
	v_mfma_f32_16x16x32_bf16 v[92:95], v[132:135], v[216:219], v[92:95]
	v_mfma_f32_16x16x32_bf16 v[88:91], v[140:143], v[216:219], v[88:91]
	v_mfma_f32_16x16x32_bf16 v[76:79], v[132:135], v[224:227], v[76:79]
	v_mfma_f32_16x16x32_bf16 v[72:75], v[140:143], v[224:227], v[72:75]
	v_mfma_f32_16x16x32_bf16 v[116:119], v[164:167], v[196:199], v[116:119]
	v_mfma_f32_16x16x32_bf16 v[112:115], v[182:185], v[196:199], v[112:115]
	v_mfma_f32_16x16x32_bf16 v[100:103], v[164:167], v[204:207], v[100:103]
	v_mfma_f32_16x16x32_bf16 v[96:99], v[182:185], v[204:207], v[96:99]
	v_mfma_f32_16x16x32_bf16 v[84:87], v[164:167], v[212:215], v[84:87]
	v_mfma_f32_16x16x32_bf16 v[80:83], v[182:185], v[212:215], v[80:83]
	v_mfma_f32_16x16x32_bf16 v[68:71], v[164:167], v[220:223], v[68:71]
	v_mfma_f32_16x16x32_bf16 v[64:67], v[182:185], v[220:223], v[64:67]
	v_mfma_f32_16x16x32_bf16 v[116:119], v[178:181], v[200:203], v[116:119]
	v_mfma_f32_16x16x32_bf16 v[112:115], v[192:195], v[200:203], v[112:115]
	v_mfma_f32_16x16x32_bf16 v[100:103], v[178:181], v[208:211], v[100:103]
	v_mfma_f32_16x16x32_bf16 v[96:99], v[192:195], v[208:211], v[96:99]
	v_mfma_f32_16x16x32_bf16 v[84:87], v[178:181], v[216:219], v[84:87]
	v_mfma_f32_16x16x32_bf16 v[80:83], v[192:195], v[216:219], v[80:83]
	v_mfma_f32_16x16x32_bf16 v[68:71], v[178:181], v[224:227], v[68:71]
	v_mfma_f32_16x16x32_bf16 v[64:67], v[192:195], v[224:227], v[64:67]
	s_barrier
; #define PG8_STAGE(bufoff, gbase, voff) do { _Pragma("unroll") for (int _i = 0; _i < 2; ++_i) \
;         __builtin_amdgcn_global_load_lds((const unsigned*)((const char*)(gbase) + (voff)[_i]), (PG8_LAS unsigned*)(lds + (bufoff) + ldsw + _i * 8192), 16, 0, 0); } while (0)
; #define PG8_LDA(dst, b, h) do { _Pragma("unroll") for (int m = 0; m < 4; ++m) _Pragma("unroll") for (int k = 0; k < 2; ++k) dst[m][k] = *(const PG8_LAS bf16x8*)(lds + PG8_SA(b, h) + aoff + m * 2048 + k * 1024); } while (0)
; #define PG8_LDB(dst, b, h) do { _Pragma("unroll") for (int n = 0; n < 2; ++n) _Pragma("unroll") for (int k = 0; k < 2; ++k) dst[n][k] = *(const PG8_LAS bf16x8*)(lds + PG8_SB(b, h) + boff + n * 2048 + k * 1024); } while (0)
; template <class Epi, class Sched, bool ALIGN_EPI = false, bool SP2 = false>
; __device__ __forceinline__ void gemm_phase(PG8_LAS unsigned char* lds, const Gemm g, const Sched& S, const Epi& E) {
;     ...
;         for (int t = 0; t < nt; t += 2) {
;             const bool last = (t == nt - 2);
;             const char* a1 = cA + (size_t)(t + 1) * kstep;
;             const char* a2 = last ? nA : cA + (size_t)(t + 2) * kstep; const char* b2 = last ? nB : cB + (size_t)(t + 2) * kstep;
;             const char* a3 = a2 + kstep; const char* b3 = b2 + kstep;
;             if (last && has_next) S.a_ready(nxt);
;             if constexpr (SP2) {
;             PG8_LDB(B0, 0, 0); PG8_LDB(B1, 0, 1); PG8_SCHED; PG8_LDA(At, 0, 0); PG8_STAGE(PG8_SA(1, 1), a1 + hstep, voffA);
;             PG8_WAIT_V(8); PG8_WAIT_L(0); PG8_BAR; PG8_MMA(0, 0, At, B0); PG8_MMA(0, 1, At, B1); PG8_BAR; PG8_SCHED;
;             PG8_LDA(At, 0, 1); PG8_STAGE(PG8_SB(0, 0), b2, voffB); PG8_STAGE(PG8_SB(0, 1), b2 + hstep, voffB); PG8_STAGE(PG8_SA(0, 0), a2, voffA);
;             PG8_WAIT_V(8); PG8_WAIT_L(0); PG8_BAR; PG8_MMA(1, 0, At, B0); PG8_MMA(1, 1, At, B1); PG8_BAR; PG8_SCHED;
;             PG8_LDB(B0, 1, 0); PG8_LDB(B1, 1, 1); PG8_SCHED; PG8_LDA(At, 1, 0); PG8_STAGE(PG8_SA(0, 1), a2 + hstep, voffA);
;             PG8_WAIT_V(8); PG8_WAIT_L(0); PG8_BAR; PG8_MMA(0, 0, At, B0); PG8_MMA(0, 1, At, B1); PG8_BAR; PG8_SCHED;
;             PG8_LDA(At, 1, 1); PG8_STAGE(PG8_SB(1, 0), b3, voffB); PG8_STAGE(PG8_SB(1, 1), b3 + hstep, voffB); PG8_STAGE(PG8_SA(1, 0), a3, voffA);
;             PG8_WAIT_V(8); PG8_WAIT_L(0); PG8_BAR; PG8_MMA(1, 0, At, B0); PG8_MMA(1, 1, At, B1); PG8_BAR; PG8_SCHED;
	s_add_i32 s40, s61, s33
	v_lshl_add_u64 v[168:169], v[168:169], 0, s[16:17]
	s_mov_b32 m0, s40
	ds_read_b128 v[196:199], v173 offset:49152
	ds_read_b128 v[200:203], v173 offset:50176
	ds_read_b128 v[204:207], v173 offset:51200
	ds_read_b128 v[208:211], v173 offset:52224
	ds_read_b128 v[212:215], v173 offset:53248
	ds_read_b128 v[216:219], v173 offset:54272
	ds_read_b128 v[220:223], v173 offset:55296
	ds_read_b128 v[224:227], v173 offset:56320
	global_load_lds_dwordx4 v[168:169], off
	s_add_i32 m0, s40, 0x2000
	s_add_u32 s38, s38, 0x40080
	v_lshl_add_u64 v[168:169], v[186:187], 0, s[16:17]
	s_addc_u32 s39, s39, 0
	s_add_i32 s40, s62, s33
	global_load_lds_dwordx4 v[168:169], off
	v_lshl_add_u64 v[168:169], s[38:39], 0, v[148:149]
	s_mov_b32 m0, s40
	s_nop 0
	global_load_lds_dwordx4 v[168:169], off
	v_lshl_add_u64 v[168:169], s[38:39], 0, v[144:145]
	s_add_i32 m0, s40, 0x2000
	s_nop 0
	global_load_lds_dwordx4 v[168:169], off
	v_lshl_add_u64 v[168:169], v[228:229], 0, s[16:17]
	s_mov_b32 m0, s48
	s_nop 0
	global_load_lds_dwordx4 v[168:169], off
	v_lshl_add_u64 v[168:169], v[230:231], 0, s[16:17]
	s_mov_b32 m0, s49
	s_nop 0
	global_load_lds_dwordx4 v[168:169], off
	s_waitcnt vmcnt(8)
	s_waitcnt lgkmcnt(0)
	s_barrier
	v_mfma_f32_16x16x32_bf16 v[60:63], v[128:131], v[196:199], v[60:63]
	v_mfma_f32_16x16x32_bf16 v[56:59], v[136:139], v[196:199], v[56:59]
	v_mfma_f32_16x16x32_bf16 v[44:47], v[128:131], v[204:207], v[44:47]
	v_mfma_f32_16x16x32_bf16 v[40:43], v[136:139], v[204:207], v[40:43]
	v_mfma_f32_16x16x32_bf16 v[28:31], v[128:131], v[212:215], v[28:31]
	v_mfma_f32_16x16x32_bf16 v[24:27], v[136:139], v[212:215], v[24:27]
	v_mfma_f32_16x16x32_bf16 v[12:15], v[128:131], v[220:223], v[12:15]
	v_mfma_f32_16x16x32_bf16 v[8:11], v[136:139], v[220:223], v[8:11]
	v_mfma_f32_16x16x32_bf16 v[60:63], v[132:135], v[200:203], v[60:63]
	v_mfma_f32_16x16x32_bf16 v[56:59], v[140:143], v[200:203], v[56:59]
	v_mfma_f32_16x16x32_bf16 v[44:47], v[132:135], v[208:211], v[44:47]
	v_mfma_f32_16x16x32_bf16 v[40:43], v[140:143], v[208:211], v[40:43]
	v_mfma_f32_16x16x32_bf16 v[28:31], v[132:135], v[216:219], v[28:31]
	v_mfma_f32_16x16x32_bf16 v[24:27], v[140:143], v[216:219], v[24:27]
	v_mfma_f32_16x16x32_bf16 v[12:15], v[132:135], v[224:227], v[12:15]
	v_mfma_f32_16x16x32_bf16 v[8:11], v[140:143], v[224:227], v[8:11]
	v_mfma_f32_16x16x32_bf16 v[52:55], v[164:167], v[196:199], v[52:55]
	v_mfma_f32_16x16x32_bf16 v[48:51], v[182:185], v[196:199], v[48:51]
	v_mfma_f32_16x16x32_bf16 v[36:39], v[164:167], v[204:207], v[36:39]
	v_mfma_f32_16x16x32_bf16 v[32:35], v[182:185], v[204:207], v[32:35]
	v_mfma_f32_16x16x32_bf16 v[20:23], v[164:167], v[212:215], v[20:23]
	v_mfma_f32_16x16x32_bf16 v[16:19], v[182:185], v[212:215], v[16:19]
	v_mfma_f32_16x16x32_bf16 v[4:7], v[164:167], v[220:223], v[4:7]
	v_mfma_f32_16x16x32_bf16 v[0:3], v[182:185], v[220:223], v[0:3]
	v_mfma_f32_16x16x32_bf16 v[52:55], v[178:181], v[200:203], v[52:55]
	v_mfma_f32_16x16x32_bf16 v[48:51], v[192:195], v[200:203], v[48:51]
	v_mfma_f32_16x16x32_bf16 v[36:39], v[178:181], v[208:211], v[36:39]
	v_mfma_f32_16x16x32_bf16 v[32:35], v[192:195], v[208:211], v[32:35]
	v_mfma_f32_16x16x32_bf16 v[20:23], v[178:181], v[216:219], v[20:23]
	v_mfma_f32_16x16x32_bf16 v[16:19], v[192:195], v[216:219], v[16:19]
	v_mfma_f32_16x16x32_bf16 v[4:7], v[178:181], v[224:227], v[4:7]
	v_mfma_f32_16x16x32_bf16 v[0:3], v[192:195], v[224:227], v[0:3]
	s_barrier
	s_add_i32 s60, s60, 2
	s_add_u32 s2, s2, 0x100
	s_addc_u32 s3, s3, 0
	s_add_u32 s58, s58, 0x100
	s_addc_u32 s59, s59, 0
.LBB0_374:
	ds_read_b128 v[128:131], v171
	ds_read_b128 v[132:135], v171 offset:1024
	ds_read_b128 v[136:139], v171 offset:2048
	ds_read_b128 v[140:143], v171 offset:3072
	ds_read_b128 v[164:167], v172
	ds_read_b128 v[178:181], v172 offset:1024
	ds_read_b128 v[182:185], v172 offset:2048
	ds_read_b128 v[192:195], v172 offset:3072
	s_add_u32 s38, s2, 0xfffc0080
	s_addc_u32 s39, s3, -1
	s_cmp_eq_u32 s60, 12
	s_cselect_b32 s41, s1, s39
	s_cselect_b32 s40, s25, s38
	s_cselect_b32 s39, s29, s59
	s_cselect_b32 s38, s31, s58
	v_lshl_add_u64 v[168:169], s[2:3], 0, v[156:157]
	s_add_i32 m0, s44, 0xc000
	ds_read_b128 v[196:199], v173
	ds_read_b128 v[200:203], v173 offset:1024
	ds_read_b128 v[204:207], v173 offset:2048
	ds_read_b128 v[208:211], v173 offset:3072
	ds_read_b128 v[212:215], v173 offset:4096
	ds_read_b128 v[216:219], v173 offset:5120
	ds_read_b128 v[220:223], v173 offset:6144
	ds_read_b128 v[224:227], v173 offset:7168
	global_load_lds_dwordx4 v[168:169], off
	v_lshl_add_u64 v[168:169], s[2:3], 0, v[158:159]
	s_add_i32 m0, s44, 0xe000
	s_nop 0
	global_load_lds_dwordx4 v[168:169], off
	s_waitcnt vmcnt(8)
	s_waitcnt lgkmcnt(0)
	s_barrier
; #define PG8_STAGE(bufoff, gbase, voff) do { _Pragma("unroll") for (int _i = 0; _i < 2; ++_i) \
;         __builtin_amdgcn_global_load_lds((const unsigned*)((const char*)(gbase) + (voff)[_i]), (PG8_LAS unsigned*)(lds + (bufoff) + ldsw + _i * 8192), 16, 0, 0); } while (0)
; #define PG8_LDA(dst, b, h) do { _Pragma("unroll") for (int m = 0; m < 4; ++m) _Pragma("unroll") for (int k = 0; k < 2; ++k) dst[m][k] = *(const PG8_LAS bf16x8*)(lds + PG8_SA(b, h) + aoff + m * 2048 + k * 1024); } while (0)
; #define PG8_LDB(dst, b, h) do { _Pragma("unroll") for (int n = 0; n < 2; ++n) _Pragma("unroll") for (int k = 0; k < 2; ++k) dst[n][k] = *(const PG8_LAS bf16x8*)(lds + PG8_SB(b, h) + boff + n * 2048 + k * 1024); } while (0)
; #define PG8_MMA(ai, bj, At, Bt) do { __builtin_amdgcn_s_setprio(1); _Pragma("unroll") for (int m = 0; m < 4; ++m) _Pragma("unroll") for (int n = 0; n < 2; ++n) _Pragma("unroll") for (int k = 0; k < 2; ++k) \
;         acc[ai][bj][m][n] = __builtin_amdgcn_mfma_f32_16x16x32_bf16(Bt[n][k], At[m][k], acc[ai][bj][m][n], 0, 0, 0); __builtin_amdgcn_s_setprio(0); } while (0)
; #define PG8_WAIT_V(n) asm volatile("s_waitcnt vmcnt(" #n ")" ::: "memory")
; template <class Epi, class Sched, bool ALIGN_EPI = false, bool SP2 = false>
; __device__ __forceinline__ void gemm_phase(PG8_LAS unsigned char* lds, const Gemm g, const Sched& S, const Epi& E) {
;     ...
;             PG8_LDB(B0, 0, 0); PG8_LDB(B1, 0, 1); PG8_SCHED; PG8_LDA(At, 0, 0); PG8_STAGE(PG8_SA(1, 1), a1 + hstep, voffA);
;             PG8_WAIT_V(8); PG8_WAIT_L(0); PG8_BAR; PG8_MMA(0, 0, At, B0); PG8_MMA(0, 1, At, B1); PG8_BAR; PG8_SCHED;
;             PG8_LDA(At, 0, 1); PG8_STAGE(PG8_SB(0, 0), b2, voffB); PG8_STAGE(PG8_SB(0, 1), b2 + hstep, voffB); PG8_STAGE(PG8_SA(0, 0), a2, voffA);
;             PG8_WAIT_V(8); PG8_WAIT_L(0); PG8_BAR; PG8_MMA(1, 0, At, B0); PG8_MMA(1, 1, At, B1); PG8_BAR; PG8_SCHED;
;             PG8_LDB(B0, 1, 0); PG8_LDB(B1, 1, 1); PG8_SCHED; PG8_LDA(At, 1, 0); PG8_STAGE(PG8_SA(0, 1), a2 + hstep, voffA);
;             PG8_WAIT_V(8); PG8_WAIT_L(0); PG8_BAR; PG8_MMA(0, 0, At, B0); PG8_MMA(0, 1, At, B1); PG8_BAR; PG8_SCHED;
;             PG8_LDA(At, 1, 1); PG8_STAGE(PG8_SB(1, 0), b3, voffB); PG8_STAGE(PG8_SB(1, 1), b3 + hstep, voffB); PG8_STAGE(PG8_SA(1, 0), a3, voffA);
;             PG8_WAIT_V(8); PG8_WAIT_L(0); PG8_BAR; PG8_MMA(1, 0, At, B0); PG8_MMA(1, 1, At, B1); PG8_BAR; PG8_SCHED;
	v_mfma_f32_16x16x32_bf16 v[124:127], v[128:131], v[196:199], v[124:127]
	v_mfma_f32_16x16x32_bf16 v[120:123], v[136:139], v[196:199], v[120:123]
	v_mfma_f32_16x16x32_bf16 v[108:111], v[128:131], v[204:207], v[108:111]
	v_mfma_f32_16x16x32_bf16 v[104:107], v[136:139], v[204:207], v[104:107]
	v_mfma_f32_16x16x32_bf16 v[92:95], v[128:131], v[212:215], v[92:95]
	v_mfma_f32_16x16x32_bf16 v[88:91], v[136:139], v[212:215], v[88:91]
	v_mfma_f32_16x16x32_bf16 v[76:79], v[128:131], v[220:223], v[76:79]
	v_mfma_f32_16x16x32_bf16 v[72:75], v[136:139], v[220:223], v[72:75]
	v_mfma_f32_16x16x32_bf16 v[124:127], v[132:135], v[200:203], v[124:127]
	v_mfma_f32_16x16x32_bf16 v[120:123], v[140:143], v[200:203], v[120:123]
	v_mfma_f32_16x16x32_bf16 v[108:111], v[132:135], v[208:211], v[108:111]
	v_mfma_f32_16x16x32_bf16 v[104:107], v[140:143], v[208:211], v[104:107]
	v_mfma_f32_16x16x32_bf16 v[92:95], v[132:135], v[216:219], v[92:95]
	v_mfma_f32_16x16x32_bf16 v[88:91], v[140:143], v[216:219], v[88:91]
	v_mfma_f32_16x16x32_bf16 v[76:79], v[132:135], v[224:227], v[76:79]
	v_mfma_f32_16x16x32_bf16 v[72:75], v[140:143], v[224:227], v[72:75]
	v_mfma_f32_16x16x32_bf16 v[116:119], v[164:167], v[196:199], v[116:119]
	v_mfma_f32_16x16x32_bf16 v[112:115], v[182:185], v[196:199], v[112:115]
	v_mfma_f32_16x16x32_bf16 v[100:103], v[164:167], v[204:207], v[100:103]
	v_mfma_f32_16x16x32_bf16 v[96:99], v[182:185], v[204:207], v[96:99]
	v_mfma_f32_16x16x32_bf16 v[84:87], v[164:167], v[212:215], v[84:87]
	v_mfma_f32_16x16x32_bf16 v[80:83], v[182:185], v[212:215], v[80:83]
	v_mfma_f32_16x16x32_bf16 v[68:71], v[164:167], v[220:223], v[68:71]
	v_mfma_f32_16x16x32_bf16 v[64:67], v[182:185], v[220:223], v[64:67]
	v_mfma_f32_16x16x32_bf16 v[116:119], v[178:181], v[200:203], v[116:119]
	v_mfma_f32_16x16x32_bf16 v[112:115], v[192:195], v[200:203], v[112:115]
	v_mfma_f32_16x16x32_bf16 v[100:103], v[178:181], v[208:211], v[100:103]
	v_mfma_f32_16x16x32_bf16 v[96:99], v[192:195], v[208:211], v[96:99]
	v_mfma_f32_16x16x32_bf16 v[84:87], v[178:181], v[216:219], v[84:87]
	v_mfma_f32_16x16x32_bf16 v[80:83], v[192:195], v[216:219], v[80:83]
	v_mfma_f32_16x16x32_bf16 v[68:71], v[178:181], v[224:227], v[68:71]
	v_mfma_f32_16x16x32_bf16 v[64:67], v[192:195], v[224:227], v[64:67]
	s_barrier
	s_add_i32 s61, s52, s33
	v_lshl_add_u64 v[168:169], s[38:39], 0, v[148:149]
	s_mov_b32 m0, s61
	ds_read_b128 v[196:199], v173 offset:16384
	ds_read_b128 v[200:203], v173 offset:17408
	ds_read_b128 v[204:207], v173 offset:18432
	ds_read_b128 v[208:211], v173 offset:19456
	ds_read_b128 v[212:215], v173 offset:20480
	ds_read_b128 v[216:219], v173 offset:21504
	ds_read_b128 v[220:223], v173 offset:22528
	ds_read_b128 v[224:227], v173 offset:23552
	global_load_lds_dwordx4 v[168:169], off
	s_add_i32 m0, s61, 0x2000
	s_add_u32 s62, s38, 0x40000
	v_lshl_add_u64 v[186:187], s[38:39], 0, v[144:145]
	s_addc_u32 s63, s39, 0
	s_add_i32 s61, s53, s33
	global_load_lds_dwordx4 v[186:187], off
	v_lshl_add_u64 v[228:229], s[62:63], 0, v[148:149]
	s_mov_b32 m0, s61
	v_lshl_add_u64 v[230:231], s[40:41], 0, v[146:147]
	global_load_lds_dwordx4 v[228:229], off
	v_lshl_add_u64 v[228:229], s[62:63], 0, v[144:145]
	s_add_i32 m0, s61, 0x2000
	s_nop 0
	global_load_lds_dwordx4 v[228:229], off
	v_lshl_add_u64 v[228:229], s[40:41], 0, v[150:151]
	s_mov_b32 m0, s44
	s_nop 0
	global_load_lds_dwordx4 v[228:229], off
	s_mov_b32 m0, s45
	s_nop 0
	global_load_lds_dwordx4 v[230:231], off
	s_waitcnt vmcnt(8)
	s_waitcnt lgkmcnt(0)
	s_barrier
	v_mfma_f32_16x16x32_bf16 v[60:63], v[128:131], v[196:199], v[60:63]
	v_mfma_f32_16x16x32_bf16 v[56:59], v[136:139], v[196:199], v[56:59]
	v_mfma_f32_16x16x32_bf16 v[44:47], v[128:131], v[204:207], v[44:47]
	v_mfma_f32_16x16x32_bf16 v[40:43], v[136:139], v[204:207], v[40:43]
	v_mfma_f32_16x16x32_bf16 v[28:31], v[128:131], v[212:215], v[28:31]
	v_mfma_f32_16x16x32_bf16 v[24:27], v[136:139], v[212:215], v[24:27]
	v_mfma_f32_16x16x32_bf16 v[12:15], v[128:131], v[220:223], v[12:15]
	v_mfma_f32_16x16x32_bf16 v[8:11], v[136:139], v[220:223], v[8:11]
	v_mfma_f32_16x16x32_bf16 v[60:63], v[132:135], v[200:203], v[60:63]
	v_mfma_f32_16x16x32_bf16 v[56:59], v[140:143], v[200:203], v[56:59]
	v_mfma_f32_16x16x32_bf16 v[44:47], v[132:135], v[208:211], v[44:47]
	v_mfma_f32_16x16x32_bf16 v[40:43], v[140:143], v[208:211], v[40:43]
	v_mfma_f32_16x16x32_bf16 v[28:31], v[132:135], v[216:219], v[28:31]
	v_mfma_f32_16x16x32_bf16 v[24:27], v[140:143], v[216:219], v[24:27]
	v_mfma_f32_16x16x32_bf16 v[12:15], v[132:135], v[224:227], v[12:15]
	v_mfma_f32_16x16x32_bf16 v[8:11], v[140:143], v[224:227], v[8:11]
	v_mfma_f32_16x16x32_bf16 v[52:55], v[164:167], v[196:199], v[52:55]
	v_mfma_f32_16x16x32_bf16 v[48:51], v[182:185], v[196:199], v[48:51]
	v_mfma_f32_16x16x32_bf16 v[36:39], v[164:167], v[204:207], v[36:39]
	v_mfma_f32_16x16x32_bf16 v[32:35], v[182:185], v[204:207], v[32:35]
	v_mfma_f32_16x16x32_bf16 v[20:23], v[164:167], v[212:215], v[20:23]
	v_mfma_f32_16x16x32_bf16 v[16:19], v[182:185], v[212:215], v[16:19]
	v_mfma_f32_16x16x32_bf16 v[4:7], v[164:167], v[220:223], v[4:7]
	v_mfma_f32_16x16x32_bf16 v[0:3], v[182:185], v[220:223], v[0:3]
	v_mfma_f32_16x16x32_bf16 v[52:55], v[178:181], v[200:203], v[52:55]
	v_mfma_f32_16x16x32_bf16 v[48:51], v[192:195], v[200:203], v[48:51]
	v_mfma_f32_16x16x32_bf16 v[36:39], v[178:181], v[208:211], v[36:39]
	v_mfma_f32_16x16x32_bf16 v[32:35], v[192:195], v[208:211], v[32:35]
	v_mfma_f32_16x16x32_bf16 v[20:23], v[178:181], v[216:219], v[20:23]
	v_mfma_f32_16x16x32_bf16 v[16:19], v[192:195], v[216:219], v[16:19]
	v_mfma_f32_16x16x32_bf16 v[4:7], v[178:181], v[224:227], v[4:7]
	v_mfma_f32_16x16x32_bf16 v[0:3], v[192:195], v[224:227], v[0:3]
	s_barrier
; #define PG8_STAGE(bufoff, gbase, voff) do { _Pragma("unroll") for (int _i = 0; _i < 2; ++_i) \
;         __builtin_amdgcn_global_load_lds((const unsigned*)((const char*)(gbase) + (voff)[_i]), (PG8_LAS unsigned*)(lds + (bufoff) + ldsw + _i * 8192), 16, 0, 0); } while (0)
; #define PG8_LDA(dst, b, h) do { _Pragma("unroll") for (int m = 0; m < 4; ++m) _Pragma("unroll") for (int k = 0; k < 2; ++k) dst[m][k] = *(const PG8_LAS bf16x8*)(lds + PG8_SA(b, h) + aoff + m * 2048 + k * 1024); } while (0)
; #define PG8_LDB(dst, b, h) do { _Pragma("unroll") for (int n = 0; n < 2; ++n) _Pragma("unroll") for (int k = 0; k < 2; ++k) dst[n][k] = *(const PG8_LAS bf16x8*)(lds + PG8_SB(b, h) + boff + n * 2048 + k * 1024); } while (0)
; #define PG8_MMA(ai, bj, At, Bt) do { __builtin_amdgcn_s_setprio(1); _Pragma("unroll") for (int m = 0; m < 4; ++m) _Pragma("unroll") for (int n = 0; n < 2; ++n) _Pragma("unroll") for (int k = 0; k < 2; ++k) \
;         acc[ai][bj][m][n] = __builtin_amdgcn_mfma_f32_16x16x32_bf16(Bt[n][k], At[m][k], acc[ai][bj][m][n], 0, 0, 0); __builtin_amdgcn_s_setprio(0); } while (0)
; #define PG8_WAIT_V(n) asm volatile("s_waitcnt vmcnt(" #n ")" ::: "memory")
; #define PG8_WAIT_L(n) asm volatile("s_waitcnt lgkmcnt(" #n ")" ::: "memory")
; #define PG8_BAR __builtin_amdgcn_s_barrier()
; #define PG8_SCHED __builtin_amdgcn_sched_barrier(0)
; template <class Epi, class Sched, bool ALIGN_EPI = false, bool SP2 = false>
; __device__ __forceinline__ void gemm_phase(PG8_LAS unsigned char* lds, const Gemm g, const Sched& S, const Epi& E) {
;     ...
;             PG8_LDB(B0, 1, 0); PG8_LDB(B1, 1, 1); PG8_SCHED; PG8_LDA(At, 1, 0); PG8_STAGE(PG8_SA(0, 1), a2 + hstep, voffA);
;             PG8_WAIT_V(8); PG8_WAIT_L(0); PG8_BAR; PG8_MMA(0, 0, At, B0); PG8_MMA(0, 1, At, B1); PG8_BAR; PG8_SCHED;
	s_add_i32 s61, 0, 0x18000
	s_add_i32 s62, 0, 0x1c000
	v_add_u32_e32 v140, s61, v170
	v_add_u32_e32 v152, s62, v170
	ds_read_b128 v[128:131], v140
	ds_read_b128 v[132:135], v140 offset:1024
	ds_read_b128 v[136:139], v140 offset:2048
	ds_read_b128 v[140:143], v140 offset:3072
	ds_read_b128 v[164:167], v152
	ds_read_b128 v[178:181], v152 offset:1024
	ds_read_b128 v[182:185], v152 offset:2048
	ds_read_b128 v[192:195], v152 offset:3072
	s_add_u32 s40, s40, 0x40000
	s_addc_u32 s41, s41, 0
	s_mov_b32 m0, s46
	v_lshl_add_u64 v[232:233], s[40:41], 0, v[150:151]
	ds_read_b128 v[196:199], v173 offset:32768
	ds_read_b128 v[200:203], v173 offset:33792
	ds_read_b128 v[204:207], v173 offset:34816
	ds_read_b128 v[208:211], v173 offset:35840
	ds_read_b128 v[212:215], v173 offset:36864
	ds_read_b128 v[216:219], v173 offset:37888
	ds_read_b128 v[220:223], v173 offset:38912
	ds_read_b128 v[224:227], v173 offset:39936
	global_load_lds_dwordx4 v[232:233], off
	v_lshl_add_u64 v[232:233], s[40:41], 0, v[146:147]
	s_mov_b32 m0, s47
	s_nop 0
	global_load_lds_dwordx4 v[232:233], off
	s_waitcnt vmcnt(8)
	s_waitcnt lgkmcnt(0)
	s_barrier
	v_mfma_f32_16x16x32_bf16 v[124:127], v[128:131], v[196:199], v[124:127]
	v_mfma_f32_16x16x32_bf16 v[120:123], v[136:139], v[196:199], v[120:123]
	v_mfma_f32_16x16x32_bf16 v[108:111], v[128:131], v[204:207], v[108:111]
	v_mfma_f32_16x16x32_bf16 v[104:107], v[136:139], v[204:207], v[104:107]
	v_mfma_f32_16x16x32_bf16 v[92:95], v[128:131], v[212:215], v[92:95]
	v_mfma_f32_16x16x32_bf16 v[88:91], v[136:139], v[212:215], v[88:91]
	v_mfma_f32_16x16x32_bf16 v[76:79], v[128:131], v[220:223], v[76:79]
	v_mfma_f32_16x16x32_bf16 v[72:75], v[136:139], v[220:223], v[72:75]
	v_mfma_f32_16x16x32_bf16 v[124:127], v[132:135], v[200:203], v[124:127]
	v_mfma_f32_16x16x32_bf16 v[120:123], v[140:143], v[200:203], v[120:123]
	v_mfma_f32_16x16x32_bf16 v[108:111], v[132:135], v[208:211], v[108:111]
	v_mfma_f32_16x16x32_bf16 v[104:107], v[140:143], v[208:211], v[104:107]
	v_mfma_f32_16x16x32_bf16 v[92:95], v[132:135], v[216:219], v[92:95]
	v_mfma_f32_16x16x32_bf16 v[88:91], v[140:143], v[216:219], v[88:91]
	v_mfma_f32_16x16x32_bf16 v[76:79], v[132:135], v[224:227], v[76:79]
	v_mfma_f32_16x16x32_bf16 v[72:75], v[140:143], v[224:227], v[72:75]
	v_mfma_f32_16x16x32_bf16 v[116:119], v[164:167], v[196:199], v[116:119]
	v_mfma_f32_16x16x32_bf16 v[112:115], v[182:185], v[196:199], v[112:115]
	v_mfma_f32_16x16x32_bf16 v[100:103], v[164:167], v[204:207], v[100:103]
	v_mfma_f32_16x16x32_bf16 v[96:99], v[182:185], v[204:207], v[96:99]
	v_mfma_f32_16x16x32_bf16 v[84:87], v[164:167], v[212:215], v[84:87]
	v_mfma_f32_16x16x32_bf16 v[80:83], v[182:185], v[212:215], v[80:83]
	v_mfma_f32_16x16x32_bf16 v[68:71], v[164:167], v[220:223], v[68:71]
	v_mfma_f32_16x16x32_bf16 v[64:67], v[182:185], v[220:223], v[64:67]
	v_mfma_f32_16x16x32_bf16 v[116:119], v[178:181], v[200:203], v[116:119]
	v_mfma_f32_16x16x32_bf16 v[112:115], v[192:195], v[200:203], v[112:115]
	v_mfma_f32_16x16x32_bf16 v[100:103], v[178:181], v[208:211], v[100:103]
	v_mfma_f32_16x16x32_bf16 v[96:99], v[192:195], v[208:211], v[96:99]
	v_mfma_f32_16x16x32_bf16 v[84:87], v[178:181], v[216:219], v[84:87]
	v_mfma_f32_16x16x32_bf16 v[80:83], v[192:195], v[216:219], v[80:83]
	v_mfma_f32_16x16x32_bf16 v[68:71], v[178:181], v[224:227], v[68:71]
	v_mfma_f32_16x16x32_bf16 v[64:67], v[192:195], v[224:227], v[64:67]
	s_barrier
; #define PG8_STAGE(bufoff, gbase, voff) do { _Pragma("unroll") for (int _i = 0; _i < 2; ++_i) \
;         __builtin_amdgcn_global_load_lds((const unsigned*)((const char*)(gbase) + (voff)[_i]), (PG8_LAS unsigned*)(lds + (bufoff) + ldsw + _i * 8192), 16, 0, 0); } while (0)
; #define PG8_LDA(dst, b, h) do { _Pragma("unroll") for (int m = 0; m < 4; ++m) _Pragma("unroll") for (int k = 0; k < 2; ++k) dst[m][k] = *(const PG8_LAS bf16x8*)(lds + PG8_SA(b, h) + aoff + m * 2048 + k * 1024); } while (0)
; #define PG8_MMA(ai, bj, At, Bt) do { __builtin_amdgcn_s_setprio(1); _Pragma("unroll") for (int m = 0; m < 4; ++m) _Pragma("unroll") for (int n = 0; n < 2; ++n) _Pragma("unroll") for (int k = 0; k < 2; ++k) \
;         acc[ai][bj][m][n] = __builtin_amdgcn_mfma_f32_16x16x32_bf16(Bt[n][k], At[m][k], acc[ai][bj][m][n], 0, 0, 0); __builtin_amdgcn_s_setprio(0); } while (0)
; #define PG8_WAIT_V(n) asm volatile("s_waitcnt vmcnt(" #n ")" ::: "memory")
; #define PG8_WAIT_L(n) asm volatile("s_waitcnt lgkmcnt(" #n ")" ::: "memory")
; #define PG8_BAR __builtin_amdgcn_s_barrier()
; #define PG8_SCHED __builtin_amdgcn_sched_barrier(0)
; template <class Epi, class Sched, bool ALIGN_EPI = false, bool SP2 = false>
; __device__ __forceinline__ void gemm_phase(PG8_LAS unsigned char* lds, const Gemm g, const Sched& S, const Epi& E) {
;     ...
;             PG8_LDA(At, 1, 1); PG8_STAGE(PG8_SB(1, 0), b3, voffB); PG8_STAGE(PG8_SB(1, 1), b3 + hstep, voffB); PG8_STAGE(PG8_SA(1, 0), a3, voffA);
;             PG8_WAIT_V(8); PG8_WAIT_L(0); PG8_BAR; PG8_MMA(1, 0, At, B0); PG8_MMA(1, 1, At, B1); PG8_BAR; PG8_SCHED;
;     ...
;         if constexpr (ALIGN_EPI) { if (wr == 0) PG8_BAR; }
;         if constexpr (!Epi::AFTER_DRAIN) { E(acc, cur, wr, wc, fr, fq); S.done(cur); }
;         if (!has_next) break;
	s_add_i32 s40, s61, s33
	v_lshl_add_u64 v[168:169], v[168:169], 0, s[16:17]
	s_mov_b32 m0, s40
	ds_read_b128 v[196:199], v173 offset:49152
	ds_read_b128 v[200:203], v173 offset:50176
	ds_read_b128 v[204:207], v173 offset:51200
	ds_read_b128 v[208:211], v173 offset:52224
	ds_read_b128 v[212:215], v173 offset:53248
	ds_read_b128 v[216:219], v173 offset:54272
	ds_read_b128 v[220:223], v173 offset:55296
	ds_read_b128 v[224:227], v173 offset:56320
	global_load_lds_dwordx4 v[168:169], off
	s_add_i32 m0, s40, 0x2000
	s_add_u32 s38, s38, 0x40080
	v_lshl_add_u64 v[168:169], v[186:187], 0, s[16:17]
	s_addc_u32 s39, s39, 0
	s_add_i32 s40, s62, s33
	global_load_lds_dwordx4 v[168:169], off
	v_lshl_add_u64 v[168:169], s[38:39], 0, v[148:149]
	s_mov_b32 m0, s40
	s_nop 0
	global_load_lds_dwordx4 v[168:169], off
	v_lshl_add_u64 v[168:169], s[38:39], 0, v[144:145]
	s_add_i32 m0, s40, 0x2000
	s_nop 0
	global_load_lds_dwordx4 v[168:169], off
	v_lshl_add_u64 v[168:169], v[228:229], 0, s[16:17]
	s_mov_b32 m0, s48
	s_nop 0
	global_load_lds_dwordx4 v[168:169], off
	v_lshl_add_u64 v[168:169], v[230:231], 0, s[16:17]
	s_mov_b32 m0, s49
	s_nop 0
	global_load_lds_dwordx4 v[168:169], off
	s_waitcnt vmcnt(8)
	s_waitcnt lgkmcnt(0)
	s_barrier
	v_mfma_f32_16x16x32_bf16 v[60:63], v[128:131], v[196:199], v[60:63]
	v_mfma_f32_16x16x32_bf16 v[56:59], v[136:139], v[196:199], v[56:59]
	v_mfma_f32_16x16x32_bf16 v[44:47], v[128:131], v[204:207], v[44:47]
	v_mfma_f32_16x16x32_bf16 v[40:43], v[136:139], v[204:207], v[40:43]
	v_mfma_f32_16x16x32_bf16 v[28:31], v[128:131], v[212:215], v[28:31]
	v_mfma_f32_16x16x32_bf16 v[24:27], v[136:139], v[212:215], v[24:27]
	v_mfma_f32_16x16x32_bf16 v[12:15], v[128:131], v[220:223], v[12:15]
	v_mfma_f32_16x16x32_bf16 v[8:11], v[136:139], v[220:223], v[8:11]
	v_mfma_f32_16x16x32_bf16 v[60:63], v[132:135], v[200:203], v[60:63]
	v_mfma_f32_16x16x32_bf16 v[56:59], v[140:143], v[200:203], v[56:59]
	v_mfma_f32_16x16x32_bf16 v[44:47], v[132:135], v[208:211], v[44:47]
	v_mfma_f32_16x16x32_bf16 v[40:43], v[140:143], v[208:211], v[40:43]
	v_mfma_f32_16x16x32_bf16 v[28:31], v[132:135], v[216:219], v[28:31]
	v_mfma_f32_16x16x32_bf16 v[24:27], v[140:143], v[216:219], v[24:27]
	v_mfma_f32_16x16x32_bf16 v[12:15], v[132:135], v[224:227], v[12:15]
	v_mfma_f32_16x16x32_bf16 v[8:11], v[140:143], v[224:227], v[8:11]
	v_mfma_f32_16x16x32_bf16 v[52:55], v[164:167], v[196:199], v[52:55]
	v_mfma_f32_16x16x32_bf16 v[48:51], v[182:185], v[196:199], v[48:51]
	v_mfma_f32_16x16x32_bf16 v[36:39], v[164:167], v[204:207], v[36:39]
	v_mfma_f32_16x16x32_bf16 v[32:35], v[182:185], v[204:207], v[32:35]
	v_mfma_f32_16x16x32_bf16 v[20:23], v[164:167], v[212:215], v[20:23]
	v_mfma_f32_16x16x32_bf16 v[16:19], v[182:185], v[212:215], v[16:19]
	v_mfma_f32_16x16x32_bf16 v[4:7], v[164:167], v[220:223], v[4:7]
	v_mfma_f32_16x16x32_bf16 v[0:3], v[182:185], v[220:223], v[0:3]
	v_mfma_f32_16x16x32_bf16 v[52:55], v[178:181], v[200:203], v[52:55]
	v_mfma_f32_16x16x32_bf16 v[48:51], v[192:195], v[200:203], v[48:51]
	v_mfma_f32_16x16x32_bf16 v[36:39], v[178:181], v[208:211], v[36:39]
	v_mfma_f32_16x16x32_bf16 v[32:35], v[192:195], v[208:211], v[32:35]
	v_mfma_f32_16x16x32_bf16 v[20:23], v[178:181], v[216:219], v[20:23]
	v_mfma_f32_16x16x32_bf16 v[16:19], v[192:195], v[216:219], v[16:19]
	v_mfma_f32_16x16x32_bf16 v[4:7], v[178:181], v[224:227], v[4:7]
	v_mfma_f32_16x16x32_bf16 v[0:3], v[192:195], v[224:227], v[0:3]
	s_barrier
	s_add_i32 s60, s60, 2
	s_add_u32 s2, s2, 0x100
	s_addc_u32 s3, s3, 0
	s_add_u32 s58, s58, 0x100
	s_addc_u32 s59, s59, 0
	s_cmp_gt_u32 s60, 13
	s_cbranch_scc0 .LBB0_374
	s_and_b64 vcc, exec, s[18:19]
	s_cbranch_vccnz .LBB0_379
	v_lshl_add_u32 v164, s0, 8, v155
	s_cmp_gt_i32 s57, 3
	s_mov_b64 s[0:1], -1
	s_cbranch_scc1 .LBB0_380

; #define PG8_STAGE(bufoff, gbase, voff) do { _Pragma("unroll") for (int _i = 0; _i < 2; ++_i) \
;         __builtin_amdgcn_global_load_lds((const unsigned*)((const char*)(gbase) + (voff)[_i]), (PG8_LAS unsigned*)(lds + (bufoff) + ldsw + _i * 8192), 16, 0, 0); } while (0)
; #define PG8_WAIT_V(n) asm volatile("s_waitcnt vmcnt(" #n ")" ::: "memory")
; #define PG8_BAR __builtin_amdgcn_s_barrier()
; template <class Epi, class Sched, bool ALIGN_EPI = false, bool SP2 = false>
; __device__ __forceinline__ void gemm_phase(PG8_LAS unsigned char* lds, const Gemm g, const Sched& S, const Epi& E) {
;     ...
;     for (int i = 0; i < 2; ++i) { int R, C; stage_rc(tid * 16 + i * 8192, R, C); const int Rb = Epi::PERM ? ((R & ~31) + perm32(R & 31)) : R;
;         voffA[i] = (unsigned)(R * K + C) * 2u; voffB[i] = (unsigned)(Rb * K + C) * 2u; }
;     const size_t kstep = (size_t)(BK * 2);
;     const size_t hstep = (size_t)HALF * K * 2;
;     const size_t tstep = 2 * hstep;
;     const unsigned ldsw = (unsigned)wid * 1024u;
;     const int aoff = lds_byte(wr * 64 + fr, fq * 8), boff = lds_byte(wc * 32 + fr, fq * 8);
;     ...
;         PG8_STAGE(PG8_SB(0, 0), cB, voffB); PG8_STAGE(PG8_SB(0, 1), cB + hstep, voffB); PG8_STAGE(PG8_SA(0, 0), cA, voffA); PG8_STAGE(PG8_SA(0, 1), cA + hstep, voffA);
;         if (wr == 1) PG8_BAR;
;         PG8_WAIT_V(2); PG8_BAR;
;         PG8_STAGE(PG8_SB(1, 0), cB + kstep, voffB); PG8_STAGE(PG8_SA(1, 0), cA + kstep, voffA); PG8_STAGE(PG8_SB(1, 1), cB + hstep + kstep, voffB);
;         PG8_WAIT_V(6); PG8_BAR;
.LBB0_688:
	s_lshl_b32 s2, s2, 5
	s_and_b32 s14, s2, 0x60
	s_mov_b64 s[2:3], 0x80
	s_add_i32 m0, s25, 0x18000
	v_lshl_add_u64 v[6:7], v[6:7], 0, s[2:3]
	s_lshl_b32 s12, s5, 13
	s_lshl_b32 s13, s14, 7
	s_waitcnt vmcnt(2)
	s_barrier
	global_load_lds_dwordx4 v[6:7], off
	v_lshl_add_u64 v[4:5], v[4:5], 0, s[2:3]
	s_add_i32 m0, s25, 0x1a000
	s_add_i32 s40, s25, 0x8000
	s_add_i32 s41, s25, 0xa000
	global_load_lds_dwordx4 v[4:5], off
	v_lshl_add_u64 v[0:1], v[0:1], 0, s[2:3]
	s_mov_b32 m0, s40
	s_add_u32 s6, s28, 0x40080
	global_load_lds_dwordx4 v[0:1], off
	v_lshl_add_u64 v[0:1], v[2:3], 0, s[2:3]
	s_mov_b32 m0, s41
	s_addc_u32 s7, s29, 0
	global_load_lds_dwordx4 v[0:1], off
	s_add_i32 m0, s25, 0x1c000
	v_lshl_add_u64 v[0:1], s[6:7], 0, v[130:131]
	global_load_lds_dwordx4 v[0:1], off
	v_lshl_add_u64 v[0:1], s[6:7], 0, v[134:135]
	s_add_i32 m0, s25, 0x1e000
	s_cmpk_lt_u32 s4, 0x100
	global_load_lds_dwordx4 v[0:1], off
	v_bfe_u32 v1, v8, 4, 2
	v_and_b32_e32 v0, 15, v8
	v_lshlrev_b32_e32 v2, 4, v1
	v_lshl_or_b32 v148, s5, 6, v0
	v_lshl_or_b32 v0, v0, 6, v2
	v_lshlrev_b32_e32 v2, 2, v8
	v_and_b32_e32 v2, 32, v2
	v_bitop3_b32 v3, v0, s12, v2 bitop3:0xde
	v_bitop3_b32 v149, v0, s13, v2 bitop3:0xde
	v_lshlrev_b32_e32 v0, 14, v9
	v_and_b32_e32 v0, 0xffff8000, v0
	v_cmp_eq_u32_e64 s[4:5], 0, v1
	v_lshl_or_b32 v150, v1, 3, s14
	v_lshl_add_u32 v0, v10, 11, v0
	v_and_b32_e32 v1, 1, v9
	v_lshl_or_b32 v0, v1, 6, v0
	v_lshl_add_u32 v136, v11, 1, v0
	v_lshlrev_b32_e32 v0, 14, v12
	v_and_b32_e32 v0, 0xffff8000, v0
	s_waitcnt vmcnt(6)
	v_readlane_b32 s6, v235, 6
	v_lshl_add_u32 v0, v13, 11, v0
	v_and_b32_e32 v1, 1, v12
	s_cselect_b64 s[12:13], -1, 0
	s_ashr_i32 s42, s6, 31
	s_mov_b32 s43, s6
	v_readlane_b32 s6, v235, 0
	v_lshl_or_b32 v0, v1, 6, v0
	s_add_i32 s45, 0, 0x10000
	s_add_i32 s46, 0, 0x14000
	s_ashr_i32 s44, s6, 31
	v_mov_b32_e32 v137, v131
	v_lshl_add_u32 v138, v14, 1, v0
	v_mov_b32_e32 v139, v131
	v_mov_b64_e32 v[140:141], 0x200
	v_mov_b64_e32 v[142:143], 0x1ff
	v_add_u32_e32 v151, s45, v149
	v_add_u32_e32 v152, s46, v149
	v_add_u32_e32 v153, 0, v3
	v_mbcnt_hi_u32_b32 v154, -1, v190
	s_barrier
	v_readlane_b32 s7, v235, 7
	v_readfirstlane_b32 s99, v189
	s_nop 0
	s_lshr_b32 s99, s99, 6
	s_cmp_ge_u32 s99, 4
	s_cbranch_scc0 .Lprio_691
	s_setprio 1
.Lprio_691:
	s_branch .LBB0_691
.LBB0_689:
	s_mov_b64 s[6:7], 0

; #define PG8_STAGE(bufoff, gbase, voff) do { _Pragma("unroll") for (int _i = 0; _i < 2; ++_i) \
;         __builtin_amdgcn_global_load_lds((const unsigned*)((const char*)(gbase) + (voff)[_i]), (PG8_LAS unsigned*)(lds + (bufoff) + ldsw + _i * 8192), 16, 0, 0); } while (0)
; #define PG8_LDA(dst, b, h) do { _Pragma("unroll") for (int m = 0; m < 4; ++m) _Pragma("unroll") for (int k = 0; k < 2; ++k) dst[m][k] = *(const PG8_LAS bf16x8*)(lds + PG8_SA(b, h) + aoff + m * 2048 + k * 1024); } while (0)
; #define PG8_LDB(dst, b, h) do { _Pragma("unroll") for (int n = 0; n < 2; ++n) _Pragma("unroll") for (int k = 0; k < 2; ++k) dst[n][k] = *(const PG8_LAS bf16x8*)(lds + PG8_SB(b, h) + boff + n * 2048 + k * 1024); } while (0)
; #define PG8_WAIT_V(n) asm volatile("s_waitcnt vmcnt(" #n ")" ::: "memory")
; #define PG8_WAIT_L(n) asm volatile("s_waitcnt lgkmcnt(" #n ")" ::: "memory")
; #define PG8_BAR __builtin_amdgcn_s_barrier()
; #define PG8_SCHED __builtin_amdgcn_sched_barrier(0)
; template <class Epi, class Sched, bool ALIGN_EPI = false, bool SP2 = false>
; __device__ __forceinline__ void gemm_phase(PG8_LAS unsigned char* lds, const Gemm g, const Sched& S, const Epi& E) {
;     ...
;         const bool has_next = S.next(ui + 1, nxt);
;         const char* nA = has_next ? (const char*)g.A + (size_t)nxt.pm * tstep : cA; const char* nB = has_next ? (const char*)g.Bt + (size_t)nxt.pn * tstep : cB;
;         for (int t = 0; t < nt; t += 2) {
;             const bool last = (t == nt - 2);
;             const char* a1 = cA + (size_t)(t + 1) * kstep;
;             const char* a2 = last ? nA : cA + (size_t)(t + 2) * kstep; const char* b2 = last ? nB : cB + (size_t)(t + 2) * kstep;
;             const char* a3 = a2 + kstep; const char* b3 = b2 + kstep;
;             if (last && has_next) S.a_ready(nxt);
;             if constexpr (SP2) {
;             PG8_LDB(B0, 0, 0); PG8_LDB(B1, 0, 1); PG8_SCHED; PG8_LDA(At, 0, 0); PG8_STAGE(PG8_SA(1, 1), a1 + hstep, voffA);
;             PG8_WAIT_V(8); PG8_WAIT_L(0); PG8_BAR; PG8_MMA(0, 0, At, B0); PG8_MMA(0, 1, At, B1); PG8_BAR; PG8_SCHED;
;             PG8_LDA(At, 0, 1); PG8_STAGE(PG8_SB(0, 0), b2, voffB); PG8_STAGE(PG8_SB(0, 1), b2 + hstep, voffB); PG8_STAGE(PG8_SA(0, 0), a2, voffA);
;             PG8_WAIT_V(8); PG8_WAIT_L(0); PG8_BAR; PG8_MMA(1, 0, At, B0); PG8_MMA(1, 1, At, B1); PG8_BAR; PG8_SCHED;
.LBB0_697:
	s_ashr_i32 s17, s16, 31
	s_lshl_b64 s[18:19], s[16:17], 19
	v_readlane_b32 s48, v235, 2
	v_readlane_b32 s49, v235, 3
	s_add_u32 s18, s48, s18
	s_addc_u32 s19, s49, s19
	s_and_b64 s[20:21], s[6:7], exec
	s_cselect_b32 s17, s19, s27
	s_cselect_b32 s23, s18, s26
	s_ashr_i32 s15, s14, 31
	s_lshl_b64 s[20:21], s[14:15], 19
	s_add_u32 s20, s33, s20
	s_addc_u32 s21, s34, s21
	s_and_b64 s[30:31], s[6:7], exec
	s_cselect_b32 s15, s21, s29
	s_cselect_b32 s47, s20, s28
	s_add_u32 s26, s26, 0x40080
	s_addc_u32 s27, s27, 0
	v_readlane_b32 s50, v235, 4
	s_add_u32 s48, s28, 0x100
	s_addc_u32 s49, s29, 0
	s_mov_b32 s50, -2
	s_waitcnt lgkmcnt(0)
	v_readlane_b32 s51, v235, 5
	ds_read_b128 v[144:147], v151
	ds_read_b128 v[156:159], v151 offset:1024
	ds_read_b128 v[160:163], v151 offset:2048
	ds_read_b128 v[164:167], v151 offset:3072
	ds_read_b128 v[168:171], v152
	ds_read_b128 v[172:175], v152 offset:1024
	ds_read_b128 v[176:179], v152 offset:2048
	ds_read_b128 v[180:183], v152 offset:3072
	s_add_u32 s28, s26, 0xfffc0080
	s_addc_u32 s29, s27, -1
	s_cmp_eq_u32 s50, 12
	s_cselect_b32 s31, s17, s29
	s_cselect_b32 s30, s23, s28
	s_cselect_b32 s29, s15, s49
	s_cselect_b32 s28, s47, s48
	v_lshl_add_u64 v[218:219], s[26:27], 0, v[136:137]
	s_add_i32 m0, s25, 0xc000
	ds_read_b128 v[184:187], v153
	ds_read_b128 v[190:193], v153 offset:1024
	ds_read_b128 v[194:197], v153 offset:2048
	ds_read_b128 v[198:201], v153 offset:3072
	ds_read_b128 v[202:205], v153 offset:4096
	ds_read_b128 v[206:209], v153 offset:5120
	ds_read_b128 v[210:213], v153 offset:6144
	ds_read_b128 v[214:217], v153 offset:7168
	global_load_lds_dwordx4 v[218:219], off
	v_lshl_add_u64 v[218:219], s[26:27], 0, v[138:139]
	s_add_i32 m0, s25, 0xe000
	s_nop 0
	global_load_lds_dwordx4 v[218:219], off
	s_waitcnt vmcnt(8)
	s_waitcnt lgkmcnt(0)
	s_barrier
	v_mfma_f32_16x16x32_bf16 v[124:127], v[144:147], v[184:187], 0
	v_mfma_f32_16x16x32_bf16 v[120:123], v[160:163], v[184:187], 0
	v_mfma_f32_16x16x32_bf16 v[108:111], v[144:147], v[194:197], 0
	v_mfma_f32_16x16x32_bf16 v[104:107], v[160:163], v[194:197], 0
	v_mfma_f32_16x16x32_bf16 v[92:95], v[144:147], v[202:205], 0
	v_mfma_f32_16x16x32_bf16 v[88:91], v[160:163], v[202:205], 0
	v_mfma_f32_16x16x32_bf16 v[76:79], v[144:147], v[210:213], 0
	v_mfma_f32_16x16x32_bf16 v[72:75], v[160:163], v[210:213], 0
	v_mfma_f32_16x16x32_bf16 v[124:127], v[156:159], v[190:193], v[124:127]
	v_mfma_f32_16x16x32_bf16 v[120:123], v[164:167], v[190:193], v[120:123]
	v_mfma_f32_16x16x32_bf16 v[108:111], v[156:159], v[198:201], v[108:111]
	v_mfma_f32_16x16x32_bf16 v[104:107], v[164:167], v[198:201], v[104:107]
	v_mfma_f32_16x16x32_bf16 v[92:95], v[156:159], v[206:209], v[92:95]
	v_mfma_f32_16x16x32_bf16 v[88:91], v[164:167], v[206:209], v[88:91]
	v_mfma_f32_16x16x32_bf16 v[76:79], v[156:159], v[214:217], v[76:79]
	v_mfma_f32_16x16x32_bf16 v[72:75], v[164:167], v[214:217], v[72:75]
	v_mfma_f32_16x16x32_bf16 v[116:119], v[168:171], v[184:187], 0
	v_mfma_f32_16x16x32_bf16 v[112:115], v[176:179], v[184:187], 0
	v_mfma_f32_16x16x32_bf16 v[100:103], v[168:171], v[194:197], 0
	v_mfma_f32_16x16x32_bf16 v[96:99], v[176:179], v[194:197], 0
	v_mfma_f32_16x16x32_bf16 v[84:87], v[168:171], v[202:205], 0
	v_mfma_f32_16x16x32_bf16 v[80:83], v[176:179], v[202:205], 0
	v_mfma_f32_16x16x32_bf16 v[68:71], v[168:171], v[210:213], 0
	v_mfma_f32_16x16x32_bf16 v[64:67], v[176:179], v[210:213], 0
	v_mfma_f32_16x16x32_bf16 v[116:119], v[172:175], v[190:193], v[116:119]
	v_mfma_f32_16x16x32_bf16 v[112:115], v[180:183], v[190:193], v[112:115]
	v_mfma_f32_16x16x32_bf16 v[100:103], v[172:175], v[198:201], v[100:103]
	v_mfma_f32_16x16x32_bf16 v[96:99], v[180:183], v[198:201], v[96:99]
	v_mfma_f32_16x16x32_bf16 v[84:87], v[172:175], v[206:209], v[84:87]
	v_mfma_f32_16x16x32_bf16 v[80:83], v[180:183], v[206:209], v[80:83]
	v_mfma_f32_16x16x32_bf16 v[68:71], v[172:175], v[214:217], v[68:71]
	v_mfma_f32_16x16x32_bf16 v[64:67], v[180:183], v[214:217], v[64:67]
	s_barrier
	s_add_i32 s51, s45, s35
	v_lshl_add_u64 v[218:219], s[28:29], 0, v[130:131]
	s_mov_b32 m0, s51
	ds_read_b128 v[184:187], v153 offset:16384
	ds_read_b128 v[190:193], v153 offset:17408
	ds_read_b128 v[194:197], v153 offset:18432
	ds_read_b128 v[198:201], v153 offset:19456
	ds_read_b128 v[202:205], v153 offset:20480
	ds_read_b128 v[206:209], v153 offset:21504
	ds_read_b128 v[210:213], v153 offset:22528
	ds_read_b128 v[214:217], v153 offset:23552
	global_load_lds_dwordx4 v[218:219], off
	s_add_i32 m0, s51, 0x2000
	s_add_u32 s52, s28, 0x40000
	v_lshl_add_u64 v[220:221], s[28:29], 0, v[134:135]
	s_addc_u32 s53, s29, 0
	s_add_i32 s51, s46, s35
	global_load_lds_dwordx4 v[220:221], off
	v_lshl_add_u64 v[222:223], s[52:53], 0, v[130:131]
	s_mov_b32 m0, s51
	v_lshl_add_u64 v[224:225], s[30:31], 0, v[132:133]
	global_load_lds_dwordx4 v[222:223], off
	v_lshl_add_u64 v[222:223], s[52:53], 0, v[134:135]
	s_add_i32 m0, s51, 0x2000
	s_nop 0
	global_load_lds_dwordx4 v[222:223], off
	v_lshl_add_u64 v[222:223], s[30:31], 0, v[128:129]
	s_mov_b32 m0, s25
	s_nop 0
	global_load_lds_dwordx4 v[222:223], off
	s_mov_b32 m0, s36
	s_nop 0
	global_load_lds_dwordx4 v[224:225], off
	s_waitcnt vmcnt(8)
	s_waitcnt lgkmcnt(0)
	s_barrier
; #define PG8_STAGE(bufoff, gbase, voff) do { _Pragma("unroll") for (int _i = 0; _i < 2; ++_i) \
;         __builtin_amdgcn_global_load_lds((const unsigned*)((const char*)(gbase) + (voff)[_i]), (PG8_LAS unsigned*)(lds + (bufoff) + ldsw + _i * 8192), 16, 0, 0); } while (0)
; #define PG8_LDA(dst, b, h) do { _Pragma("unroll") for (int m = 0; m < 4; ++m) _Pragma("unroll") for (int k = 0; k < 2; ++k) dst[m][k] = *(const PG8_LAS bf16x8*)(lds + PG8_SA(b, h) + aoff + m * 2048 + k * 1024); } while (0)
; #define PG8_LDB(dst, b, h) do { _Pragma("unroll") for (int n = 0; n < 2; ++n) _Pragma("unroll") for (int k = 0; k < 2; ++k) dst[n][k] = *(const PG8_LAS bf16x8*)(lds + PG8_SB(b, h) + boff + n * 2048 + k * 1024); } while (0)
; #define PG8_MMA(ai, bj, At, Bt) do { __builtin_amdgcn_s_setprio(1); _Pragma("unroll") for (int m = 0; m < 4; ++m) _Pragma("unroll") for (int n = 0; n < 2; ++n) _Pragma("unroll") for (int k = 0; k < 2; ++k) \
;         acc[ai][bj][m][n] = __builtin_amdgcn_mfma_f32_16x16x32_bf16(Bt[n][k], At[m][k], acc[ai][bj][m][n], 0, 0, 0); __builtin_amdgcn_s_setprio(0); } while (0)
; #define PG8_WAIT_V(n) asm volatile("s_waitcnt vmcnt(" #n ")" ::: "memory")
; template <class Epi, class Sched, bool ALIGN_EPI = false, bool SP2 = false>
; __device__ __forceinline__ void gemm_phase(PG8_LAS unsigned char* lds, const Gemm g, const Sched& S, const Epi& E) {
;     ...
;             PG8_LDB(B0, 0, 0); PG8_LDB(B1, 0, 1); PG8_SCHED; PG8_LDA(At, 0, 0); PG8_STAGE(PG8_SA(1, 1), a1 + hstep, voffA);
;             PG8_WAIT_V(8); PG8_WAIT_L(0); PG8_BAR; PG8_MMA(0, 0, At, B0); PG8_MMA(0, 1, At, B1); PG8_BAR; PG8_SCHED;
;             PG8_LDA(At, 0, 1); PG8_STAGE(PG8_SB(0, 0), b2, voffB); PG8_STAGE(PG8_SB(0, 1), b2 + hstep, voffB); PG8_STAGE(PG8_SA(0, 0), a2, voffA);
;             PG8_WAIT_V(8); PG8_WAIT_L(0); PG8_BAR; PG8_MMA(1, 0, At, B0); PG8_MMA(1, 1, At, B1); PG8_BAR; PG8_SCHED;
;             PG8_LDB(B0, 1, 0); PG8_LDB(B1, 1, 1); PG8_SCHED; PG8_LDA(At, 1, 0); PG8_STAGE(PG8_SA(0, 1), a2 + hstep, voffA);
;             PG8_WAIT_V(8); PG8_WAIT_L(0); PG8_BAR; PG8_MMA(0, 0, At, B0); PG8_MMA(0, 1, At, B1); PG8_BAR; PG8_SCHED;
;             PG8_LDA(At, 1, 1); PG8_STAGE(PG8_SB(1, 0), b3, voffB); PG8_STAGE(PG8_SB(1, 1), b3 + hstep, voffB); PG8_STAGE(PG8_SA(1, 0), a3, voffA);
;             PG8_WAIT_V(8); PG8_WAIT_L(0); PG8_BAR; PG8_MMA(1, 0, At, B0); PG8_MMA(1, 1, At, B1); PG8_BAR; PG8_SCHED;
	v_mfma_f32_16x16x32_bf16 v[60:63], v[144:147], v[184:187], 0
	v_mfma_f32_16x16x32_bf16 v[56:59], v[160:163], v[184:187], 0
	v_mfma_f32_16x16x32_bf16 v[44:47], v[144:147], v[194:197], 0
	v_mfma_f32_16x16x32_bf16 v[40:43], v[160:163], v[194:197], 0
	v_mfma_f32_16x16x32_bf16 v[28:31], v[144:147], v[202:205], 0
	v_mfma_f32_16x16x32_bf16 v[24:27], v[160:163], v[202:205], 0
	v_mfma_f32_16x16x32_bf16 v[12:15], v[144:147], v[210:213], 0
	v_mfma_f32_16x16x32_bf16 v[8:11], v[160:163], v[210:213], 0
	v_mfma_f32_16x16x32_bf16 v[60:63], v[156:159], v[190:193], v[60:63]
	v_mfma_f32_16x16x32_bf16 v[56:59], v[164:167], v[190:193], v[56:59]
	v_mfma_f32_16x16x32_bf16 v[44:47], v[156:159], v[198:201], v[44:47]
	v_mfma_f32_16x16x32_bf16 v[40:43], v[164:167], v[198:201], v[40:43]
	v_mfma_f32_16x16x32_bf16 v[28:31], v[156:159], v[206:209], v[28:31]
	v_mfma_f32_16x16x32_bf16 v[24:27], v[164:167], v[206:209], v[24:27]
	v_mfma_f32_16x16x32_bf16 v[12:15], v[156:159], v[214:217], v[12:15]
	v_mfma_f32_16x16x32_bf16 v[8:11], v[164:167], v[214:217], v[8:11]
	v_mfma_f32_16x16x32_bf16 v[52:55], v[168:171], v[184:187], 0
	v_mfma_f32_16x16x32_bf16 v[48:51], v[176:179], v[184:187], 0
	v_mfma_f32_16x16x32_bf16 v[36:39], v[168:171], v[194:197], 0
	v_mfma_f32_16x16x32_bf16 v[32:35], v[176:179], v[194:197], 0
	v_mfma_f32_16x16x32_bf16 v[20:23], v[168:171], v[202:205], 0
	v_mfma_f32_16x16x32_bf16 v[16:19], v[176:179], v[202:205], 0
	v_mfma_f32_16x16x32_bf16 v[4:7], v[168:171], v[210:213], 0
	v_mfma_f32_16x16x32_bf16 v[0:3], v[176:179], v[210:213], 0
	v_mfma_f32_16x16x32_bf16 v[52:55], v[172:175], v[190:193], v[52:55]
	v_mfma_f32_16x16x32_bf16 v[48:51], v[180:183], v[190:193], v[48:51]
	v_mfma_f32_16x16x32_bf16 v[36:39], v[172:175], v[198:201], v[36:39]
	v_mfma_f32_16x16x32_bf16 v[32:35], v[180:183], v[198:201], v[32:35]
	v_mfma_f32_16x16x32_bf16 v[20:23], v[172:175], v[206:209], v[20:23]
	v_mfma_f32_16x16x32_bf16 v[16:19], v[180:183], v[206:209], v[16:19]
	v_mfma_f32_16x16x32_bf16 v[4:7], v[172:175], v[214:217], v[4:7]
	v_mfma_f32_16x16x32_bf16 v[0:3], v[180:183], v[214:217], v[0:3]
	s_barrier
	s_add_i32 s51, 0, 0x18000
	v_add_u32_e32 v155, s51, v149
	s_add_i32 s52, 0, 0x1c000
	ds_read_b128 v[144:147], v155
	ds_read_b128 v[156:159], v155 offset:1024
	ds_read_b128 v[160:163], v155 offset:2048
	ds_read_b128 v[164:167], v155 offset:3072
	v_add_u32_e32 v155, s52, v149
	ds_read_b128 v[168:171], v155
	ds_read_b128 v[172:175], v155 offset:1024
	ds_read_b128 v[176:179], v155 offset:2048
	ds_read_b128 v[180:183], v155 offset:3072
	s_add_u32 s30, s30, 0x40000
	s_addc_u32 s31, s31, 0
	s_mov_b32 m0, s37
	v_lshl_add_u64 v[226:227], s[30:31], 0, v[128:129]
	ds_read_b128 v[184:187], v153 offset:32768
	ds_read_b128 v[190:193], v153 offset:33792
	ds_read_b128 v[194:197], v153 offset:34816
	ds_read_b128 v[198:201], v153 offset:35840
	ds_read_b128 v[202:205], v153 offset:36864
	ds_read_b128 v[206:209], v153 offset:37888
	ds_read_b128 v[210:213], v153 offset:38912
	ds_read_b128 v[214:217], v153 offset:39936
	global_load_lds_dwordx4 v[226:227], off
	v_lshl_add_u64 v[226:227], s[30:31], 0, v[132:133]
	s_mov_b32 m0, s38
	s_nop 0
	global_load_lds_dwordx4 v[226:227], off
	s_waitcnt vmcnt(8)
	s_waitcnt lgkmcnt(0)
	s_barrier
	v_mfma_f32_16x16x32_bf16 v[124:127], v[144:147], v[184:187], v[124:127]
	v_mfma_f32_16x16x32_bf16 v[120:123], v[160:163], v[184:187], v[120:123]
	v_mfma_f32_16x16x32_bf16 v[108:111], v[144:147], v[194:197], v[108:111]
	v_mfma_f32_16x16x32_bf16 v[104:107], v[160:163], v[194:197], v[104:107]
	v_mfma_f32_16x16x32_bf16 v[92:95], v[144:147], v[202:205], v[92:95]
	v_mfma_f32_16x16x32_bf16 v[88:91], v[160:163], v[202:205], v[88:91]
	v_mfma_f32_16x16x32_bf16 v[76:79], v[144:147], v[210:213], v[76:79]
	v_mfma_f32_16x16x32_bf16 v[72:75], v[160:163], v[210:213], v[72:75]
	v_mfma_f32_16x16x32_bf16 v[124:127], v[156:159], v[190:193], v[124:127]
	v_mfma_f32_16x16x32_bf16 v[120:123], v[164:167], v[190:193], v[120:123]
	v_mfma_f32_16x16x32_bf16 v[108:111], v[156:159], v[198:201], v[108:111]
	v_mfma_f32_16x16x32_bf16 v[104:107], v[164:167], v[198:201], v[104:107]
	v_mfma_f32_16x16x32_bf16 v[92:95], v[156:159], v[206:209], v[92:95]
	v_mfma_f32_16x16x32_bf16 v[88:91], v[164:167], v[206:209], v[88:91]
	v_mfma_f32_16x16x32_bf16 v[76:79], v[156:159], v[214:217], v[76:79]
	v_mfma_f32_16x16x32_bf16 v[72:75], v[164:167], v[214:217], v[72:75]
	v_mfma_f32_16x16x32_bf16 v[116:119], v[168:171], v[184:187], v[116:119]
	v_mfma_f32_16x16x32_bf16 v[112:115], v[176:179], v[184:187], v[112:115]
	v_mfma_f32_16x16x32_bf16 v[100:103], v[168:171], v[194:197], v[100:103]
	v_mfma_f32_16x16x32_bf16 v[96:99], v[176:179], v[194:197], v[96:99]
	v_mfma_f32_16x16x32_bf16 v[84:87], v[168:171], v[202:205], v[84:87]
	v_mfma_f32_16x16x32_bf16 v[80:83], v[176:179], v[202:205], v[80:83]
	v_mfma_f32_16x16x32_bf16 v[68:71], v[168:171], v[210:213], v[68:71]
	v_mfma_f32_16x16x32_bf16 v[64:67], v[176:179], v[210:213], v[64:67]
	v_mfma_f32_16x16x32_bf16 v[116:119], v[172:175], v[190:193], v[116:119]
	v_mfma_f32_16x16x32_bf16 v[112:115], v[180:183], v[190:193], v[112:115]
	v_mfma_f32_16x16x32_bf16 v[100:103], v[172:175], v[198:201], v[100:103]
	v_mfma_f32_16x16x32_bf16 v[96:99], v[180:183], v[198:201], v[96:99]
	v_mfma_f32_16x16x32_bf16 v[84:87], v[172:175], v[206:209], v[84:87]
	v_mfma_f32_16x16x32_bf16 v[80:83], v[180:183], v[206:209], v[80:83]
	v_mfma_f32_16x16x32_bf16 v[68:71], v[172:175], v[214:217], v[68:71]
	v_mfma_f32_16x16x32_bf16 v[64:67], v[180:183], v[214:217], v[64:67]
	s_barrier
; #define PG8_STAGE(bufoff, gbase, voff) do { _Pragma("unroll") for (int _i = 0; _i < 2; ++_i) \
;         __builtin_amdgcn_global_load_lds((const unsigned*)((const char*)(gbase) + (voff)[_i]), (PG8_LAS unsigned*)(lds + (bufoff) + ldsw + _i * 8192), 16, 0, 0); } while (0)
; #define PG8_LDA(dst, b, h) do { _Pragma("unroll") for (int m = 0; m < 4; ++m) _Pragma("unroll") for (int k = 0; k < 2; ++k) dst[m][k] = *(const PG8_LAS bf16x8*)(lds + PG8_SA(b, h) + aoff + m * 2048 + k * 1024); } while (0)
; #define PG8_LDB(dst, b, h) do { _Pragma("unroll") for (int n = 0; n < 2; ++n) _Pragma("unroll") for (int k = 0; k < 2; ++k) dst[n][k] = *(const PG8_LAS bf16x8*)(lds + PG8_SB(b, h) + boff + n * 2048 + k * 1024); } while (0)
; template <class Epi, class Sched, bool ALIGN_EPI = false, bool SP2 = false>
; __device__ __forceinline__ void gemm_phase(PG8_LAS unsigned char* lds, const Gemm g, const Sched& S, const Epi& E) {
;     ...
;         for (int t = 0; t < nt; t += 2) {
;             const bool last = (t == nt - 2);
;             const char* a1 = cA + (size_t)(t + 1) * kstep;
;             const char* a2 = last ? nA : cA + (size_t)(t + 2) * kstep; const char* b2 = last ? nB : cB + (size_t)(t + 2) * kstep;
;             const char* a3 = a2 + kstep; const char* b3 = b2 + kstep;
;             if (last && has_next) S.a_ready(nxt);
;             if constexpr (SP2) {
;             PG8_LDB(B0, 0, 0); PG8_LDB(B1, 0, 1); PG8_SCHED; PG8_LDA(At, 0, 0); PG8_STAGE(PG8_SA(1, 1), a1 + hstep, voffA);
;             PG8_WAIT_V(8); PG8_WAIT_L(0); PG8_BAR; PG8_MMA(0, 0, At, B0); PG8_MMA(0, 1, At, B1); PG8_BAR; PG8_SCHED;
;             PG8_LDA(At, 0, 1); PG8_STAGE(PG8_SB(0, 0), b2, voffB); PG8_STAGE(PG8_SB(0, 1), b2 + hstep, voffB); PG8_STAGE(PG8_SA(0, 0), a2, voffA);
;             PG8_WAIT_V(8); PG8_WAIT_L(0); PG8_BAR; PG8_MMA(1, 0, At, B0); PG8_MMA(1, 1, At, B1); PG8_BAR; PG8_SCHED;
;             PG8_LDB(B0, 1, 0); PG8_LDB(B1, 1, 1); PG8_SCHED; PG8_LDA(At, 1, 0); PG8_STAGE(PG8_SA(0, 1), a2 + hstep, voffA);
;             PG8_WAIT_V(8); PG8_WAIT_L(0); PG8_BAR; PG8_MMA(0, 0, At, B0); PG8_MMA(0, 1, At, B1); PG8_BAR; PG8_SCHED;
;             PG8_LDA(At, 1, 1); PG8_STAGE(PG8_SB(1, 0), b3, voffB); PG8_STAGE(PG8_SB(1, 1), b3 + hstep, voffB); PG8_STAGE(PG8_SA(1, 0), a3, voffA);
;             PG8_WAIT_V(8); PG8_WAIT_L(0); PG8_BAR; PG8_MMA(1, 0, At, B0); PG8_MMA(1, 1, At, B1); PG8_BAR; PG8_SCHED;
	s_add_i32 s30, s51, s35
	v_lshl_add_u64 v[218:219], v[218:219], 0, s[2:3]
	s_mov_b32 m0, s30
	ds_read_b128 v[184:187], v153 offset:49152
	ds_read_b128 v[190:193], v153 offset:50176
	ds_read_b128 v[194:197], v153 offset:51200
	ds_read_b128 v[198:201], v153 offset:52224
	ds_read_b128 v[202:205], v153 offset:53248
	ds_read_b128 v[206:209], v153 offset:54272
	ds_read_b128 v[210:213], v153 offset:55296
	ds_read_b128 v[214:217], v153 offset:56320
	global_load_lds_dwordx4 v[218:219], off
	s_add_i32 m0, s30, 0x2000
	s_add_u32 s28, s28, 0x40080
	v_lshl_add_u64 v[218:219], v[220:221], 0, s[2:3]
	s_addc_u32 s29, s29, 0
	s_add_i32 s30, s52, s35
	global_load_lds_dwordx4 v[218:219], off
	v_lshl_add_u64 v[218:219], s[28:29], 0, v[130:131]
	s_mov_b32 m0, s30
	s_nop 0
	global_load_lds_dwordx4 v[218:219], off
	v_lshl_add_u64 v[218:219], s[28:29], 0, v[134:135]
	s_add_i32 m0, s30, 0x2000
	s_nop 0
	global_load_lds_dwordx4 v[218:219], off
	v_lshl_add_u64 v[218:219], v[222:223], 0, s[2:3]
	s_mov_b32 m0, s40
	s_nop 0
	global_load_lds_dwordx4 v[218:219], off
	v_lshl_add_u64 v[218:219], v[224:225], 0, s[2:3]
	s_mov_b32 m0, s41
	s_nop 0
	global_load_lds_dwordx4 v[218:219], off
	s_waitcnt vmcnt(8)
	s_waitcnt lgkmcnt(0)
	s_barrier
	v_mfma_f32_16x16x32_bf16 v[60:63], v[144:147], v[184:187], v[60:63]
	v_mfma_f32_16x16x32_bf16 v[56:59], v[160:163], v[184:187], v[56:59]
	v_mfma_f32_16x16x32_bf16 v[44:47], v[144:147], v[194:197], v[44:47]
	v_mfma_f32_16x16x32_bf16 v[40:43], v[160:163], v[194:197], v[40:43]
	v_mfma_f32_16x16x32_bf16 v[28:31], v[144:147], v[202:205], v[28:31]
	v_mfma_f32_16x16x32_bf16 v[24:27], v[160:163], v[202:205], v[24:27]
	v_mfma_f32_16x16x32_bf16 v[12:15], v[144:147], v[210:213], v[12:15]
	v_mfma_f32_16x16x32_bf16 v[8:11], v[160:163], v[210:213], v[8:11]
	v_mfma_f32_16x16x32_bf16 v[60:63], v[156:159], v[190:193], v[60:63]
	v_mfma_f32_16x16x32_bf16 v[56:59], v[164:167], v[190:193], v[56:59]
	v_mfma_f32_16x16x32_bf16 v[44:47], v[156:159], v[198:201], v[44:47]
	v_mfma_f32_16x16x32_bf16 v[40:43], v[164:167], v[198:201], v[40:43]
	v_mfma_f32_16x16x32_bf16 v[28:31], v[156:159], v[206:209], v[28:31]
	v_mfma_f32_16x16x32_bf16 v[24:27], v[164:167], v[206:209], v[24:27]
	v_mfma_f32_16x16x32_bf16 v[12:15], v[156:159], v[214:217], v[12:15]
	v_mfma_f32_16x16x32_bf16 v[8:11], v[164:167], v[214:217], v[8:11]
	v_mfma_f32_16x16x32_bf16 v[52:55], v[168:171], v[184:187], v[52:55]
	v_mfma_f32_16x16x32_bf16 v[48:51], v[176:179], v[184:187], v[48:51]
	v_mfma_f32_16x16x32_bf16 v[36:39], v[168:171], v[194:197], v[36:39]
	v_mfma_f32_16x16x32_bf16 v[32:35], v[176:179], v[194:197], v[32:35]
	v_mfma_f32_16x16x32_bf16 v[20:23], v[168:171], v[202:205], v[20:23]
	v_mfma_f32_16x16x32_bf16 v[16:19], v[176:179], v[202:205], v[16:19]
	v_mfma_f32_16x16x32_bf16 v[4:7], v[168:171], v[210:213], v[4:7]
	v_mfma_f32_16x16x32_bf16 v[0:3], v[176:179], v[210:213], v[0:3]
	v_mfma_f32_16x16x32_bf16 v[52:55], v[172:175], v[190:193], v[52:55]
	v_mfma_f32_16x16x32_bf16 v[48:51], v[180:183], v[190:193], v[48:51]
	v_mfma_f32_16x16x32_bf16 v[36:39], v[172:175], v[198:201], v[36:39]
	v_mfma_f32_16x16x32_bf16 v[32:35], v[180:183], v[198:201], v[32:35]
	v_mfma_f32_16x16x32_bf16 v[20:23], v[172:175], v[206:209], v[20:23]
	v_mfma_f32_16x16x32_bf16 v[16:19], v[180:183], v[206:209], v[16:19]
	v_mfma_f32_16x16x32_bf16 v[4:7], v[172:175], v[214:217], v[4:7]
	v_mfma_f32_16x16x32_bf16 v[0:3], v[180:183], v[214:217], v[0:3]
	s_barrier
	s_add_i32 s50, s50, 2
	s_add_u32 s26, s26, 0x100
	s_addc_u32 s27, s27, 0
	s_add_u32 s48, s48, 0x100
	s_addc_u32 s49, s49, 0
.LBB0_698:
	ds_read_b128 v[144:147], v151
	ds_read_b128 v[156:159], v151 offset:1024
	ds_read_b128 v[160:163], v151 offset:2048
	ds_read_b128 v[164:167], v151 offset:3072
	ds_read_b128 v[168:171], v152
	ds_read_b128 v[172:175], v152 offset:1024
	ds_read_b128 v[176:179], v152 offset:2048
	ds_read_b128 v[180:183], v152 offset:3072
	s_add_u32 s28, s26, 0xfffc0080
	s_addc_u32 s29, s27, -1
	s_cmp_eq_u32 s50, 12
	s_cselect_b32 s31, s17, s29
	s_cselect_b32 s30, s23, s28
	s_cselect_b32 s29, s15, s49
	s_cselect_b32 s28, s47, s48
	v_lshl_add_u64 v[218:219], s[26:27], 0, v[136:137]
	s_add_i32 m0, s25, 0xc000
	ds_read_b128 v[184:187], v153
	ds_read_b128 v[190:193], v153 offset:1024
	ds_read_b128 v[194:197], v153 offset:2048
	ds_read_b128 v[198:201], v153 offset:3072
	ds_read_b128 v[202:205], v153 offset:4096
	ds_read_b128 v[206:209], v153 offset:5120
	ds_read_b128 v[210:213], v153 offset:6144
	ds_read_b128 v[214:217], v153 offset:7168
	global_load_lds_dwordx4 v[218:219], off
	v_lshl_add_u64 v[218:219], s[26:27], 0, v[138:139]
	s_add_i32 m0, s25, 0xe000
	s_nop 0
	global_load_lds_dwordx4 v[218:219], off
	s_waitcnt vmcnt(8)
	s_waitcnt lgkmcnt(0)
	s_barrier
; #define PG8_STAGE(bufoff, gbase, voff) do { _Pragma("unroll") for (int _i = 0; _i < 2; ++_i) \
;         __builtin_amdgcn_global_load_lds((const unsigned*)((const char*)(gbase) + (voff)[_i]), (PG8_LAS unsigned*)(lds + (bufoff) + ldsw + _i * 8192), 16, 0, 0); } while (0)
; #define PG8_LDA(dst, b, h) do { _Pragma("unroll") for (int m = 0; m < 4; ++m) _Pragma("unroll") for (int k = 0; k < 2; ++k) dst[m][k] = *(const PG8_LAS bf16x8*)(lds + PG8_SA(b, h) + aoff + m * 2048 + k * 1024); } while (0)
; #define PG8_LDB(dst, b, h) do { _Pragma("unroll") for (int n = 0; n < 2; ++n) _Pragma("unroll") for (int k = 0; k < 2; ++k) dst[n][k] = *(const PG8_LAS bf16x8*)(lds + PG8_SB(b, h) + boff + n * 2048 + k * 1024); } while (0)
; #define PG8_MMA(ai, bj, At, Bt) do { __builtin_amdgcn_s_setprio(1); _Pragma("unroll") for (int m = 0; m < 4; ++m) _Pragma("unroll") for (int n = 0; n < 2; ++n) _Pragma("unroll") for (int k = 0; k < 2; ++k) \
;         acc[ai][bj][m][n] = __builtin_amdgcn_mfma_f32_16x16x32_bf16(Bt[n][k], At[m][k], acc[ai][bj][m][n], 0, 0, 0); __builtin_amdgcn_s_setprio(0); } while (0)
; #define PG8_WAIT_V(n) asm volatile("s_waitcnt vmcnt(" #n ")" ::: "memory")
; template <class Epi, class Sched, bool ALIGN_EPI = false, bool SP2 = false>
; __device__ __forceinline__ void gemm_phase(PG8_LAS unsigned char* lds, const Gemm g, const Sched& S, const Epi& E) {
;     ...
;             PG8_LDB(B0, 0, 0); PG8_LDB(B1, 0, 1); PG8_SCHED; PG8_LDA(At, 0, 0); PG8_STAGE(PG8_SA(1, 1), a1 + hstep, voffA);
;             PG8_WAIT_V(8); PG8_WAIT_L(0); PG8_BAR; PG8_MMA(0, 0, At, B0); PG8_MMA(0, 1, At, B1); PG8_BAR; PG8_SCHED;
;             PG8_LDA(At, 0, 1); PG8_STAGE(PG8_SB(0, 0), b2, voffB); PG8_STAGE(PG8_SB(0, 1), b2 + hstep, voffB); PG8_STAGE(PG8_SA(0, 0), a2, voffA);
;             PG8_WAIT_V(8); PG8_WAIT_L(0); PG8_BAR; PG8_MMA(1, 0, At, B0); PG8_MMA(1, 1, At, B1); PG8_BAR; PG8_SCHED;
;             PG8_LDB(B0, 1, 0); PG8_LDB(B1, 1, 1); PG8_SCHED; PG8_LDA(At, 1, 0); PG8_STAGE(PG8_SA(0, 1), a2 + hstep, voffA);
;             PG8_WAIT_V(8); PG8_WAIT_L(0); PG8_BAR; PG8_MMA(0, 0, At, B0); PG8_MMA(0, 1, At, B1); PG8_BAR; PG8_SCHED;
;             PG8_LDA(At, 1, 1); PG8_STAGE(PG8_SB(1, 0), b3, voffB); PG8_STAGE(PG8_SB(1, 1), b3 + hstep, voffB); PG8_STAGE(PG8_SA(1, 0), a3, voffA);
;             PG8_WAIT_V(8); PG8_WAIT_L(0); PG8_BAR; PG8_MMA(1, 0, At, B0); PG8_MMA(1, 1, At, B1); PG8_BAR; PG8_SCHED;
	v_mfma_f32_16x16x32_bf16 v[124:127], v[144:147], v[184:187], v[124:127]
	v_mfma_f32_16x16x32_bf16 v[120:123], v[160:163], v[184:187], v[120:123]
	v_mfma_f32_16x16x32_bf16 v[108:111], v[144:147], v[194:197], v[108:111]
	v_mfma_f32_16x16x32_bf16 v[104:107], v[160:163], v[194:197], v[104:107]
	v_mfma_f32_16x16x32_bf16 v[92:95], v[144:147], v[202:205], v[92:95]
	v_mfma_f32_16x16x32_bf16 v[88:91], v[160:163], v[202:205], v[88:91]
	v_mfma_f32_16x16x32_bf16 v[76:79], v[144:147], v[210:213], v[76:79]
	v_mfma_f32_16x16x32_bf16 v[72:75], v[160:163], v[210:213], v[72:75]
	v_mfma_f32_16x16x32_bf16 v[124:127], v[156:159], v[190:193], v[124:127]
	v_mfma_f32_16x16x32_bf16 v[120:123], v[164:167], v[190:193], v[120:123]
	v_mfma_f32_16x16x32_bf16 v[108:111], v[156:159], v[198:201], v[108:111]
	v_mfma_f32_16x16x32_bf16 v[104:107], v[164:167], v[198:201], v[104:107]
	v_mfma_f32_16x16x32_bf16 v[92:95], v[156:159], v[206:209], v[92:95]
	v_mfma_f32_16x16x32_bf16 v[88:91], v[164:167], v[206:209], v[88:91]
	v_mfma_f32_16x16x32_bf16 v[76:79], v[156:159], v[214:217], v[76:79]
	v_mfma_f32_16x16x32_bf16 v[72:75], v[164:167], v[214:217], v[72:75]
	v_mfma_f32_16x16x32_bf16 v[116:119], v[168:171], v[184:187], v[116:119]
	v_mfma_f32_16x16x32_bf16 v[112:115], v[176:179], v[184:187], v[112:115]
	v_mfma_f32_16x16x32_bf16 v[100:103], v[168:171], v[194:197], v[100:103]
	v_mfma_f32_16x16x32_bf16 v[96:99], v[176:179], v[194:197], v[96:99]
	v_mfma_f32_16x16x32_bf16 v[84:87], v[168:171], v[202:205], v[84:87]
	v_mfma_f32_16x16x32_bf16 v[80:83], v[176:179], v[202:205], v[80:83]
	v_mfma_f32_16x16x32_bf16 v[68:71], v[168:171], v[210:213], v[68:71]
	v_mfma_f32_16x16x32_bf16 v[64:67], v[176:179], v[210:213], v[64:67]
	v_mfma_f32_16x16x32_bf16 v[116:119], v[172:175], v[190:193], v[116:119]
	v_mfma_f32_16x16x32_bf16 v[112:115], v[180:183], v[190:193], v[112:115]
	v_mfma_f32_16x16x32_bf16 v[100:103], v[172:175], v[198:201], v[100:103]
	v_mfma_f32_16x16x32_bf16 v[96:99], v[180:183], v[198:201], v[96:99]
	v_mfma_f32_16x16x32_bf16 v[84:87], v[172:175], v[206:209], v[84:87]
	v_mfma_f32_16x16x32_bf16 v[80:83], v[180:183], v[206:209], v[80:83]
	v_mfma_f32_16x16x32_bf16 v[68:71], v[172:175], v[214:217], v[68:71]
	v_mfma_f32_16x16x32_bf16 v[64:67], v[180:183], v[214:217], v[64:67]
	s_barrier
	s_add_i32 s51, s45, s35
	v_lshl_add_u64 v[218:219], s[28:29], 0, v[130:131]
	s_mov_b32 m0, s51
	ds_read_b128 v[184:187], v153 offset:16384
	ds_read_b128 v[190:193], v153 offset:17408
	ds_read_b128 v[194:197], v153 offset:18432
	ds_read_b128 v[198:201], v153 offset:19456
	ds_read_b128 v[202:205], v153 offset:20480
	ds_read_b128 v[206:209], v153 offset:21504
	ds_read_b128 v[210:213], v153 offset:22528
	ds_read_b128 v[214:217], v153 offset:23552
	global_load_lds_dwordx4 v[218:219], off
	s_add_i32 m0, s51, 0x2000
	s_add_u32 s52, s28, 0x40000
	v_lshl_add_u64 v[220:221], s[28:29], 0, v[134:135]
	s_addc_u32 s53, s29, 0
	s_add_i32 s51, s46, s35
	global_load_lds_dwordx4 v[220:221], off
	v_lshl_add_u64 v[222:223], s[52:53], 0, v[130:131]
	s_mov_b32 m0, s51
	v_lshl_add_u64 v[224:225], s[30:31], 0, v[132:133]
	global_load_lds_dwordx4 v[222:223], off
	v_lshl_add_u64 v[222:223], s[52:53], 0, v[134:135]
	s_add_i32 m0, s51, 0x2000
	s_nop 0
	global_load_lds_dwordx4 v[222:223], off
	v_lshl_add_u64 v[222:223], s[30:31], 0, v[128:129]
	s_mov_b32 m0, s25
	s_nop 0
	global_load_lds_dwordx4 v[222:223], off
	s_mov_b32 m0, s36
	s_nop 0
	global_load_lds_dwordx4 v[224:225], off
	s_waitcnt vmcnt(8)
	s_waitcnt lgkmcnt(0)
	s_barrier
	v_mfma_f32_16x16x32_bf16 v[60:63], v[144:147], v[184:187], v[60:63]
	v_mfma_f32_16x16x32_bf16 v[56:59], v[160:163], v[184:187], v[56:59]
	v_mfma_f32_16x16x32_bf16 v[44:47], v[144:147], v[194:197], v[44:47]
	v_mfma_f32_16x16x32_bf16 v[40:43], v[160:163], v[194:197], v[40:43]
	v_mfma_f32_16x16x32_bf16 v[28:31], v[144:147], v[202:205], v[28:31]
	v_mfma_f32_16x16x32_bf16 v[24:27], v[160:163], v[202:205], v[24:27]
	v_mfma_f32_16x16x32_bf16 v[12:15], v[144:147], v[210:213], v[12:15]
	v_mfma_f32_16x16x32_bf16 v[8:11], v[160:163], v[210:213], v[8:11]
	v_mfma_f32_16x16x32_bf16 v[60:63], v[156:159], v[190:193], v[60:63]
	v_mfma_f32_16x16x32_bf16 v[56:59], v[164:167], v[190:193], v[56:59]
	v_mfma_f32_16x16x32_bf16 v[44:47], v[156:159], v[198:201], v[44:47]
	v_mfma_f32_16x16x32_bf16 v[40:43], v[164:167], v[198:201], v[40:43]
	v_mfma_f32_16x16x32_bf16 v[28:31], v[156:159], v[206:209], v[28:31]
	v_mfma_f32_16x16x32_bf16 v[24:27], v[164:167], v[206:209], v[24:27]
	v_mfma_f32_16x16x32_bf16 v[12:15], v[156:159], v[214:217], v[12:15]
	v_mfma_f32_16x16x32_bf16 v[8:11], v[164:167], v[214:217], v[8:11]
	v_mfma_f32_16x16x32_bf16 v[52:55], v[168:171], v[184:187], v[52:55]
	v_mfma_f32_16x16x32_bf16 v[48:51], v[176:179], v[184:187], v[48:51]
	v_mfma_f32_16x16x32_bf16 v[36:39], v[168:171], v[194:197], v[36:39]
	v_mfma_f32_16x16x32_bf16 v[32:35], v[176:179], v[194:197], v[32:35]
	v_mfma_f32_16x16x32_bf16 v[20:23], v[168:171], v[202:205], v[20:23]
	v_mfma_f32_16x16x32_bf16 v[16:19], v[176:179], v[202:205], v[16:19]
	v_mfma_f32_16x16x32_bf16 v[4:7], v[168:171], v[210:213], v[4:7]
	v_mfma_f32_16x16x32_bf16 v[0:3], v[176:179], v[210:213], v[0:3]
	v_mfma_f32_16x16x32_bf16 v[52:55], v[172:175], v[190:193], v[52:55]
	v_mfma_f32_16x16x32_bf16 v[48:51], v[180:183], v[190:193], v[48:51]
	v_mfma_f32_16x16x32_bf16 v[36:39], v[172:175], v[198:201], v[36:39]
	v_mfma_f32_16x16x32_bf16 v[32:35], v[180:183], v[198:201], v[32:35]
	v_mfma_f32_16x16x32_bf16 v[20:23], v[172:175], v[206:209], v[20:23]
	v_mfma_f32_16x16x32_bf16 v[16:19], v[180:183], v[206:209], v[16:19]
	v_mfma_f32_16x16x32_bf16 v[4:7], v[172:175], v[214:217], v[4:7]
	v_mfma_f32_16x16x32_bf16 v[0:3], v[180:183], v[214:217], v[0:3]
	s_barrier
; #define PG8_STAGE(bufoff, gbase, voff) do { _Pragma("unroll") for (int _i = 0; _i < 2; ++_i) \
;         __builtin_amdgcn_global_load_lds((const unsigned*)((const char*)(gbase) + (voff)[_i]), (PG8_LAS unsigned*)(lds + (bufoff) + ldsw + _i * 8192), 16, 0, 0); } while (0)
; #define PG8_LDA(dst, b, h) do { _Pragma("unroll") for (int m = 0; m < 4; ++m) _Pragma("unroll") for (int k = 0; k < 2; ++k) dst[m][k] = *(const PG8_LAS bf16x8*)(lds + PG8_SA(b, h) + aoff + m * 2048 + k * 1024); } while (0)
; #define PG8_LDB(dst, b, h) do { _Pragma("unroll") for (int n = 0; n < 2; ++n) _Pragma("unroll") for (int k = 0; k < 2; ++k) dst[n][k] = *(const PG8_LAS bf16x8*)(lds + PG8_SB(b, h) + boff + n * 2048 + k * 1024); } while (0)
; #define PG8_MMA(ai, bj, At, Bt) do { __builtin_amdgcn_s_setprio(1); _Pragma("unroll") for (int m = 0; m < 4; ++m) _Pragma("unroll") for (int n = 0; n < 2; ++n) _Pragma("unroll") for (int k = 0; k < 2; ++k) \
;         acc[ai][bj][m][n] = __builtin_amdgcn_mfma_f32_16x16x32_bf16(Bt[n][k], At[m][k], acc[ai][bj][m][n], 0, 0, 0); __builtin_amdgcn_s_setprio(0); } while (0)
; #define PG8_WAIT_V(n) asm volatile("s_waitcnt vmcnt(" #n ")" ::: "memory")
; #define PG8_WAIT_L(n) asm volatile("s_waitcnt lgkmcnt(" #n ")" ::: "memory")
; #define PG8_BAR __builtin_amdgcn_s_barrier()
; #define PG8_SCHED __builtin_amdgcn_sched_barrier(0)
; template <class Epi, class Sched, bool ALIGN_EPI = false, bool SP2 = false>
; __device__ __forceinline__ void gemm_phase(PG8_LAS unsigned char* lds, const Gemm g, const Sched& S, const Epi& E) {
;     ...
;             PG8_LDB(B0, 1, 0); PG8_LDB(B1, 1, 1); PG8_SCHED; PG8_LDA(At, 1, 0); PG8_STAGE(PG8_SA(0, 1), a2 + hstep, voffA);
;             PG8_WAIT_V(8); PG8_WAIT_L(0); PG8_BAR; PG8_MMA(0, 0, At, B0); PG8_MMA(0, 1, At, B1); PG8_BAR; PG8_SCHED;
	s_add_i32 s51, 0, 0x18000
	v_add_u32_e32 v155, s51, v149
	s_add_i32 s52, 0, 0x1c000
	ds_read_b128 v[144:147], v155
	ds_read_b128 v[156:159], v155 offset:1024
	ds_read_b128 v[160:163], v155 offset:2048
	ds_read_b128 v[164:167], v155 offset:3072
	v_add_u32_e32 v155, s52, v149
	ds_read_b128 v[168:171], v155
	ds_read_b128 v[172:175], v155 offset:1024
	ds_read_b128 v[176:179], v155 offset:2048
	ds_read_b128 v[180:183], v155 offset:3072
	s_add_u32 s30, s30, 0x40000
	s_addc_u32 s31, s31, 0
	s_mov_b32 m0, s37
	v_lshl_add_u64 v[226:227], s[30:31], 0, v[128:129]
	ds_read_b128 v[184:187], v153 offset:32768
	ds_read_b128 v[190:193], v153 offset:33792
	ds_read_b128 v[194:197], v153 offset:34816
	ds_read_b128 v[198:201], v153 offset:35840
	ds_read_b128 v[202:205], v153 offset:36864
	ds_read_b128 v[206:209], v153 offset:37888
	ds_read_b128 v[210:213], v153 offset:38912
	ds_read_b128 v[214:217], v153 offset:39936
	global_load_lds_dwordx4 v[226:227], off
	v_lshl_add_u64 v[226:227], s[30:31], 0, v[132:133]
	s_mov_b32 m0, s38
	s_nop 0
	global_load_lds_dwordx4 v[226:227], off
	s_waitcnt vmcnt(8)
	s_waitcnt lgkmcnt(0)
	s_barrier
	v_mfma_f32_16x16x32_bf16 v[124:127], v[144:147], v[184:187], v[124:127]
	v_mfma_f32_16x16x32_bf16 v[120:123], v[160:163], v[184:187], v[120:123]
	v_mfma_f32_16x16x32_bf16 v[108:111], v[144:147], v[194:197], v[108:111]
	v_mfma_f32_16x16x32_bf16 v[104:107], v[160:163], v[194:197], v[104:107]
	v_mfma_f32_16x16x32_bf16 v[92:95], v[144:147], v[202:205], v[92:95]
	v_mfma_f32_16x16x32_bf16 v[88:91], v[160:163], v[202:205], v[88:91]
	v_mfma_f32_16x16x32_bf16 v[76:79], v[144:147], v[210:213], v[76:79]
	v_mfma_f32_16x16x32_bf16 v[72:75], v[160:163], v[210:213], v[72:75]
	v_mfma_f32_16x16x32_bf16 v[124:127], v[156:159], v[190:193], v[124:127]
	v_mfma_f32_16x16x32_bf16 v[120:123], v[164:167], v[190:193], v[120:123]
	v_mfma_f32_16x16x32_bf16 v[108:111], v[156:159], v[198:201], v[108:111]
	v_mfma_f32_16x16x32_bf16 v[104:107], v[164:167], v[198:201], v[104:107]
	v_mfma_f32_16x16x32_bf16 v[92:95], v[156:159], v[206:209], v[92:95]
	v_mfma_f32_16x16x32_bf16 v[88:91], v[164:167], v[206:209], v[88:91]
	v_mfma_f32_16x16x32_bf16 v[76:79], v[156:159], v[214:217], v[76:79]
	v_mfma_f32_16x16x32_bf16 v[72:75], v[164:167], v[214:217], v[72:75]
	v_mfma_f32_16x16x32_bf16 v[116:119], v[168:171], v[184:187], v[116:119]
	v_mfma_f32_16x16x32_bf16 v[112:115], v[176:179], v[184:187], v[112:115]
	v_mfma_f32_16x16x32_bf16 v[100:103], v[168:171], v[194:197], v[100:103]
	v_mfma_f32_16x16x32_bf16 v[96:99], v[176:179], v[194:197], v[96:99]
	v_mfma_f32_16x16x32_bf16 v[84:87], v[168:171], v[202:205], v[84:87]
	v_mfma_f32_16x16x32_bf16 v[80:83], v[176:179], v[202:205], v[80:83]
	v_mfma_f32_16x16x32_bf16 v[68:71], v[168:171], v[210:213], v[68:71]
	v_mfma_f32_16x16x32_bf16 v[64:67], v[176:179], v[210:213], v[64:67]
	v_mfma_f32_16x16x32_bf16 v[116:119], v[172:175], v[190:193], v[116:119]
	v_mfma_f32_16x16x32_bf16 v[112:115], v[180:183], v[190:193], v[112:115]
	v_mfma_f32_16x16x32_bf16 v[100:103], v[172:175], v[198:201], v[100:103]
	v_mfma_f32_16x16x32_bf16 v[96:99], v[180:183], v[198:201], v[96:99]
	v_mfma_f32_16x16x32_bf16 v[84:87], v[172:175], v[206:209], v[84:87]
	v_mfma_f32_16x16x32_bf16 v[80:83], v[180:183], v[206:209], v[80:83]
	v_mfma_f32_16x16x32_bf16 v[68:71], v[172:175], v[214:217], v[68:71]
	v_mfma_f32_16x16x32_bf16 v[64:67], v[180:183], v[214:217], v[64:67]
	s_barrier
; #define PG8_STAGE(bufoff, gbase, voff) do { _Pragma("unroll") for (int _i = 0; _i < 2; ++_i) \
;         __builtin_amdgcn_global_load_lds((const unsigned*)((const char*)(gbase) + (voff)[_i]), (PG8_LAS unsigned*)(lds + (bufoff) + ldsw + _i * 8192), 16, 0, 0); } while (0)
; #define PG8_LDA(dst, b, h) do { _Pragma("unroll") for (int m = 0; m < 4; ++m) _Pragma("unroll") for (int k = 0; k < 2; ++k) dst[m][k] = *(const PG8_LAS bf16x8*)(lds + PG8_SA(b, h) + aoff + m * 2048 + k * 1024); } while (0)
; #define PG8_MMA(ai, bj, At, Bt) do { __builtin_amdgcn_s_setprio(1); _Pragma("unroll") for (int m = 0; m < 4; ++m) _Pragma("unroll") for (int n = 0; n < 2; ++n) _Pragma("unroll") for (int k = 0; k < 2; ++k) \
;         acc[ai][bj][m][n] = __builtin_amdgcn_mfma_f32_16x16x32_bf16(Bt[n][k], At[m][k], acc[ai][bj][m][n], 0, 0, 0); __builtin_amdgcn_s_setprio(0); } while (0)
; #define PG8_WAIT_V(n) asm volatile("s_waitcnt vmcnt(" #n ")" ::: "memory")
; #define PG8_WAIT_L(n) asm volatile("s_waitcnt lgkmcnt(" #n ")" ::: "memory")
; #define PG8_BAR __builtin_amdgcn_s_barrier()
; #define PG8_SCHED __builtin_amdgcn_sched_barrier(0)
; template <class Epi, class Sched, bool ALIGN_EPI = false, bool SP2 = false>
; __device__ __forceinline__ void gemm_phase(PG8_LAS unsigned char* lds, const Gemm g, const Sched& S, const Epi& E) {
;     ...
;             PG8_LDA(At, 1, 1); PG8_STAGE(PG8_SB(1, 0), b3, voffB); PG8_STAGE(PG8_SB(1, 1), b3 + hstep, voffB); PG8_STAGE(PG8_SA(1, 0), a3, voffA);
;             PG8_WAIT_V(8); PG8_WAIT_L(0); PG8_BAR; PG8_MMA(1, 0, At, B0); PG8_MMA(1, 1, At, B1); PG8_BAR; PG8_SCHED;
;     ...
;         if constexpr (ALIGN_EPI) { if (wr == 0) PG8_BAR; }
;         if constexpr (!Epi::AFTER_DRAIN) { E(acc, cur, wr, wc, fr, fq); S.done(cur); }
;         if (!has_next) break;
	s_add_i32 s30, s51, s35
	v_lshl_add_u64 v[218:219], v[218:219], 0, s[2:3]
	s_mov_b32 m0, s30
	ds_read_b128 v[184:187], v153 offset:49152
	ds_read_b128 v[190:193], v153 offset:50176
	ds_read_b128 v[194:197], v153 offset:51200
	ds_read_b128 v[198:201], v153 offset:52224
	ds_read_b128 v[202:205], v153 offset:53248
	ds_read_b128 v[206:209], v153 offset:54272
	ds_read_b128 v[210:213], v153 offset:55296
	ds_read_b128 v[214:217], v153 offset:56320
	global_load_lds_dwordx4 v[218:219], off
	s_add_i32 m0, s30, 0x2000
	s_add_u32 s28, s28, 0x40080
	v_lshl_add_u64 v[218:219], v[220:221], 0, s[2:3]
	s_addc_u32 s29, s29, 0
	s_add_i32 s30, s52, s35
	global_load_lds_dwordx4 v[218:219], off
	v_lshl_add_u64 v[218:219], s[28:29], 0, v[130:131]
	s_mov_b32 m0, s30
	s_nop 0
	global_load_lds_dwordx4 v[218:219], off
	v_lshl_add_u64 v[218:219], s[28:29], 0, v[134:135]
	s_add_i32 m0, s30, 0x2000
	s_nop 0
	global_load_lds_dwordx4 v[218:219], off
	v_lshl_add_u64 v[218:219], v[222:223], 0, s[2:3]
	s_mov_b32 m0, s40
	s_nop 0
	global_load_lds_dwordx4 v[218:219], off
	v_lshl_add_u64 v[218:219], v[224:225], 0, s[2:3]
	s_mov_b32 m0, s41
	s_nop 0
	global_load_lds_dwordx4 v[218:219], off
	s_waitcnt vmcnt(8)
	s_waitcnt lgkmcnt(0)
	s_barrier
	v_mfma_f32_16x16x32_bf16 v[60:63], v[144:147], v[184:187], v[60:63]
	v_mfma_f32_16x16x32_bf16 v[56:59], v[160:163], v[184:187], v[56:59]
	v_mfma_f32_16x16x32_bf16 v[44:47], v[144:147], v[194:197], v[44:47]
	v_mfma_f32_16x16x32_bf16 v[40:43], v[160:163], v[194:197], v[40:43]
	v_mfma_f32_16x16x32_bf16 v[28:31], v[144:147], v[202:205], v[28:31]
	v_mfma_f32_16x16x32_bf16 v[24:27], v[160:163], v[202:205], v[24:27]
	v_mfma_f32_16x16x32_bf16 v[12:15], v[144:147], v[210:213], v[12:15]
	v_mfma_f32_16x16x32_bf16 v[8:11], v[160:163], v[210:213], v[8:11]
	v_mfma_f32_16x16x32_bf16 v[60:63], v[156:159], v[190:193], v[60:63]
	v_mfma_f32_16x16x32_bf16 v[56:59], v[164:167], v[190:193], v[56:59]
	v_mfma_f32_16x16x32_bf16 v[44:47], v[156:159], v[198:201], v[44:47]
	v_mfma_f32_16x16x32_bf16 v[40:43], v[164:167], v[198:201], v[40:43]
	v_mfma_f32_16x16x32_bf16 v[28:31], v[156:159], v[206:209], v[28:31]
	v_mfma_f32_16x16x32_bf16 v[24:27], v[164:167], v[206:209], v[24:27]
	v_mfma_f32_16x16x32_bf16 v[12:15], v[156:159], v[214:217], v[12:15]
	v_mfma_f32_16x16x32_bf16 v[8:11], v[164:167], v[214:217], v[8:11]
	v_mfma_f32_16x16x32_bf16 v[52:55], v[168:171], v[184:187], v[52:55]
	v_mfma_f32_16x16x32_bf16 v[48:51], v[176:179], v[184:187], v[48:51]
	v_mfma_f32_16x16x32_bf16 v[36:39], v[168:171], v[194:197], v[36:39]
	v_mfma_f32_16x16x32_bf16 v[32:35], v[176:179], v[194:197], v[32:35]
	v_mfma_f32_16x16x32_bf16 v[20:23], v[168:171], v[202:205], v[20:23]
	v_mfma_f32_16x16x32_bf16 v[16:19], v[176:179], v[202:205], v[16:19]
	v_mfma_f32_16x16x32_bf16 v[4:7], v[168:171], v[210:213], v[4:7]
	v_mfma_f32_16x16x32_bf16 v[0:3], v[176:179], v[210:213], v[0:3]
	v_mfma_f32_16x16x32_bf16 v[52:55], v[172:175], v[190:193], v[52:55]
	v_mfma_f32_16x16x32_bf16 v[48:51], v[180:183], v[190:193], v[48:51]
	v_mfma_f32_16x16x32_bf16 v[36:39], v[172:175], v[198:201], v[36:39]
	v_mfma_f32_16x16x32_bf16 v[32:35], v[180:183], v[198:201], v[32:35]
	v_mfma_f32_16x16x32_bf16 v[20:23], v[172:175], v[206:209], v[20:23]
	v_mfma_f32_16x16x32_bf16 v[16:19], v[180:183], v[206:209], v[16:19]
	v_mfma_f32_16x16x32_bf16 v[4:7], v[172:175], v[214:217], v[4:7]
	v_mfma_f32_16x16x32_bf16 v[0:3], v[180:183], v[214:217], v[0:3]
	s_barrier
	s_add_i32 s50, s50, 2
	s_add_u32 s26, s26, 0x100
	s_addc_u32 s27, s27, 0
	s_add_u32 s48, s48, 0x100
	s_addc_u32 s49, s49, 0
	s_cmp_gt_u32 s50, 13
	s_cbranch_scc0 .LBB0_698
	s_and_b64 vcc, exec, s[12:13]
	s_cbranch_vccz .LBB0_701
	s_barrier

; #define PG8_STAGE(bufoff, gbase, voff) do { _Pragma("unroll") for (int _i = 0; _i < 2; ++_i) \
;         __builtin_amdgcn_global_load_lds((const unsigned*)((const char*)(gbase) + (voff)[_i]), (PG8_LAS unsigned*)(lds + (bufoff) + ldsw + _i * 8192), 16, 0, 0); } while (0)
; #define PG8_WAIT_V(n) asm volatile("s_waitcnt vmcnt(" #n ")" ::: "memory")
; #define PG8_BAR __builtin_amdgcn_s_barrier()
; template <class Epi, class Sched, bool ALIGN_EPI = false, bool SP2 = false>
; __device__ __forceinline__ void gemm_phase(PG8_LAS unsigned char* lds, const Gemm g, const Sched& S, const Epi& E) {
;     ...
;     for (int i = 0; i < 2; ++i) { int R, C; stage_rc(tid * 16 + i * 8192, R, C); const int Rb = Epi::PERM ? ((R & ~31) + perm32(R & 31)) : R;
;         voffA[i] = (unsigned)(R * K + C) * 2u; voffB[i] = (unsigned)(Rb * K + C) * 2u; }
;     const size_t kstep = (size_t)(BK * 2);
;     const size_t hstep = (size_t)HALF * K * 2;
;     const size_t tstep = 2 * hstep;
;     const unsigned ldsw = (unsigned)wid * 1024u;
;     const int aoff = lds_byte(wr * 64 + fr, fq * 8), boff = lds_byte(wc * 32 + fr, fq * 8);
;     ...
;         PG8_STAGE(PG8_SB(0, 0), cB, voffB); PG8_STAGE(PG8_SB(0, 1), cB + hstep, voffB); PG8_STAGE(PG8_SA(0, 0), cA, voffA); PG8_STAGE(PG8_SA(0, 1), cA + hstep, voffA);
;         if (wr == 1) PG8_BAR;
;         PG8_WAIT_V(2); PG8_BAR;
;         PG8_STAGE(PG8_SB(1, 0), cB + kstep, voffB); PG8_STAGE(PG8_SA(1, 0), cA + kstep, voffA); PG8_STAGE(PG8_SB(1, 1), cB + hstep + kstep, voffB);
;         PG8_WAIT_V(6); PG8_BAR;
.LBB0_776:
	s_lshl_b32 s1, s6, 5
	s_mov_b64 s[6:7], 0x80
	s_and_b32 s16, s1, 0x60
	s_add_i32 m0, s34, 0x18000
	v_lshl_add_u64 v[6:7], v[6:7], 0, s[6:7]
	s_lshl_b32 s13, s12, 13
	s_lshl_b32 s17, s16, 7
	s_waitcnt vmcnt(2)
	s_barrier
	global_load_lds_dwordx4 v[6:7], off
	v_lshl_add_u64 v[4:5], v[4:5], 0, s[6:7]
	s_add_i32 m0, s34, 0x1a000
	s_add_i32 s39, s34, 0x8000
	s_add_i32 s40, s34, 0xa000
	global_load_lds_dwordx4 v[4:5], off
	v_lshl_add_u64 v[0:1], v[0:1], 0, s[6:7]
	s_mov_b32 m0, s39
	s_add_u32 s14, s24, 0x40080
	global_load_lds_dwordx4 v[0:1], off
	v_lshl_add_u64 v[0:1], v[2:3], 0, s[6:7]
	s_mov_b32 m0, s40
	s_addc_u32 s15, s25, 0
	global_load_lds_dwordx4 v[0:1], off
	s_add_i32 m0, s34, 0x1c000
	v_lshl_add_u64 v[0:1], s[14:15], 0, v[132:133]
	global_load_lds_dwordx4 v[0:1], off
	v_lshl_add_u64 v[0:1], s[14:15], 0, v[128:129]
	s_add_i32 m0, s34, 0x1e000
	s_cmpk_lt_u32 s5, 0x100
	global_load_lds_dwordx4 v[0:1], off
	v_lshrrev_b32_e32 v1, 1, v9
	v_and_b32_e32 v1, 24, v1
	v_and_b32_e32 v0, 15, v9
	v_lshlrev_b32_e32 v2, 1, v1
	v_lshl_or_b32 v148, s12, 6, v0
	v_lshl_or_b32 v0, v0, 6, v2
	v_lshlrev_b32_e32 v2, 2, v9
	v_and_b32_e32 v2, 32, v2
	v_bitop3_b32 v3, v0, s13, v2 bitop3:0xde
	v_bitop3_b32 v149, v0, s17, v2 bitop3:0xde
	v_lshlrev_b32_e32 v0, 14, v13
	v_and_b32_e32 v0, 0xffff8000, v0
	v_or_b32_e32 v150, s16, v1
	v_lshl_add_u32 v0, v12, 11, v0
	v_and_b32_e32 v1, 1, v13
	v_lshl_or_b32 v0, v1, 6, v0
	v_lshl_add_u32 v136, v14, 1, v0
	v_lshlrev_b32_e32 v0, 14, v8
	v_and_b32_e32 v0, 0xffff8000, v0
	s_waitcnt vmcnt(0)
	v_lshl_add_u32 v0, v10, 11, v0
	v_and_b32_e32 v1, 1, v8
	s_sext_i32_i8 s1, s4
	s_cselect_b64 s[12:13], -1, 0
	v_readlane_b32 s4, v235, 6
	v_lshl_or_b32 v0, v1, 6, v0
	s_add_i32 s43, 0, 0x10000
	s_add_i32 s44, 0, 0x14000
	s_ashr_i32 s41, s4, 31
	s_mov_b32 s42, s4
	v_mov_b32_e32 v137, v133
	v_lshl_add_u32 v138, v11, 1, v0
	v_mov_b32_e32 v139, v133
	v_mov_b64_e32 v[140:141], 0xb00
	v_mov_b64_e32 v[142:143], 0xaff
	v_add_u32_e32 v151, s43, v149
	v_add_u32_e32 v152, s44, v149
	v_add_u32_e32 v153, 0, v3
	v_mov_b32_e32 v154, 0x358637bd
	s_mov_b32 s45, 0x800000
	s_movk_i32 s46, 0x1600
	s_barrier
	v_readlane_b32 s5, v235, 7
	v_readfirstlane_b32 s99, v189
	s_nop 0
	s_lshr_b32 s99, s99, 6
	s_cmp_ge_u32 s99, 4
	s_cbranch_scc0 .Lprio_779
	s_setprio 1
.Lprio_779:
	s_branch .LBB0_779
.LBB0_777:
	s_mov_b64 s[0:1], 0

; #define PG8_STAGE(bufoff, gbase, voff) do { _Pragma("unroll") for (int _i = 0; _i < 2; ++_i) \
;         __builtin_amdgcn_global_load_lds((const unsigned*)((const char*)(gbase) + (voff)[_i]), (PG8_LAS unsigned*)(lds + (bufoff) + ldsw + _i * 8192), 16, 0, 0); } while (0)
; #define PG8_LDA(dst, b, h) do { _Pragma("unroll") for (int m = 0; m < 4; ++m) _Pragma("unroll") for (int k = 0; k < 2; ++k) dst[m][k] = *(const PG8_LAS bf16x8*)(lds + PG8_SA(b, h) + aoff + m * 2048 + k * 1024); } while (0)
; #define PG8_LDB(dst, b, h) do { _Pragma("unroll") for (int n = 0; n < 2; ++n) _Pragma("unroll") for (int k = 0; k < 2; ++k) dst[n][k] = *(const PG8_LAS bf16x8*)(lds + PG8_SB(b, h) + boff + n * 2048 + k * 1024); } while (0)
; #define PG8_WAIT_V(n) asm volatile("s_waitcnt vmcnt(" #n ")" ::: "memory")
; #define PG8_WAIT_L(n) asm volatile("s_waitcnt lgkmcnt(" #n ")" ::: "memory")
; #define PG8_BAR __builtin_amdgcn_s_barrier()
; #define PG8_SCHED __builtin_amdgcn_sched_barrier(0)
; template <class Epi, class Sched, bool ALIGN_EPI = false, bool SP2 = false>
; __device__ __forceinline__ void gemm_phase(PG8_LAS unsigned char* lds, const Gemm g, const Sched& S, const Epi& E) {
;     ...
;         const bool has_next = S.next(ui + 1, nxt);
;         const char* nA = has_next ? (const char*)g.A + (size_t)nxt.pm * tstep : cA; const char* nB = has_next ? (const char*)g.Bt + (size_t)nxt.pn * tstep : cB;
;         for (int t = 0; t < nt; t += 2) {
;             const bool last = (t == nt - 2);
;             const char* a1 = cA + (size_t)(t + 1) * kstep;
;             const char* a2 = last ? nA : cA + (size_t)(t + 2) * kstep; const char* b2 = last ? nB : cB + (size_t)(t + 2) * kstep;
;             const char* a3 = a2 + kstep; const char* b3 = b2 + kstep;
;             if (last && has_next) S.a_ready(nxt);
;             if constexpr (SP2) {
;             PG8_LDB(B0, 0, 0); PG8_LDB(B1, 0, 1); PG8_SCHED; PG8_LDA(At, 0, 0); PG8_STAGE(PG8_SA(1, 1), a1 + hstep, voffA);
;             PG8_WAIT_V(8); PG8_WAIT_L(0); PG8_BAR; PG8_MMA(0, 0, At, B0); PG8_MMA(0, 1, At, B1); PG8_BAR; PG8_SCHED;
;             PG8_LDA(At, 0, 1); PG8_STAGE(PG8_SB(0, 0), b2, voffB); PG8_STAGE(PG8_SB(0, 1), b2 + hstep, voffB); PG8_STAGE(PG8_SA(0, 0), a2, voffA);
;             PG8_WAIT_V(8); PG8_WAIT_L(0); PG8_BAR; PG8_MMA(1, 0, At, B0); PG8_MMA(1, 1, At, B1); PG8_BAR; PG8_SCHED;
.LBB0_781:
	s_ashr_i32 s17, s16, 31
	s_lshl_b64 s[18:19], s[16:17], 19
	s_add_u32 s18, s8, s18
	s_addc_u32 s19, s9, s19
	s_and_b64 s[20:21], s[4:5], exec
	s_cselect_b32 s17, s19, s23
	s_cselect_b32 s47, s18, s22
	s_ashr_i32 s15, s14, 31
	s_lshl_b64 s[20:21], s[14:15], 19
	s_add_u32 s20, s28, s20
	s_addc_u32 s21, s29, s21
	s_and_b64 s[26:27], s[4:5], exec
	s_cselect_b32 s15, s21, s25
	s_cselect_b32 s48, s20, s24
	s_add_u32 s22, s22, 0x40080
	s_addc_u32 s23, s23, 0
	s_add_u32 s49, s24, 0x100
	s_addc_u32 s50, s25, 0
	s_mov_b32 s51, -2
	ds_read_b128 v[144:147], v151
	ds_read_b128 v[156:159], v151 offset:1024
	ds_read_b128 v[160:163], v151 offset:2048
	ds_read_b128 v[164:167], v151 offset:3072
	ds_read_b128 v[168:171], v152
	ds_read_b128 v[172:175], v152 offset:1024
	ds_read_b128 v[176:179], v152 offset:2048
	ds_read_b128 v[180:183], v152 offset:3072
	s_add_u32 s24, s22, 0xfffc0080
	s_addc_u32 s25, s23, -1
	s_cmp_eq_u32 s51, 12
	s_cselect_b32 s27, s17, s25
	s_cselect_b32 s26, s47, s24
	s_cselect_b32 s25, s15, s50
	s_cselect_b32 s24, s48, s49
	v_lshl_add_u64 v[218:219], s[22:23], 0, v[136:137]
	s_add_i32 m0, s34, 0xc000
	ds_read_b128 v[184:187], v153
	ds_read_b128 v[190:193], v153 offset:1024
	ds_read_b128 v[194:197], v153 offset:2048
	ds_read_b128 v[198:201], v153 offset:3072
	ds_read_b128 v[202:205], v153 offset:4096
	ds_read_b128 v[206:209], v153 offset:5120
	ds_read_b128 v[210:213], v153 offset:6144
	ds_read_b128 v[214:217], v153 offset:7168
	global_load_lds_dwordx4 v[218:219], off
	v_lshl_add_u64 v[218:219], s[22:23], 0, v[138:139]
	s_add_i32 m0, s34, 0xe000
	s_nop 0
	global_load_lds_dwordx4 v[218:219], off
	s_waitcnt vmcnt(16)
	s_waitcnt lgkmcnt(0)
	s_barrier
	v_mfma_f32_16x16x32_bf16 v[116:119], v[144:147], v[184:187], 0
	v_mfma_f32_16x16x32_bf16 v[112:115], v[160:163], v[184:187], 0
	v_mfma_f32_16x16x32_bf16 v[100:103], v[144:147], v[194:197], 0
	v_mfma_f32_16x16x32_bf16 v[96:99], v[160:163], v[194:197], 0
	v_mfma_f32_16x16x32_bf16 v[84:87], v[144:147], v[202:205], 0
	v_mfma_f32_16x16x32_bf16 v[80:83], v[160:163], v[202:205], 0
	v_mfma_f32_16x16x32_bf16 v[72:75], v[144:147], v[210:213], 0
	v_mfma_f32_16x16x32_bf16 v[64:67], v[160:163], v[210:213], 0
	v_mfma_f32_16x16x32_bf16 v[116:119], v[156:159], v[190:193], v[116:119]
	v_mfma_f32_16x16x32_bf16 v[112:115], v[164:167], v[190:193], v[112:115]
	v_mfma_f32_16x16x32_bf16 v[100:103], v[156:159], v[198:201], v[100:103]
	v_mfma_f32_16x16x32_bf16 v[96:99], v[164:167], v[198:201], v[96:99]
	v_mfma_f32_16x16x32_bf16 v[84:87], v[156:159], v[206:209], v[84:87]
	v_mfma_f32_16x16x32_bf16 v[80:83], v[164:167], v[206:209], v[80:83]
	v_mfma_f32_16x16x32_bf16 v[72:75], v[156:159], v[214:217], v[72:75]
	v_mfma_f32_16x16x32_bf16 v[64:67], v[164:167], v[214:217], v[64:67]
	v_mfma_f32_16x16x32_bf16 v[124:127], v[168:171], v[184:187], 0
	v_mfma_f32_16x16x32_bf16 v[120:123], v[176:179], v[184:187], 0
	v_mfma_f32_16x16x32_bf16 v[108:111], v[168:171], v[194:197], 0
	v_mfma_f32_16x16x32_bf16 v[104:107], v[176:179], v[194:197], 0
	v_mfma_f32_16x16x32_bf16 v[92:95], v[168:171], v[202:205], 0
	v_mfma_f32_16x16x32_bf16 v[88:91], v[176:179], v[202:205], 0
	v_mfma_f32_16x16x32_bf16 v[76:79], v[168:171], v[210:213], 0
	v_mfma_f32_16x16x32_bf16 v[68:71], v[176:179], v[210:213], 0
	v_mfma_f32_16x16x32_bf16 v[124:127], v[172:175], v[190:193], v[124:127]
	v_mfma_f32_16x16x32_bf16 v[120:123], v[180:183], v[190:193], v[120:123]
	v_mfma_f32_16x16x32_bf16 v[108:111], v[172:175], v[198:201], v[108:111]
	v_mfma_f32_16x16x32_bf16 v[104:107], v[180:183], v[198:201], v[104:107]
	v_mfma_f32_16x16x32_bf16 v[92:95], v[172:175], v[206:209], v[92:95]
	v_mfma_f32_16x16x32_bf16 v[88:91], v[180:183], v[206:209], v[88:91]
	v_mfma_f32_16x16x32_bf16 v[76:79], v[172:175], v[214:217], v[76:79]
	v_mfma_f32_16x16x32_bf16 v[68:71], v[180:183], v[214:217], v[68:71]
	s_barrier
	s_add_i32 s52, s43, s30
	v_lshl_add_u64 v[218:219], s[24:25], 0, v[132:133]
	s_mov_b32 m0, s52
	ds_read_b128 v[184:187], v153 offset:16384
	ds_read_b128 v[190:193], v153 offset:17408
	ds_read_b128 v[194:197], v153 offset:18432
	ds_read_b128 v[198:201], v153 offset:19456
	ds_read_b128 v[202:205], v153 offset:20480
	ds_read_b128 v[206:209], v153 offset:21504
	ds_read_b128 v[210:213], v153 offset:22528
	ds_read_b128 v[214:217], v153 offset:23552
	global_load_lds_dwordx4 v[218:219], off
	s_add_i32 m0, s52, 0x2000
	s_add_u32 s52, s24, 0x40000
	v_lshl_add_u64 v[220:221], s[24:25], 0, v[128:129]
	s_addc_u32 s53, s25, 0
	s_add_i32 s54, s44, s30
	global_load_lds_dwordx4 v[220:221], off
	v_lshl_add_u64 v[222:223], s[52:53], 0, v[132:133]
	s_mov_b32 m0, s54
	v_lshl_add_u64 v[224:225], s[26:27], 0, v[130:131]
	global_load_lds_dwordx4 v[222:223], off
	v_lshl_add_u64 v[222:223], s[52:53], 0, v[128:129]
	s_add_i32 m0, s54, 0x2000
	s_nop 0
	global_load_lds_dwordx4 v[222:223], off
	v_lshl_add_u64 v[222:223], s[26:27], 0, v[134:135]
	s_mov_b32 m0, s34
	s_nop 0
	global_load_lds_dwordx4 v[222:223], off
	s_mov_b32 m0, s35
	s_nop 0
	global_load_lds_dwordx4 v[224:225], off
	s_waitcnt vmcnt(16)
	s_waitcnt lgkmcnt(0)
	s_barrier
; #define PG8_STAGE(bufoff, gbase, voff) do { _Pragma("unroll") for (int _i = 0; _i < 2; ++_i) \
;         __builtin_amdgcn_global_load_lds((const unsigned*)((const char*)(gbase) + (voff)[_i]), (PG8_LAS unsigned*)(lds + (bufoff) + ldsw + _i * 8192), 16, 0, 0); } while (0)
; #define PG8_LDA(dst, b, h) do { _Pragma("unroll") for (int m = 0; m < 4; ++m) _Pragma("unroll") for (int k = 0; k < 2; ++k) dst[m][k] = *(const PG8_LAS bf16x8*)(lds + PG8_SA(b, h) + aoff + m * 2048 + k * 1024); } while (0)
; #define PG8_LDB(dst, b, h) do { _Pragma("unroll") for (int n = 0; n < 2; ++n) _Pragma("unroll") for (int k = 0; k < 2; ++k) dst[n][k] = *(const PG8_LAS bf16x8*)(lds + PG8_SB(b, h) + boff + n * 2048 + k * 1024); } while (0)
; #define PG8_MMA(ai, bj, At, Bt) do { __builtin_amdgcn_s_setprio(1); _Pragma("unroll") for (int m = 0; m < 4; ++m) _Pragma("unroll") for (int n = 0; n < 2; ++n) _Pragma("unroll") for (int k = 0; k < 2; ++k) \
;         acc[ai][bj][m][n] = __builtin_amdgcn_mfma_f32_16x16x32_bf16(Bt[n][k], At[m][k], acc[ai][bj][m][n], 0, 0, 0); __builtin_amdgcn_s_setprio(0); } while (0)
; #define PG8_WAIT_V(n) asm volatile("s_waitcnt vmcnt(" #n ")" ::: "memory")
; template <class Epi, class Sched, bool ALIGN_EPI = false, bool SP2 = false>
; __device__ __forceinline__ void gemm_phase(PG8_LAS unsigned char* lds, const Gemm g, const Sched& S, const Epi& E) {
;     ...
;             PG8_LDB(B0, 0, 0); PG8_LDB(B1, 0, 1); PG8_SCHED; PG8_LDA(At, 0, 0); PG8_STAGE(PG8_SA(1, 1), a1 + hstep, voffA);
;             PG8_WAIT_V(8); PG8_WAIT_L(0); PG8_BAR; PG8_MMA(0, 0, At, B0); PG8_MMA(0, 1, At, B1); PG8_BAR; PG8_SCHED;
;             PG8_LDA(At, 0, 1); PG8_STAGE(PG8_SB(0, 0), b2, voffB); PG8_STAGE(PG8_SB(0, 1), b2 + hstep, voffB); PG8_STAGE(PG8_SA(0, 0), a2, voffA);
;             PG8_WAIT_V(8); PG8_WAIT_L(0); PG8_BAR; PG8_MMA(1, 0, At, B0); PG8_MMA(1, 1, At, B1); PG8_BAR; PG8_SCHED;
;             PG8_LDB(B0, 1, 0); PG8_LDB(B1, 1, 1); PG8_SCHED; PG8_LDA(At, 1, 0); PG8_STAGE(PG8_SA(0, 1), a2 + hstep, voffA);
;             PG8_WAIT_V(8); PG8_WAIT_L(0); PG8_BAR; PG8_MMA(0, 0, At, B0); PG8_MMA(0, 1, At, B1); PG8_BAR; PG8_SCHED;
;             PG8_LDA(At, 1, 1); PG8_STAGE(PG8_SB(1, 0), b3, voffB); PG8_STAGE(PG8_SB(1, 1), b3 + hstep, voffB); PG8_STAGE(PG8_SA(1, 0), a3, voffA);
;             PG8_WAIT_V(8); PG8_WAIT_L(0); PG8_BAR; PG8_MMA(1, 0, At, B0); PG8_MMA(1, 1, At, B1); PG8_BAR; PG8_SCHED;
	v_mfma_f32_16x16x32_bf16 v[56:59], v[144:147], v[184:187], 0
	v_mfma_f32_16x16x32_bf16 v[48:51], v[160:163], v[184:187], 0
	v_mfma_f32_16x16x32_bf16 v[40:43], v[144:147], v[194:197], 0
	v_mfma_f32_16x16x32_bf16 v[32:35], v[160:163], v[194:197], 0
	v_mfma_f32_16x16x32_bf16 v[24:27], v[144:147], v[202:205], 0
	v_mfma_f32_16x16x32_bf16 v[16:19], v[160:163], v[202:205], 0
	v_mfma_f32_16x16x32_bf16 v[8:11], v[144:147], v[210:213], 0
	v_mfma_f32_16x16x32_bf16 v[0:3], v[160:163], v[210:213], 0
	v_mfma_f32_16x16x32_bf16 v[56:59], v[156:159], v[190:193], v[56:59]
	v_mfma_f32_16x16x32_bf16 v[48:51], v[164:167], v[190:193], v[48:51]
	v_mfma_f32_16x16x32_bf16 v[40:43], v[156:159], v[198:201], v[40:43]
	v_mfma_f32_16x16x32_bf16 v[32:35], v[164:167], v[198:201], v[32:35]
	v_mfma_f32_16x16x32_bf16 v[24:27], v[156:159], v[206:209], v[24:27]
	v_mfma_f32_16x16x32_bf16 v[16:19], v[164:167], v[206:209], v[16:19]
	v_mfma_f32_16x16x32_bf16 v[8:11], v[156:159], v[214:217], v[8:11]
	v_mfma_f32_16x16x32_bf16 v[0:3], v[164:167], v[214:217], v[0:3]
	v_mfma_f32_16x16x32_bf16 v[60:63], v[168:171], v[184:187], 0
	v_mfma_f32_16x16x32_bf16 v[52:55], v[176:179], v[184:187], 0
	v_mfma_f32_16x16x32_bf16 v[44:47], v[168:171], v[194:197], 0
	v_mfma_f32_16x16x32_bf16 v[36:39], v[176:179], v[194:197], 0
	v_mfma_f32_16x16x32_bf16 v[28:31], v[168:171], v[202:205], 0
	v_mfma_f32_16x16x32_bf16 v[20:23], v[176:179], v[202:205], 0
	v_mfma_f32_16x16x32_bf16 v[12:15], v[168:171], v[210:213], 0
	v_mfma_f32_16x16x32_bf16 v[4:7], v[176:179], v[210:213], 0
	v_mfma_f32_16x16x32_bf16 v[60:63], v[172:175], v[190:193], v[60:63]
	v_mfma_f32_16x16x32_bf16 v[52:55], v[180:183], v[190:193], v[52:55]
	v_mfma_f32_16x16x32_bf16 v[44:47], v[172:175], v[198:201], v[44:47]
	v_mfma_f32_16x16x32_bf16 v[36:39], v[180:183], v[198:201], v[36:39]
	v_mfma_f32_16x16x32_bf16 v[28:31], v[172:175], v[206:209], v[28:31]
	v_mfma_f32_16x16x32_bf16 v[20:23], v[180:183], v[206:209], v[20:23]
	v_mfma_f32_16x16x32_bf16 v[12:15], v[172:175], v[214:217], v[12:15]
	v_mfma_f32_16x16x32_bf16 v[4:7], v[180:183], v[214:217], v[4:7]
	s_barrier
	s_add_i32 s52, 0, 0x18000
	v_add_u32_e32 v155, s52, v149
	s_add_i32 s53, 0, 0x1c000
	ds_read_b128 v[144:147], v155
	ds_read_b128 v[156:159], v155 offset:1024
	ds_read_b128 v[160:163], v155 offset:2048
	ds_read_b128 v[164:167], v155 offset:3072
	v_add_u32_e32 v155, s53, v149
	ds_read_b128 v[168:171], v155
	ds_read_b128 v[172:175], v155 offset:1024
	ds_read_b128 v[176:179], v155 offset:2048
	ds_read_b128 v[180:183], v155 offset:3072
	s_add_u32 s26, s26, 0x40000
	s_addc_u32 s27, s27, 0
	s_mov_b32 m0, s36
	v_lshl_add_u64 v[226:227], s[26:27], 0, v[134:135]
	ds_read_b128 v[184:187], v153 offset:32768
	ds_read_b128 v[190:193], v153 offset:33792
	ds_read_b128 v[194:197], v153 offset:34816
	ds_read_b128 v[198:201], v153 offset:35840
	ds_read_b128 v[202:205], v153 offset:36864
	ds_read_b128 v[206:209], v153 offset:37888
	ds_read_b128 v[210:213], v153 offset:38912
	ds_read_b128 v[214:217], v153 offset:39936
	global_load_lds_dwordx4 v[226:227], off
	v_lshl_add_u64 v[226:227], s[26:27], 0, v[130:131]
	s_mov_b32 m0, s37
	s_nop 0
	global_load_lds_dwordx4 v[226:227], off
	s_waitcnt vmcnt(8)
	s_waitcnt lgkmcnt(0)
	s_barrier
	v_mfma_f32_16x16x32_bf16 v[116:119], v[144:147], v[184:187], v[116:119]
	v_mfma_f32_16x16x32_bf16 v[112:115], v[160:163], v[184:187], v[112:115]
	v_mfma_f32_16x16x32_bf16 v[100:103], v[144:147], v[194:197], v[100:103]
	v_mfma_f32_16x16x32_bf16 v[96:99], v[160:163], v[194:197], v[96:99]
	v_mfma_f32_16x16x32_bf16 v[84:87], v[144:147], v[202:205], v[84:87]
	v_mfma_f32_16x16x32_bf16 v[80:83], v[160:163], v[202:205], v[80:83]
	v_mfma_f32_16x16x32_bf16 v[72:75], v[144:147], v[210:213], v[72:75]
	v_mfma_f32_16x16x32_bf16 v[64:67], v[160:163], v[210:213], v[64:67]
	v_mfma_f32_16x16x32_bf16 v[116:119], v[156:159], v[190:193], v[116:119]
	v_mfma_f32_16x16x32_bf16 v[112:115], v[164:167], v[190:193], v[112:115]
	v_mfma_f32_16x16x32_bf16 v[100:103], v[156:159], v[198:201], v[100:103]
	v_mfma_f32_16x16x32_bf16 v[96:99], v[164:167], v[198:201], v[96:99]
	v_mfma_f32_16x16x32_bf16 v[84:87], v[156:159], v[206:209], v[84:87]
	v_mfma_f32_16x16x32_bf16 v[80:83], v[164:167], v[206:209], v[80:83]
	v_mfma_f32_16x16x32_bf16 v[72:75], v[156:159], v[214:217], v[72:75]
	v_mfma_f32_16x16x32_bf16 v[64:67], v[164:167], v[214:217], v[64:67]
	v_mfma_f32_16x16x32_bf16 v[124:127], v[168:171], v[184:187], v[124:127]
	v_mfma_f32_16x16x32_bf16 v[120:123], v[176:179], v[184:187], v[120:123]
	v_mfma_f32_16x16x32_bf16 v[108:111], v[168:171], v[194:197], v[108:111]
	v_mfma_f32_16x16x32_bf16 v[104:107], v[176:179], v[194:197], v[104:107]
	v_mfma_f32_16x16x32_bf16 v[92:95], v[168:171], v[202:205], v[92:95]
	v_mfma_f32_16x16x32_bf16 v[88:91], v[176:179], v[202:205], v[88:91]
	v_mfma_f32_16x16x32_bf16 v[76:79], v[168:171], v[210:213], v[76:79]
	v_mfma_f32_16x16x32_bf16 v[68:71], v[176:179], v[210:213], v[68:71]
	v_mfma_f32_16x16x32_bf16 v[124:127], v[172:175], v[190:193], v[124:127]
	v_mfma_f32_16x16x32_bf16 v[120:123], v[180:183], v[190:193], v[120:123]
	v_mfma_f32_16x16x32_bf16 v[108:111], v[172:175], v[198:201], v[108:111]
	v_mfma_f32_16x16x32_bf16 v[104:107], v[180:183], v[198:201], v[104:107]
	v_mfma_f32_16x16x32_bf16 v[92:95], v[172:175], v[206:209], v[92:95]
	v_mfma_f32_16x16x32_bf16 v[88:91], v[180:183], v[206:209], v[88:91]
	v_mfma_f32_16x16x32_bf16 v[76:79], v[172:175], v[214:217], v[76:79]
	v_mfma_f32_16x16x32_bf16 v[68:71], v[180:183], v[214:217], v[68:71]
	s_barrier
; #define PG8_STAGE(bufoff, gbase, voff) do { _Pragma("unroll") for (int _i = 0; _i < 2; ++_i) \
;         __builtin_amdgcn_global_load_lds((const unsigned*)((const char*)(gbase) + (voff)[_i]), (PG8_LAS unsigned*)(lds + (bufoff) + ldsw + _i * 8192), 16, 0, 0); } while (0)
; #define PG8_LDA(dst, b, h) do { _Pragma("unroll") for (int m = 0; m < 4; ++m) _Pragma("unroll") for (int k = 0; k < 2; ++k) dst[m][k] = *(const PG8_LAS bf16x8*)(lds + PG8_SA(b, h) + aoff + m * 2048 + k * 1024); } while (0)
; #define PG8_LDB(dst, b, h) do { _Pragma("unroll") for (int n = 0; n < 2; ++n) _Pragma("unroll") for (int k = 0; k < 2; ++k) dst[n][k] = *(const PG8_LAS bf16x8*)(lds + PG8_SB(b, h) + boff + n * 2048 + k * 1024); } while (0)
; template <class Epi, class Sched, bool ALIGN_EPI = false, bool SP2 = false>
; __device__ __forceinline__ void gemm_phase(PG8_LAS unsigned char* lds, const Gemm g, const Sched& S, const Epi& E) {
;     ...
;         for (int t = 0; t < nt; t += 2) {
;             const bool last = (t == nt - 2);
;             const char* a1 = cA + (size_t)(t + 1) * kstep;
;             const char* a2 = last ? nA : cA + (size_t)(t + 2) * kstep; const char* b2 = last ? nB : cB + (size_t)(t + 2) * kstep;
;             const char* a3 = a2 + kstep; const char* b3 = b2 + kstep;
;             if (last && has_next) S.a_ready(nxt);
;             if constexpr (SP2) {
;             PG8_LDB(B0, 0, 0); PG8_LDB(B1, 0, 1); PG8_SCHED; PG8_LDA(At, 0, 0); PG8_STAGE(PG8_SA(1, 1), a1 + hstep, voffA);
;             PG8_WAIT_V(8); PG8_WAIT_L(0); PG8_BAR; PG8_MMA(0, 0, At, B0); PG8_MMA(0, 1, At, B1); PG8_BAR; PG8_SCHED;
;             PG8_LDA(At, 0, 1); PG8_STAGE(PG8_SB(0, 0), b2, voffB); PG8_STAGE(PG8_SB(0, 1), b2 + hstep, voffB); PG8_STAGE(PG8_SA(0, 0), a2, voffA);
;             PG8_WAIT_V(8); PG8_WAIT_L(0); PG8_BAR; PG8_MMA(1, 0, At, B0); PG8_MMA(1, 1, At, B1); PG8_BAR; PG8_SCHED;
;             PG8_LDB(B0, 1, 0); PG8_LDB(B1, 1, 1); PG8_SCHED; PG8_LDA(At, 1, 0); PG8_STAGE(PG8_SA(0, 1), a2 + hstep, voffA);
;             PG8_WAIT_V(8); PG8_WAIT_L(0); PG8_BAR; PG8_MMA(0, 0, At, B0); PG8_MMA(0, 1, At, B1); PG8_BAR; PG8_SCHED;
;             PG8_LDA(At, 1, 1); PG8_STAGE(PG8_SB(1, 0), b3, voffB); PG8_STAGE(PG8_SB(1, 1), b3 + hstep, voffB); PG8_STAGE(PG8_SA(1, 0), a3, voffA);
;             PG8_WAIT_V(8); PG8_WAIT_L(0); PG8_BAR; PG8_MMA(1, 0, At, B0); PG8_MMA(1, 1, At, B1); PG8_BAR; PG8_SCHED;
	s_add_i32 s26, s52, s30
	v_lshl_add_u64 v[218:219], v[218:219], 0, s[6:7]
	s_mov_b32 m0, s26
	ds_read_b128 v[184:187], v153 offset:49152
	ds_read_b128 v[190:193], v153 offset:50176
	ds_read_b128 v[194:197], v153 offset:51200
	ds_read_b128 v[198:201], v153 offset:52224
	ds_read_b128 v[202:205], v153 offset:53248
	ds_read_b128 v[206:209], v153 offset:54272
	ds_read_b128 v[210:213], v153 offset:55296
	ds_read_b128 v[214:217], v153 offset:56320
	global_load_lds_dwordx4 v[218:219], off
	s_add_i32 m0, s26, 0x2000
	s_add_u32 s24, s24, 0x40080
	v_lshl_add_u64 v[218:219], v[220:221], 0, s[6:7]
	s_addc_u32 s25, s25, 0
	s_add_i32 s26, s53, s30
	global_load_lds_dwordx4 v[218:219], off
	v_lshl_add_u64 v[218:219], s[24:25], 0, v[132:133]
	s_mov_b32 m0, s26
	s_nop 0
	global_load_lds_dwordx4 v[218:219], off
	v_lshl_add_u64 v[218:219], s[24:25], 0, v[128:129]
	s_add_i32 m0, s26, 0x2000
	s_nop 0
	global_load_lds_dwordx4 v[218:219], off
	v_lshl_add_u64 v[218:219], v[222:223], 0, s[6:7]
	s_mov_b32 m0, s39
	s_nop 0
	global_load_lds_dwordx4 v[218:219], off
	v_lshl_add_u64 v[218:219], v[224:225], 0, s[6:7]
	s_mov_b32 m0, s40
	s_nop 0
	global_load_lds_dwordx4 v[218:219], off
	s_waitcnt vmcnt(8)
	s_waitcnt lgkmcnt(0)
	s_barrier
	v_mfma_f32_16x16x32_bf16 v[56:59], v[144:147], v[184:187], v[56:59]
	v_mfma_f32_16x16x32_bf16 v[48:51], v[160:163], v[184:187], v[48:51]
	v_mfma_f32_16x16x32_bf16 v[40:43], v[144:147], v[194:197], v[40:43]
	v_mfma_f32_16x16x32_bf16 v[32:35], v[160:163], v[194:197], v[32:35]
	v_mfma_f32_16x16x32_bf16 v[24:27], v[144:147], v[202:205], v[24:27]
	v_mfma_f32_16x16x32_bf16 v[16:19], v[160:163], v[202:205], v[16:19]
	v_mfma_f32_16x16x32_bf16 v[8:11], v[144:147], v[210:213], v[8:11]
	v_mfma_f32_16x16x32_bf16 v[0:3], v[160:163], v[210:213], v[0:3]
	v_mfma_f32_16x16x32_bf16 v[56:59], v[156:159], v[190:193], v[56:59]
	v_mfma_f32_16x16x32_bf16 v[48:51], v[164:167], v[190:193], v[48:51]
	v_mfma_f32_16x16x32_bf16 v[40:43], v[156:159], v[198:201], v[40:43]
	v_mfma_f32_16x16x32_bf16 v[32:35], v[164:167], v[198:201], v[32:35]
	v_mfma_f32_16x16x32_bf16 v[24:27], v[156:159], v[206:209], v[24:27]
	v_mfma_f32_16x16x32_bf16 v[16:19], v[164:167], v[206:209], v[16:19]
	v_mfma_f32_16x16x32_bf16 v[8:11], v[156:159], v[214:217], v[8:11]
	v_mfma_f32_16x16x32_bf16 v[0:3], v[164:167], v[214:217], v[0:3]
	v_mfma_f32_16x16x32_bf16 v[60:63], v[168:171], v[184:187], v[60:63]
	v_mfma_f32_16x16x32_bf16 v[52:55], v[176:179], v[184:187], v[52:55]
	v_mfma_f32_16x16x32_bf16 v[44:47], v[168:171], v[194:197], v[44:47]
	v_mfma_f32_16x16x32_bf16 v[36:39], v[176:179], v[194:197], v[36:39]
	v_mfma_f32_16x16x32_bf16 v[28:31], v[168:171], v[202:205], v[28:31]
	v_mfma_f32_16x16x32_bf16 v[20:23], v[176:179], v[202:205], v[20:23]
	v_mfma_f32_16x16x32_bf16 v[12:15], v[168:171], v[210:213], v[12:15]
	v_mfma_f32_16x16x32_bf16 v[4:7], v[176:179], v[210:213], v[4:7]
	v_mfma_f32_16x16x32_bf16 v[60:63], v[172:175], v[190:193], v[60:63]
	v_mfma_f32_16x16x32_bf16 v[52:55], v[180:183], v[190:193], v[52:55]
	v_mfma_f32_16x16x32_bf16 v[44:47], v[172:175], v[198:201], v[44:47]
	v_mfma_f32_16x16x32_bf16 v[36:39], v[180:183], v[198:201], v[36:39]
	v_mfma_f32_16x16x32_bf16 v[28:31], v[172:175], v[206:209], v[28:31]
	v_mfma_f32_16x16x32_bf16 v[20:23], v[180:183], v[206:209], v[20:23]
	v_mfma_f32_16x16x32_bf16 v[12:15], v[172:175], v[214:217], v[12:15]
	v_mfma_f32_16x16x32_bf16 v[4:7], v[180:183], v[214:217], v[4:7]
	s_barrier
	s_add_i32 s51, s51, 2
	s_add_u32 s22, s22, 0x100
	s_addc_u32 s23, s23, 0
	s_add_u32 s49, s49, 0x100
	s_addc_u32 s50, s50, 0
.LBB0_782:
	ds_read_b128 v[144:147], v151
	ds_read_b128 v[156:159], v151 offset:1024
	ds_read_b128 v[160:163], v151 offset:2048
	ds_read_b128 v[164:167], v151 offset:3072
	ds_read_b128 v[168:171], v152
	ds_read_b128 v[172:175], v152 offset:1024
	ds_read_b128 v[176:179], v152 offset:2048
	ds_read_b128 v[180:183], v152 offset:3072
	s_add_u32 s24, s22, 0xfffc0080
	s_addc_u32 s25, s23, -1
	s_cmp_eq_u32 s51, 12
	s_cselect_b32 s27, s17, s25
	s_cselect_b32 s26, s47, s24
	s_cselect_b32 s25, s15, s50
	s_cselect_b32 s24, s48, s49
	v_lshl_add_u64 v[218:219], s[22:23], 0, v[136:137]
	s_add_i32 m0, s34, 0xc000
	ds_read_b128 v[184:187], v153
	ds_read_b128 v[190:193], v153 offset:1024
	ds_read_b128 v[194:197], v153 offset:2048
	ds_read_b128 v[198:201], v153 offset:3072
	ds_read_b128 v[202:205], v153 offset:4096
	ds_read_b128 v[206:209], v153 offset:5120
	ds_read_b128 v[210:213], v153 offset:6144
	ds_read_b128 v[214:217], v153 offset:7168
	global_load_lds_dwordx4 v[218:219], off
	v_lshl_add_u64 v[218:219], s[22:23], 0, v[138:139]
	s_add_i32 m0, s34, 0xe000
	s_nop 0
	global_load_lds_dwordx4 v[218:219], off
	s_waitcnt vmcnt(8)
	s_waitcnt lgkmcnt(0)
	s_barrier
; #define PG8_STAGE(bufoff, gbase, voff) do { _Pragma("unroll") for (int _i = 0; _i < 2; ++_i) \
;         __builtin_amdgcn_global_load_lds((const unsigned*)((const char*)(gbase) + (voff)[_i]), (PG8_LAS unsigned*)(lds + (bufoff) + ldsw + _i * 8192), 16, 0, 0); } while (0)
; #define PG8_LDA(dst, b, h) do { _Pragma("unroll") for (int m = 0; m < 4; ++m) _Pragma("unroll") for (int k = 0; k < 2; ++k) dst[m][k] = *(const PG8_LAS bf16x8*)(lds + PG8_SA(b, h) + aoff + m * 2048 + k * 1024); } while (0)
; #define PG8_LDB(dst, b, h) do { _Pragma("unroll") for (int n = 0; n < 2; ++n) _Pragma("unroll") for (int k = 0; k < 2; ++k) dst[n][k] = *(const PG8_LAS bf16x8*)(lds + PG8_SB(b, h) + boff + n * 2048 + k * 1024); } while (0)
; #define PG8_MMA(ai, bj, At, Bt) do { __builtin_amdgcn_s_setprio(1); _Pragma("unroll") for (int m = 0; m < 4; ++m) _Pragma("unroll") for (int n = 0; n < 2; ++n) _Pragma("unroll") for (int k = 0; k < 2; ++k) \
;         acc[ai][bj][m][n] = __builtin_amdgcn_mfma_f32_16x16x32_bf16(Bt[n][k], At[m][k], acc[ai][bj][m][n], 0, 0, 0); __builtin_amdgcn_s_setprio(0); } while (0)
; #define PG8_WAIT_V(n) asm volatile("s_waitcnt vmcnt(" #n ")" ::: "memory")
; template <class Epi, class Sched, bool ALIGN_EPI = false, bool SP2 = false>
; __device__ __forceinline__ void gemm_phase(PG8_LAS unsigned char* lds, const Gemm g, const Sched& S, const Epi& E) {
;     ...
;             PG8_LDB(B0, 0, 0); PG8_LDB(B1, 0, 1); PG8_SCHED; PG8_LDA(At, 0, 0); PG8_STAGE(PG8_SA(1, 1), a1 + hstep, voffA);
;             PG8_WAIT_V(8); PG8_WAIT_L(0); PG8_BAR; PG8_MMA(0, 0, At, B0); PG8_MMA(0, 1, At, B1); PG8_BAR; PG8_SCHED;
;             PG8_LDA(At, 0, 1); PG8_STAGE(PG8_SB(0, 0), b2, voffB); PG8_STAGE(PG8_SB(0, 1), b2 + hstep, voffB); PG8_STAGE(PG8_SA(0, 0), a2, voffA);
;             PG8_WAIT_V(8); PG8_WAIT_L(0); PG8_BAR; PG8_MMA(1, 0, At, B0); PG8_MMA(1, 1, At, B1); PG8_BAR; PG8_SCHED;
;             PG8_LDB(B0, 1, 0); PG8_LDB(B1, 1, 1); PG8_SCHED; PG8_LDA(At, 1, 0); PG8_STAGE(PG8_SA(0, 1), a2 + hstep, voffA);
;             PG8_WAIT_V(8); PG8_WAIT_L(0); PG8_BAR; PG8_MMA(0, 0, At, B0); PG8_MMA(0, 1, At, B1); PG8_BAR; PG8_SCHED;
;             PG8_LDA(At, 1, 1); PG8_STAGE(PG8_SB(1, 0), b3, voffB); PG8_STAGE(PG8_SB(1, 1), b3 + hstep, voffB); PG8_STAGE(PG8_SA(1, 0), a3, voffA);
;             PG8_WAIT_V(8); PG8_WAIT_L(0); PG8_BAR; PG8_MMA(1, 0, At, B0); PG8_MMA(1, 1, At, B1); PG8_BAR; PG8_SCHED;
	v_mfma_f32_16x16x32_bf16 v[116:119], v[144:147], v[184:187], v[116:119]
	v_mfma_f32_16x16x32_bf16 v[112:115], v[160:163], v[184:187], v[112:115]
	v_mfma_f32_16x16x32_bf16 v[100:103], v[144:147], v[194:197], v[100:103]
	v_mfma_f32_16x16x32_bf16 v[96:99], v[160:163], v[194:197], v[96:99]
	v_mfma_f32_16x16x32_bf16 v[84:87], v[144:147], v[202:205], v[84:87]
	v_mfma_f32_16x16x32_bf16 v[80:83], v[160:163], v[202:205], v[80:83]
	v_mfma_f32_16x16x32_bf16 v[72:75], v[144:147], v[210:213], v[72:75]
	v_mfma_f32_16x16x32_bf16 v[64:67], v[160:163], v[210:213], v[64:67]
	v_mfma_f32_16x16x32_bf16 v[116:119], v[156:159], v[190:193], v[116:119]
	v_mfma_f32_16x16x32_bf16 v[112:115], v[164:167], v[190:193], v[112:115]
	v_mfma_f32_16x16x32_bf16 v[100:103], v[156:159], v[198:201], v[100:103]
	v_mfma_f32_16x16x32_bf16 v[96:99], v[164:167], v[198:201], v[96:99]
	v_mfma_f32_16x16x32_bf16 v[84:87], v[156:159], v[206:209], v[84:87]
	v_mfma_f32_16x16x32_bf16 v[80:83], v[164:167], v[206:209], v[80:83]
	v_mfma_f32_16x16x32_bf16 v[72:75], v[156:159], v[214:217], v[72:75]
	v_mfma_f32_16x16x32_bf16 v[64:67], v[164:167], v[214:217], v[64:67]
	v_mfma_f32_16x16x32_bf16 v[124:127], v[168:171], v[184:187], v[124:127]
	v_mfma_f32_16x16x32_bf16 v[120:123], v[176:179], v[184:187], v[120:123]
	v_mfma_f32_16x16x32_bf16 v[108:111], v[168:171], v[194:197], v[108:111]
	v_mfma_f32_16x16x32_bf16 v[104:107], v[176:179], v[194:197], v[104:107]
	v_mfma_f32_16x16x32_bf16 v[92:95], v[168:171], v[202:205], v[92:95]
	v_mfma_f32_16x16x32_bf16 v[88:91], v[176:179], v[202:205], v[88:91]
	v_mfma_f32_16x16x32_bf16 v[76:79], v[168:171], v[210:213], v[76:79]
	v_mfma_f32_16x16x32_bf16 v[68:71], v[176:179], v[210:213], v[68:71]
	v_mfma_f32_16x16x32_bf16 v[124:127], v[172:175], v[190:193], v[124:127]
	v_mfma_f32_16x16x32_bf16 v[120:123], v[180:183], v[190:193], v[120:123]
	v_mfma_f32_16x16x32_bf16 v[108:111], v[172:175], v[198:201], v[108:111]
	v_mfma_f32_16x16x32_bf16 v[104:107], v[180:183], v[198:201], v[104:107]
	v_mfma_f32_16x16x32_bf16 v[92:95], v[172:175], v[206:209], v[92:95]
	v_mfma_f32_16x16x32_bf16 v[88:91], v[180:183], v[206:209], v[88:91]
	v_mfma_f32_16x16x32_bf16 v[76:79], v[172:175], v[214:217], v[76:79]
	v_mfma_f32_16x16x32_bf16 v[68:71], v[180:183], v[214:217], v[68:71]
	s_barrier
	s_add_i32 s52, s43, s30
	v_lshl_add_u64 v[218:219], s[24:25], 0, v[132:133]
	s_mov_b32 m0, s52
	ds_read_b128 v[184:187], v153 offset:16384
	ds_read_b128 v[190:193], v153 offset:17408
	ds_read_b128 v[194:197], v153 offset:18432
	ds_read_b128 v[198:201], v153 offset:19456
	ds_read_b128 v[202:205], v153 offset:20480
	ds_read_b128 v[206:209], v153 offset:21504
	ds_read_b128 v[210:213], v153 offset:22528
	ds_read_b128 v[214:217], v153 offset:23552
	global_load_lds_dwordx4 v[218:219], off
	s_add_i32 m0, s52, 0x2000
	s_add_u32 s52, s24, 0x40000
	v_lshl_add_u64 v[220:221], s[24:25], 0, v[128:129]
	s_addc_u32 s53, s25, 0
	s_add_i32 s54, s44, s30
	global_load_lds_dwordx4 v[220:221], off
	v_lshl_add_u64 v[222:223], s[52:53], 0, v[132:133]
	s_mov_b32 m0, s54
	v_lshl_add_u64 v[224:225], s[26:27], 0, v[130:131]
	global_load_lds_dwordx4 v[222:223], off
	v_lshl_add_u64 v[222:223], s[52:53], 0, v[128:129]
	s_add_i32 m0, s54, 0x2000
	s_nop 0
	global_load_lds_dwordx4 v[222:223], off
	v_lshl_add_u64 v[222:223], s[26:27], 0, v[134:135]
	s_mov_b32 m0, s34
	s_nop 0
	global_load_lds_dwordx4 v[222:223], off
	s_mov_b32 m0, s35
	s_nop 0
	global_load_lds_dwordx4 v[224:225], off
	s_waitcnt vmcnt(8)
	s_waitcnt lgkmcnt(0)
	s_barrier
	v_mfma_f32_16x16x32_bf16 v[56:59], v[144:147], v[184:187], v[56:59]
	v_mfma_f32_16x16x32_bf16 v[48:51], v[160:163], v[184:187], v[48:51]
	v_mfma_f32_16x16x32_bf16 v[40:43], v[144:147], v[194:197], v[40:43]
	v_mfma_f32_16x16x32_bf16 v[32:35], v[160:163], v[194:197], v[32:35]
	v_mfma_f32_16x16x32_bf16 v[24:27], v[144:147], v[202:205], v[24:27]
	v_mfma_f32_16x16x32_bf16 v[16:19], v[160:163], v[202:205], v[16:19]
	v_mfma_f32_16x16x32_bf16 v[8:11], v[144:147], v[210:213], v[8:11]
	v_mfma_f32_16x16x32_bf16 v[0:3], v[160:163], v[210:213], v[0:3]
	v_mfma_f32_16x16x32_bf16 v[56:59], v[156:159], v[190:193], v[56:59]
	v_mfma_f32_16x16x32_bf16 v[48:51], v[164:167], v[190:193], v[48:51]
	v_mfma_f32_16x16x32_bf16 v[40:43], v[156:159], v[198:201], v[40:43]
	v_mfma_f32_16x16x32_bf16 v[32:35], v[164:167], v[198:201], v[32:35]
	v_mfma_f32_16x16x32_bf16 v[24:27], v[156:159], v[206:209], v[24:27]
	v_mfma_f32_16x16x32_bf16 v[16:19], v[164:167], v[206:209], v[16:19]
	v_mfma_f32_16x16x32_bf16 v[8:11], v[156:159], v[214:217], v[8:11]
	v_mfma_f32_16x16x32_bf16 v[0:3], v[164:167], v[214:217], v[0:3]
	v_mfma_f32_16x16x32_bf16 v[60:63], v[168:171], v[184:187], v[60:63]
	v_mfma_f32_16x16x32_bf16 v[52:55], v[176:179], v[184:187], v[52:55]
	v_mfma_f32_16x16x32_bf16 v[44:47], v[168:171], v[194:197], v[44:47]
	v_mfma_f32_16x16x32_bf16 v[36:39], v[176:179], v[194:197], v[36:39]
	v_mfma_f32_16x16x32_bf16 v[28:31], v[168:171], v[202:205], v[28:31]
	v_mfma_f32_16x16x32_bf16 v[20:23], v[176:179], v[202:205], v[20:23]
	v_mfma_f32_16x16x32_bf16 v[12:15], v[168:171], v[210:213], v[12:15]
	v_mfma_f32_16x16x32_bf16 v[4:7], v[176:179], v[210:213], v[4:7]
	v_mfma_f32_16x16x32_bf16 v[60:63], v[172:175], v[190:193], v[60:63]
	v_mfma_f32_16x16x32_bf16 v[52:55], v[180:183], v[190:193], v[52:55]
	v_mfma_f32_16x16x32_bf16 v[44:47], v[172:175], v[198:201], v[44:47]
	v_mfma_f32_16x16x32_bf16 v[36:39], v[180:183], v[198:201], v[36:39]
	v_mfma_f32_16x16x32_bf16 v[28:31], v[172:175], v[206:209], v[28:31]
	v_mfma_f32_16x16x32_bf16 v[20:23], v[180:183], v[206:209], v[20:23]
	v_mfma_f32_16x16x32_bf16 v[12:15], v[172:175], v[214:217], v[12:15]
	v_mfma_f32_16x16x32_bf16 v[4:7], v[180:183], v[214:217], v[4:7]
	s_barrier
; #define PG8_STAGE(bufoff, gbase, voff) do { _Pragma("unroll") for (int _i = 0; _i < 2; ++_i) \
;         __builtin_amdgcn_global_load_lds((const unsigned*)((const char*)(gbase) + (voff)[_i]), (PG8_LAS unsigned*)(lds + (bufoff) + ldsw + _i * 8192), 16, 0, 0); } while (0)
; #define PG8_LDA(dst, b, h) do { _Pragma("unroll") for (int m = 0; m < 4; ++m) _Pragma("unroll") for (int k = 0; k < 2; ++k) dst[m][k] = *(const PG8_LAS bf16x8*)(lds + PG8_SA(b, h) + aoff + m * 2048 + k * 1024); } while (0)
; #define PG8_LDB(dst, b, h) do { _Pragma("unroll") for (int n = 0; n < 2; ++n) _Pragma("unroll") for (int k = 0; k < 2; ++k) dst[n][k] = *(const PG8_LAS bf16x8*)(lds + PG8_SB(b, h) + boff + n * 2048 + k * 1024); } while (0)
; #define PG8_MMA(ai, bj, At, Bt) do { __builtin_amdgcn_s_setprio(1); _Pragma("unroll") for (int m = 0; m < 4; ++m) _Pragma("unroll") for (int n = 0; n < 2; ++n) _Pragma("unroll") for (int k = 0; k < 2; ++k) \
;         acc[ai][bj][m][n] = __builtin_amdgcn_mfma_f32_16x16x32_bf16(Bt[n][k], At[m][k], acc[ai][bj][m][n], 0, 0, 0); __builtin_amdgcn_s_setprio(0); } while (0)
; #define PG8_WAIT_V(n) asm volatile("s_waitcnt vmcnt(" #n ")" ::: "memory")
; #define PG8_WAIT_L(n) asm volatile("s_waitcnt lgkmcnt(" #n ")" ::: "memory")
; #define PG8_BAR __builtin_amdgcn_s_barrier()
; #define PG8_SCHED __builtin_amdgcn_sched_barrier(0)
; template <class Epi, class Sched, bool ALIGN_EPI = false, bool SP2 = false>
; __device__ __forceinline__ void gemm_phase(PG8_LAS unsigned char* lds, const Gemm g, const Sched& S, const Epi& E) {
;     ...
;             PG8_LDB(B0, 1, 0); PG8_LDB(B1, 1, 1); PG8_SCHED; PG8_LDA(At, 1, 0); PG8_STAGE(PG8_SA(0, 1), a2 + hstep, voffA);
;             PG8_WAIT_V(8); PG8_WAIT_L(0); PG8_BAR; PG8_MMA(0, 0, At, B0); PG8_MMA(0, 1, At, B1); PG8_BAR; PG8_SCHED;
	s_add_i32 s52, 0, 0x18000
	v_add_u32_e32 v155, s52, v149
	s_add_i32 s53, 0, 0x1c000
	ds_read_b128 v[144:147], v155
	ds_read_b128 v[156:159], v155 offset:1024
	ds_read_b128 v[160:163], v155 offset:2048
	ds_read_b128 v[164:167], v155 offset:3072
	v_add_u32_e32 v155, s53, v149
	ds_read_b128 v[168:171], v155
	ds_read_b128 v[172:175], v155 offset:1024
	ds_read_b128 v[176:179], v155 offset:2048
	ds_read_b128 v[180:183], v155 offset:3072
	s_add_u32 s26, s26, 0x40000
	s_addc_u32 s27, s27, 0
	s_mov_b32 m0, s36
	v_lshl_add_u64 v[226:227], s[26:27], 0, v[134:135]
	ds_read_b128 v[184:187], v153 offset:32768
	ds_read_b128 v[190:193], v153 offset:33792
	ds_read_b128 v[194:197], v153 offset:34816
	ds_read_b128 v[198:201], v153 offset:35840
	ds_read_b128 v[202:205], v153 offset:36864
	ds_read_b128 v[206:209], v153 offset:37888
	ds_read_b128 v[210:213], v153 offset:38912
	ds_read_b128 v[214:217], v153 offset:39936
	global_load_lds_dwordx4 v[226:227], off
	v_lshl_add_u64 v[226:227], s[26:27], 0, v[130:131]
	s_mov_b32 m0, s37
	s_nop 0
	global_load_lds_dwordx4 v[226:227], off
	s_waitcnt vmcnt(8)
	s_waitcnt lgkmcnt(0)
	s_barrier
	v_mfma_f32_16x16x32_bf16 v[116:119], v[144:147], v[184:187], v[116:119]
	v_mfma_f32_16x16x32_bf16 v[112:115], v[160:163], v[184:187], v[112:115]
	v_mfma_f32_16x16x32_bf16 v[100:103], v[144:147], v[194:197], v[100:103]
	v_mfma_f32_16x16x32_bf16 v[96:99], v[160:163], v[194:197], v[96:99]
	v_mfma_f32_16x16x32_bf16 v[84:87], v[144:147], v[202:205], v[84:87]
	v_mfma_f32_16x16x32_bf16 v[80:83], v[160:163], v[202:205], v[80:83]
	v_mfma_f32_16x16x32_bf16 v[72:75], v[144:147], v[210:213], v[72:75]
	v_mfma_f32_16x16x32_bf16 v[64:67], v[160:163], v[210:213], v[64:67]
	v_mfma_f32_16x16x32_bf16 v[116:119], v[156:159], v[190:193], v[116:119]
	v_mfma_f32_16x16x32_bf16 v[112:115], v[164:167], v[190:193], v[112:115]
	v_mfma_f32_16x16x32_bf16 v[100:103], v[156:159], v[198:201], v[100:103]
	v_mfma_f32_16x16x32_bf16 v[96:99], v[164:167], v[198:201], v[96:99]
	v_mfma_f32_16x16x32_bf16 v[84:87], v[156:159], v[206:209], v[84:87]
	v_mfma_f32_16x16x32_bf16 v[80:83], v[164:167], v[206:209], v[80:83]
	v_mfma_f32_16x16x32_bf16 v[72:75], v[156:159], v[214:217], v[72:75]
	v_mfma_f32_16x16x32_bf16 v[64:67], v[164:167], v[214:217], v[64:67]
	v_mfma_f32_16x16x32_bf16 v[124:127], v[168:171], v[184:187], v[124:127]
	v_mfma_f32_16x16x32_bf16 v[120:123], v[176:179], v[184:187], v[120:123]
	v_mfma_f32_16x16x32_bf16 v[108:111], v[168:171], v[194:197], v[108:111]
	v_mfma_f32_16x16x32_bf16 v[104:107], v[176:179], v[194:197], v[104:107]
	v_mfma_f32_16x16x32_bf16 v[92:95], v[168:171], v[202:205], v[92:95]
	v_mfma_f32_16x16x32_bf16 v[88:91], v[176:179], v[202:205], v[88:91]
	v_mfma_f32_16x16x32_bf16 v[76:79], v[168:171], v[210:213], v[76:79]
	v_mfma_f32_16x16x32_bf16 v[68:71], v[176:179], v[210:213], v[68:71]
	v_mfma_f32_16x16x32_bf16 v[124:127], v[172:175], v[190:193], v[124:127]
	v_mfma_f32_16x16x32_bf16 v[120:123], v[180:183], v[190:193], v[120:123]
	v_mfma_f32_16x16x32_bf16 v[108:111], v[172:175], v[198:201], v[108:111]
	v_mfma_f32_16x16x32_bf16 v[104:107], v[180:183], v[198:201], v[104:107]
	v_mfma_f32_16x16x32_bf16 v[92:95], v[172:175], v[206:209], v[92:95]
	v_mfma_f32_16x16x32_bf16 v[88:91], v[180:183], v[206:209], v[88:91]
	v_mfma_f32_16x16x32_bf16 v[76:79], v[172:175], v[214:217], v[76:79]
	v_mfma_f32_16x16x32_bf16 v[68:71], v[180:183], v[214:217], v[68:71]
	s_barrier
; #define PG8_STAGE(bufoff, gbase, voff) do { _Pragma("unroll") for (int _i = 0; _i < 2; ++_i) \
;         __builtin_amdgcn_global_load_lds((const unsigned*)((const char*)(gbase) + (voff)[_i]), (PG8_LAS unsigned*)(lds + (bufoff) + ldsw + _i * 8192), 16, 0, 0); } while (0)
; #define PG8_LDA(dst, b, h) do { _Pragma("unroll") for (int m = 0; m < 4; ++m) _Pragma("unroll") for (int k = 0; k < 2; ++k) dst[m][k] = *(const PG8_LAS bf16x8*)(lds + PG8_SA(b, h) + aoff + m * 2048 + k * 1024); } while (0)
; #define PG8_MMA(ai, bj, At, Bt) do { __builtin_amdgcn_s_setprio(1); _Pragma("unroll") for (int m = 0; m < 4; ++m) _Pragma("unroll") for (int n = 0; n < 2; ++n) _Pragma("unroll") for (int k = 0; k < 2; ++k) \
;         acc[ai][bj][m][n] = __builtin_amdgcn_mfma_f32_16x16x32_bf16(Bt[n][k], At[m][k], acc[ai][bj][m][n], 0, 0, 0); __builtin_amdgcn_s_setprio(0); } while (0)
; #define PG8_WAIT_V(n) asm volatile("s_waitcnt vmcnt(" #n ")" ::: "memory")
; #define PG8_WAIT_L(n) asm volatile("s_waitcnt lgkmcnt(" #n ")" ::: "memory")
; #define PG8_BAR __builtin_amdgcn_s_barrier()
; #define PG8_SCHED __builtin_amdgcn_sched_barrier(0)
; template <class Epi, class Sched, bool ALIGN_EPI = false, bool SP2 = false>
; __device__ __forceinline__ void gemm_phase(PG8_LAS unsigned char* lds, const Gemm g, const Sched& S, const Epi& E) {
;     ...
;             PG8_LDA(At, 1, 1); PG8_STAGE(PG8_SB(1, 0), b3, voffB); PG8_STAGE(PG8_SB(1, 1), b3 + hstep, voffB); PG8_STAGE(PG8_SA(1, 0), a3, voffA);
;             PG8_WAIT_V(8); PG8_WAIT_L(0); PG8_BAR; PG8_MMA(1, 0, At, B0); PG8_MMA(1, 1, At, B1); PG8_BAR; PG8_SCHED;
;     ...
;         if constexpr (ALIGN_EPI) { if (wr == 0) PG8_BAR; }
;         if constexpr (!Epi::AFTER_DRAIN) { E(acc, cur, wr, wc, fr, fq); S.done(cur); }
;         if (!has_next) break;
	s_add_i32 s26, s52, s30
	v_lshl_add_u64 v[218:219], v[218:219], 0, s[6:7]
	s_mov_b32 m0, s26
	ds_read_b128 v[184:187], v153 offset:49152
	ds_read_b128 v[190:193], v153 offset:50176
	ds_read_b128 v[194:197], v153 offset:51200
	ds_read_b128 v[198:201], v153 offset:52224
	ds_read_b128 v[202:205], v153 offset:53248
	ds_read_b128 v[206:209], v153 offset:54272
	ds_read_b128 v[210:213], v153 offset:55296
	ds_read_b128 v[214:217], v153 offset:56320
	global_load_lds_dwordx4 v[218:219], off
	s_add_i32 m0, s26, 0x2000
	s_add_u32 s24, s24, 0x40080
	v_lshl_add_u64 v[218:219], v[220:221], 0, s[6:7]
	s_addc_u32 s25, s25, 0
	s_add_i32 s26, s53, s30
	global_load_lds_dwordx4 v[218:219], off
	v_lshl_add_u64 v[218:219], s[24:25], 0, v[132:133]
	s_mov_b32 m0, s26
	s_nop 0
	global_load_lds_dwordx4 v[218:219], off
	v_lshl_add_u64 v[218:219], s[24:25], 0, v[128:129]
	s_add_i32 m0, s26, 0x2000
	s_nop 0
	global_load_lds_dwordx4 v[218:219], off
	v_lshl_add_u64 v[218:219], v[222:223], 0, s[6:7]
	s_mov_b32 m0, s39
	s_nop 0
	global_load_lds_dwordx4 v[218:219], off
	v_lshl_add_u64 v[218:219], v[224:225], 0, s[6:7]
	s_mov_b32 m0, s40
	s_nop 0
	global_load_lds_dwordx4 v[218:219], off
	s_waitcnt vmcnt(8)
	s_waitcnt lgkmcnt(0)
	s_barrier
	v_mfma_f32_16x16x32_bf16 v[56:59], v[144:147], v[184:187], v[56:59]
	v_mfma_f32_16x16x32_bf16 v[48:51], v[160:163], v[184:187], v[48:51]
	v_mfma_f32_16x16x32_bf16 v[40:43], v[144:147], v[194:197], v[40:43]
	v_mfma_f32_16x16x32_bf16 v[32:35], v[160:163], v[194:197], v[32:35]
	v_mfma_f32_16x16x32_bf16 v[24:27], v[144:147], v[202:205], v[24:27]
	v_mfma_f32_16x16x32_bf16 v[16:19], v[160:163], v[202:205], v[16:19]
	v_mfma_f32_16x16x32_bf16 v[8:11], v[144:147], v[210:213], v[8:11]
	v_mfma_f32_16x16x32_bf16 v[0:3], v[160:163], v[210:213], v[0:3]
	v_mfma_f32_16x16x32_bf16 v[56:59], v[156:159], v[190:193], v[56:59]
	v_mfma_f32_16x16x32_bf16 v[48:51], v[164:167], v[190:193], v[48:51]
	v_mfma_f32_16x16x32_bf16 v[40:43], v[156:159], v[198:201], v[40:43]
	v_mfma_f32_16x16x32_bf16 v[32:35], v[164:167], v[198:201], v[32:35]
	v_mfma_f32_16x16x32_bf16 v[24:27], v[156:159], v[206:209], v[24:27]
	v_mfma_f32_16x16x32_bf16 v[16:19], v[164:167], v[206:209], v[16:19]
	v_mfma_f32_16x16x32_bf16 v[8:11], v[156:159], v[214:217], v[8:11]
	v_mfma_f32_16x16x32_bf16 v[0:3], v[164:167], v[214:217], v[0:3]
	v_mfma_f32_16x16x32_bf16 v[60:63], v[168:171], v[184:187], v[60:63]
	v_mfma_f32_16x16x32_bf16 v[52:55], v[176:179], v[184:187], v[52:55]
	v_mfma_f32_16x16x32_bf16 v[44:47], v[168:171], v[194:197], v[44:47]
	v_mfma_f32_16x16x32_bf16 v[36:39], v[176:179], v[194:197], v[36:39]
	v_mfma_f32_16x16x32_bf16 v[28:31], v[168:171], v[202:205], v[28:31]
	v_mfma_f32_16x16x32_bf16 v[20:23], v[176:179], v[202:205], v[20:23]
	v_mfma_f32_16x16x32_bf16 v[12:15], v[168:171], v[210:213], v[12:15]
	v_mfma_f32_16x16x32_bf16 v[4:7], v[176:179], v[210:213], v[4:7]
	v_mfma_f32_16x16x32_bf16 v[60:63], v[172:175], v[190:193], v[60:63]
	v_mfma_f32_16x16x32_bf16 v[52:55], v[180:183], v[190:193], v[52:55]
	v_mfma_f32_16x16x32_bf16 v[44:47], v[172:175], v[198:201], v[44:47]
	v_mfma_f32_16x16x32_bf16 v[36:39], v[180:183], v[198:201], v[36:39]
	v_mfma_f32_16x16x32_bf16 v[28:31], v[172:175], v[206:209], v[28:31]
	v_mfma_f32_16x16x32_bf16 v[20:23], v[180:183], v[206:209], v[20:23]
	v_mfma_f32_16x16x32_bf16 v[12:15], v[172:175], v[214:217], v[12:15]
	v_mfma_f32_16x16x32_bf16 v[4:7], v[180:183], v[214:217], v[4:7]
	s_barrier
	s_add_i32 s51, s51, 2
	s_add_u32 s22, s22, 0x100
	s_addc_u32 s23, s23, 0
	s_add_u32 s49, s49, 0x100
	s_addc_u32 s50, s50, 0
	s_cmp_gt_u32 s51, 13
	s_cbranch_scc0 .LBB0_782
	s_and_b64 vcc, exec, s[12:13]
	s_cbranch_vccz .LBB0_785
	s_barrier

; #define PG8_STAGE(bufoff, gbase, voff) do { _Pragma("unroll") for (int _i = 0; _i < 2; ++_i) \
;         __builtin_amdgcn_global_load_lds((const unsigned*)((const char*)(gbase) + (voff)[_i]), (PG8_LAS unsigned*)(lds + (bufoff) + ldsw + _i * 8192), 16, 0, 0); } while (0)
; #define PG8_WAIT_V(n) asm volatile("s_waitcnt vmcnt(" #n ")" ::: "memory")
; #define PG8_BAR __builtin_amdgcn_s_barrier()
; template <class Epi, class Sched, bool ALIGN_EPI = false, bool SP2 = false>
; __device__ __forceinline__ void gemm_phase(PG8_LAS unsigned char* lds, const Gemm g, const Sched& S, const Epi& E) {
;     ...
;     for (int i = 0; i < 2; ++i) { int R, C; stage_rc(tid * 16 + i * 8192, R, C); const int Rb = Epi::PERM ? ((R & ~31) + perm32(R & 31)) : R;
;         voffA[i] = (unsigned)(R * K + C) * 2u; voffB[i] = (unsigned)(Rb * K + C) * 2u; }
;     const size_t kstep = (size_t)(BK * 2);
;     const size_t hstep = (size_t)HALF * K * 2;
;     const size_t tstep = 2 * hstep;
;     const unsigned ldsw = (unsigned)wid * 1024u;
;     const int aoff = lds_byte(wr * 64 + fr, fq * 8), boff = lds_byte(wc * 32 + fr, fq * 8);
;     ...
;         PG8_STAGE(PG8_SB(0, 0), cB, voffB); PG8_STAGE(PG8_SB(0, 1), cB + hstep, voffB); PG8_STAGE(PG8_SA(0, 0), cA, voffA); PG8_STAGE(PG8_SA(0, 1), cA + hstep, voffA);
;         if (wr == 1) PG8_BAR;
;         PG8_WAIT_V(2); PG8_BAR;
;         PG8_STAGE(PG8_SB(1, 0), cB + kstep, voffB); PG8_STAGE(PG8_SA(1, 0), cA + kstep, voffA); PG8_STAGE(PG8_SB(1, 1), cB + hstep + kstep, voffB);
;         PG8_WAIT_V(6); PG8_BAR;
.LBB0_848:
	s_lshl_b32 s6, s6, 5
	s_and_b32 s14, s6, 0x60
	s_mov_b64 s[6:7], 0x80
	s_add_i32 m0, s35, 0x18000
	v_lshl_add_u64 v[6:7], v[6:7], 0, s[6:7]
	s_lshl_b32 s12, s0, 13
	s_lshl_b32 s13, s14, 7
	s_waitcnt vmcnt(2)
	s_barrier
	global_load_lds_dwordx4 v[6:7], off
	v_lshl_add_u64 v[4:5], v[4:5], 0, s[6:7]
	s_add_i32 m0, s35, 0x1a000
	s_add_i32 s40, s35, 0x8000
	s_add_i32 s41, s35, 0xa000
	global_load_lds_dwordx4 v[4:5], off
	v_lshl_add_u64 v[0:1], v[0:1], 0, s[6:7]
	s_mov_b32 m0, s40
	s_add_u32 s10, s24, 0xb0080
	global_load_lds_dwordx4 v[0:1], off
	v_lshl_add_u64 v[0:1], v[2:3], 0, s[6:7]
	s_mov_b32 m0, s41
	s_addc_u32 s11, s25, 0
	global_load_lds_dwordx4 v[0:1], off
	s_add_i32 m0, s35, 0x1c000
	v_lshl_add_u64 v[0:1], s[10:11], 0, v[130:131]
	global_load_lds_dwordx4 v[0:1], off
	v_lshl_add_u64 v[0:1], s[10:11], 0, v[134:135]
	s_add_i32 m0, s35, 0x1e000
	s_sext_i32_i8 s48, s5
	global_load_lds_dwordx4 v[0:1], off
	v_bfe_u32 v1, v189, 4, 2
	v_and_b32_e32 v0, 15, v189
	v_lshlrev_b32_e32 v2, 4, v1
	v_lshl_or_b32 v150, s0, 6, v0
	v_lshl_or_b32 v0, v0, 6, v2
	v_lshlrev_b32_e32 v2, 2, v189
	v_and_b32_e32 v2, 32, v2
	s_cmpk_lt_u32 s4, 0x100
	v_readlane_b32 s4, v235, 6
	v_bitop3_b32 v3, v0, s12, v2 bitop3:0xde
	v_bitop3_b32 v151, v0, s13, v2 bitop3:0xde
	v_readlane_b32 s5, v235, 7
	v_lshl_or_b32 v152, v1, 3, s14
	v_lshrrev_b32_e32 v1, 1, v8
	v_mul_lo_u32 v0, v10, s1
	s_mov_b32 s0, 0xb000
	s_cselect_b64 s[10:11], -1, 0
	s_ashr_i32 s42, s4, 31
	v_mad_u64_u32 v[0:1], s[4:5], v1, s0, v[0:1]
	v_or_b32_e32 v0, v0, v9
	s_mov_b64 s[12:13], 0xb0080
	v_add_lshl_u32 v0, v0, v11, 1
	v_mov_b32_e32 v1, v131
	v_lshl_add_u64 v[136:137], v[0:1], 0, s[12:13]
	v_lshrrev_b32_e32 v1, 1, v12
	v_mul_lo_u32 v0, v13, s1
	v_mad_u64_u32 v[0:1], s[0:1], v1, s0, v[0:1]
	s_waitcnt vmcnt(6)
	v_or_b32_e32 v0, v0, v14
	v_add_lshl_u32 v0, v0, v15, 1
	v_mov_b32_e32 v1, v131
	s_add_i32 s43, 0, 0x10000
	s_add_i32 s44, 0, 0x14000
	v_lshl_add_u64 v[138:139], v[0:1], 0, s[12:13]
	v_mov_b64_e32 v[140:141], 0x200
	v_mov_b64_e32 v[142:143], 0x1ff
	v_add_u32_e32 v153, s43, v151
	v_add_u32_e32 v154, s44, v151
	v_add_u32_e32 v155, 0, v3
	s_mov_b64 s[12:13], 0x20000
	s_mov_b64 s[14:15], 0x24000
	s_mov_b64 s[16:17], 0x28000
	s_mov_b64 s[18:19], 0x2c000
	s_barrier
	v_readfirstlane_b32 s99, v189
	s_nop 0
	s_lshr_b32 s99, s99, 6
	s_cmp_ge_u32 s99, 4
	s_cbranch_scc0 .Lprio_851
	s_setprio 1
.Lprio_851:
	s_branch .LBB0_851
.LBB0_849:
	s_mov_b64 s[0:1], 0

; #define PG8_STAGE(bufoff, gbase, voff) do { _Pragma("unroll") for (int _i = 0; _i < 2; ++_i) \
;         __builtin_amdgcn_global_load_lds((const unsigned*)((const char*)(gbase) + (voff)[_i]), (PG8_LAS unsigned*)(lds + (bufoff) + ldsw + _i * 8192), 16, 0, 0); } while (0)
; #define PG8_LDA(dst, b, h) do { _Pragma("unroll") for (int m = 0; m < 4; ++m) _Pragma("unroll") for (int k = 0; k < 2; ++k) dst[m][k] = *(const PG8_LAS bf16x8*)(lds + PG8_SA(b, h) + aoff + m * 2048 + k * 1024); } while (0)
; #define PG8_LDB(dst, b, h) do { _Pragma("unroll") for (int n = 0; n < 2; ++n) _Pragma("unroll") for (int k = 0; k < 2; ++k) dst[n][k] = *(const PG8_LAS bf16x8*)(lds + PG8_SB(b, h) + boff + n * 2048 + k * 1024); } while (0)
; #define PG8_MMA(ai, bj, At, Bt) do { __builtin_amdgcn_s_setprio(1); _Pragma("unroll") for (int m = 0; m < 4; ++m) _Pragma("unroll") for (int n = 0; n < 2; ++n) _Pragma("unroll") for (int k = 0; k < 2; ++k) \
;         acc[ai][bj][m][n] = __builtin_amdgcn_mfma_f32_16x16x32_bf16(Bt[n][k], At[m][k], acc[ai][bj][m][n], 0, 0, 0); __builtin_amdgcn_s_setprio(0); } while (0)
; #define PG8_WAIT_V(n) asm volatile("s_waitcnt vmcnt(" #n ")" ::: "memory")
; #define PG8_WAIT_L(n) asm volatile("s_waitcnt lgkmcnt(" #n ")" ::: "memory")
; #define PG8_BAR __builtin_amdgcn_s_barrier()
; #define PG8_SCHED __builtin_amdgcn_sched_barrier(0)
; template <class Epi, class Sched, bool ALIGN_EPI = false, bool SP2 = false>
; __device__ __forceinline__ void gemm_phase(PG8_LAS unsigned char* lds, const Gemm g, const Sched& S, const Epi& E) {
;     ...
;             PG8_LDB(B0, 0, 0); PG8_LDB(B1, 0, 1); PG8_SCHED; PG8_LDA(At, 0, 0); PG8_STAGE(PG8_SA(1, 1), a1 + hstep, voffA);
;             PG8_WAIT_V(8); PG8_WAIT_L(0); PG8_BAR; PG8_MMA(0, 0, At, B0); PG8_MMA(0, 1, At, B1); PG8_BAR; PG8_SCHED;
;             PG8_LDA(At, 0, 1); PG8_STAGE(PG8_SB(0, 0), b2, voffB); PG8_STAGE(PG8_SB(0, 1), b2 + hstep, voffB); PG8_STAGE(PG8_SA(0, 0), a2, voffA);
;             PG8_WAIT_V(8); PG8_WAIT_L(0); PG8_BAR; PG8_MMA(1, 0, At, B0); PG8_MMA(1, 1, At, B1); PG8_BAR; PG8_SCHED;
.LBB0_861:
	s_add_u32 s49, s24, 0x100
	s_addc_u32 s50, s25, 0
	s_mov_b32 s51, -2
	ds_read_b128 v[144:147], v153
	ds_read_b128 v[156:159], v153 offset:1024
	ds_read_b128 v[160:163], v153 offset:2048
	ds_read_b128 v[164:167], v153 offset:3072
	ds_read_b128 v[168:171], v154
	ds_read_b128 v[172:175], v154 offset:1024
	ds_read_b128 v[176:179], v154 offset:2048
	ds_read_b128 v[180:183], v154 offset:3072
	s_add_u32 s24, s22, 0x100
	s_addc_u32 s25, s23, 0
	s_cmp_eq_u32 s51, 40
	s_cselect_b32 s29, s5, s25
	s_cselect_b32 s28, s4, s24
	s_cselect_b32 s27, s21, s50
	s_cselect_b32 s26, s20, s49
	v_lshl_add_u64 v[148:149], s[22:23], 0, v[136:137]
	s_add_i32 m0, s35, 0xc000
	ds_read_b128 v[184:187], v155
	ds_read_b128 v[188:191], v155 offset:1024
	ds_read_b128 v[192:195], v155 offset:2048
	ds_read_b128 v[196:199], v155 offset:3072
	ds_read_b128 v[200:203], v155 offset:4096
	ds_read_b128 v[204:207], v155 offset:5120
	ds_read_b128 v[208:211], v155 offset:6144
	ds_read_b128 v[212:215], v155 offset:7168
	global_load_lds_dwordx4 v[148:149], off
	v_lshl_add_u64 v[148:149], s[22:23], 0, v[138:139]
	s_add_i32 m0, s35, 0xe000
	s_nop 0
	global_load_lds_dwordx4 v[148:149], off
	s_waitcnt vmcnt(8)
	s_waitcnt lgkmcnt(0)
	s_barrier
	v_mfma_f32_16x16x32_bf16 v[124:127], v[144:147], v[184:187], 0
	v_mfma_f32_16x16x32_bf16 v[120:123], v[160:163], v[184:187], 0
	v_mfma_f32_16x16x32_bf16 v[108:111], v[144:147], v[192:195], 0
	v_mfma_f32_16x16x32_bf16 v[104:107], v[160:163], v[192:195], 0
	v_mfma_f32_16x16x32_bf16 v[92:95], v[144:147], v[200:203], 0
	v_mfma_f32_16x16x32_bf16 v[88:91], v[160:163], v[200:203], 0
	v_mfma_f32_16x16x32_bf16 v[76:79], v[144:147], v[208:211], 0
	v_mfma_f32_16x16x32_bf16 v[72:75], v[160:163], v[208:211], 0
	v_mfma_f32_16x16x32_bf16 v[124:127], v[156:159], v[188:191], v[124:127]
	v_mfma_f32_16x16x32_bf16 v[120:123], v[164:167], v[188:191], v[120:123]
	v_mfma_f32_16x16x32_bf16 v[108:111], v[156:159], v[196:199], v[108:111]
	v_mfma_f32_16x16x32_bf16 v[104:107], v[164:167], v[196:199], v[104:107]
	v_mfma_f32_16x16x32_bf16 v[92:95], v[156:159], v[204:207], v[92:95]
	v_mfma_f32_16x16x32_bf16 v[88:91], v[164:167], v[204:207], v[88:91]
	v_mfma_f32_16x16x32_bf16 v[76:79], v[156:159], v[212:215], v[76:79]
	v_mfma_f32_16x16x32_bf16 v[72:75], v[164:167], v[212:215], v[72:75]
	v_mfma_f32_16x16x32_bf16 v[116:119], v[168:171], v[184:187], 0
	v_mfma_f32_16x16x32_bf16 v[112:115], v[176:179], v[184:187], 0
	v_mfma_f32_16x16x32_bf16 v[100:103], v[168:171], v[192:195], 0
	v_mfma_f32_16x16x32_bf16 v[96:99], v[176:179], v[192:195], 0
	v_mfma_f32_16x16x32_bf16 v[84:87], v[168:171], v[200:203], 0
	v_mfma_f32_16x16x32_bf16 v[80:83], v[176:179], v[200:203], 0
	v_mfma_f32_16x16x32_bf16 v[68:71], v[168:171], v[208:211], 0
	v_mfma_f32_16x16x32_bf16 v[64:67], v[176:179], v[208:211], 0
	v_mfma_f32_16x16x32_bf16 v[116:119], v[172:175], v[188:191], v[116:119]
	v_mfma_f32_16x16x32_bf16 v[112:115], v[180:183], v[188:191], v[112:115]
	v_mfma_f32_16x16x32_bf16 v[100:103], v[172:175], v[196:199], v[100:103]
	v_mfma_f32_16x16x32_bf16 v[96:99], v[180:183], v[196:199], v[96:99]
	v_mfma_f32_16x16x32_bf16 v[84:87], v[172:175], v[204:207], v[84:87]
	v_mfma_f32_16x16x32_bf16 v[80:83], v[180:183], v[204:207], v[80:83]
	v_mfma_f32_16x16x32_bf16 v[68:71], v[172:175], v[212:215], v[68:71]
	v_mfma_f32_16x16x32_bf16 v[64:67], v[180:183], v[212:215], v[64:67]
	s_barrier
	s_add_i32 s22, s43, s34
	v_lshl_add_u64 v[148:149], s[26:27], 0, v[130:131]
	s_mov_b32 m0, s22
	ds_read_b128 v[184:187], v155 offset:16384
	ds_read_b128 v[188:191], v155 offset:17408
	ds_read_b128 v[192:195], v155 offset:18432
	ds_read_b128 v[196:199], v155 offset:19456
	ds_read_b128 v[200:203], v155 offset:20480
	ds_read_b128 v[204:207], v155 offset:21504
	ds_read_b128 v[208:211], v155 offset:22528
	ds_read_b128 v[212:215], v155 offset:23552
	global_load_lds_dwordx4 v[148:149], off
	s_add_i32 m0, s22, 0x2000
	s_add_u32 s22, s26, 0xb0000
	v_lshl_add_u64 v[216:217], s[26:27], 0, v[134:135]
	s_addc_u32 s23, s27, 0
	s_add_i32 s52, s44, s34
	global_load_lds_dwordx4 v[216:217], off
	v_lshl_add_u64 v[218:219], s[22:23], 0, v[130:131]
	s_mov_b32 m0, s52
	v_lshl_add_u64 v[220:221], s[28:29], 0, v[132:133]
	global_load_lds_dwordx4 v[218:219], off
	v_lshl_add_u64 v[218:219], s[22:23], 0, v[134:135]
	s_add_i32 m0, s52, 0x2000
	s_nop 0
	global_load_lds_dwordx4 v[218:219], off
	v_lshl_add_u64 v[218:219], s[28:29], 0, v[128:129]
	s_mov_b32 m0, s35
	s_nop 0
	global_load_lds_dwordx4 v[218:219], off
	s_mov_b32 m0, s36
	s_nop 0
	global_load_lds_dwordx4 v[220:221], off
	s_waitcnt vmcnt(8)
	s_waitcnt lgkmcnt(0)
	s_barrier
; #define PG8_STAGE(bufoff, gbase, voff) do { _Pragma("unroll") for (int _i = 0; _i < 2; ++_i) \
;         __builtin_amdgcn_global_load_lds((const unsigned*)((const char*)(gbase) + (voff)[_i]), (PG8_LAS unsigned*)(lds + (bufoff) + ldsw + _i * 8192), 16, 0, 0); } while (0)
; #define PG8_LDA(dst, b, h) do { _Pragma("unroll") for (int m = 0; m < 4; ++m) _Pragma("unroll") for (int k = 0; k < 2; ++k) dst[m][k] = *(const PG8_LAS bf16x8*)(lds + PG8_SA(b, h) + aoff + m * 2048 + k * 1024); } while (0)
; #define PG8_LDB(dst, b, h) do { _Pragma("unroll") for (int n = 0; n < 2; ++n) _Pragma("unroll") for (int k = 0; k < 2; ++k) dst[n][k] = *(const PG8_LAS bf16x8*)(lds + PG8_SB(b, h) + boff + n * 2048 + k * 1024); } while (0)
; #define PG8_MMA(ai, bj, At, Bt) do { __builtin_amdgcn_s_setprio(1); _Pragma("unroll") for (int m = 0; m < 4; ++m) _Pragma("unroll") for (int n = 0; n < 2; ++n) _Pragma("unroll") for (int k = 0; k < 2; ++k) \
;         acc[ai][bj][m][n] = __builtin_amdgcn_mfma_f32_16x16x32_bf16(Bt[n][k], At[m][k], acc[ai][bj][m][n], 0, 0, 0); __builtin_amdgcn_s_setprio(0); } while (0)
; #define PG8_WAIT_V(n) asm volatile("s_waitcnt vmcnt(" #n ")" ::: "memory")
; template <class Epi, class Sched, bool ALIGN_EPI = false, bool SP2 = false>
; __device__ __forceinline__ void gemm_phase(PG8_LAS unsigned char* lds, const Gemm g, const Sched& S, const Epi& E) {
;     ...
;             PG8_LDB(B0, 0, 0); PG8_LDB(B1, 0, 1); PG8_SCHED; PG8_LDA(At, 0, 0); PG8_STAGE(PG8_SA(1, 1), a1 + hstep, voffA);
;             PG8_WAIT_V(8); PG8_WAIT_L(0); PG8_BAR; PG8_MMA(0, 0, At, B0); PG8_MMA(0, 1, At, B1); PG8_BAR; PG8_SCHED;
;             PG8_LDA(At, 0, 1); PG8_STAGE(PG8_SB(0, 0), b2, voffB); PG8_STAGE(PG8_SB(0, 1), b2 + hstep, voffB); PG8_STAGE(PG8_SA(0, 0), a2, voffA);
;             PG8_WAIT_V(8); PG8_WAIT_L(0); PG8_BAR; PG8_MMA(1, 0, At, B0); PG8_MMA(1, 1, At, B1); PG8_BAR; PG8_SCHED;
;             PG8_LDB(B0, 1, 0); PG8_LDB(B1, 1, 1); PG8_SCHED; PG8_LDA(At, 1, 0); PG8_STAGE(PG8_SA(0, 1), a2 + hstep, voffA);
;             PG8_WAIT_V(8); PG8_WAIT_L(0); PG8_BAR; PG8_MMA(0, 0, At, B0); PG8_MMA(0, 1, At, B1); PG8_BAR; PG8_SCHED;
;             PG8_LDA(At, 1, 1); PG8_STAGE(PG8_SB(1, 0), b3, voffB); PG8_STAGE(PG8_SB(1, 1), b3 + hstep, voffB); PG8_STAGE(PG8_SA(1, 0), a3, voffA);
;             PG8_WAIT_V(8); PG8_WAIT_L(0); PG8_BAR; PG8_MMA(1, 0, At, B0); PG8_MMA(1, 1, At, B1); PG8_BAR; PG8_SCHED;
	v_mfma_f32_16x16x32_bf16 v[60:63], v[144:147], v[184:187], 0
	v_mfma_f32_16x16x32_bf16 v[56:59], v[160:163], v[184:187], 0
	v_mfma_f32_16x16x32_bf16 v[44:47], v[144:147], v[192:195], 0
	v_mfma_f32_16x16x32_bf16 v[40:43], v[160:163], v[192:195], 0
	v_mfma_f32_16x16x32_bf16 v[28:31], v[144:147], v[200:203], 0
	v_mfma_f32_16x16x32_bf16 v[24:27], v[160:163], v[200:203], 0
	v_mfma_f32_16x16x32_bf16 v[12:15], v[144:147], v[208:211], 0
	v_mfma_f32_16x16x32_bf16 v[8:11], v[160:163], v[208:211], 0
	v_mfma_f32_16x16x32_bf16 v[60:63], v[156:159], v[188:191], v[60:63]
	v_mfma_f32_16x16x32_bf16 v[56:59], v[164:167], v[188:191], v[56:59]
	v_mfma_f32_16x16x32_bf16 v[44:47], v[156:159], v[196:199], v[44:47]
	v_mfma_f32_16x16x32_bf16 v[40:43], v[164:167], v[196:199], v[40:43]
	v_mfma_f32_16x16x32_bf16 v[28:31], v[156:159], v[204:207], v[28:31]
	v_mfma_f32_16x16x32_bf16 v[24:27], v[164:167], v[204:207], v[24:27]
	v_mfma_f32_16x16x32_bf16 v[12:15], v[156:159], v[212:215], v[12:15]
	v_mfma_f32_16x16x32_bf16 v[8:11], v[164:167], v[212:215], v[8:11]
	v_mfma_f32_16x16x32_bf16 v[52:55], v[168:171], v[184:187], 0
	v_mfma_f32_16x16x32_bf16 v[48:51], v[176:179], v[184:187], 0
	v_mfma_f32_16x16x32_bf16 v[36:39], v[168:171], v[192:195], 0
	v_mfma_f32_16x16x32_bf16 v[32:35], v[176:179], v[192:195], 0
	v_mfma_f32_16x16x32_bf16 v[20:23], v[168:171], v[200:203], 0
	v_mfma_f32_16x16x32_bf16 v[16:19], v[176:179], v[200:203], 0
	v_mfma_f32_16x16x32_bf16 v[4:7], v[168:171], v[208:211], 0
	v_mfma_f32_16x16x32_bf16 v[0:3], v[176:179], v[208:211], 0
	v_mfma_f32_16x16x32_bf16 v[52:55], v[172:175], v[188:191], v[52:55]
	v_mfma_f32_16x16x32_bf16 v[48:51], v[180:183], v[188:191], v[48:51]
	v_mfma_f32_16x16x32_bf16 v[36:39], v[172:175], v[196:199], v[36:39]
	v_mfma_f32_16x16x32_bf16 v[32:35], v[180:183], v[196:199], v[32:35]
	v_mfma_f32_16x16x32_bf16 v[20:23], v[172:175], v[204:207], v[20:23]
	v_mfma_f32_16x16x32_bf16 v[16:19], v[180:183], v[204:207], v[16:19]
	v_mfma_f32_16x16x32_bf16 v[4:7], v[172:175], v[212:215], v[4:7]
	v_mfma_f32_16x16x32_bf16 v[0:3], v[180:183], v[212:215], v[0:3]
	s_barrier
	s_add_i32 s52, 0, 0x18000
	s_add_i32 s53, 0, 0x1c000
	v_add_u32_e32 v164, s52, v151
	v_add_u32_e32 v180, s53, v151
	ds_read_b128 v[144:147], v164
	ds_read_b128 v[156:159], v164 offset:1024
	ds_read_b128 v[160:163], v164 offset:2048
	ds_read_b128 v[164:167], v164 offset:3072
	ds_read_b128 v[168:171], v180
	ds_read_b128 v[172:175], v180 offset:1024
	ds_read_b128 v[176:179], v180 offset:2048
	ds_read_b128 v[180:183], v180 offset:3072
	s_add_u32 s22, s28, 0xb0000
	s_addc_u32 s23, s29, 0
	s_mov_b32 m0, s37
	v_lshl_add_u64 v[222:223], s[22:23], 0, v[128:129]
	ds_read_b128 v[184:187], v155 offset:32768
	ds_read_b128 v[188:191], v155 offset:33792
	ds_read_b128 v[192:195], v155 offset:34816
	ds_read_b128 v[196:199], v155 offset:35840
	ds_read_b128 v[200:203], v155 offset:36864
	ds_read_b128 v[204:207], v155 offset:37888
	ds_read_b128 v[208:211], v155 offset:38912
	ds_read_b128 v[212:215], v155 offset:39936
	global_load_lds_dwordx4 v[222:223], off
	v_lshl_add_u64 v[222:223], s[22:23], 0, v[132:133]
	s_mov_b32 m0, s38
	s_nop 0
	global_load_lds_dwordx4 v[222:223], off
	s_waitcnt vmcnt(8)
	s_waitcnt lgkmcnt(0)
	s_barrier
	v_mfma_f32_16x16x32_bf16 v[124:127], v[144:147], v[184:187], v[124:127]
	v_mfma_f32_16x16x32_bf16 v[120:123], v[160:163], v[184:187], v[120:123]
	v_mfma_f32_16x16x32_bf16 v[108:111], v[144:147], v[192:195], v[108:111]
	v_mfma_f32_16x16x32_bf16 v[104:107], v[160:163], v[192:195], v[104:107]
	v_mfma_f32_16x16x32_bf16 v[92:95], v[144:147], v[200:203], v[92:95]
	v_mfma_f32_16x16x32_bf16 v[88:91], v[160:163], v[200:203], v[88:91]
	v_mfma_f32_16x16x32_bf16 v[76:79], v[144:147], v[208:211], v[76:79]
	v_mfma_f32_16x16x32_bf16 v[72:75], v[160:163], v[208:211], v[72:75]
	v_mfma_f32_16x16x32_bf16 v[124:127], v[156:159], v[188:191], v[124:127]
	v_mfma_f32_16x16x32_bf16 v[120:123], v[164:167], v[188:191], v[120:123]
	v_mfma_f32_16x16x32_bf16 v[108:111], v[156:159], v[196:199], v[108:111]
	v_mfma_f32_16x16x32_bf16 v[104:107], v[164:167], v[196:199], v[104:107]
	v_mfma_f32_16x16x32_bf16 v[92:95], v[156:159], v[204:207], v[92:95]
	v_mfma_f32_16x16x32_bf16 v[88:91], v[164:167], v[204:207], v[88:91]
	v_mfma_f32_16x16x32_bf16 v[76:79], v[156:159], v[212:215], v[76:79]
	v_mfma_f32_16x16x32_bf16 v[72:75], v[164:167], v[212:215], v[72:75]
	v_mfma_f32_16x16x32_bf16 v[116:119], v[168:171], v[184:187], v[116:119]
	v_mfma_f32_16x16x32_bf16 v[112:115], v[176:179], v[184:187], v[112:115]
	v_mfma_f32_16x16x32_bf16 v[100:103], v[168:171], v[192:195], v[100:103]
	v_mfma_f32_16x16x32_bf16 v[96:99], v[176:179], v[192:195], v[96:99]
	v_mfma_f32_16x16x32_bf16 v[84:87], v[168:171], v[200:203], v[84:87]
	v_mfma_f32_16x16x32_bf16 v[80:83], v[176:179], v[200:203], v[80:83]
	v_mfma_f32_16x16x32_bf16 v[68:71], v[168:171], v[208:211], v[68:71]
	v_mfma_f32_16x16x32_bf16 v[64:67], v[176:179], v[208:211], v[64:67]
	v_mfma_f32_16x16x32_bf16 v[116:119], v[172:175], v[188:191], v[116:119]
	v_mfma_f32_16x16x32_bf16 v[112:115], v[180:183], v[188:191], v[112:115]
	v_mfma_f32_16x16x32_bf16 v[100:103], v[172:175], v[196:199], v[100:103]
	v_mfma_f32_16x16x32_bf16 v[96:99], v[180:183], v[196:199], v[96:99]
	v_mfma_f32_16x16x32_bf16 v[84:87], v[172:175], v[204:207], v[84:87]
	v_mfma_f32_16x16x32_bf16 v[80:83], v[180:183], v[204:207], v[80:83]
	v_mfma_f32_16x16x32_bf16 v[68:71], v[172:175], v[212:215], v[68:71]
	v_mfma_f32_16x16x32_bf16 v[64:67], v[180:183], v[212:215], v[64:67]
	s_barrier
; #define PG8_STAGE(bufoff, gbase, voff) do { _Pragma("unroll") for (int _i = 0; _i < 2; ++_i) \
;         __builtin_amdgcn_global_load_lds((const unsigned*)((const char*)(gbase) + (voff)[_i]), (PG8_LAS unsigned*)(lds + (bufoff) + ldsw + _i * 8192), 16, 0, 0); } while (0)
; #define PG8_LDA(dst, b, h) do { _Pragma("unroll") for (int m = 0; m < 4; ++m) _Pragma("unroll") for (int k = 0; k < 2; ++k) dst[m][k] = *(const PG8_LAS bf16x8*)(lds + PG8_SA(b, h) + aoff + m * 2048 + k * 1024); } while (0)
; #define PG8_LDB(dst, b, h) do { _Pragma("unroll") for (int n = 0; n < 2; ++n) _Pragma("unroll") for (int k = 0; k < 2; ++k) dst[n][k] = *(const PG8_LAS bf16x8*)(lds + PG8_SB(b, h) + boff + n * 2048 + k * 1024); } while (0)
; #define PG8_MMA(ai, bj, At, Bt) do { __builtin_amdgcn_s_setprio(1); _Pragma("unroll") for (int m = 0; m < 4; ++m) _Pragma("unroll") for (int n = 0; n < 2; ++n) _Pragma("unroll") for (int k = 0; k < 2; ++k) \
;         acc[ai][bj][m][n] = __builtin_amdgcn_mfma_f32_16x16x32_bf16(Bt[n][k], At[m][k], acc[ai][bj][m][n], 0, 0, 0); __builtin_amdgcn_s_setprio(0); } while (0)
; #define PG8_WAIT_V(n) asm volatile("s_waitcnt vmcnt(" #n ")" ::: "memory")
; template <class Epi, class Sched, bool ALIGN_EPI = false, bool SP2 = false>
; __device__ __forceinline__ void gemm_phase(PG8_LAS unsigned char* lds, const Gemm g, const Sched& S, const Epi& E) {
;     ...
;             PG8_LDB(B0, 0, 0); PG8_LDB(B1, 0, 1); PG8_SCHED; PG8_LDA(At, 0, 0); PG8_STAGE(PG8_SA(1, 1), a1 + hstep, voffA);
;             PG8_WAIT_V(8); PG8_WAIT_L(0); PG8_BAR; PG8_MMA(0, 0, At, B0); PG8_MMA(0, 1, At, B1); PG8_BAR; PG8_SCHED;
;             PG8_LDA(At, 0, 1); PG8_STAGE(PG8_SB(0, 0), b2, voffB); PG8_STAGE(PG8_SB(0, 1), b2 + hstep, voffB); PG8_STAGE(PG8_SA(0, 0), a2, voffA);
;             PG8_WAIT_V(8); PG8_WAIT_L(0); PG8_BAR; PG8_MMA(1, 0, At, B0); PG8_MMA(1, 1, At, B1); PG8_BAR; PG8_SCHED;
;             PG8_LDB(B0, 1, 0); PG8_LDB(B1, 1, 1); PG8_SCHED; PG8_LDA(At, 1, 0); PG8_STAGE(PG8_SA(0, 1), a2 + hstep, voffA);
;             PG8_WAIT_V(8); PG8_WAIT_L(0); PG8_BAR; PG8_MMA(0, 0, At, B0); PG8_MMA(0, 1, At, B1); PG8_BAR; PG8_SCHED;
;             PG8_LDA(At, 1, 1); PG8_STAGE(PG8_SB(1, 0), b3, voffB); PG8_STAGE(PG8_SB(1, 1), b3 + hstep, voffB); PG8_STAGE(PG8_SA(1, 0), a3, voffA);
;             PG8_WAIT_V(8); PG8_WAIT_L(0); PG8_BAR; PG8_MMA(1, 0, At, B0); PG8_MMA(1, 1, At, B1); PG8_BAR; PG8_SCHED;
	s_add_i32 s22, s52, s34
	v_lshl_add_u64 v[148:149], v[148:149], 0, s[6:7]
	s_mov_b32 m0, s22
	ds_read_b128 v[184:187], v155 offset:49152
	ds_read_b128 v[188:191], v155 offset:50176
	ds_read_b128 v[192:195], v155 offset:51200
	ds_read_b128 v[196:199], v155 offset:52224
	ds_read_b128 v[200:203], v155 offset:53248
	ds_read_b128 v[204:207], v155 offset:54272
	ds_read_b128 v[208:211], v155 offset:55296
	ds_read_b128 v[212:215], v155 offset:56320
	global_load_lds_dwordx4 v[148:149], off
	s_add_i32 m0, s22, 0x2000
	s_add_u32 s22, s26, 0xb0080
	v_lshl_add_u64 v[148:149], v[216:217], 0, s[6:7]
	s_addc_u32 s23, s27, 0
	s_add_i32 s26, s53, s34
	global_load_lds_dwordx4 v[148:149], off
	v_lshl_add_u64 v[148:149], s[22:23], 0, v[130:131]
	s_mov_b32 m0, s26
	s_nop 0
	global_load_lds_dwordx4 v[148:149], off
	v_lshl_add_u64 v[148:149], s[22:23], 0, v[134:135]
	s_add_i32 m0, s26, 0x2000
	s_nop 0
	global_load_lds_dwordx4 v[148:149], off
	v_lshl_add_u64 v[148:149], v[218:219], 0, s[6:7]
	s_mov_b32 m0, s40
	s_nop 0
	global_load_lds_dwordx4 v[148:149], off
	v_lshl_add_u64 v[148:149], v[220:221], 0, s[6:7]
	s_mov_b32 m0, s41
	s_nop 0
	global_load_lds_dwordx4 v[148:149], off
	s_waitcnt vmcnt(8)
	s_waitcnt lgkmcnt(0)
	s_barrier
	v_mfma_f32_16x16x32_bf16 v[60:63], v[144:147], v[184:187], v[60:63]
	v_mfma_f32_16x16x32_bf16 v[56:59], v[160:163], v[184:187], v[56:59]
	v_mfma_f32_16x16x32_bf16 v[44:47], v[144:147], v[192:195], v[44:47]
	v_mfma_f32_16x16x32_bf16 v[40:43], v[160:163], v[192:195], v[40:43]
	v_mfma_f32_16x16x32_bf16 v[28:31], v[144:147], v[200:203], v[28:31]
	v_mfma_f32_16x16x32_bf16 v[24:27], v[160:163], v[200:203], v[24:27]
	v_mfma_f32_16x16x32_bf16 v[12:15], v[144:147], v[208:211], v[12:15]
	v_mfma_f32_16x16x32_bf16 v[8:11], v[160:163], v[208:211], v[8:11]
	v_mfma_f32_16x16x32_bf16 v[60:63], v[156:159], v[188:191], v[60:63]
	v_mfma_f32_16x16x32_bf16 v[56:59], v[164:167], v[188:191], v[56:59]
	v_mfma_f32_16x16x32_bf16 v[44:47], v[156:159], v[196:199], v[44:47]
	v_mfma_f32_16x16x32_bf16 v[40:43], v[164:167], v[196:199], v[40:43]
	v_mfma_f32_16x16x32_bf16 v[28:31], v[156:159], v[204:207], v[28:31]
	v_mfma_f32_16x16x32_bf16 v[24:27], v[164:167], v[204:207], v[24:27]
	v_mfma_f32_16x16x32_bf16 v[12:15], v[156:159], v[212:215], v[12:15]
	v_mfma_f32_16x16x32_bf16 v[8:11], v[164:167], v[212:215], v[8:11]
	v_mfma_f32_16x16x32_bf16 v[52:55], v[168:171], v[184:187], v[52:55]
	v_mfma_f32_16x16x32_bf16 v[48:51], v[176:179], v[184:187], v[48:51]
	v_mfma_f32_16x16x32_bf16 v[36:39], v[168:171], v[192:195], v[36:39]
	v_mfma_f32_16x16x32_bf16 v[32:35], v[176:179], v[192:195], v[32:35]
	v_mfma_f32_16x16x32_bf16 v[20:23], v[168:171], v[200:203], v[20:23]
	v_mfma_f32_16x16x32_bf16 v[16:19], v[176:179], v[200:203], v[16:19]
	v_mfma_f32_16x16x32_bf16 v[4:7], v[168:171], v[208:211], v[4:7]
	v_mfma_f32_16x16x32_bf16 v[0:3], v[176:179], v[208:211], v[0:3]
	v_mfma_f32_16x16x32_bf16 v[52:55], v[172:175], v[188:191], v[52:55]
	v_mfma_f32_16x16x32_bf16 v[48:51], v[180:183], v[188:191], v[48:51]
	v_mfma_f32_16x16x32_bf16 v[36:39], v[172:175], v[196:199], v[36:39]
	v_mfma_f32_16x16x32_bf16 v[32:35], v[180:183], v[196:199], v[32:35]
	v_mfma_f32_16x16x32_bf16 v[20:23], v[172:175], v[204:207], v[20:23]
	v_mfma_f32_16x16x32_bf16 v[16:19], v[180:183], v[204:207], v[16:19]
	v_mfma_f32_16x16x32_bf16 v[4:7], v[172:175], v[212:215], v[4:7]
	v_mfma_f32_16x16x32_bf16 v[0:3], v[180:183], v[212:215], v[0:3]
	s_barrier
	s_add_i32 s51, s51, 2
	s_add_u32 s49, s49, 0x100
	s_addc_u32 s50, s50, 0
	s_mov_b64 s[22:23], s[24:25]
.LBB0_862:
	ds_read_b128 v[144:147], v153
	ds_read_b128 v[156:159], v153 offset:1024
	ds_read_b128 v[160:163], v153 offset:2048
	ds_read_b128 v[164:167], v153 offset:3072
	ds_read_b128 v[168:171], v154
	ds_read_b128 v[172:175], v154 offset:1024
	ds_read_b128 v[176:179], v154 offset:2048
	ds_read_b128 v[180:183], v154 offset:3072
	s_add_u32 s24, s22, 0x100
	s_addc_u32 s25, s23, 0
	s_cmp_eq_u32 s51, 40
	s_cselect_b32 s29, s5, s25
	s_cselect_b32 s28, s4, s24
	s_cselect_b32 s27, s21, s50
	s_cselect_b32 s26, s20, s49
	v_lshl_add_u64 v[148:149], s[22:23], 0, v[136:137]
	s_add_i32 m0, s35, 0xc000
	ds_read_b128 v[184:187], v155
	ds_read_b128 v[188:191], v155 offset:1024
	ds_read_b128 v[192:195], v155 offset:2048
	ds_read_b128 v[196:199], v155 offset:3072
	ds_read_b128 v[200:203], v155 offset:4096
	ds_read_b128 v[204:207], v155 offset:5120
	ds_read_b128 v[208:211], v155 offset:6144
	ds_read_b128 v[212:215], v155 offset:7168
	global_load_lds_dwordx4 v[148:149], off
	v_lshl_add_u64 v[148:149], s[22:23], 0, v[138:139]
	s_add_i32 m0, s35, 0xe000
	s_nop 0
	global_load_lds_dwordx4 v[148:149], off
	s_waitcnt vmcnt(8)
	s_waitcnt lgkmcnt(0)
	s_barrier
; #define PG8_STAGE(bufoff, gbase, voff) do { _Pragma("unroll") for (int _i = 0; _i < 2; ++_i) \
;         __builtin_amdgcn_global_load_lds((const unsigned*)((const char*)(gbase) + (voff)[_i]), (PG8_LAS unsigned*)(lds + (bufoff) + ldsw + _i * 8192), 16, 0, 0); } while (0)
; #define PG8_LDA(dst, b, h) do { _Pragma("unroll") for (int m = 0; m < 4; ++m) _Pragma("unroll") for (int k = 0; k < 2; ++k) dst[m][k] = *(const PG8_LAS bf16x8*)(lds + PG8_SA(b, h) + aoff + m * 2048 + k * 1024); } while (0)
; #define PG8_LDB(dst, b, h) do { _Pragma("unroll") for (int n = 0; n < 2; ++n) _Pragma("unroll") for (int k = 0; k < 2; ++k) dst[n][k] = *(const PG8_LAS bf16x8*)(lds + PG8_SB(b, h) + boff + n * 2048 + k * 1024); } while (0)
; #define PG8_MMA(ai, bj, At, Bt) do { __builtin_amdgcn_s_setprio(1); _Pragma("unroll") for (int m = 0; m < 4; ++m) _Pragma("unroll") for (int n = 0; n < 2; ++n) _Pragma("unroll") for (int k = 0; k < 2; ++k) \
;         acc[ai][bj][m][n] = __builtin_amdgcn_mfma_f32_16x16x32_bf16(Bt[n][k], At[m][k], acc[ai][bj][m][n], 0, 0, 0); __builtin_amdgcn_s_setprio(0); } while (0)
; #define PG8_WAIT_V(n) asm volatile("s_waitcnt vmcnt(" #n ")" ::: "memory")
; #define PG8_WAIT_L(n) asm volatile("s_waitcnt lgkmcnt(" #n ")" ::: "memory")
; #define PG8_BAR __builtin_amdgcn_s_barrier()
; #define PG8_SCHED __builtin_amdgcn_sched_barrier(0)
; template <class Epi, class Sched, bool ALIGN_EPI = false, bool SP2 = false>
; __device__ __forceinline__ void gemm_phase(PG8_LAS unsigned char* lds, const Gemm g, const Sched& S, const Epi& E) {
;     ...
;             PG8_LDB(B0, 0, 0); PG8_LDB(B1, 0, 1); PG8_SCHED; PG8_LDA(At, 0, 0); PG8_STAGE(PG8_SA(1, 1), a1 + hstep, voffA);
;             PG8_WAIT_V(8); PG8_WAIT_L(0); PG8_BAR; PG8_MMA(0, 0, At, B0); PG8_MMA(0, 1, At, B1); PG8_BAR; PG8_SCHED;
;             PG8_LDA(At, 0, 1); PG8_STAGE(PG8_SB(0, 0), b2, voffB); PG8_STAGE(PG8_SB(0, 1), b2 + hstep, voffB); PG8_STAGE(PG8_SA(0, 0), a2, voffA);
;             PG8_WAIT_V(8); PG8_WAIT_L(0); PG8_BAR; PG8_MMA(1, 0, At, B0); PG8_MMA(1, 1, At, B1); PG8_BAR; PG8_SCHED;
;             PG8_LDB(B0, 1, 0); PG8_LDB(B1, 1, 1); PG8_SCHED; PG8_LDA(At, 1, 0); PG8_STAGE(PG8_SA(0, 1), a2 + hstep, voffA);
;             PG8_WAIT_V(8); PG8_WAIT_L(0); PG8_BAR; PG8_MMA(0, 0, At, B0); PG8_MMA(0, 1, At, B1); PG8_BAR; PG8_SCHED;
	v_mfma_f32_16x16x32_bf16 v[124:127], v[144:147], v[184:187], v[124:127]
	v_mfma_f32_16x16x32_bf16 v[120:123], v[160:163], v[184:187], v[120:123]
	v_mfma_f32_16x16x32_bf16 v[108:111], v[144:147], v[192:195], v[108:111]
	v_mfma_f32_16x16x32_bf16 v[104:107], v[160:163], v[192:195], v[104:107]
	v_mfma_f32_16x16x32_bf16 v[92:95], v[144:147], v[200:203], v[92:95]
	v_mfma_f32_16x16x32_bf16 v[88:91], v[160:163], v[200:203], v[88:91]
	v_mfma_f32_16x16x32_bf16 v[76:79], v[144:147], v[208:211], v[76:79]
	v_mfma_f32_16x16x32_bf16 v[72:75], v[160:163], v[208:211], v[72:75]
	v_mfma_f32_16x16x32_bf16 v[124:127], v[156:159], v[188:191], v[124:127]
	v_mfma_f32_16x16x32_bf16 v[120:123], v[164:167], v[188:191], v[120:123]
	v_mfma_f32_16x16x32_bf16 v[108:111], v[156:159], v[196:199], v[108:111]
	v_mfma_f32_16x16x32_bf16 v[104:107], v[164:167], v[196:199], v[104:107]
	v_mfma_f32_16x16x32_bf16 v[92:95], v[156:159], v[204:207], v[92:95]
	v_mfma_f32_16x16x32_bf16 v[88:91], v[164:167], v[204:207], v[88:91]
	v_mfma_f32_16x16x32_bf16 v[76:79], v[156:159], v[212:215], v[76:79]
	v_mfma_f32_16x16x32_bf16 v[72:75], v[164:167], v[212:215], v[72:75]
	v_mfma_f32_16x16x32_bf16 v[116:119], v[168:171], v[184:187], v[116:119]
	v_mfma_f32_16x16x32_bf16 v[112:115], v[176:179], v[184:187], v[112:115]
	v_mfma_f32_16x16x32_bf16 v[100:103], v[168:171], v[192:195], v[100:103]
	v_mfma_f32_16x16x32_bf16 v[96:99], v[176:179], v[192:195], v[96:99]
	v_mfma_f32_16x16x32_bf16 v[84:87], v[168:171], v[200:203], v[84:87]
	v_mfma_f32_16x16x32_bf16 v[80:83], v[176:179], v[200:203], v[80:83]
	v_mfma_f32_16x16x32_bf16 v[68:71], v[168:171], v[208:211], v[68:71]
	v_mfma_f32_16x16x32_bf16 v[64:67], v[176:179], v[208:211], v[64:67]
	v_mfma_f32_16x16x32_bf16 v[116:119], v[172:175], v[188:191], v[116:119]
	v_mfma_f32_16x16x32_bf16 v[112:115], v[180:183], v[188:191], v[112:115]
	v_mfma_f32_16x16x32_bf16 v[100:103], v[172:175], v[196:199], v[100:103]
	v_mfma_f32_16x16x32_bf16 v[96:99], v[180:183], v[196:199], v[96:99]
	v_mfma_f32_16x16x32_bf16 v[84:87], v[172:175], v[204:207], v[84:87]
	v_mfma_f32_16x16x32_bf16 v[80:83], v[180:183], v[204:207], v[80:83]
	v_mfma_f32_16x16x32_bf16 v[68:71], v[172:175], v[212:215], v[68:71]
	v_mfma_f32_16x16x32_bf16 v[64:67], v[180:183], v[212:215], v[64:67]
	s_barrier
	s_add_i32 s22, s43, s34
	v_lshl_add_u64 v[148:149], s[26:27], 0, v[130:131]
	s_mov_b32 m0, s22
	ds_read_b128 v[184:187], v155 offset:16384
	ds_read_b128 v[188:191], v155 offset:17408
	ds_read_b128 v[192:195], v155 offset:18432
	ds_read_b128 v[196:199], v155 offset:19456
	ds_read_b128 v[200:203], v155 offset:20480
	ds_read_b128 v[204:207], v155 offset:21504
	ds_read_b128 v[208:211], v155 offset:22528
	ds_read_b128 v[212:215], v155 offset:23552
	global_load_lds_dwordx4 v[148:149], off
	s_add_i32 m0, s22, 0x2000
	s_add_u32 s22, s26, 0xb0000
	v_lshl_add_u64 v[216:217], s[26:27], 0, v[134:135]
	s_addc_u32 s23, s27, 0
	s_add_i32 s52, s44, s34
	global_load_lds_dwordx4 v[216:217], off
	v_lshl_add_u64 v[218:219], s[22:23], 0, v[130:131]
	s_mov_b32 m0, s52
	v_lshl_add_u64 v[220:221], s[28:29], 0, v[132:133]
	global_load_lds_dwordx4 v[218:219], off
	v_lshl_add_u64 v[218:219], s[22:23], 0, v[134:135]
	s_add_i32 m0, s52, 0x2000
	s_nop 0
	global_load_lds_dwordx4 v[218:219], off
	v_lshl_add_u64 v[218:219], s[28:29], 0, v[128:129]
	s_mov_b32 m0, s35
	s_nop 0
	global_load_lds_dwordx4 v[218:219], off
	s_mov_b32 m0, s36
	s_nop 0
	global_load_lds_dwordx4 v[220:221], off
	s_waitcnt vmcnt(8)
	s_waitcnt lgkmcnt(0)
	s_barrier
	v_mfma_f32_16x16x32_bf16 v[60:63], v[144:147], v[184:187], v[60:63]
	v_mfma_f32_16x16x32_bf16 v[56:59], v[160:163], v[184:187], v[56:59]
	v_mfma_f32_16x16x32_bf16 v[44:47], v[144:147], v[192:195], v[44:47]
	v_mfma_f32_16x16x32_bf16 v[40:43], v[160:163], v[192:195], v[40:43]
	v_mfma_f32_16x16x32_bf16 v[28:31], v[144:147], v[200:203], v[28:31]
	v_mfma_f32_16x16x32_bf16 v[24:27], v[160:163], v[200:203], v[24:27]
	v_mfma_f32_16x16x32_bf16 v[12:15], v[144:147], v[208:211], v[12:15]
	v_mfma_f32_16x16x32_bf16 v[8:11], v[160:163], v[208:211], v[8:11]
	v_mfma_f32_16x16x32_bf16 v[60:63], v[156:159], v[188:191], v[60:63]
	v_mfma_f32_16x16x32_bf16 v[56:59], v[164:167], v[188:191], v[56:59]
	v_mfma_f32_16x16x32_bf16 v[44:47], v[156:159], v[196:199], v[44:47]
	v_mfma_f32_16x16x32_bf16 v[40:43], v[164:167], v[196:199], v[40:43]
	v_mfma_f32_16x16x32_bf16 v[28:31], v[156:159], v[204:207], v[28:31]
	v_mfma_f32_16x16x32_bf16 v[24:27], v[164:167], v[204:207], v[24:27]
	v_mfma_f32_16x16x32_bf16 v[12:15], v[156:159], v[212:215], v[12:15]
	v_mfma_f32_16x16x32_bf16 v[8:11], v[164:167], v[212:215], v[8:11]
	v_mfma_f32_16x16x32_bf16 v[52:55], v[168:171], v[184:187], v[52:55]
	v_mfma_f32_16x16x32_bf16 v[48:51], v[176:179], v[184:187], v[48:51]
	v_mfma_f32_16x16x32_bf16 v[36:39], v[168:171], v[192:195], v[36:39]
	v_mfma_f32_16x16x32_bf16 v[32:35], v[176:179], v[192:195], v[32:35]
	v_mfma_f32_16x16x32_bf16 v[20:23], v[168:171], v[200:203], v[20:23]
	v_mfma_f32_16x16x32_bf16 v[16:19], v[176:179], v[200:203], v[16:19]
	v_mfma_f32_16x16x32_bf16 v[4:7], v[168:171], v[208:211], v[4:7]
	v_mfma_f32_16x16x32_bf16 v[0:3], v[176:179], v[208:211], v[0:3]
	v_mfma_f32_16x16x32_bf16 v[52:55], v[172:175], v[188:191], v[52:55]
	v_mfma_f32_16x16x32_bf16 v[48:51], v[180:183], v[188:191], v[48:51]
	v_mfma_f32_16x16x32_bf16 v[36:39], v[172:175], v[196:199], v[36:39]
	v_mfma_f32_16x16x32_bf16 v[32:35], v[180:183], v[196:199], v[32:35]
	v_mfma_f32_16x16x32_bf16 v[20:23], v[172:175], v[204:207], v[20:23]
	v_mfma_f32_16x16x32_bf16 v[16:19], v[180:183], v[204:207], v[16:19]
	v_mfma_f32_16x16x32_bf16 v[4:7], v[172:175], v[212:215], v[4:7]
	v_mfma_f32_16x16x32_bf16 v[0:3], v[180:183], v[212:215], v[0:3]
	s_barrier
; #define PG8_STAGE(bufoff, gbase, voff) do { _Pragma("unroll") for (int _i = 0; _i < 2; ++_i) \
;         __builtin_amdgcn_global_load_lds((const unsigned*)((const char*)(gbase) + (voff)[_i]), (PG8_LAS unsigned*)(lds + (bufoff) + ldsw + _i * 8192), 16, 0, 0); } while (0)
; #define PG8_LDA(dst, b, h) do { _Pragma("unroll") for (int m = 0; m < 4; ++m) _Pragma("unroll") for (int k = 0; k < 2; ++k) dst[m][k] = *(const PG8_LAS bf16x8*)(lds + PG8_SA(b, h) + aoff + m * 2048 + k * 1024); } while (0)
; #define PG8_LDB(dst, b, h) do { _Pragma("unroll") for (int n = 0; n < 2; ++n) _Pragma("unroll") for (int k = 0; k < 2; ++k) dst[n][k] = *(const PG8_LAS bf16x8*)(lds + PG8_SB(b, h) + boff + n * 2048 + k * 1024); } while (0)
; #define PG8_MMA(ai, bj, At, Bt) do { __builtin_amdgcn_s_setprio(1); _Pragma("unroll") for (int m = 0; m < 4; ++m) _Pragma("unroll") for (int n = 0; n < 2; ++n) _Pragma("unroll") for (int k = 0; k < 2; ++k) \
;         acc[ai][bj][m][n] = __builtin_amdgcn_mfma_f32_16x16x32_bf16(Bt[n][k], At[m][k], acc[ai][bj][m][n], 0, 0, 0); __builtin_amdgcn_s_setprio(0); } while (0)
; #define PG8_WAIT_V(n) asm volatile("s_waitcnt vmcnt(" #n ")" ::: "memory")
; #define PG8_WAIT_L(n) asm volatile("s_waitcnt lgkmcnt(" #n ")" ::: "memory")
; #define PG8_BAR __builtin_amdgcn_s_barrier()
; #define PG8_SCHED __builtin_amdgcn_sched_barrier(0)
; template <class Epi, class Sched, bool ALIGN_EPI = false, bool SP2 = false>
; __device__ __forceinline__ void gemm_phase(PG8_LAS unsigned char* lds, const Gemm g, const Sched& S, const Epi& E) {
;     ...
;             PG8_LDB(B0, 1, 0); PG8_LDB(B1, 1, 1); PG8_SCHED; PG8_LDA(At, 1, 0); PG8_STAGE(PG8_SA(0, 1), a2 + hstep, voffA);
;             PG8_WAIT_V(8); PG8_WAIT_L(0); PG8_BAR; PG8_MMA(0, 0, At, B0); PG8_MMA(0, 1, At, B1); PG8_BAR; PG8_SCHED;
;             PG8_LDA(At, 1, 1); PG8_STAGE(PG8_SB(1, 0), b3, voffB); PG8_STAGE(PG8_SB(1, 1), b3 + hstep, voffB); PG8_STAGE(PG8_SA(1, 0), a3, voffA);
;             PG8_WAIT_V(8); PG8_WAIT_L(0); PG8_BAR; PG8_MMA(1, 0, At, B0); PG8_MMA(1, 1, At, B1); PG8_BAR; PG8_SCHED;
	s_add_i32 s52, 0, 0x18000
	s_add_i32 s53, 0, 0x1c000
	v_add_u32_e32 v164, s52, v151
	v_add_u32_e32 v180, s53, v151
	ds_read_b128 v[144:147], v164
	ds_read_b128 v[156:159], v164 offset:1024
	ds_read_b128 v[160:163], v164 offset:2048
	ds_read_b128 v[164:167], v164 offset:3072
	ds_read_b128 v[168:171], v180
	ds_read_b128 v[172:175], v180 offset:1024
	ds_read_b128 v[176:179], v180 offset:2048
	ds_read_b128 v[180:183], v180 offset:3072
	s_add_u32 s22, s28, 0xb0000
	s_addc_u32 s23, s29, 0
	s_mov_b32 m0, s37
	v_lshl_add_u64 v[222:223], s[22:23], 0, v[128:129]
	ds_read_b128 v[184:187], v155 offset:32768
	ds_read_b128 v[188:191], v155 offset:33792
	ds_read_b128 v[192:195], v155 offset:34816
	ds_read_b128 v[196:199], v155 offset:35840
	ds_read_b128 v[200:203], v155 offset:36864
	ds_read_b128 v[204:207], v155 offset:37888
	ds_read_b128 v[208:211], v155 offset:38912
	ds_read_b128 v[212:215], v155 offset:39936
	global_load_lds_dwordx4 v[222:223], off
	v_lshl_add_u64 v[222:223], s[22:23], 0, v[132:133]
	s_mov_b32 m0, s38
	s_nop 0
	global_load_lds_dwordx4 v[222:223], off
	s_waitcnt vmcnt(8)
	s_waitcnt lgkmcnt(0)
	s_barrier
	v_mfma_f32_16x16x32_bf16 v[124:127], v[144:147], v[184:187], v[124:127]
	v_mfma_f32_16x16x32_bf16 v[120:123], v[160:163], v[184:187], v[120:123]
	v_mfma_f32_16x16x32_bf16 v[108:111], v[144:147], v[192:195], v[108:111]
	v_mfma_f32_16x16x32_bf16 v[104:107], v[160:163], v[192:195], v[104:107]
	v_mfma_f32_16x16x32_bf16 v[92:95], v[144:147], v[200:203], v[92:95]
	v_mfma_f32_16x16x32_bf16 v[88:91], v[160:163], v[200:203], v[88:91]
	v_mfma_f32_16x16x32_bf16 v[76:79], v[144:147], v[208:211], v[76:79]
	v_mfma_f32_16x16x32_bf16 v[72:75], v[160:163], v[208:211], v[72:75]
	v_mfma_f32_16x16x32_bf16 v[124:127], v[156:159], v[188:191], v[124:127]
	v_mfma_f32_16x16x32_bf16 v[120:123], v[164:167], v[188:191], v[120:123]
	v_mfma_f32_16x16x32_bf16 v[108:111], v[156:159], v[196:199], v[108:111]
	v_mfma_f32_16x16x32_bf16 v[104:107], v[164:167], v[196:199], v[104:107]
	v_mfma_f32_16x16x32_bf16 v[92:95], v[156:159], v[204:207], v[92:95]
	v_mfma_f32_16x16x32_bf16 v[88:91], v[164:167], v[204:207], v[88:91]
	v_mfma_f32_16x16x32_bf16 v[76:79], v[156:159], v[212:215], v[76:79]
	v_mfma_f32_16x16x32_bf16 v[72:75], v[164:167], v[212:215], v[72:75]
	v_mfma_f32_16x16x32_bf16 v[116:119], v[168:171], v[184:187], v[116:119]
	v_mfma_f32_16x16x32_bf16 v[112:115], v[176:179], v[184:187], v[112:115]
	v_mfma_f32_16x16x32_bf16 v[100:103], v[168:171], v[192:195], v[100:103]
	v_mfma_f32_16x16x32_bf16 v[96:99], v[176:179], v[192:195], v[96:99]
	v_mfma_f32_16x16x32_bf16 v[84:87], v[168:171], v[200:203], v[84:87]
	v_mfma_f32_16x16x32_bf16 v[80:83], v[176:179], v[200:203], v[80:83]
	v_mfma_f32_16x16x32_bf16 v[68:71], v[168:171], v[208:211], v[68:71]
	v_mfma_f32_16x16x32_bf16 v[64:67], v[176:179], v[208:211], v[64:67]
	v_mfma_f32_16x16x32_bf16 v[116:119], v[172:175], v[188:191], v[116:119]
	v_mfma_f32_16x16x32_bf16 v[112:115], v[180:183], v[188:191], v[112:115]
	v_mfma_f32_16x16x32_bf16 v[100:103], v[172:175], v[196:199], v[100:103]
	v_mfma_f32_16x16x32_bf16 v[96:99], v[180:183], v[196:199], v[96:99]
	v_mfma_f32_16x16x32_bf16 v[84:87], v[172:175], v[204:207], v[84:87]
	v_mfma_f32_16x16x32_bf16 v[80:83], v[180:183], v[204:207], v[80:83]
	v_mfma_f32_16x16x32_bf16 v[68:71], v[172:175], v[212:215], v[68:71]
	v_mfma_f32_16x16x32_bf16 v[64:67], v[180:183], v[212:215], v[64:67]
	s_barrier
	s_add_i32 s22, s52, s34
	v_lshl_add_u64 v[148:149], v[148:149], 0, s[6:7]
	s_mov_b32 m0, s22
	ds_read_b128 v[184:187], v155 offset:49152
	ds_read_b128 v[188:191], v155 offset:50176
	ds_read_b128 v[192:195], v155 offset:51200
	ds_read_b128 v[196:199], v155 offset:52224
	ds_read_b128 v[200:203], v155 offset:53248
	ds_read_b128 v[204:207], v155 offset:54272
	ds_read_b128 v[208:211], v155 offset:55296
	ds_read_b128 v[212:215], v155 offset:56320
	global_load_lds_dwordx4 v[148:149], off
	s_add_i32 m0, s22, 0x2000
	s_add_u32 s22, s26, 0xb0080
	v_lshl_add_u64 v[148:149], v[216:217], 0, s[6:7]
	s_addc_u32 s23, s27, 0
	s_add_i32 s26, s53, s34
	global_load_lds_dwordx4 v[148:149], off
	v_lshl_add_u64 v[148:149], s[22:23], 0, v[130:131]
	s_mov_b32 m0, s26
	s_nop 0
	global_load_lds_dwordx4 v[148:149], off
	v_lshl_add_u64 v[148:149], s[22:23], 0, v[134:135]
	s_add_i32 m0, s26, 0x2000
	s_nop 0
	global_load_lds_dwordx4 v[148:149], off
	v_lshl_add_u64 v[148:149], v[218:219], 0, s[6:7]
	s_mov_b32 m0, s40
	s_nop 0
	global_load_lds_dwordx4 v[148:149], off
	v_lshl_add_u64 v[148:149], v[220:221], 0, s[6:7]
	s_mov_b32 m0, s41
	s_nop 0
	global_load_lds_dwordx4 v[148:149], off
	s_waitcnt vmcnt(8)
	s_waitcnt lgkmcnt(0)
	s_barrier
	v_mfma_f32_16x16x32_bf16 v[60:63], v[144:147], v[184:187], v[60:63]
	v_mfma_f32_16x16x32_bf16 v[56:59], v[160:163], v[184:187], v[56:59]
	v_mfma_f32_16x16x32_bf16 v[44:47], v[144:147], v[192:195], v[44:47]
	v_mfma_f32_16x16x32_bf16 v[40:43], v[160:163], v[192:195], v[40:43]
	v_mfma_f32_16x16x32_bf16 v[28:31], v[144:147], v[200:203], v[28:31]
	v_mfma_f32_16x16x32_bf16 v[24:27], v[160:163], v[200:203], v[24:27]
	v_mfma_f32_16x16x32_bf16 v[12:15], v[144:147], v[208:211], v[12:15]
	v_mfma_f32_16x16x32_bf16 v[8:11], v[160:163], v[208:211], v[8:11]
	v_mfma_f32_16x16x32_bf16 v[60:63], v[156:159], v[188:191], v[60:63]
	v_mfma_f32_16x16x32_bf16 v[56:59], v[164:167], v[188:191], v[56:59]
	v_mfma_f32_16x16x32_bf16 v[44:47], v[156:159], v[196:199], v[44:47]
	v_mfma_f32_16x16x32_bf16 v[40:43], v[164:167], v[196:199], v[40:43]
	v_mfma_f32_16x16x32_bf16 v[28:31], v[156:159], v[204:207], v[28:31]
	v_mfma_f32_16x16x32_bf16 v[24:27], v[164:167], v[204:207], v[24:27]
	v_mfma_f32_16x16x32_bf16 v[12:15], v[156:159], v[212:215], v[12:15]
	v_mfma_f32_16x16x32_bf16 v[8:11], v[164:167], v[212:215], v[8:11]
	v_mfma_f32_16x16x32_bf16 v[52:55], v[168:171], v[184:187], v[52:55]
	v_mfma_f32_16x16x32_bf16 v[48:51], v[176:179], v[184:187], v[48:51]
	v_mfma_f32_16x16x32_bf16 v[36:39], v[168:171], v[192:195], v[36:39]
	v_mfma_f32_16x16x32_bf16 v[32:35], v[176:179], v[192:195], v[32:35]
	v_mfma_f32_16x16x32_bf16 v[20:23], v[168:171], v[200:203], v[20:23]
	v_mfma_f32_16x16x32_bf16 v[16:19], v[176:179], v[200:203], v[16:19]
	v_mfma_f32_16x16x32_bf16 v[4:7], v[168:171], v[208:211], v[4:7]
	v_mfma_f32_16x16x32_bf16 v[0:3], v[176:179], v[208:211], v[0:3]
	v_mfma_f32_16x16x32_bf16 v[52:55], v[172:175], v[188:191], v[52:55]
	v_mfma_f32_16x16x32_bf16 v[48:51], v[180:183], v[188:191], v[48:51]
	v_mfma_f32_16x16x32_bf16 v[36:39], v[172:175], v[196:199], v[36:39]
	v_mfma_f32_16x16x32_bf16 v[32:35], v[180:183], v[196:199], v[32:35]
	v_mfma_f32_16x16x32_bf16 v[20:23], v[172:175], v[204:207], v[20:23]
	v_mfma_f32_16x16x32_bf16 v[16:19], v[180:183], v[204:207], v[16:19]
	v_mfma_f32_16x16x32_bf16 v[4:7], v[172:175], v[212:215], v[4:7]
	v_mfma_f32_16x16x32_bf16 v[0:3], v[180:183], v[212:215], v[0:3]
	s_barrier
	s_add_i32 s51, s51, 2
	s_add_u32 s49, s49, 0x100
	s_addc_u32 s50, s50, 0
	s_cmp_gt_u32 s51, 41
	s_mov_b64 s[22:23], s[24:25]
	s_cbranch_scc0 .LBB0_862
	s_and_b64 vcc, exec, s[10:11]
	s_cbranch_vccz .LBB0_865
	s_barrier
